# opt19
# speedup vs baseline: 1.0015x; 1.0015x over previous
.Lpf1_join:
	s_add_i32 s0, s71, 0x18000
	s_add_i32 s1, s71, 0x1a000
	s_mov_b32 s6, s58
	s_mov_b32 s7, s59
	v_and_b32_e32 v2, 15, v133
	v_lshlrev_b32_e32 v0, 12, v0
	v_and_b32_e32 v126, 0x3000, v0
	v_lshlrev_b32_e32 v0, 6, v2
	v_lshlrev_b32_e32 v2, 2, v133
	v_and_b32_e32 v26, 48, v133
	v_and_b32_e32 v27, 32, v2
	v_bitop3_b32 v127, v0, v27, v26 bitop3:0x36
	s_add_i32 s69, 0, 0x10000
	v_add_u32_e32 v0, s69, v127
	v_add_u32_e32 v139, v0, v126
	s_barrier
	ds_read_b128 v[2:5], v139
	ds_read_b128 v[6:9], v139 offset:1024
	ds_read_b128 v[10:13], v139 offset:2048
	ds_read_b128 v[14:17], v139 offset:3072
	v_lshlrev_b32_e32 v0, 13, v1
	v_add_u32_e32 v1, 0, v127
	v_add_u32_e32 v134, v1, v0
	v_lshlrev_b32_e32 v1, 6, v133
	s_movk_i32 s70, 0x3c0
	v_and_or_b32 v1, v1, s70, v26
	v_xad_u32 v1, v1, v27, 0
	v_or_b32_e32 v26, 0x800, v0
	v_or_b32_e32 v34, 0x1000, v0
	v_or_b32_e32 v0, 0x1800, v0
	s_add_i32 s88, s71, 0xc000
	v_add_u32_e32 v135, v1, v26
	v_add_u32_e32 v136, v1, v34
	v_add_u32_e32 v137, v1, v0
	s_mov_b32 m0, s88
	s_add_i32 s87, s71, 0xe000
	ds_read_b128 v[18:21], v134
	ds_read_b128 v[22:25], v134 offset:1024
	ds_read_b128 v[26:29], v135
	ds_read_b128 v[30:33], v135 offset:1024
	ds_read_b128 v[34:37], v136
	ds_read_b128 v[38:41], v136 offset:1024
	ds_read_b128 v[42:45], v137
	ds_read_b128 v[46:49], v137 offset:1024
	buffer_load_dwordx4 v138, s[56:59], s17 offen lds
	s_mov_b32 m0, s87
	s_nop 0
	buffer_load_dwordx4 v138, s[56:59], s18 offen lds
	s_waitcnt lgkmcnt(8)
	s_barrier
	s_waitcnt lgkmcnt(0)
	s_setprio 0
	s_waitcnt lgkmcnt(7)
	v_mfma_f32_16x16x32_bf16 v[50:53], v[18:21], v[2:5], 0
	v_mfma_f32_16x16x32_bf16 v[54:57], v[18:21], v[10:13], 0
	s_waitcnt lgkmcnt(5)
	v_mfma_f32_16x16x32_bf16 v[58:61], v[26:29], v[2:5], 0
	v_mfma_f32_16x16x32_bf16 v[62:65], v[26:29], v[10:13], 0
	s_waitcnt lgkmcnt(3)
	v_mfma_f32_16x16x32_bf16 v[66:69], v[34:37], v[2:5], 0
	v_mfma_f32_16x16x32_bf16 v[70:73], v[34:37], v[10:13], 0
	s_waitcnt lgkmcnt(1)
	v_mfma_f32_16x16x32_bf16 v[74:77], v[42:45], v[2:5], 0
	v_mfma_f32_16x16x32_bf16 v[78:81], v[42:45], v[10:13], 0
	v_mfma_f32_16x16x32_bf16 v[50:53], v[22:25], v[6:9], v[50:53]
	v_mfma_f32_16x16x32_bf16 v[54:57], v[22:25], v[14:17], v[54:57]
	v_mfma_f32_16x16x32_bf16 v[58:61], v[30:33], v[6:9], v[58:61]
	v_mfma_f32_16x16x32_bf16 v[62:65], v[30:33], v[14:17], v[62:65]
	v_mfma_f32_16x16x32_bf16 v[66:69], v[38:41], v[6:9], v[66:69]
	v_mfma_f32_16x16x32_bf16 v[70:73], v[38:41], v[14:17], v[70:73]
	s_waitcnt lgkmcnt(0)
	v_mfma_f32_16x16x32_bf16 v[74:77], v[46:49], v[6:9], v[74:77]
	v_mfma_f32_16x16x32_bf16 v[78:81], v[46:49], v[14:17], v[78:81]
	s_setprio 1
	s_barrier
	s_add_i32 s70, 0, 0x14000
	v_add_u32_e32 v0, s70, v127
	v_add_u32_e32 v140, v0, v126
	s_mov_b32 m0, s74
	ds_read_b128 v[82:85], v140
	ds_read_b128 v[86:89], v140 offset:1024
	ds_read_b128 v[90:93], v140 offset:2048
	ds_read_b128 v[94:97], v140 offset:3072
	buffer_load_dwordx4 v138, s[4:7], s19 offen lds
	s_mov_b32 m0, s75
	s_nop 0
	buffer_load_dwordx4 v138, s[4:7], s24 offen lds
	s_barrier
	s_waitcnt lgkmcnt(0)
	s_setprio 0
	s_waitcnt lgkmcnt(3)
	v_mfma_f32_16x16x32_bf16 v[98:101], v[18:21], v[82:85], 0
	s_waitcnt lgkmcnt(1)
	v_mfma_f32_16x16x32_bf16 v[18:21], v[18:21], v[90:93], 0
	s_waitcnt lgkmcnt(0)
	v_mfma_f32_16x16x32_bf16 v[102:105], v[22:25], v[94:97], v[18:21]
	v_mfma_f32_16x16x32_bf16 v[18:21], v[26:29], v[82:85], 0
	v_mfma_f32_16x16x32_bf16 v[106:109], v[30:33], v[86:89], v[18:21]
	v_mfma_f32_16x16x32_bf16 v[18:21], v[26:29], v[90:93], 0
	v_mfma_f32_16x16x32_bf16 v[110:113], v[30:33], v[94:97], v[18:21]
	v_mfma_f32_16x16x32_bf16 v[18:21], v[34:37], v[82:85], 0
	v_mfma_f32_16x16x32_bf16 v[114:117], v[38:41], v[86:89], v[18:21]
	v_mfma_f32_16x16x32_bf16 v[18:21], v[34:37], v[90:93], 0
	v_mfma_f32_16x16x32_bf16 v[32:35], v[38:41], v[94:97], v[18:21]
	v_mfma_f32_16x16x32_bf16 v[18:21], v[42:45], v[82:85], 0
	v_mfma_f32_16x16x32_bf16 v[36:39], v[46:49], v[86:89], v[18:21]
	v_mfma_f32_16x16x32_bf16 v[18:21], v[42:45], v[90:93], 0
	v_mfma_f32_16x16x32_bf16 v[98:101], v[22:25], v[86:89], v[98:101]
	v_mfma_f32_16x16x32_bf16 v[118:121], v[46:49], v[94:97], v[18:21]
	s_setprio 1
	s_mov_b32 m0, s71
	s_barrier
	s_nop 2
	ds_read_b128 v[18:21], v134 offset:16384
	ds_read_b128 v[22:25], v134 offset:17408
	ds_read_b128 v[26:29], v135 offset:16384
	ds_read_b128 v[40:43], v135 offset:17408
	ds_read_b128 v[44:47], v136 offset:16384
	ds_read_b128 v[122:125], v136 offset:17408
	ds_read_b128 v[142:145], v137 offset:16384
	ds_read_b128 v[146:149], v137 offset:17408
	buffer_load_dwordx4 v138, s[56:59], s19 offen lds
	s_mov_b32 m0, s76
	s_nop 0
	buffer_load_dwordx4 v138, s[56:59], s24 offen lds
	s_barrier
	s_waitcnt lgkmcnt(0)
	s_setprio 0
	s_waitcnt lgkmcnt(7)
	v_mfma_f32_16x16x32_bf16 v[150:153], v[18:21], v[2:5], 0
	s_waitcnt lgkmcnt(5)
	v_mfma_f32_16x16x32_bf16 v[158:161], v[26:29], v[2:5], 0
	s_waitcnt lgkmcnt(3)
	v_mfma_f32_16x16x32_bf16 v[166:169], v[44:47], v[2:5], 0
	s_waitcnt lgkmcnt(1)
	v_mfma_f32_16x16x32_bf16 v[0:3], v[142:145], v[2:5], 0
	v_mfma_f32_16x16x32_bf16 v[154:157], v[18:21], v[10:13], 0
	v_mfma_f32_16x16x32_bf16 v[162:165], v[26:29], v[10:13], 0
	v_mfma_f32_16x16x32_bf16 v[170:173], v[44:47], v[10:13], 0
	s_waitcnt lgkmcnt(0)
	v_mfma_f32_16x16x32_bf16 v[174:177], v[146:149], v[6:9], v[0:3]
	v_mfma_f32_16x16x32_bf16 v[0:3], v[142:145], v[10:13], 0
	v_mfma_f32_16x16x32_bf16 v[150:153], v[22:25], v[6:9], v[150:153]
	v_mfma_f32_16x16x32_bf16 v[154:157], v[22:25], v[14:17], v[154:157]
	v_mfma_f32_16x16x32_bf16 v[158:161], v[40:43], v[6:9], v[158:161]
	v_mfma_f32_16x16x32_bf16 v[162:165], v[40:43], v[14:17], v[162:165]
	v_mfma_f32_16x16x32_bf16 v[166:169], v[122:125], v[6:9], v[166:169]
	v_mfma_f32_16x16x32_bf16 v[170:173], v[122:125], v[14:17], v[170:173]
	v_mfma_f32_16x16x32_bf16 v[178:181], v[146:149], v[14:17], v[0:3]
	s_setprio 1
	s_barrier
	s_mov_b32 m0, s78
	s_nop 0
	buffer_load_dwordx4 v138, s[4:7], s25 offen lds
	s_mov_b32 m0, s79
	s_nop 0
	buffer_load_dwordx4 v138, s[4:7], s26 offen lds
	s_waitcnt vmcnt(6)
	s_barrier
	s_setprio 0
	v_mfma_f32_16x16x32_bf16 v[0:3], v[18:21], v[82:85], 0
	v_mfma_f32_16x16x32_bf16 v[182:185], v[22:25], v[86:89], v[0:3]
	v_mfma_f32_16x16x32_bf16 v[0:3], v[18:21], v[90:93], 0
	v_mfma_f32_16x16x32_bf16 v[186:189], v[22:25], v[94:97], v[0:3]
	v_mfma_f32_16x16x32_bf16 v[0:3], v[26:29], v[82:85], 0
	v_mfma_f32_16x16x32_bf16 v[194:197], v[40:43], v[86:89], v[0:3]
	v_mfma_f32_16x16x32_bf16 v[0:3], v[26:29], v[90:93], 0
	v_mfma_f32_16x16x32_bf16 v[198:201], v[40:43], v[94:97], v[0:3]
	v_mfma_f32_16x16x32_bf16 v[0:3], v[44:47], v[82:85], 0
	v_mfma_f32_16x16x32_bf16 v[202:205], v[122:125], v[86:89], v[0:3]
	v_mfma_f32_16x16x32_bf16 v[0:3], v[44:47], v[90:93], 0
	v_mfma_f32_16x16x32_bf16 v[206:209], v[122:125], v[94:97], v[0:3]
	v_mfma_f32_16x16x32_bf16 v[0:3], v[142:145], v[82:85], 0
	v_mfma_f32_16x16x32_bf16 v[210:213], v[146:149], v[86:89], v[0:3]
	v_mfma_f32_16x16x32_bf16 v[0:3], v[142:145], v[90:93], 0
	v_mfma_f32_16x16x32_bf16 v[144:147], v[146:149], v[94:97], v[0:3]
	s_setprio 1
	s_nop 5
	v_add_u32_e32 v0, s97, v127
	v_add_u32_e32 v141, v0, v126
	s_barrier
	ds_read_b128 v[122:125], v141
	ds_read_b128 v[214:217], v141 offset:1024
	ds_read_b128 v[218:221], v141 offset:2048
	ds_read_b128 v[222:225], v141 offset:3072
	s_mov_b32 m0, s81
	ds_read_b128 v[40:43], v134 offset:32768
	ds_read_b128 v[44:47], v134 offset:33792
	ds_read_b128 v[82:85], v135 offset:32768
	ds_read_b128 v[86:89], v135 offset:33792
	ds_read_b128 v[90:93], v136 offset:32768
	ds_read_b128 v[94:97], v136 offset:33792
	ds_read_b128 v[226:229], v137 offset:32768
	ds_read_b128 v[230:233], v137 offset:33792
	buffer_load_dwordx4 v138, s[56:59], s25 offen lds
	s_mov_b32 m0, s82
	s_nop 0
	buffer_load_dwordx4 v138, s[56:59], s26 offen lds
	s_waitcnt lgkmcnt(8)
	s_barrier
	s_waitcnt lgkmcnt(0)
	s_setprio 0
	s_waitcnt lgkmcnt(7)
	v_mfma_f32_16x16x32_bf16 v[0:3], v[40:43], v[122:125], v[50:53]
	s_waitcnt lgkmcnt(6)
	v_mfma_f32_16x16x32_bf16 v[28:31], v[44:47], v[214:217], v[0:3]
	v_mfma_f32_16x16x32_bf16 v[0:3], v[40:43], v[218:221], v[54:57]
	v_mfma_f32_16x16x32_bf16 v[24:27], v[44:47], v[222:225], v[0:3]
	s_waitcnt lgkmcnt(5)
	v_mfma_f32_16x16x32_bf16 v[0:3], v[82:85], v[122:125], v[58:61]
	s_waitcnt lgkmcnt(4)
	v_mfma_f32_16x16x32_bf16 v[20:23], v[86:89], v[214:217], v[0:3]
	v_mfma_f32_16x16x32_bf16 v[0:3], v[82:85], v[218:221], v[62:65]
	v_mfma_f32_16x16x32_bf16 v[16:19], v[86:89], v[222:225], v[0:3]
	s_waitcnt lgkmcnt(3)
	v_mfma_f32_16x16x32_bf16 v[0:3], v[90:93], v[122:125], v[66:69]
	s_waitcnt lgkmcnt(2)
	v_mfma_f32_16x16x32_bf16 v[12:15], v[94:97], v[214:217], v[0:3]
	v_mfma_f32_16x16x32_bf16 v[0:3], v[90:93], v[218:221], v[70:73]
	v_mfma_f32_16x16x32_bf16 v[8:11], v[94:97], v[222:225], v[0:3]
	s_waitcnt lgkmcnt(1)
	v_mfma_f32_16x16x32_bf16 v[0:3], v[226:229], v[122:125], v[74:77]
	s_waitcnt lgkmcnt(0)
	v_mfma_f32_16x16x32_bf16 v[4:7], v[230:233], v[214:217], v[0:3]
	v_mfma_f32_16x16x32_bf16 v[0:3], v[226:229], v[218:221], v[78:81]
	v_mfma_f32_16x16x32_bf16 v[0:3], v[230:233], v[222:225], v[0:3]
	s_setprio 1
	s_barrier
	v_add_u32_e32 v48, s68, v127
	v_add_u32_e32 v142, v48, v126
	s_mov_b32 m0, s0
	ds_read_b128 v[234:237], v142
	ds_read_b128 v[238:241], v142 offset:1024
	ds_read_b128 v[242:245], v142 offset:2048
	ds_read_b128 v[246:249], v142 offset:3072
	buffer_load_dwordx4 v138, s[4:7], s27 offen lds
	s_mov_b32 m0, s1
	s_nop 0
	buffer_load_dwordx4 v138, s[4:7], s28 offen lds
	s_barrier
	s_waitcnt lgkmcnt(0)
	s_setprio 0
	s_waitcnt lgkmcnt(3)
	v_mfma_f32_16x16x32_bf16 v[48:51], v[40:43], v[234:237], v[98:101]
	s_waitcnt lgkmcnt(1)
	v_mfma_f32_16x16x32_bf16 v[40:43], v[40:43], v[242:245], v[102:105]
	s_waitcnt lgkmcnt(0)
	v_mfma_f32_16x16x32_bf16 v[56:59], v[44:47], v[246:249], v[40:43]
	v_mfma_f32_16x16x32_bf16 v[40:43], v[82:85], v[234:237], v[106:109]
	v_mfma_f32_16x16x32_bf16 v[52:55], v[86:89], v[238:241], v[40:43]
	v_mfma_f32_16x16x32_bf16 v[40:43], v[82:85], v[242:245], v[110:113]
	v_mfma_f32_16x16x32_bf16 v[60:63], v[44:47], v[238:241], v[48:51]
	v_mfma_f32_16x16x32_bf16 v[48:51], v[86:89], v[246:249], v[40:43]
	v_mfma_f32_16x16x32_bf16 v[40:43], v[90:93], v[234:237], v[114:117]
	v_mfma_f32_16x16x32_bf16 v[32:35], v[90:93], v[242:245], v[32:35]
	v_mfma_f32_16x16x32_bf16 v[44:47], v[94:97], v[238:241], v[40:43]
	v_mfma_f32_16x16x32_bf16 v[40:43], v[94:97], v[246:249], v[32:35]
	v_mfma_f32_16x16x32_bf16 v[32:35], v[226:229], v[234:237], v[36:39]
	v_mfma_f32_16x16x32_bf16 v[36:39], v[230:233], v[238:241], v[32:35]
	v_mfma_f32_16x16x32_bf16 v[32:35], v[226:229], v[242:245], v[118:121]
	v_mfma_f32_16x16x32_bf16 v[32:35], v[230:233], v[246:249], v[32:35]
	s_setprio 1
	s_mov_b32 m0, s83
	s_barrier
	ds_read_b128 v[96:99], v134 offset:49152
	ds_read_b128 v[100:103], v134 offset:50176
	ds_read_b128 v[104:107], v135 offset:49152
	ds_read_b128 v[108:111], v135 offset:50176
	ds_read_b128 v[226:229], v136 offset:49152
	ds_read_b128 v[230:233], v136 offset:50176
	ds_read_b128 v[250:253], v137 offset:49152
	ds_read_b128 v[190:193], v137 offset:50176
	buffer_load_dwordx4 v138, s[56:59], s27 offen lds
	s_mov_b32 m0, s84
	s_nop 0
	buffer_load_dwordx4 v138, s[56:59], s28 offen lds
	s_barrier
	s_waitcnt lgkmcnt(0)
	s_setprio 0
	s_waitcnt lgkmcnt(7)
	v_mfma_f32_16x16x32_bf16 v[64:67], v[96:99], v[122:125], v[150:153]
	s_waitcnt lgkmcnt(6)
	v_mfma_f32_16x16x32_bf16 v[92:95], v[100:103], v[214:217], v[64:67]
	v_mfma_f32_16x16x32_bf16 v[64:67], v[96:99], v[218:221], v[154:157]
	v_mfma_f32_16x16x32_bf16 v[88:91], v[100:103], v[222:225], v[64:67]
	s_waitcnt lgkmcnt(5)
	v_mfma_f32_16x16x32_bf16 v[64:67], v[104:107], v[122:125], v[158:161]
	s_waitcnt lgkmcnt(4)
	v_mfma_f32_16x16x32_bf16 v[84:87], v[108:111], v[214:217], v[64:67]
	v_mfma_f32_16x16x32_bf16 v[64:67], v[104:107], v[218:221], v[162:165]
	v_mfma_f32_16x16x32_bf16 v[80:83], v[108:111], v[222:225], v[64:67]
	s_waitcnt lgkmcnt(3)
	v_mfma_f32_16x16x32_bf16 v[64:67], v[226:229], v[122:125], v[166:169]
	s_waitcnt lgkmcnt(2)
	v_mfma_f32_16x16x32_bf16 v[76:79], v[230:233], v[214:217], v[64:67]
	v_mfma_f32_16x16x32_bf16 v[64:67], v[226:229], v[218:221], v[170:173]
	v_mfma_f32_16x16x32_bf16 v[72:75], v[230:233], v[222:225], v[64:67]
	s_waitcnt lgkmcnt(1)
	v_mfma_f32_16x16x32_bf16 v[64:67], v[250:253], v[122:125], v[174:177]
	s_waitcnt lgkmcnt(0)
	v_mfma_f32_16x16x32_bf16 v[68:71], v[190:193], v[214:217], v[64:67]
	v_mfma_f32_16x16x32_bf16 v[64:67], v[250:253], v[218:221], v[178:181]
	v_mfma_f32_16x16x32_bf16 v[64:67], v[190:193], v[222:225], v[64:67]
	s_setprio 1
	s_barrier
	s_mov_b32 m0, s85
	s_mov_b32 s89, 0x40180
	buffer_load_dwordx4 v138, s[4:7], s89 offen lds
	s_mov_b32 m0, s86
	s_mov_b32 s89, 0x60180
	buffer_load_dwordx4 v138, s[4:7], s89 offen lds
	s_waitcnt vmcnt(6)
	s_barrier
	s_setprio 0
	v_mfma_f32_16x16x32_bf16 v[112:115], v[96:99], v[234:237], v[182:185]
	v_mfma_f32_16x16x32_bf16 v[96:99], v[96:99], v[242:245], v[186:189]
	v_mfma_f32_16x16x32_bf16 v[120:123], v[100:103], v[246:249], v[96:99]
	v_mfma_f32_16x16x32_bf16 v[96:99], v[104:107], v[234:237], v[194:197]
	v_mfma_f32_16x16x32_bf16 v[116:119], v[108:111], v[238:241], v[96:99]
	v_mfma_f32_16x16x32_bf16 v[96:99], v[104:107], v[242:245], v[198:201]
	v_mfma_f32_16x16x32_bf16 v[124:127], v[100:103], v[238:241], v[112:115]
	v_mfma_f32_16x16x32_bf16 v[112:115], v[108:111], v[246:249], v[96:99]
	v_mfma_f32_16x16x32_bf16 v[96:99], v[226:229], v[234:237], v[202:205]
	v_mfma_f32_16x16x32_bf16 v[108:111], v[230:233], v[238:241], v[96:99]
	v_mfma_f32_16x16x32_bf16 v[96:99], v[226:229], v[242:245], v[206:209]
	v_mfma_f32_16x16x32_bf16 v[104:107], v[230:233], v[246:249], v[96:99]
	v_mfma_f32_16x16x32_bf16 v[96:99], v[250:253], v[234:237], v[210:213]
	v_mfma_f32_16x16x32_bf16 v[100:103], v[190:193], v[238:241], v[96:99]
	v_mfma_f32_16x16x32_bf16 v[96:99], v[250:253], v[242:245], v[144:147]
	v_mfma_f32_16x16x32_bf16 v[96:99], v[190:193], v[246:249], v[96:99]
	s_setprio 1
	s_mov_b32 s89, 0
	s_mov_b32 s90, 0x60280
	s_barrier
.LBB0_139:
	ds_read_b128 v[144:147], v139
	ds_read_b128 v[148:151], v139 offset:1024
	ds_read_b128 v[152:155], v139 offset:2048
	ds_read_b128 v[156:159], v139 offset:3072
	s_mov_b32 m0, s88
	s_add_i32 s91, s90, 0xfffdff00
	ds_read_b128 v[160:163], v134
	ds_read_b128 v[164:167], v134 offset:1024
	ds_read_b128 v[168:171], v135
	ds_read_b128 v[172:175], v135 offset:1024
	ds_read_b128 v[176:179], v136
	ds_read_b128 v[180:183], v136 offset:1024
	ds_read_b128 v[184:187], v137
	ds_read_b128 v[188:191], v137 offset:1024
	buffer_load_dwordx4 v138, s[56:59], s91 offen lds
	s_add_i32 s91, s90, 0xffffff00
	s_mov_b32 m0, s87
	s_nop 0
	buffer_load_dwordx4 v138, s[56:59], s91 offen lds
	s_waitcnt lgkmcnt(8)
	s_barrier
	s_waitcnt lgkmcnt(0)
	s_setprio 0
	s_waitcnt lgkmcnt(7)
	v_mfma_f32_16x16x32_bf16 v[28:31], v[160:163], v[144:147], v[28:31]
	v_mfma_f32_16x16x32_bf16 v[24:27], v[160:163], v[152:155], v[24:27]
	s_waitcnt lgkmcnt(5)
	v_mfma_f32_16x16x32_bf16 v[20:23], v[168:171], v[144:147], v[20:23]
	v_mfma_f32_16x16x32_bf16 v[16:19], v[168:171], v[152:155], v[16:19]
	s_waitcnt lgkmcnt(3)
	v_mfma_f32_16x16x32_bf16 v[12:15], v[176:179], v[144:147], v[12:15]
	v_mfma_f32_16x16x32_bf16 v[8:11], v[176:179], v[152:155], v[8:11]
	s_waitcnt lgkmcnt(1)
	v_mfma_f32_16x16x32_bf16 v[4:7], v[184:187], v[144:147], v[4:7]
	v_mfma_f32_16x16x32_bf16 v[0:3], v[184:187], v[152:155], v[0:3]
	v_mfma_f32_16x16x32_bf16 v[28:31], v[164:167], v[148:151], v[28:31]
	v_mfma_f32_16x16x32_bf16 v[24:27], v[164:167], v[156:159], v[24:27]
	v_mfma_f32_16x16x32_bf16 v[20:23], v[172:175], v[148:151], v[20:23]
	v_mfma_f32_16x16x32_bf16 v[16:19], v[172:175], v[156:159], v[16:19]
	v_mfma_f32_16x16x32_bf16 v[12:15], v[180:183], v[148:151], v[12:15]
	v_mfma_f32_16x16x32_bf16 v[8:11], v[180:183], v[156:159], v[8:11]
	s_waitcnt lgkmcnt(0)
	v_mfma_f32_16x16x32_bf16 v[4:7], v[188:191], v[148:151], v[4:7]
	v_mfma_f32_16x16x32_bf16 v[0:3], v[188:191], v[156:159], v[0:3]
	s_setprio 1
	s_barrier
	s_mov_b32 m0, s74
	s_add_i32 s91, s90, 0xfff9ff80
	ds_read_b128 v[192:195], v140
	ds_read_b128 v[196:199], v140 offset:1024
	ds_read_b128 v[200:203], v140 offset:2048
	ds_read_b128 v[204:207], v140 offset:3072
	buffer_load_dwordx4 v138, s[4:7], s91 offen lds
	s_add_i32 s92, s90, 0xfffbff80
	s_mov_b32 m0, s75
	s_nop 0
	buffer_load_dwordx4 v138, s[4:7], s92 offen lds
	s_barrier
	s_waitcnt lgkmcnt(0)
	s_setprio 0
	s_waitcnt lgkmcnt(3)
	v_mfma_f32_16x16x32_bf16 v[60:63], v[160:163], v[192:195], v[60:63]
	s_waitcnt lgkmcnt(1)
	v_mfma_f32_16x16x32_bf16 v[56:59], v[160:163], v[200:203], v[56:59]
	v_mfma_f32_16x16x32_bf16 v[52:55], v[168:171], v[192:195], v[52:55]
	v_mfma_f32_16x16x32_bf16 v[48:51], v[168:171], v[200:203], v[48:51]
	v_mfma_f32_16x16x32_bf16 v[44:47], v[176:179], v[192:195], v[44:47]
	v_mfma_f32_16x16x32_bf16 v[40:43], v[176:179], v[200:203], v[40:43]
	v_mfma_f32_16x16x32_bf16 v[36:39], v[184:187], v[192:195], v[36:39]
	v_mfma_f32_16x16x32_bf16 v[32:35], v[184:187], v[200:203], v[32:35]
	v_mfma_f32_16x16x32_bf16 v[60:63], v[164:167], v[196:199], v[60:63]
	s_waitcnt lgkmcnt(0)
	v_mfma_f32_16x16x32_bf16 v[56:59], v[164:167], v[204:207], v[56:59]
	v_mfma_f32_16x16x32_bf16 v[52:55], v[172:175], v[196:199], v[52:55]
	v_mfma_f32_16x16x32_bf16 v[48:51], v[172:175], v[204:207], v[48:51]
	v_mfma_f32_16x16x32_bf16 v[44:47], v[180:183], v[196:199], v[44:47]
	v_mfma_f32_16x16x32_bf16 v[40:43], v[180:183], v[204:207], v[40:43]
	v_mfma_f32_16x16x32_bf16 v[36:39], v[188:191], v[196:199], v[36:39]
	v_mfma_f32_16x16x32_bf16 v[32:35], v[188:191], v[204:207], v[32:35]
	s_setprio 1
	s_mov_b32 m0, s71
	s_barrier
	ds_read_b128 v[160:163], v134 offset:16384
	ds_read_b128 v[164:167], v134 offset:17408
	ds_read_b128 v[168:171], v135 offset:16384
	ds_read_b128 v[172:175], v135 offset:17408
	ds_read_b128 v[176:179], v136 offset:16384
	ds_read_b128 v[180:183], v136 offset:17408
	ds_read_b128 v[184:187], v137 offset:16384
	ds_read_b128 v[188:191], v137 offset:17408
	buffer_load_dwordx4 v138, s[56:59], s91 offen lds
	s_mov_b32 m0, s76
	s_nop 0
	buffer_load_dwordx4 v138, s[56:59], s92 offen lds
	s_barrier
	s_waitcnt lgkmcnt(0)
	s_setprio 0
	s_waitcnt lgkmcnt(7)
	v_mfma_f32_16x16x32_bf16 v[92:95], v[160:163], v[144:147], v[92:95]
	v_mfma_f32_16x16x32_bf16 v[88:91], v[160:163], v[152:155], v[88:91]
	s_waitcnt lgkmcnt(5)
	v_mfma_f32_16x16x32_bf16 v[84:87], v[168:171], v[144:147], v[84:87]
	v_mfma_f32_16x16x32_bf16 v[80:83], v[168:171], v[152:155], v[80:83]
	s_waitcnt lgkmcnt(3)
	v_mfma_f32_16x16x32_bf16 v[76:79], v[176:179], v[144:147], v[76:79]
	v_mfma_f32_16x16x32_bf16 v[72:75], v[176:179], v[152:155], v[72:75]
	s_waitcnt lgkmcnt(1)
	v_mfma_f32_16x16x32_bf16 v[68:71], v[184:187], v[144:147], v[68:71]
	v_mfma_f32_16x16x32_bf16 v[64:67], v[184:187], v[152:155], v[64:67]
	v_mfma_f32_16x16x32_bf16 v[92:95], v[164:167], v[148:151], v[92:95]
	v_mfma_f32_16x16x32_bf16 v[88:91], v[164:167], v[156:159], v[88:91]
	v_mfma_f32_16x16x32_bf16 v[84:87], v[172:175], v[148:151], v[84:87]
	v_mfma_f32_16x16x32_bf16 v[80:83], v[172:175], v[156:159], v[80:83]
	v_mfma_f32_16x16x32_bf16 v[76:79], v[180:183], v[148:151], v[76:79]
	v_mfma_f32_16x16x32_bf16 v[72:75], v[180:183], v[156:159], v[72:75]
	s_waitcnt lgkmcnt(0)
	v_mfma_f32_16x16x32_bf16 v[68:71], v[188:191], v[148:151], v[68:71]
	v_mfma_f32_16x16x32_bf16 v[64:67], v[188:191], v[156:159], v[64:67]
	s_setprio 1
	s_barrier
	s_mov_b32 m0, s78
	s_add_i32 s91, s90, 0xfffdff80
	buffer_load_dwordx4 v138, s[4:7], s91 offen lds
	s_add_i32 s92, s90, 0xffffff80
	s_mov_b32 m0, s79
	s_nop 0
	buffer_load_dwordx4 v138, s[4:7], s92 offen lds
	s_waitcnt vmcnt(6)
	s_barrier
	s_setprio 0
	v_mfma_f32_16x16x32_bf16 v[124:127], v[160:163], v[192:195], v[124:127]
	v_mfma_f32_16x16x32_bf16 v[120:123], v[160:163], v[200:203], v[120:123]
	v_mfma_f32_16x16x32_bf16 v[116:119], v[168:171], v[192:195], v[116:119]
	v_mfma_f32_16x16x32_bf16 v[112:115], v[168:171], v[200:203], v[112:115]
	v_mfma_f32_16x16x32_bf16 v[108:111], v[176:179], v[192:195], v[108:111]
	v_mfma_f32_16x16x32_bf16 v[104:107], v[176:179], v[200:203], v[104:107]
	v_mfma_f32_16x16x32_bf16 v[100:103], v[184:187], v[192:195], v[100:103]
	v_mfma_f32_16x16x32_bf16 v[96:99], v[184:187], v[200:203], v[96:99]
	v_mfma_f32_16x16x32_bf16 v[124:127], v[164:167], v[196:199], v[124:127]
	v_mfma_f32_16x16x32_bf16 v[120:123], v[164:167], v[204:207], v[120:123]
	v_mfma_f32_16x16x32_bf16 v[116:119], v[172:175], v[196:199], v[116:119]
	v_mfma_f32_16x16x32_bf16 v[112:115], v[172:175], v[204:207], v[112:115]
	v_mfma_f32_16x16x32_bf16 v[108:111], v[180:183], v[196:199], v[108:111]
	v_mfma_f32_16x16x32_bf16 v[104:107], v[180:183], v[204:207], v[104:107]
	v_mfma_f32_16x16x32_bf16 v[100:103], v[188:191], v[196:199], v[100:103]
	v_mfma_f32_16x16x32_bf16 v[96:99], v[188:191], v[204:207], v[96:99]
	s_setprio 1
	s_barrier
	ds_read_b128 v[144:147], v141
	ds_read_b128 v[148:151], v141 offset:1024
	ds_read_b128 v[152:155], v141 offset:2048
	ds_read_b128 v[156:159], v141 offset:3072
	s_mov_b32 m0, s81
	ds_read_b128 v[160:163], v134 offset:32768
	ds_read_b128 v[164:167], v134 offset:33792
	ds_read_b128 v[168:171], v135 offset:32768
	ds_read_b128 v[172:175], v135 offset:33792
	ds_read_b128 v[176:179], v136 offset:32768
	ds_read_b128 v[180:183], v136 offset:33792
	ds_read_b128 v[184:187], v137 offset:32768
	ds_read_b128 v[188:191], v137 offset:33792
	buffer_load_dwordx4 v138, s[56:59], s91 offen lds
	s_mov_b32 m0, s82
	s_nop 0
	buffer_load_dwordx4 v138, s[56:59], s92 offen lds
	s_waitcnt lgkmcnt(8)
	s_barrier
	s_waitcnt lgkmcnt(0)
	s_setprio 0
	s_waitcnt lgkmcnt(7)
	v_mfma_f32_16x16x32_bf16 v[28:31], v[160:163], v[144:147], v[28:31]
	v_mfma_f32_16x16x32_bf16 v[24:27], v[160:163], v[152:155], v[24:27]
	s_waitcnt lgkmcnt(5)
	v_mfma_f32_16x16x32_bf16 v[20:23], v[168:171], v[144:147], v[20:23]
	v_mfma_f32_16x16x32_bf16 v[16:19], v[168:171], v[152:155], v[16:19]
	s_waitcnt lgkmcnt(3)
	v_mfma_f32_16x16x32_bf16 v[12:15], v[176:179], v[144:147], v[12:15]
	v_mfma_f32_16x16x32_bf16 v[8:11], v[176:179], v[152:155], v[8:11]
	s_waitcnt lgkmcnt(1)
	v_mfma_f32_16x16x32_bf16 v[4:7], v[184:187], v[144:147], v[4:7]
	v_mfma_f32_16x16x32_bf16 v[0:3], v[184:187], v[152:155], v[0:3]
	v_mfma_f32_16x16x32_bf16 v[28:31], v[164:167], v[148:151], v[28:31]
	v_mfma_f32_16x16x32_bf16 v[24:27], v[164:167], v[156:159], v[24:27]
	v_mfma_f32_16x16x32_bf16 v[20:23], v[172:175], v[148:151], v[20:23]
	v_mfma_f32_16x16x32_bf16 v[16:19], v[172:175], v[156:159], v[16:19]
	v_mfma_f32_16x16x32_bf16 v[12:15], v[180:183], v[148:151], v[12:15]
	v_mfma_f32_16x16x32_bf16 v[8:11], v[180:183], v[156:159], v[8:11]
	s_waitcnt lgkmcnt(0)
	v_mfma_f32_16x16x32_bf16 v[4:7], v[188:191], v[148:151], v[4:7]
	v_mfma_f32_16x16x32_bf16 v[0:3], v[188:191], v[156:159], v[0:3]
	s_setprio 1
	s_barrier
	s_mov_b32 m0, s0
	s_add_i32 s91, s90, 0xfffa0000
	ds_read_b128 v[192:195], v142
	ds_read_b128 v[196:199], v142 offset:1024
	ds_read_b128 v[200:203], v142 offset:2048
	ds_read_b128 v[204:207], v142 offset:3072
	buffer_load_dwordx4 v138, s[4:7], s91 offen lds
	s_add_i32 s92, s90, 0xfffc0000
	s_mov_b32 m0, s1
	s_nop 0
	buffer_load_dwordx4 v138, s[4:7], s92 offen lds
	s_barrier
	s_waitcnt lgkmcnt(0)
	s_setprio 0
	s_waitcnt lgkmcnt(3)
	v_mfma_f32_16x16x32_bf16 v[60:63], v[160:163], v[192:195], v[60:63]
	s_waitcnt lgkmcnt(1)
	v_mfma_f32_16x16x32_bf16 v[56:59], v[160:163], v[200:203], v[56:59]
	v_mfma_f32_16x16x32_bf16 v[52:55], v[168:171], v[192:195], v[52:55]
	v_mfma_f32_16x16x32_bf16 v[48:51], v[168:171], v[200:203], v[48:51]
	v_mfma_f32_16x16x32_bf16 v[44:47], v[176:179], v[192:195], v[44:47]
	v_mfma_f32_16x16x32_bf16 v[40:43], v[176:179], v[200:203], v[40:43]
	v_mfma_f32_16x16x32_bf16 v[36:39], v[184:187], v[192:195], v[36:39]
	v_mfma_f32_16x16x32_bf16 v[32:35], v[184:187], v[200:203], v[32:35]
	v_mfma_f32_16x16x32_bf16 v[60:63], v[164:167], v[196:199], v[60:63]
	s_waitcnt lgkmcnt(0)
	v_mfma_f32_16x16x32_bf16 v[56:59], v[164:167], v[204:207], v[56:59]
	v_mfma_f32_16x16x32_bf16 v[52:55], v[172:175], v[196:199], v[52:55]
	v_mfma_f32_16x16x32_bf16 v[48:51], v[172:175], v[204:207], v[48:51]
	v_mfma_f32_16x16x32_bf16 v[44:47], v[180:183], v[196:199], v[44:47]
	v_mfma_f32_16x16x32_bf16 v[40:43], v[180:183], v[204:207], v[40:43]
	v_mfma_f32_16x16x32_bf16 v[36:39], v[188:191], v[196:199], v[36:39]
	v_mfma_f32_16x16x32_bf16 v[32:35], v[188:191], v[204:207], v[32:35]
	s_setprio 1
	s_mov_b32 m0, s83
	s_barrier
	ds_read_b128 v[160:163], v134 offset:49152
	ds_read_b128 v[164:167], v134 offset:50176
	ds_read_b128 v[168:171], v135 offset:49152
	ds_read_b128 v[172:175], v135 offset:50176
	ds_read_b128 v[176:179], v136 offset:49152
	ds_read_b128 v[180:183], v136 offset:50176
	ds_read_b128 v[184:187], v137 offset:49152
	ds_read_b128 v[188:191], v137 offset:50176
	buffer_load_dwordx4 v138, s[56:59], s91 offen lds
	s_mov_b32 m0, s84
	s_nop 0
	buffer_load_dwordx4 v138, s[56:59], s92 offen lds
	s_barrier
	s_waitcnt lgkmcnt(0)
	s_setprio 0
	s_waitcnt lgkmcnt(7)
	v_mfma_f32_16x16x32_bf16 v[92:95], v[160:163], v[144:147], v[92:95]
	v_mfma_f32_16x16x32_bf16 v[88:91], v[160:163], v[152:155], v[88:91]
	s_waitcnt lgkmcnt(5)
	v_mfma_f32_16x16x32_bf16 v[84:87], v[168:171], v[144:147], v[84:87]
	v_mfma_f32_16x16x32_bf16 v[80:83], v[168:171], v[152:155], v[80:83]
	s_waitcnt lgkmcnt(3)
	v_mfma_f32_16x16x32_bf16 v[76:79], v[176:179], v[144:147], v[76:79]
	v_mfma_f32_16x16x32_bf16 v[72:75], v[176:179], v[152:155], v[72:75]
	s_waitcnt lgkmcnt(1)
	v_mfma_f32_16x16x32_bf16 v[68:71], v[184:187], v[144:147], v[68:71]
	v_mfma_f32_16x16x32_bf16 v[64:67], v[184:187], v[152:155], v[64:67]
	v_mfma_f32_16x16x32_bf16 v[92:95], v[164:167], v[148:151], v[92:95]
	v_mfma_f32_16x16x32_bf16 v[88:91], v[164:167], v[156:159], v[88:91]
	v_mfma_f32_16x16x32_bf16 v[84:87], v[172:175], v[148:151], v[84:87]
	v_mfma_f32_16x16x32_bf16 v[80:83], v[172:175], v[156:159], v[80:83]
	v_mfma_f32_16x16x32_bf16 v[76:79], v[180:183], v[148:151], v[76:79]
	v_mfma_f32_16x16x32_bf16 v[72:75], v[180:183], v[156:159], v[72:75]
	s_waitcnt lgkmcnt(0)
	v_mfma_f32_16x16x32_bf16 v[68:71], v[188:191], v[148:151], v[68:71]
	v_mfma_f32_16x16x32_bf16 v[64:67], v[188:191], v[156:159], v[64:67]
	s_setprio 1
	s_barrier
	s_add_i32 s91, s90, 0xfffe0000
	s_mov_b32 m0, s85
	s_nop 0
	buffer_load_dwordx4 v138, s[4:7], s91 offen lds
	s_mov_b32 m0, s86
	s_nop 0
	buffer_load_dwordx4 v138, s[4:7], s90 offen lds
	s_waitcnt vmcnt(6)
	s_barrier
; #define LDA(dst, b, h)                                                                             \
;   _Pragma("unroll") for (int m = 0; m < 4; ++m) _Pragma("unroll") for (int k = 0; k < 2; ++k)      \
;       dst[m][k] = *reinterpret_cast<const bf16x8*>(SA(b, h) + lds_byte(wr * 64 + m * 16 + fr, k * 32 + fq * 8))
; #define LDB(dst, b, h)                                                                             \
;   _Pragma("unroll") for (int n = 0; n < 2; ++n) _Pragma("unroll") for (int k = 0; k < 2; ++k)      \
;       dst[n][k] = *reinterpret_cast<const bf16x8*>(SB(b, h) + lds_byte(wc * 32 + n * 16 + fr, k * 32 + fq * 8))
; #define WAIT_L(n) asm volatile("s_waitcnt lgkmcnt(" #n ")" ::: "memory")
; #define BAR __builtin_amdgcn_s_barrier()
; template <bool PEEL = false>
; __device__ __forceinline__ void gemm_tile(f32x4 (&acc)[2][2][4][2], const u16* __restrict__ A, int lda,
;                                           const u16* __restrict__ B, int K) {
;     ...
;   {
;     LDB(B0, 0, 0); LDA(At, 0, 0); STAGE_A(SA(1, 1), 1, nt - 1);
;     BAR; WAIT_L(0); MMA(0, 0, At, B0); BAR;
;     LDB(B1, 0, 1); BAR; WAIT_L(0); MMA(0, 1, At, B1); BAR;
	s_setprio 0
	v_mfma_f32_16x16x32_bf16 v[124:127], v[160:163], v[192:195], v[124:127]
	v_mfma_f32_16x16x32_bf16 v[120:123], v[160:163], v[200:203], v[120:123]
	v_mfma_f32_16x16x32_bf16 v[116:119], v[168:171], v[192:195], v[116:119]
	v_mfma_f32_16x16x32_bf16 v[112:115], v[168:171], v[200:203], v[112:115]
	v_mfma_f32_16x16x32_bf16 v[108:111], v[176:179], v[192:195], v[108:111]
	v_mfma_f32_16x16x32_bf16 v[104:107], v[176:179], v[200:203], v[104:107]
	v_mfma_f32_16x16x32_bf16 v[100:103], v[184:187], v[192:195], v[100:103]
	v_mfma_f32_16x16x32_bf16 v[96:99], v[184:187], v[200:203], v[96:99]
	v_mfma_f32_16x16x32_bf16 v[124:127], v[164:167], v[196:199], v[124:127]
	v_mfma_f32_16x16x32_bf16 v[120:123], v[164:167], v[204:207], v[120:123]
	v_mfma_f32_16x16x32_bf16 v[116:119], v[172:175], v[196:199], v[116:119]
	v_mfma_f32_16x16x32_bf16 v[112:115], v[172:175], v[204:207], v[112:115]
	v_mfma_f32_16x16x32_bf16 v[108:111], v[180:183], v[196:199], v[108:111]
	v_mfma_f32_16x16x32_bf16 v[104:107], v[180:183], v[204:207], v[104:107]
	v_mfma_f32_16x16x32_bf16 v[100:103], v[188:191], v[196:199], v[100:103]
	v_mfma_f32_16x16x32_bf16 v[96:99], v[188:191], v[204:207], v[96:99]
	s_setprio 1
	s_add_i32 s89, s89, 2
	s_addk_i32 s90, 0x100
	s_cmp_lt_u32 s89, 12
	s_barrier
	s_cbranch_scc1 .LBB0_139
	v_mov_b32_e32 v244, v138
	s_mov_b32 m0, s88
	s_mov_b32 s0, 0x40780
	ds_read_b128 v[144:147], v139
	ds_read_b128 v[148:151], v139 offset:1024
	ds_read_b128 v[152:155], v139 offset:2048
	ds_read_b128 v[156:159], v139 offset:3072
	ds_read_b128 v[160:163], v134
	ds_read_b128 v[164:167], v134 offset:1024
	ds_read_b128 v[168:171], v135
	ds_read_b128 v[172:175], v135 offset:1024
	ds_read_b128 v[176:179], v136
	ds_read_b128 v[180:183], v136 offset:1024
	ds_read_b128 v[184:187], v137
	ds_read_b128 v[188:191], v137 offset:1024
	buffer_load_dwordx4 v138, s[56:59], s0 offen lds
	s_mov_b32 s0, 0x60780
	s_mov_b32 m0, s87
	s_nop 0
	buffer_load_dwordx4 v138, s[56:59], s0 offen lds
	s_barrier
	s_waitcnt lgkmcnt(0)
	s_setprio 0
	s_waitcnt lgkmcnt(7)
	v_mfma_f32_16x16x32_bf16 v[28:31], v[160:163], v[144:147], v[28:31]
	v_mfma_f32_16x16x32_bf16 v[24:27], v[160:163], v[152:155], v[24:27]
	s_waitcnt lgkmcnt(5)
	v_mfma_f32_16x16x32_bf16 v[20:23], v[168:171], v[144:147], v[20:23]
	v_mfma_f32_16x16x32_bf16 v[16:19], v[168:171], v[152:155], v[16:19]
	s_waitcnt lgkmcnt(3)
	v_mfma_f32_16x16x32_bf16 v[12:15], v[176:179], v[144:147], v[12:15]
	v_mfma_f32_16x16x32_bf16 v[8:11], v[176:179], v[152:155], v[8:11]
	s_waitcnt lgkmcnt(1)
	v_mfma_f32_16x16x32_bf16 v[4:7], v[184:187], v[144:147], v[4:7]
	v_mfma_f32_16x16x32_bf16 v[0:3], v[184:187], v[152:155], v[0:3]
	v_mfma_f32_16x16x32_bf16 v[28:31], v[164:167], v[148:151], v[28:31]
	v_mfma_f32_16x16x32_bf16 v[24:27], v[164:167], v[156:159], v[24:27]
	v_mfma_f32_16x16x32_bf16 v[20:23], v[172:175], v[148:151], v[20:23]
	v_mfma_f32_16x16x32_bf16 v[16:19], v[172:175], v[156:159], v[16:19]
	v_mfma_f32_16x16x32_bf16 v[12:15], v[180:183], v[148:151], v[12:15]
	v_mfma_f32_16x16x32_bf16 v[8:11], v[180:183], v[156:159], v[8:11]
	s_waitcnt lgkmcnt(0)
	v_mfma_f32_16x16x32_bf16 v[4:7], v[188:191], v[148:151], v[4:7]
	v_mfma_f32_16x16x32_bf16 v[0:3], v[188:191], v[156:159], v[0:3]
	s_setprio 1
	s_barrier
	ds_read_b128 v[192:195], v140
	ds_read_b128 v[196:199], v140 offset:1024
	ds_read_b128 v[200:203], v140 offset:2048
	ds_read_b128 v[204:207], v140 offset:3072
	s_barrier
	s_waitcnt lgkmcnt(0)
	s_setprio 0
	s_waitcnt lgkmcnt(3)
	v_mfma_f32_16x16x32_bf16 v[60:63], v[160:163], v[192:195], v[60:63]
	s_waitcnt lgkmcnt(1)
	v_mfma_f32_16x16x32_bf16 v[56:59], v[160:163], v[200:203], v[56:59]
	v_mfma_f32_16x16x32_bf16 v[52:55], v[168:171], v[192:195], v[52:55]
	v_mfma_f32_16x16x32_bf16 v[48:51], v[168:171], v[200:203], v[48:51]
	v_mfma_f32_16x16x32_bf16 v[44:47], v[176:179], v[192:195], v[44:47]
	v_mfma_f32_16x16x32_bf16 v[40:43], v[176:179], v[200:203], v[40:43]
	v_mfma_f32_16x16x32_bf16 v[36:39], v[184:187], v[192:195], v[36:39]
	v_mfma_f32_16x16x32_bf16 v[32:35], v[184:187], v[200:203], v[32:35]
	v_mfma_f32_16x16x32_bf16 v[60:63], v[164:167], v[196:199], v[60:63]
	s_waitcnt lgkmcnt(0)
	v_mfma_f32_16x16x32_bf16 v[56:59], v[164:167], v[204:207], v[56:59]
	v_mfma_f32_16x16x32_bf16 v[52:55], v[172:175], v[196:199], v[52:55]
	v_mfma_f32_16x16x32_bf16 v[48:51], v[172:175], v[204:207], v[48:51]
	v_mfma_f32_16x16x32_bf16 v[44:47], v[180:183], v[196:199], v[44:47]
	v_mfma_f32_16x16x32_bf16 v[40:43], v[180:183], v[204:207], v[40:43]
	v_mfma_f32_16x16x32_bf16 v[36:39], v[188:191], v[196:199], v[36:39]
	v_mfma_f32_16x16x32_bf16 v[32:35], v[188:191], v[204:207], v[32:35]
	s_setprio 1
	s_barrier
	ds_read_b128 v[160:163], v134 offset:16384
	ds_read_b128 v[164:167], v134 offset:17408
	ds_read_b128 v[168:171], v135 offset:16384
	ds_read_b128 v[172:175], v135 offset:17408
	ds_read_b128 v[176:179], v136 offset:16384
	ds_read_b128 v[180:183], v136 offset:17408
	ds_read_b128 v[184:187], v137 offset:16384
	ds_read_b128 v[188:191], v137 offset:17408
	s_cmp_eq_u32 s8, 21
	s_cbranch_scc1 .Lt1_a_last
	s_add_u32 s4, s4, 0x80000
	s_addc_u32 s5, s5, 0
	s_mov_b32 m0, s74
	s_nop 0
	buffer_load_dwordx4 v244, s[4:7], 0 offen lds
	s_mov_b32 m0, s75
	s_nop 0
	buffer_load_dwordx4 v244, s[4:7], s63 offen lds
	s_mov_b32 m0, s71
	s_nop 0
	buffer_load_dwordx4 v244, s[56:59], 0 offen lds
	s_mov_b32 m0, s76
	s_nop 0
	buffer_load_dwordx4 v244, s[56:59], s63 offen lds
	s_waitcnt vmcnt(8)
	s_branch .Lt1_a_join

; #define LDA(dst, b, h)                                                                             \
;   _Pragma("unroll") for (int m = 0; m < 4; ++m) _Pragma("unroll") for (int k = 0; k < 2; ++k)      \
;       dst[m][k] = *reinterpret_cast<const bf16x8*>(SA(b, h) + lds_byte(wr * 64 + m * 16 + fr, k * 32 + fq * 8))
; #define WAIT_V(n) asm volatile("s_waitcnt vmcnt(" #n ")" ::: "memory")
; #define WAIT_L(n) asm volatile("s_waitcnt lgkmcnt(" #n ")" ::: "memory")
; #define BAR __builtin_amdgcn_s_barrier()
; template <bool PEEL = false>
; __device__ __forceinline__ void gemm_tile(f32x4 (&acc)[2][2][4][2], const u16* __restrict__ A, int lda,
;                                           const u16* __restrict__ B, int K) {
;     ...
;     LDA(At, 0, 1); WAIT_V(4); BAR; WAIT_L(0); MMA(1, 0, At, B0); MMA(1, 1, At, B1); BAR;
;   }
.Lt1_a_join:
	s_barrier
	s_waitcnt lgkmcnt(0)
	s_setprio 0
	s_waitcnt lgkmcnt(7)
	v_mfma_f32_16x16x32_bf16 v[92:95], v[160:163], v[144:147], v[92:95]
	v_mfma_f32_16x16x32_bf16 v[88:91], v[160:163], v[152:155], v[88:91]
	s_waitcnt lgkmcnt(5)
	v_mfma_f32_16x16x32_bf16 v[84:87], v[168:171], v[144:147], v[84:87]
	v_mfma_f32_16x16x32_bf16 v[80:83], v[168:171], v[152:155], v[80:83]
	s_waitcnt lgkmcnt(3)
	v_mfma_f32_16x16x32_bf16 v[76:79], v[176:179], v[144:147], v[76:79]
	v_mfma_f32_16x16x32_bf16 v[72:75], v[176:179], v[152:155], v[72:75]
	s_waitcnt lgkmcnt(1)
	v_mfma_f32_16x16x32_bf16 v[68:71], v[184:187], v[144:147], v[68:71]
	v_mfma_f32_16x16x32_bf16 v[64:67], v[184:187], v[152:155], v[64:67]
	v_mfma_f32_16x16x32_bf16 v[208:211], v[164:167], v[148:151], v[92:95]
	v_mfma_f32_16x16x32_bf16 v[212:215], v[164:167], v[156:159], v[88:91]
	v_mfma_f32_16x16x32_bf16 v[216:219], v[172:175], v[148:151], v[84:87]
	v_mfma_f32_16x16x32_bf16 v[220:223], v[172:175], v[156:159], v[80:83]
	v_mfma_f32_16x16x32_bf16 v[224:227], v[180:183], v[148:151], v[76:79]
	v_mfma_f32_16x16x32_bf16 v[228:231], v[180:183], v[156:159], v[72:75]
	s_waitcnt lgkmcnt(0)
	v_mfma_f32_16x16x32_bf16 v[144:147], v[188:191], v[148:151], v[68:71]
	v_mfma_f32_16x16x32_bf16 v[148:151], v[188:191], v[156:159], v[64:67]
	s_setprio 1
	s_setprio 0
	v_mfma_f32_16x16x32_bf16 v[64:67], v[160:163], v[192:195], v[124:127]
	v_mfma_f32_16x16x32_bf16 v[152:155], v[164:167], v[196:199], v[64:67]
	v_mfma_f32_16x16x32_bf16 v[64:67], v[160:163], v[200:203], v[120:123]
	v_mfma_f32_16x16x32_bf16 v[156:159], v[164:167], v[204:207], v[64:67]
	v_mfma_f32_16x16x32_bf16 v[64:67], v[168:171], v[192:195], v[116:119]
	v_mfma_f32_16x16x32_bf16 v[160:163], v[172:175], v[196:199], v[64:67]
	v_mfma_f32_16x16x32_bf16 v[64:67], v[168:171], v[200:203], v[112:115]
	v_mfma_f32_16x16x32_bf16 v[164:167], v[172:175], v[204:207], v[64:67]
	v_mfma_f32_16x16x32_bf16 v[64:67], v[176:179], v[192:195], v[108:111]
	v_mfma_f32_16x16x32_bf16 v[168:171], v[180:183], v[196:199], v[64:67]
	v_mfma_f32_16x16x32_bf16 v[64:67], v[176:179], v[200:203], v[104:107]
	v_mfma_f32_16x16x32_bf16 v[172:175], v[180:183], v[204:207], v[64:67]
	v_mfma_f32_16x16x32_bf16 v[64:67], v[184:187], v[192:195], v[100:103]
	v_mfma_f32_16x16x32_bf16 v[176:179], v[188:191], v[196:199], v[64:67]
	v_mfma_f32_16x16x32_bf16 v[64:67], v[184:187], v[200:203], v[96:99]
	v_mfma_f32_16x16x32_bf16 v[180:183], v[188:191], v[204:207], v[64:67]
	s_setprio 1
	s_barrier
	ds_read_b128 v[184:187], v141
	ds_read_b128 v[188:191], v141 offset:1024
	ds_read_b128 v[192:195], v141 offset:2048
	ds_read_b128 v[138:141], v141 offset:3072
	ds_read_b128 v[72:75], v134 offset:32768
	ds_read_b128 v[76:79], v134 offset:33792
	ds_read_b128 v[88:91], v135 offset:32768
	ds_read_b128 v[92:95], v135 offset:33792
	ds_read_b128 v[196:199], v136 offset:32768
	ds_read_b128 v[200:203], v136 offset:33792
	ds_read_b128 v[204:207], v137 offset:32768
	ds_read_b128 v[232:235], v137 offset:33792
	s_cmp_eq_u32 s8, 21
	s_cbranch_scc1 .Lt1_b_last
	s_mov_b32 m0, s78
	s_nop 0
	buffer_load_dwordx4 v244, s[4:7], s9 offen lds
	s_mov_b32 m0, s79
	s_nop 0
	buffer_load_dwordx4 v244, s[4:7], s10 offen lds
	s_waitcnt vmcnt(8)
	s_branch .Lt1_b_join

; #define LDA(dst, b, h)                                                                             \
;   _Pragma("unroll") for (int m = 0; m < 4; ++m) _Pragma("unroll") for (int k = 0; k < 2; ++k)      \
;       dst[m][k] = *reinterpret_cast<const bf16x8*>(SA(b, h) + lds_byte(wr * 64 + m * 16 + fr, k * 32 + fq * 8))
; #define LDB(dst, b, h)                                                                             \
;   _Pragma("unroll") for (int n = 0; n < 2; ++n) _Pragma("unroll") for (int k = 0; k < 2; ++k)      \
;       dst[n][k] = *reinterpret_cast<const bf16x8*>(SB(b, h) + lds_byte(wc * 32 + n * 16 + fr, k * 32 + fq * 8))
; #define WAIT_V(n) asm volatile("s_waitcnt vmcnt(" #n ")" ::: "memory")
; #define WAIT_L(n) asm volatile("s_waitcnt lgkmcnt(" #n ")" ::: "memory")
; #define BAR __builtin_amdgcn_s_barrier()
; template <bool PEEL = false>
; __device__ __forceinline__ void gemm_tile(f32x4 (&acc)[2][2][4][2], const u16* __restrict__ A, int lda,
;                                           const u16* __restrict__ B, int K) {
;     ...
;     LDB(B0, 1, 0); LDA(At, 1, 0); WAIT_V(2); BAR; WAIT_L(0); MMA(0, 0, At, B0); BAR;
.Lt1_b_join:
	s_barrier
	s_waitcnt lgkmcnt(0)
	s_setprio 0
	s_waitcnt lgkmcnt(7)
	v_mfma_f32_16x16x32_bf16 v[28:31], v[72:75], v[184:187], v[28:31]
	v_mfma_f32_16x16x32_bf16 v[24:27], v[72:75], v[192:195], v[24:27]
	s_waitcnt lgkmcnt(5)
	v_mfma_f32_16x16x32_bf16 v[20:23], v[88:91], v[184:187], v[20:23]
	v_mfma_f32_16x16x32_bf16 v[16:19], v[88:91], v[192:195], v[16:19]
	s_waitcnt lgkmcnt(3)
	v_mfma_f32_16x16x32_bf16 v[12:15], v[196:199], v[184:187], v[12:15]
	v_mfma_f32_16x16x32_bf16 v[8:11], v[196:199], v[192:195], v[8:11]
	s_waitcnt lgkmcnt(1)
	v_mfma_f32_16x16x32_bf16 v[4:7], v[204:207], v[184:187], v[4:7]
	v_mfma_f32_16x16x32_bf16 v[0:3], v[204:207], v[192:195], v[0:3]
	v_mfma_f32_16x16x32_bf16 v[116:119], v[76:79], v[188:191], v[28:31]
	v_mfma_f32_16x16x32_bf16 v[112:115], v[76:79], v[138:141], v[24:27]
	v_mfma_f32_16x16x32_bf16 v[100:103], v[92:95], v[188:191], v[20:23]
	v_mfma_f32_16x16x32_bf16 v[96:99], v[92:95], v[138:141], v[16:19]
	v_mfma_f32_16x16x32_bf16 v[84:87], v[200:203], v[188:191], v[12:15]
	v_mfma_f32_16x16x32_bf16 v[80:83], v[200:203], v[138:141], v[8:11]
	s_waitcnt lgkmcnt(0)
	v_mfma_f32_16x16x32_bf16 v[68:71], v[232:235], v[188:191], v[4:7]
	v_mfma_f32_16x16x32_bf16 v[64:67], v[232:235], v[138:141], v[0:3]
	s_setprio 1
	s_barrier
	ds_read_b128 v[4:7], v142
	ds_read_b128 v[12:15], v142 offset:1024
	ds_read_b128 v[236:239], v142 offset:2048
	ds_read_b128 v[240:243], v142 offset:3072
	s_cmp_eq_u32 s8, 21
	s_cbranch_scc1 .Lt1_c_last
	s_mov_b32 m0, s81
	s_nop 0
	buffer_load_dwordx4 v244, s[56:59], s9 offen lds
	s_mov_b32 m0, s82
	s_nop 0
	buffer_load_dwordx4 v244, s[56:59], s10 offen lds
	s_waitcnt vmcnt(8)
	s_branch .Lt1_c_join

; #define LDA(dst, b, h)                                                                             \
;   _Pragma("unroll") for (int m = 0; m < 4; ++m) _Pragma("unroll") for (int k = 0; k < 2; ++k)      \
;       dst[m][k] = *reinterpret_cast<const bf16x8*>(SA(b, h) + lds_byte(wr * 64 + m * 16 + fr, k * 32 + fq * 8))
; #define LDB(dst, b, h)                                                                             \
;   _Pragma("unroll") for (int n = 0; n < 2; ++n) _Pragma("unroll") for (int k = 0; k < 2; ++k)      \
;       dst[n][k] = *reinterpret_cast<const bf16x8*>(SB(b, h) + lds_byte(wc * 32 + n * 16 + fr, k * 32 + fq * 8))
; #define WAIT_V(n) asm volatile("s_waitcnt vmcnt(" #n ")" ::: "memory")
; #define WAIT_L(n) asm volatile("s_waitcnt lgkmcnt(" #n ")" ::: "memory")
; #define BAR __builtin_amdgcn_s_barrier()
; template <bool PEEL = false>
; __device__ __forceinline__ void gemm_tile(f32x4 (&acc)[2][2][4][2], const u16* __restrict__ A, int lda,
;                                           const u16* __restrict__ B, int K) {
;     ...
;     LDB(B1, 1, 1); WAIT_V(0); BAR; WAIT_L(0); MMA(0, 1, At, B1); BAR;
;     LDA(At, 1, 1); BAR; WAIT_L(0); MMA(1, 0, At, B0); MMA(1, 1, At, B1); BAR;
;   }
;   if (wr == 0) BAR;
.Lt1_c_join:
	s_barrier
	s_waitcnt lgkmcnt(0)
	s_setprio 0
	s_waitcnt lgkmcnt(3)
	v_mfma_f32_16x16x32_bf16 v[0:3], v[72:75], v[4:7], v[60:63]
	s_waitcnt lgkmcnt(2)
	v_mfma_f32_16x16x32_bf16 v[124:127], v[76:79], v[12:15], v[0:3]
	s_waitcnt lgkmcnt(1)
	v_mfma_f32_16x16x32_bf16 v[0:3], v[72:75], v[236:239], v[56:59]
	s_waitcnt lgkmcnt(0)
	v_mfma_f32_16x16x32_bf16 v[120:123], v[76:79], v[240:243], v[0:3]
	v_mfma_f32_16x16x32_bf16 v[0:3], v[88:91], v[4:7], v[52:55]
	v_mfma_f32_16x16x32_bf16 v[108:111], v[92:95], v[12:15], v[0:3]
	v_mfma_f32_16x16x32_bf16 v[0:3], v[88:91], v[236:239], v[48:51]
	v_mfma_f32_16x16x32_bf16 v[104:107], v[92:95], v[240:243], v[0:3]
	v_mfma_f32_16x16x32_bf16 v[0:3], v[196:199], v[4:7], v[44:47]
	v_mfma_f32_16x16x32_bf16 v[92:95], v[200:203], v[12:15], v[0:3]
	v_mfma_f32_16x16x32_bf16 v[0:3], v[196:199], v[236:239], v[40:43]
	v_mfma_f32_16x16x32_bf16 v[88:91], v[200:203], v[240:243], v[0:3]
	v_mfma_f32_16x16x32_bf16 v[0:3], v[204:207], v[4:7], v[36:39]
	v_mfma_f32_16x16x32_bf16 v[76:79], v[232:235], v[12:15], v[0:3]
	v_mfma_f32_16x16x32_bf16 v[0:3], v[204:207], v[236:239], v[32:35]
	v_mfma_f32_16x16x32_bf16 v[72:75], v[232:235], v[240:243], v[0:3]
	s_setprio 1
	s_barrier
	ds_read_b128 v[24:27], v134 offset:49152
	ds_read_b128 v[28:31], v134 offset:50176
	ds_read_b128 v[36:39], v135 offset:49152
	ds_read_b128 v[196:199], v135 offset:50176
	ds_read_b128 v[200:203], v136 offset:49152
	ds_read_b128 v[204:207], v136 offset:50176
	ds_read_b128 v[232:235], v137 offset:49152
	ds_read_b128 v[134:137], v137 offset:50176
	s_cmp_eq_u32 s8, 21
	s_cbranch_scc1 .Lt1_d_skip
	s_add_i32 m0, s71, 0x18000
	s_nop 0
	buffer_load_dwordx4 v244, s[4:7], s11 offen lds
	s_add_i32 m0, s71, 0x1a000
	s_nop 0
	buffer_load_dwordx4 v244, s[4:7], s16 offen lds
	s_mov_b32 m0, s83
	s_nop 0
	buffer_load_dwordx4 v244, s[56:59], s11 offen lds
	s_mov_b32 m0, s84
	s_nop 0
	buffer_load_dwordx4 v244, s[56:59], s16 offen lds
.Lt1_d_skip:
	s_barrier
	s_waitcnt lgkmcnt(0)
	s_setprio 0
	s_waitcnt lgkmcnt(7)
	v_mfma_f32_16x16x32_bf16 v[0:3], v[24:27], v[184:187], v[208:211]
	s_waitcnt lgkmcnt(6)
	v_mfma_f32_16x16x32_bf16 v[52:55], v[28:31], v[188:191], v[0:3]
	v_mfma_f32_16x16x32_bf16 v[0:3], v[24:27], v[192:195], v[212:215]
	v_mfma_f32_16x16x32_bf16 v[48:51], v[28:31], v[138:141], v[0:3]
	s_waitcnt lgkmcnt(5)
	v_mfma_f32_16x16x32_bf16 v[0:3], v[36:39], v[184:187], v[216:219]
	s_waitcnt lgkmcnt(4)
	v_mfma_f32_16x16x32_bf16 v[40:43], v[196:199], v[188:191], v[0:3]
	v_mfma_f32_16x16x32_bf16 v[0:3], v[36:39], v[192:195], v[220:223]
	v_mfma_f32_16x16x32_bf16 v[32:35], v[196:199], v[138:141], v[0:3]
	s_waitcnt lgkmcnt(3)
	v_mfma_f32_16x16x32_bf16 v[0:3], v[200:203], v[184:187], v[224:227]
	s_waitcnt lgkmcnt(2)
	v_mfma_f32_16x16x32_bf16 v[20:23], v[204:207], v[188:191], v[0:3]
	v_mfma_f32_16x16x32_bf16 v[0:3], v[200:203], v[192:195], v[228:231]
	v_mfma_f32_16x16x32_bf16 v[16:19], v[204:207], v[138:141], v[0:3]
	s_waitcnt lgkmcnt(1)
	v_mfma_f32_16x16x32_bf16 v[0:3], v[232:235], v[184:187], v[144:147]
	s_waitcnt lgkmcnt(0)
	v_mfma_f32_16x16x32_bf16 v[8:11], v[134:137], v[188:191], v[0:3]
	v_mfma_f32_16x16x32_bf16 v[0:3], v[232:235], v[192:195], v[148:151]
	v_mfma_f32_16x16x32_bf16 v[0:3], v[134:137], v[138:141], v[0:3]
	s_setprio 1
	s_setprio 0
	v_mfma_f32_16x16x32_bf16 v[44:47], v[24:27], v[4:7], v[152:155]
	v_mfma_f32_16x16x32_bf16 v[24:27], v[24:27], v[236:239], v[156:159]
	v_mfma_f32_16x16x32_bf16 v[56:59], v[28:31], v[240:243], v[24:27]
	v_mfma_f32_16x16x32_bf16 v[24:27], v[36:39], v[4:7], v[160:163]
	v_mfma_f32_16x16x32_bf16 v[60:63], v[28:31], v[12:15], v[44:47]
	v_mfma_f32_16x16x32_bf16 v[44:47], v[196:199], v[12:15], v[24:27]
	v_mfma_f32_16x16x32_bf16 v[24:27], v[36:39], v[236:239], v[164:167]
	v_mfma_f32_16x16x32_bf16 v[36:39], v[196:199], v[240:243], v[24:27]
	v_mfma_f32_16x16x32_bf16 v[24:27], v[200:203], v[4:7], v[168:171]
	v_mfma_f32_16x16x32_bf16 v[4:7], v[232:235], v[4:7], v[176:179]
	v_mfma_f32_16x16x32_bf16 v[28:31], v[204:207], v[12:15], v[24:27]
	v_mfma_f32_16x16x32_bf16 v[24:27], v[200:203], v[236:239], v[172:175]
	v_mfma_f32_16x16x32_bf16 v[12:15], v[134:137], v[12:15], v[4:7]
	v_mfma_f32_16x16x32_bf16 v[4:7], v[232:235], v[236:239], v[180:183]
	v_mfma_f32_16x16x32_bf16 v[24:27], v[204:207], v[240:243], v[24:27]
	v_mfma_f32_16x16x32_bf16 v[4:7], v[134:137], v[240:243], v[4:7]
	s_setprio 1
	v_cmp_gt_u32_e32 vcc, s19, v133
	s_barrier
	s_and_saveexec_b64 s[0:1], vcc
	s_cbranch_execz .LBB0_135
	s_barrier
	s_branch .LBB0_135

.LBB0_153:
	ds_read_b128 v[138:141], v137
	ds_read_b128 v[142:145], v137 offset:1024
	ds_read_b128 v[146:149], v137 offset:2048
	ds_read_b128 v[150:153], v137 offset:3072
	s_mov_b32 m0, s79
	s_add_i32 s86, s85, 0xfffa7f00
	ds_read_b128 v[154:157], v132
	ds_read_b128 v[158:161], v132 offset:1024
	ds_read_b128 v[162:165], v131
	ds_read_b128 v[174:177], v131 offset:1024
	ds_read_b128 v[178:181], v130
	ds_read_b128 v[182:185], v130 offset:1024
	ds_read_b128 v[186:189], v129
	ds_read_b128 v[190:193], v129 offset:1024
	buffer_load_dwordx4 v134, s[4:7], s86 offen lds
	s_add_i32 s86, s85, 0xffffff00
	s_mov_b32 m0, s67
	s_nop 0
	buffer_load_dwordx4 v134, s[4:7], s86 offen lds
	s_waitcnt lgkmcnt(8)
	s_barrier
	s_waitcnt lgkmcnt(0)
	s_setprio 0
	s_waitcnt lgkmcnt(7)
	v_mfma_f32_16x16x32_bf16 v[124:127], v[154:157], v[138:141], v[124:127]
	v_mfma_f32_16x16x32_bf16 v[120:123], v[154:157], v[146:149], v[120:123]
	s_waitcnt lgkmcnt(5)
	v_mfma_f32_16x16x32_bf16 v[116:119], v[162:165], v[138:141], v[116:119]
	v_mfma_f32_16x16x32_bf16 v[112:115], v[162:165], v[146:149], v[112:115]
	s_waitcnt lgkmcnt(3)
	v_mfma_f32_16x16x32_bf16 v[108:111], v[178:181], v[138:141], v[108:111]
	v_mfma_f32_16x16x32_bf16 v[104:107], v[178:181], v[146:149], v[104:107]
	s_waitcnt lgkmcnt(1)
	v_mfma_f32_16x16x32_bf16 v[100:103], v[186:189], v[138:141], v[100:103]
	v_mfma_f32_16x16x32_bf16 v[96:99], v[186:189], v[146:149], v[96:99]
	v_mfma_f32_16x16x32_bf16 v[124:127], v[158:161], v[142:145], v[124:127]
	v_mfma_f32_16x16x32_bf16 v[120:123], v[158:161], v[150:153], v[120:123]
	v_mfma_f32_16x16x32_bf16 v[116:119], v[174:177], v[142:145], v[116:119]
	v_mfma_f32_16x16x32_bf16 v[112:115], v[174:177], v[150:153], v[112:115]
	v_mfma_f32_16x16x32_bf16 v[108:111], v[182:185], v[142:145], v[108:111]
	v_mfma_f32_16x16x32_bf16 v[104:107], v[182:185], v[150:153], v[104:107]
	s_waitcnt lgkmcnt(0)
	v_mfma_f32_16x16x32_bf16 v[100:103], v[190:193], v[142:145], v[100:103]
	v_mfma_f32_16x16x32_bf16 v[96:99], v[190:193], v[150:153], v[96:99]
	s_setprio 1
	s_barrier
	s_mov_b32 m0, s37
	s_add_i32 s86, s85, 0xffef7f80
	ds_read_b128 v[194:197], v136
	ds_read_b128 v[198:201], v136 offset:1024
	ds_read_b128 v[202:205], v136 offset:2048
	ds_read_b128 v[206:209], v136 offset:3072
	buffer_load_dwordx4 v134, s[8:11], s86 offen lds
	s_add_i32 s87, s85, 0xfff4ff80
	s_mov_b32 m0, s38
	s_nop 0
	buffer_load_dwordx4 v134, s[8:11], s87 offen lds
	s_barrier
	s_waitcnt lgkmcnt(0)
	s_setprio 0
	s_waitcnt lgkmcnt(3)
	v_mfma_f32_16x16x32_bf16 v[92:95], v[154:157], v[194:197], v[92:95]
	s_waitcnt lgkmcnt(1)
	v_mfma_f32_16x16x32_bf16 v[88:91], v[154:157], v[202:205], v[88:91]
	v_mfma_f32_16x16x32_bf16 v[84:87], v[162:165], v[194:197], v[84:87]
	v_mfma_f32_16x16x32_bf16 v[80:83], v[162:165], v[202:205], v[80:83]
	v_mfma_f32_16x16x32_bf16 v[76:79], v[178:181], v[194:197], v[76:79]
	v_mfma_f32_16x16x32_bf16 v[72:75], v[178:181], v[202:205], v[72:75]
	v_mfma_f32_16x16x32_bf16 v[68:71], v[186:189], v[194:197], v[68:71]
	v_mfma_f32_16x16x32_bf16 v[64:67], v[186:189], v[202:205], v[64:67]
	v_mfma_f32_16x16x32_bf16 v[92:95], v[158:161], v[198:201], v[92:95]
	s_waitcnt lgkmcnt(0)
	v_mfma_f32_16x16x32_bf16 v[88:91], v[158:161], v[206:209], v[88:91]
	v_mfma_f32_16x16x32_bf16 v[84:87], v[174:177], v[198:201], v[84:87]
	v_mfma_f32_16x16x32_bf16 v[80:83], v[174:177], v[206:209], v[80:83]
	v_mfma_f32_16x16x32_bf16 v[76:79], v[182:185], v[198:201], v[76:79]
	v_mfma_f32_16x16x32_bf16 v[72:75], v[182:185], v[206:209], v[72:75]
	v_mfma_f32_16x16x32_bf16 v[68:71], v[190:193], v[198:201], v[68:71]
	v_mfma_f32_16x16x32_bf16 v[64:67], v[190:193], v[206:209], v[64:67]
	s_setprio 1
	s_mov_b32 m0, s36
	s_barrier
	ds_read_b128 v[154:157], v132 offset:16384
	ds_read_b128 v[158:161], v132 offset:17408
	ds_read_b128 v[162:165], v131 offset:16384
	ds_read_b128 v[174:177], v131 offset:17408
	ds_read_b128 v[178:181], v130 offset:16384
	ds_read_b128 v[182:185], v130 offset:17408
	ds_read_b128 v[186:189], v129 offset:16384
	ds_read_b128 v[190:193], v129 offset:17408
	buffer_load_dwordx4 v134, s[4:7], s86 offen lds
	s_mov_b32 m0, s39
	s_nop 0
	buffer_load_dwordx4 v134, s[4:7], s87 offen lds
	s_barrier
	s_waitcnt lgkmcnt(0)
	s_setprio 0
	s_waitcnt lgkmcnt(7)
	v_mfma_f32_16x16x32_bf16 v[60:63], v[154:157], v[138:141], v[60:63]
	v_mfma_f32_16x16x32_bf16 v[56:59], v[154:157], v[146:149], v[56:59]
	s_waitcnt lgkmcnt(5)
	v_mfma_f32_16x16x32_bf16 v[52:55], v[162:165], v[138:141], v[52:55]
	v_mfma_f32_16x16x32_bf16 v[48:51], v[162:165], v[146:149], v[48:51]
	s_waitcnt lgkmcnt(3)
	v_mfma_f32_16x16x32_bf16 v[44:47], v[178:181], v[138:141], v[44:47]
	v_mfma_f32_16x16x32_bf16 v[40:43], v[178:181], v[146:149], v[40:43]
	s_waitcnt lgkmcnt(1)
	v_mfma_f32_16x16x32_bf16 v[36:39], v[186:189], v[138:141], v[36:39]
	v_mfma_f32_16x16x32_bf16 v[32:35], v[186:189], v[146:149], v[32:35]
	v_mfma_f32_16x16x32_bf16 v[60:63], v[158:161], v[142:145], v[60:63]
	v_mfma_f32_16x16x32_bf16 v[56:59], v[158:161], v[150:153], v[56:59]
	v_mfma_f32_16x16x32_bf16 v[52:55], v[174:177], v[142:145], v[52:55]
	v_mfma_f32_16x16x32_bf16 v[48:51], v[174:177], v[150:153], v[48:51]
	v_mfma_f32_16x16x32_bf16 v[44:47], v[182:185], v[142:145], v[44:47]
	v_mfma_f32_16x16x32_bf16 v[40:43], v[182:185], v[150:153], v[40:43]
	s_waitcnt lgkmcnt(0)
	v_mfma_f32_16x16x32_bf16 v[36:39], v[190:193], v[142:145], v[36:39]
	v_mfma_f32_16x16x32_bf16 v[32:35], v[190:193], v[150:153], v[32:35]
	s_setprio 1
	s_barrier
	s_mov_b32 m0, s40
	s_add_i32 s86, s85, 0xfffa7f80
	buffer_load_dwordx4 v134, s[8:11], s86 offen lds
	s_add_i32 s87, s85, 0xffffff80
	s_mov_b32 m0, s41
	s_nop 0
	buffer_load_dwordx4 v134, s[8:11], s87 offen lds
	s_waitcnt vmcnt(6)
	s_barrier
	s_setprio 0
	v_mfma_f32_16x16x32_bf16 v[28:31], v[154:157], v[194:197], v[28:31]
	v_mfma_f32_16x16x32_bf16 v[24:27], v[154:157], v[202:205], v[24:27]
	v_mfma_f32_16x16x32_bf16 v[20:23], v[162:165], v[194:197], v[20:23]
	v_mfma_f32_16x16x32_bf16 v[16:19], v[162:165], v[202:205], v[16:19]
	v_mfma_f32_16x16x32_bf16 v[12:15], v[178:181], v[194:197], v[12:15]
	v_mfma_f32_16x16x32_bf16 v[8:11], v[178:181], v[202:205], v[8:11]
	v_mfma_f32_16x16x32_bf16 v[4:7], v[186:189], v[194:197], v[4:7]
	v_mfma_f32_16x16x32_bf16 v[0:3], v[186:189], v[202:205], v[0:3]
	v_mfma_f32_16x16x32_bf16 v[28:31], v[158:161], v[198:201], v[28:31]
	v_mfma_f32_16x16x32_bf16 v[24:27], v[158:161], v[206:209], v[24:27]
	v_mfma_f32_16x16x32_bf16 v[20:23], v[174:177], v[198:201], v[20:23]
	v_mfma_f32_16x16x32_bf16 v[16:19], v[174:177], v[206:209], v[16:19]
	v_mfma_f32_16x16x32_bf16 v[12:15], v[182:185], v[198:201], v[12:15]
	v_mfma_f32_16x16x32_bf16 v[8:11], v[182:185], v[206:209], v[8:11]
	v_mfma_f32_16x16x32_bf16 v[4:7], v[190:193], v[198:201], v[4:7]
	v_mfma_f32_16x16x32_bf16 v[0:3], v[190:193], v[206:209], v[0:3]
	s_setprio 1
	s_barrier
	ds_read_b128 v[138:141], v135
	ds_read_b128 v[142:145], v135 offset:1024
	ds_read_b128 v[146:149], v135 offset:2048
	ds_read_b128 v[150:153], v135 offset:3072
	s_mov_b32 m0, s42
	ds_read_b128 v[154:157], v132 offset:32768
	ds_read_b128 v[158:161], v132 offset:33792
	ds_read_b128 v[162:165], v131 offset:32768
	ds_read_b128 v[174:177], v131 offset:33792
	ds_read_b128 v[178:181], v130 offset:32768
	ds_read_b128 v[182:185], v130 offset:33792
	ds_read_b128 v[186:189], v129 offset:32768
	ds_read_b128 v[190:193], v129 offset:33792
	buffer_load_dwordx4 v134, s[4:7], s86 offen lds
	s_mov_b32 m0, s43
	s_nop 0
	buffer_load_dwordx4 v134, s[4:7], s87 offen lds
	s_waitcnt lgkmcnt(8)
	s_barrier
	s_waitcnt lgkmcnt(0)
	s_setprio 0
	s_waitcnt lgkmcnt(7)
	v_mfma_f32_16x16x32_bf16 v[124:127], v[154:157], v[138:141], v[124:127]
	v_mfma_f32_16x16x32_bf16 v[120:123], v[154:157], v[146:149], v[120:123]
	s_waitcnt lgkmcnt(5)
	v_mfma_f32_16x16x32_bf16 v[116:119], v[162:165], v[138:141], v[116:119]
	v_mfma_f32_16x16x32_bf16 v[112:115], v[162:165], v[146:149], v[112:115]
	s_waitcnt lgkmcnt(3)
	v_mfma_f32_16x16x32_bf16 v[108:111], v[178:181], v[138:141], v[108:111]
	v_mfma_f32_16x16x32_bf16 v[104:107], v[178:181], v[146:149], v[104:107]
	s_waitcnt lgkmcnt(1)
	v_mfma_f32_16x16x32_bf16 v[100:103], v[186:189], v[138:141], v[100:103]
	v_mfma_f32_16x16x32_bf16 v[96:99], v[186:189], v[146:149], v[96:99]
	v_mfma_f32_16x16x32_bf16 v[124:127], v[158:161], v[142:145], v[124:127]
	v_mfma_f32_16x16x32_bf16 v[120:123], v[158:161], v[150:153], v[120:123]
	v_mfma_f32_16x16x32_bf16 v[116:119], v[174:177], v[142:145], v[116:119]
	v_mfma_f32_16x16x32_bf16 v[112:115], v[174:177], v[150:153], v[112:115]
	v_mfma_f32_16x16x32_bf16 v[108:111], v[182:185], v[142:145], v[108:111]
	v_mfma_f32_16x16x32_bf16 v[104:107], v[182:185], v[150:153], v[104:107]
	s_waitcnt lgkmcnt(0)
	v_mfma_f32_16x16x32_bf16 v[100:103], v[190:193], v[142:145], v[100:103]
	v_mfma_f32_16x16x32_bf16 v[96:99], v[190:193], v[150:153], v[96:99]
	s_setprio 1
	s_barrier
	s_mov_b32 m0, s45
	s_add_i32 s86, s85, 0xffef8000
	ds_read_b128 v[194:197], v133
	ds_read_b128 v[198:201], v133 offset:1024
	ds_read_b128 v[202:205], v133 offset:2048
	ds_read_b128 v[206:209], v133 offset:3072
	buffer_load_dwordx4 v134, s[8:11], s86 offen lds
	s_add_i32 s87, s85, 0xfff50000
	s_mov_b32 m0, s46
	s_nop 0
	buffer_load_dwordx4 v134, s[8:11], s87 offen lds
	s_barrier
	s_waitcnt lgkmcnt(0)
	s_setprio 0
	s_waitcnt lgkmcnt(3)
	v_mfma_f32_16x16x32_bf16 v[92:95], v[154:157], v[194:197], v[92:95]
	s_waitcnt lgkmcnt(1)
	v_mfma_f32_16x16x32_bf16 v[88:91], v[154:157], v[202:205], v[88:91]
	v_mfma_f32_16x16x32_bf16 v[84:87], v[162:165], v[194:197], v[84:87]
	v_mfma_f32_16x16x32_bf16 v[80:83], v[162:165], v[202:205], v[80:83]
	v_mfma_f32_16x16x32_bf16 v[76:79], v[178:181], v[194:197], v[76:79]
	v_mfma_f32_16x16x32_bf16 v[72:75], v[178:181], v[202:205], v[72:75]
	v_mfma_f32_16x16x32_bf16 v[68:71], v[186:189], v[194:197], v[68:71]
	v_mfma_f32_16x16x32_bf16 v[64:67], v[186:189], v[202:205], v[64:67]
	v_mfma_f32_16x16x32_bf16 v[92:95], v[158:161], v[198:201], v[92:95]
	s_waitcnt lgkmcnt(0)
	v_mfma_f32_16x16x32_bf16 v[88:91], v[158:161], v[206:209], v[88:91]
	v_mfma_f32_16x16x32_bf16 v[84:87], v[174:177], v[198:201], v[84:87]
	v_mfma_f32_16x16x32_bf16 v[80:83], v[174:177], v[206:209], v[80:83]
	v_mfma_f32_16x16x32_bf16 v[76:79], v[182:185], v[198:201], v[76:79]
	v_mfma_f32_16x16x32_bf16 v[72:75], v[182:185], v[206:209], v[72:75]
	v_mfma_f32_16x16x32_bf16 v[68:71], v[190:193], v[198:201], v[68:71]
	v_mfma_f32_16x16x32_bf16 v[64:67], v[190:193], v[206:209], v[64:67]
	s_setprio 1
	s_mov_b32 m0, s47
	s_barrier
	ds_read_b128 v[154:157], v132 offset:49152
	ds_read_b128 v[158:161], v132 offset:50176
	ds_read_b128 v[162:165], v131 offset:49152
	ds_read_b128 v[174:177], v131 offset:50176
	ds_read_b128 v[178:181], v130 offset:49152
	ds_read_b128 v[182:185], v130 offset:50176
	ds_read_b128 v[186:189], v129 offset:49152
	ds_read_b128 v[190:193], v129 offset:50176
	buffer_load_dwordx4 v134, s[4:7], s86 offen lds
	s_mov_b32 m0, s78
	s_nop 0
	buffer_load_dwordx4 v134, s[4:7], s87 offen lds
	s_barrier
; #define LDA(dst, b, h)                                                                             \
;   _Pragma("unroll") for (int m = 0; m < 4; ++m) _Pragma("unroll") for (int k = 0; k < 2; ++k)      \
;       dst[m][k] = *reinterpret_cast<const bf16x8*>(SA(b, h) + lds_byte(wr * 64 + m * 16 + fr, k * 32 + fq * 8))
; #define LDB(dst, b, h)                                                                             \
;   _Pragma("unroll") for (int n = 0; n < 2; ++n) _Pragma("unroll") for (int k = 0; k < 2; ++k)      \
;       dst[n][k] = *reinterpret_cast<const bf16x8*>(SB(b, h) + lds_byte(wc * 32 + n * 16 + fr, k * 32 + fq * 8))
; #define WAIT_V(n) asm volatile("s_waitcnt vmcnt(" #n ")" ::: "memory")
; #define WAIT_L(n) asm volatile("s_waitcnt lgkmcnt(" #n ")" ::: "memory")
; #define BAR __builtin_amdgcn_s_barrier()
; template <bool PEEL = false>
; __device__ __forceinline__ void gemm_tile(f32x4 (&acc)[2][2][4][2], const u16* __restrict__ A, int lda,
;                                           const u16* __restrict__ B, int K) {
;     ...
;   {
;     LDB(B0, 0, 0); LDA(At, 0, 0); STAGE_A(SA(1, 1), 1, nt - 1);
;     BAR; WAIT_L(0); MMA(0, 0, At, B0); BAR;
;     LDB(B1, 0, 1); BAR; WAIT_L(0); MMA(0, 1, At, B1); BAR;
;     LDA(At, 0, 1); WAIT_V(4); BAR; WAIT_L(0); MMA(1, 0, At, B0); MMA(1, 1, At, B1); BAR;
	s_waitcnt lgkmcnt(0)
	s_setprio 0
	s_waitcnt lgkmcnt(7)
	v_mfma_f32_16x16x32_bf16 v[60:63], v[154:157], v[138:141], v[60:63]
	v_mfma_f32_16x16x32_bf16 v[56:59], v[154:157], v[146:149], v[56:59]
	s_waitcnt lgkmcnt(5)
	v_mfma_f32_16x16x32_bf16 v[52:55], v[162:165], v[138:141], v[52:55]
	v_mfma_f32_16x16x32_bf16 v[48:51], v[162:165], v[146:149], v[48:51]
	s_waitcnt lgkmcnt(3)
	v_mfma_f32_16x16x32_bf16 v[44:47], v[178:181], v[138:141], v[44:47]
	v_mfma_f32_16x16x32_bf16 v[40:43], v[178:181], v[146:149], v[40:43]
	s_waitcnt lgkmcnt(1)
	v_mfma_f32_16x16x32_bf16 v[36:39], v[186:189], v[138:141], v[36:39]
	v_mfma_f32_16x16x32_bf16 v[32:35], v[186:189], v[146:149], v[32:35]
	v_mfma_f32_16x16x32_bf16 v[60:63], v[158:161], v[142:145], v[60:63]
	v_mfma_f32_16x16x32_bf16 v[56:59], v[158:161], v[150:153], v[56:59]
	v_mfma_f32_16x16x32_bf16 v[52:55], v[174:177], v[142:145], v[52:55]
	v_mfma_f32_16x16x32_bf16 v[48:51], v[174:177], v[150:153], v[48:51]
	v_mfma_f32_16x16x32_bf16 v[44:47], v[182:185], v[142:145], v[44:47]
	v_mfma_f32_16x16x32_bf16 v[40:43], v[182:185], v[150:153], v[40:43]
	s_waitcnt lgkmcnt(0)
	v_mfma_f32_16x16x32_bf16 v[36:39], v[190:193], v[142:145], v[36:39]
	v_mfma_f32_16x16x32_bf16 v[32:35], v[190:193], v[150:153], v[32:35]
	s_setprio 1
	s_barrier
	s_add_i32 s86, s85, 0xfffa8000
	s_mov_b32 m0, s82
	s_nop 0
	buffer_load_dwordx4 v134, s[8:11], s86 offen lds
	s_mov_b32 m0, s83
	s_nop 0
	buffer_load_dwordx4 v134, s[8:11], s85 offen lds
	s_waitcnt vmcnt(6)
	s_barrier
	s_setprio 0
	v_mfma_f32_16x16x32_bf16 v[28:31], v[154:157], v[194:197], v[28:31]
	v_mfma_f32_16x16x32_bf16 v[24:27], v[154:157], v[202:205], v[24:27]
	v_mfma_f32_16x16x32_bf16 v[20:23], v[162:165], v[194:197], v[20:23]
	v_mfma_f32_16x16x32_bf16 v[16:19], v[162:165], v[202:205], v[16:19]
	v_mfma_f32_16x16x32_bf16 v[12:15], v[178:181], v[194:197], v[12:15]
	v_mfma_f32_16x16x32_bf16 v[8:11], v[178:181], v[202:205], v[8:11]
	v_mfma_f32_16x16x32_bf16 v[4:7], v[186:189], v[194:197], v[4:7]
	v_mfma_f32_16x16x32_bf16 v[0:3], v[186:189], v[202:205], v[0:3]
	v_mfma_f32_16x16x32_bf16 v[28:31], v[158:161], v[198:201], v[28:31]
	v_mfma_f32_16x16x32_bf16 v[24:27], v[158:161], v[206:209], v[24:27]
	v_mfma_f32_16x16x32_bf16 v[20:23], v[174:177], v[198:201], v[20:23]
	v_mfma_f32_16x16x32_bf16 v[16:19], v[174:177], v[206:209], v[16:19]
	v_mfma_f32_16x16x32_bf16 v[12:15], v[182:185], v[198:201], v[12:15]
	v_mfma_f32_16x16x32_bf16 v[8:11], v[182:185], v[206:209], v[8:11]
	v_mfma_f32_16x16x32_bf16 v[4:7], v[190:193], v[198:201], v[4:7]
	v_mfma_f32_16x16x32_bf16 v[0:3], v[190:193], v[206:209], v[0:3]
	s_setprio 1
	s_add_i32 s84, s84, 2
	s_addk_i32 s85, 0x100
	s_cmp_lt_u32 s84, 40
	s_barrier
	s_cbranch_scc1 .LBB0_153
	s_mov_b32 s6, s10
	s_mov_b32 s7, s11
	s_mov_b32 m0, s79
	ds_read_b128 v[138:141], v137
	ds_read_b128 v[142:145], v137 offset:1024
	ds_read_b128 v[146:149], v137 offset:2048
	ds_read_b128 v[150:153], v137 offset:3072
	ds_read_b128 v[154:157], v132
	ds_read_b128 v[158:161], v132 offset:1024
	ds_read_b128 v[162:165], v131
	ds_read_b128 v[174:177], v131 offset:1024
	ds_read_b128 v[178:181], v130
	ds_read_b128 v[182:185], v130 offset:1024
	ds_read_b128 v[186:189], v129
	ds_read_b128 v[190:193], v129 offset:1024
	buffer_load_dwordx4 v134, s[4:7], s29 offen lds
	s_mov_b32 m0, s67
	s_nop 0
	buffer_load_dwordx4 v134, s[4:7], s30 offen lds
	s_barrier
	s_waitcnt lgkmcnt(0)
	s_setprio 0
	s_waitcnt lgkmcnt(7)
	v_mfma_f32_16x16x32_bf16 v[124:127], v[154:157], v[138:141], v[124:127]
	v_mfma_f32_16x16x32_bf16 v[120:123], v[154:157], v[146:149], v[120:123]
	s_waitcnt lgkmcnt(3)
	v_mfma_f32_16x16x32_bf16 v[108:111], v[178:181], v[138:141], v[108:111]
	v_mfma_f32_16x16x32_bf16 v[104:107], v[178:181], v[146:149], v[104:107]
	v_mfma_f32_16x16x32_bf16 v[124:127], v[158:161], v[142:145], v[124:127]
	v_mfma_f32_16x16x32_bf16 v[120:123], v[158:161], v[150:153], v[120:123]
	v_mfma_f32_16x16x32_bf16 v[116:119], v[162:165], v[138:141], v[116:119]
	v_mfma_f32_16x16x32_bf16 v[112:115], v[162:165], v[146:149], v[112:115]
	s_waitcnt lgkmcnt(2)
	v_mfma_f32_16x16x32_bf16 v[108:111], v[182:185], v[142:145], v[108:111]
	v_mfma_f32_16x16x32_bf16 v[104:107], v[182:185], v[150:153], v[104:107]
	s_waitcnt lgkmcnt(1)
	v_mfma_f32_16x16x32_bf16 v[100:103], v[186:189], v[138:141], v[100:103]
	v_mfma_f32_16x16x32_bf16 v[96:99], v[186:189], v[146:149], v[96:99]
	v_mfma_f32_16x16x32_bf16 v[194:197], v[174:177], v[142:145], v[116:119]
	v_mfma_f32_16x16x32_bf16 v[198:201], v[174:177], v[150:153], v[112:115]
	s_waitcnt lgkmcnt(0)
	v_mfma_f32_16x16x32_bf16 v[202:205], v[190:193], v[142:145], v[100:103]
	v_mfma_f32_16x16x32_bf16 v[206:209], v[190:193], v[150:153], v[96:99]
	s_setprio 1
	s_barrier
	s_nop 0
	ds_read_b128 v[96:99], v136
	ds_read_b128 v[100:103], v136 offset:1024
	ds_read_b128 v[112:115], v136 offset:2048
	ds_read_b128 v[116:119], v136 offset:3072
	s_barrier
	s_waitcnt lgkmcnt(0)
	s_setprio 0
	s_waitcnt lgkmcnt(3)
	v_mfma_f32_16x16x32_bf16 v[92:95], v[154:157], v[96:99], v[92:95]
	s_waitcnt lgkmcnt(1)
	v_mfma_f32_16x16x32_bf16 v[88:91], v[154:157], v[112:115], v[88:91]
	v_mfma_f32_16x16x32_bf16 v[76:79], v[178:181], v[96:99], v[76:79]
	v_mfma_f32_16x16x32_bf16 v[72:75], v[178:181], v[112:115], v[72:75]
	v_mfma_f32_16x16x32_bf16 v[92:95], v[158:161], v[100:103], v[92:95]
	s_waitcnt lgkmcnt(0)
	v_mfma_f32_16x16x32_bf16 v[88:91], v[158:161], v[116:119], v[88:91]
	v_mfma_f32_16x16x32_bf16 v[84:87], v[162:165], v[96:99], v[84:87]
	v_mfma_f32_16x16x32_bf16 v[80:83], v[162:165], v[112:115], v[80:83]
	v_mfma_f32_16x16x32_bf16 v[76:79], v[182:185], v[100:103], v[76:79]
	v_mfma_f32_16x16x32_bf16 v[72:75], v[182:185], v[116:119], v[72:75]
	v_mfma_f32_16x16x32_bf16 v[68:71], v[186:189], v[96:99], v[68:71]
	v_mfma_f32_16x16x32_bf16 v[64:67], v[186:189], v[112:115], v[64:67]
	v_mfma_f32_16x16x32_bf16 v[154:157], v[174:177], v[100:103], v[84:87]
	v_mfma_f32_16x16x32_bf16 v[158:161], v[174:177], v[116:119], v[80:83]
	v_mfma_f32_16x16x32_bf16 v[162:165], v[190:193], v[100:103], v[68:71]
	v_mfma_f32_16x16x32_bf16 v[174:177], v[190:193], v[116:119], v[64:67]
	s_setprio 1
	s_barrier
; #define LDA(dst, b, h)                                                                             \
;   _Pragma("unroll") for (int m = 0; m < 4; ++m) _Pragma("unroll") for (int k = 0; k < 2; ++k)      \
;       dst[m][k] = *reinterpret_cast<const bf16x8*>(SA(b, h) + lds_byte(wr * 64 + m * 16 + fr, k * 32 + fq * 8))
; #define LDB(dst, b, h)                                                                             \
;   _Pragma("unroll") for (int n = 0; n < 2; ++n) _Pragma("unroll") for (int k = 0; k < 2; ++k)      \
;       dst[n][k] = *reinterpret_cast<const bf16x8*>(SB(b, h) + lds_byte(wc * 32 + n * 16 + fr, k * 32 + fq * 8))
; #define WAIT_V(n) asm volatile("s_waitcnt vmcnt(" #n ")" ::: "memory")
; #define WAIT_L(n) asm volatile("s_waitcnt lgkmcnt(" #n ")" ::: "memory")
; #define BAR __builtin_amdgcn_s_barrier()
; template <bool PEEL = false>
; __device__ __forceinline__ void gemm_tile(f32x4 (&acc)[2][2][4][2], const u16* __restrict__ A, int lda,
;                                           const u16* __restrict__ B, int K) {
;     ...
;     LDA(At, 0, 1); WAIT_V(4); BAR; WAIT_L(0); MMA(1, 0, At, B0); MMA(1, 1, At, B1); BAR;
;   }
;   {
;     LDB(B0, 1, 0); LDA(At, 1, 0); WAIT_V(2); BAR; WAIT_L(0); MMA(0, 0, At, B0); BAR;
	s_nop 1
	ds_read_b128 v[64:67], v132 offset:16384
	ds_read_b128 v[68:71], v132 offset:17408
	ds_read_b128 v[80:83], v131 offset:16384
	ds_read_b128 v[84:87], v131 offset:17408
	ds_read_b128 v[178:181], v130 offset:16384
	ds_read_b128 v[182:185], v130 offset:17408
	ds_read_b128 v[186:189], v129 offset:16384
	ds_read_b128 v[190:193], v129 offset:17408
	s_waitcnt vmcnt(4)
	s_barrier
	s_waitcnt lgkmcnt(0)
	s_setprio 0
	s_waitcnt lgkmcnt(7)
	v_mfma_f32_16x16x32_bf16 v[60:63], v[64:67], v[138:141], v[60:63]
	v_mfma_f32_16x16x32_bf16 v[56:59], v[64:67], v[146:149], v[56:59]
	s_waitcnt lgkmcnt(3)
	v_mfma_f32_16x16x32_bf16 v[44:47], v[178:181], v[138:141], v[44:47]
	v_mfma_f32_16x16x32_bf16 v[40:43], v[178:181], v[146:149], v[40:43]
	v_mfma_f32_16x16x32_bf16 v[60:63], v[68:71], v[142:145], v[60:63]
	v_mfma_f32_16x16x32_bf16 v[56:59], v[68:71], v[150:153], v[56:59]
	v_mfma_f32_16x16x32_bf16 v[52:55], v[80:83], v[138:141], v[52:55]
	v_mfma_f32_16x16x32_bf16 v[48:51], v[80:83], v[146:149], v[48:51]
	s_waitcnt lgkmcnt(2)
	v_mfma_f32_16x16x32_bf16 v[44:47], v[182:185], v[142:145], v[44:47]
	v_mfma_f32_16x16x32_bf16 v[40:43], v[182:185], v[150:153], v[40:43]
	s_waitcnt lgkmcnt(1)
	v_mfma_f32_16x16x32_bf16 v[36:39], v[186:189], v[138:141], v[36:39]
	v_mfma_f32_16x16x32_bf16 v[32:35], v[186:189], v[146:149], v[32:35]
	v_mfma_f32_16x16x32_bf16 v[210:213], v[84:87], v[142:145], v[52:55]
	v_mfma_f32_16x16x32_bf16 v[214:217], v[84:87], v[150:153], v[48:51]
	s_waitcnt lgkmcnt(0)
	v_mfma_f32_16x16x32_bf16 v[136:139], v[190:193], v[142:145], v[36:39]
	v_mfma_f32_16x16x32_bf16 v[140:143], v[190:193], v[150:153], v[32:35]
	s_setprio 1
	s_setprio 0
	v_mfma_f32_16x16x32_bf16 v[28:31], v[64:67], v[96:99], v[28:31]
	v_mfma_f32_16x16x32_bf16 v[24:27], v[64:67], v[112:115], v[24:27]
	v_mfma_f32_16x16x32_bf16 v[12:15], v[178:181], v[96:99], v[12:15]
	v_mfma_f32_16x16x32_bf16 v[8:11], v[178:181], v[112:115], v[8:11]
	v_mfma_f32_16x16x32_bf16 v[28:31], v[68:71], v[100:103], v[28:31]
	v_mfma_f32_16x16x32_bf16 v[24:27], v[68:71], v[116:119], v[24:27]
	v_mfma_f32_16x16x32_bf16 v[20:23], v[80:83], v[96:99], v[20:23]
	v_mfma_f32_16x16x32_bf16 v[16:19], v[80:83], v[112:115], v[16:19]
	v_mfma_f32_16x16x32_bf16 v[12:15], v[182:185], v[100:103], v[12:15]
	v_mfma_f32_16x16x32_bf16 v[8:11], v[182:185], v[116:119], v[8:11]
	v_mfma_f32_16x16x32_bf16 v[4:7], v[186:189], v[96:99], v[4:7]
	v_mfma_f32_16x16x32_bf16 v[0:3], v[186:189], v[112:115], v[0:3]
	v_mfma_f32_16x16x32_bf16 v[144:147], v[84:87], v[100:103], v[20:23]
	v_mfma_f32_16x16x32_bf16 v[148:151], v[84:87], v[116:119], v[16:19]
	v_mfma_f32_16x16x32_bf16 v[178:181], v[190:193], v[100:103], v[4:7]
	v_mfma_f32_16x16x32_bf16 v[182:185], v[190:193], v[116:119], v[0:3]
	s_setprio 1
	s_barrier
	s_nop 1
	ds_read_b128 v[0:3], v135
	ds_read_b128 v[4:7], v135 offset:1024
	ds_read_b128 v[186:189], v135 offset:2048
	ds_read_b128 v[190:193], v135 offset:3072
	ds_read_b128 v[16:19], v132 offset:32768
	ds_read_b128 v[20:23], v132 offset:33792
	ds_read_b128 v[32:35], v131 offset:32768
	ds_read_b128 v[36:39], v131 offset:33792
	ds_read_b128 v[48:51], v130 offset:32768
	ds_read_b128 v[52:55], v130 offset:33792
	ds_read_b128 v[218:221], v129 offset:32768
	ds_read_b128 v[222:225], v129 offset:33792
	s_waitcnt vmcnt(2)
	s_barrier
	s_waitcnt lgkmcnt(0)
	s_setprio 0
	s_waitcnt lgkmcnt(7)
	v_mfma_f32_16x16x32_bf16 v[64:67], v[16:19], v[0:3], v[124:127]
	s_waitcnt lgkmcnt(6)
	v_mfma_f32_16x16x32_bf16 v[112:115], v[20:23], v[4:7], v[64:67]
	v_mfma_f32_16x16x32_bf16 v[64:67], v[16:19], v[186:189], v[120:123]
	v_mfma_f32_16x16x32_bf16 v[116:119], v[20:23], v[190:193], v[64:67]
	s_waitcnt lgkmcnt(5)
	v_mfma_f32_16x16x32_bf16 v[64:67], v[32:35], v[0:3], v[194:197]
	s_waitcnt lgkmcnt(4)
	v_mfma_f32_16x16x32_bf16 v[96:99], v[36:39], v[4:7], v[64:67]
	v_mfma_f32_16x16x32_bf16 v[64:67], v[32:35], v[186:189], v[198:201]
	v_mfma_f32_16x16x32_bf16 v[100:103], v[36:39], v[190:193], v[64:67]
	s_waitcnt lgkmcnt(3)
	v_mfma_f32_16x16x32_bf16 v[64:67], v[48:51], v[0:3], v[108:111]
	s_waitcnt lgkmcnt(2)
	v_mfma_f32_16x16x32_bf16 v[80:83], v[52:55], v[4:7], v[64:67]
	v_mfma_f32_16x16x32_bf16 v[64:67], v[48:51], v[186:189], v[104:107]
	v_mfma_f32_16x16x32_bf16 v[84:87], v[52:55], v[190:193], v[64:67]
	s_waitcnt lgkmcnt(1)
	v_mfma_f32_16x16x32_bf16 v[64:67], v[218:221], v[0:3], v[202:205]
	v_mfma_f32_16x16x32_bf16 v[68:71], v[218:221], v[186:189], v[206:209]
	s_waitcnt lgkmcnt(0)
	v_mfma_f32_16x16x32_bf16 v[64:67], v[222:225], v[4:7], v[64:67]
	v_mfma_f32_16x16x32_bf16 v[68:71], v[222:225], v[190:193], v[68:71]
	s_setprio 1
	s_barrier
; #define LDA(dst, b, h)                                                                             \
;   _Pragma("unroll") for (int m = 0; m < 4; ++m) _Pragma("unroll") for (int k = 0; k < 2; ++k)      \
;       dst[m][k] = *reinterpret_cast<const bf16x8*>(SA(b, h) + lds_byte(wr * 64 + m * 16 + fr, k * 32 + fq * 8))
; #define LDB(dst, b, h)                                                                             \
;   _Pragma("unroll") for (int n = 0; n < 2; ++n) _Pragma("unroll") for (int k = 0; k < 2; ++k)      \
;       dst[n][k] = *reinterpret_cast<const bf16x8*>(SB(b, h) + lds_byte(wc * 32 + n * 16 + fr, k * 32 + fq * 8))
; #define WAIT_V(n) asm volatile("s_waitcnt vmcnt(" #n ")" ::: "memory")
; #define WAIT_L(n) asm volatile("s_waitcnt lgkmcnt(" #n ")" ::: "memory")
; #define BAR __builtin_amdgcn_s_barrier()
; template <bool PEEL = false>
; __device__ __forceinline__ void gemm_tile(f32x4 (&acc)[2][2][4][2], const u16* __restrict__ A, int lda,
;                                           const u16* __restrict__ B, int K) {
;     ...
;     LDB(B1, 1, 1); WAIT_V(0); BAR; WAIT_L(0); MMA(0, 1, At, B1); BAR;
;     LDA(At, 1, 1); BAR; WAIT_L(0); MMA(1, 0, At, B0); MMA(1, 1, At, B1); BAR;
;   }
;   if (wr == 0) BAR;
	ds_read_b128 v[194:197], v133
	ds_read_b128 v[198:201], v133 offset:1024
	ds_read_b128 v[202:205], v133 offset:2048
	ds_read_b128 v[206:209], v133 offset:3072
	s_waitcnt vmcnt(0)
	s_barrier
	s_waitcnt lgkmcnt(0)
	s_setprio 0
	s_waitcnt lgkmcnt(3)
	v_mfma_f32_16x16x32_bf16 v[92:95], v[16:19], v[194:197], v[92:95]
	s_waitcnt lgkmcnt(1)
	v_mfma_f32_16x16x32_bf16 v[16:19], v[16:19], v[202:205], v[88:91]
	s_waitcnt lgkmcnt(0)
	v_mfma_f32_16x16x32_bf16 v[124:127], v[20:23], v[206:209], v[16:19]
	v_mfma_f32_16x16x32_bf16 v[16:19], v[32:35], v[194:197], v[154:157]
	v_mfma_f32_16x16x32_bf16 v[104:107], v[36:39], v[198:201], v[16:19]
	v_mfma_f32_16x16x32_bf16 v[16:19], v[32:35], v[202:205], v[158:161]
	v_mfma_f32_16x16x32_bf16 v[108:111], v[36:39], v[206:209], v[16:19]
	v_mfma_f32_16x16x32_bf16 v[16:19], v[48:51], v[194:197], v[76:79]
	v_mfma_f32_16x16x32_bf16 v[88:91], v[52:55], v[198:201], v[16:19]
	v_mfma_f32_16x16x32_bf16 v[16:19], v[48:51], v[202:205], v[72:75]
	v_mfma_f32_16x16x32_bf16 v[120:123], v[20:23], v[198:201], v[92:95]
	v_mfma_f32_16x16x32_bf16 v[92:95], v[52:55], v[206:209], v[16:19]
	v_mfma_f32_16x16x32_bf16 v[16:19], v[218:221], v[194:197], v[162:165]
	v_mfma_f32_16x16x32_bf16 v[72:75], v[222:225], v[198:201], v[16:19]
	v_mfma_f32_16x16x32_bf16 v[16:19], v[218:221], v[202:205], v[174:177]
	v_mfma_f32_16x16x32_bf16 v[76:79], v[222:225], v[206:209], v[16:19]
	s_setprio 1
	s_barrier
	ds_read_b128 v[152:155], v132 offset:49152
	ds_read_b128 v[132:135], v132 offset:50176
	ds_read_b128 v[156:159], v131 offset:49152
	ds_read_b128 v[160:163], v131 offset:50176
	ds_read_b128 v[164:167], v130 offset:49152
	ds_read_b128 v[174:177], v130 offset:50176
	ds_read_b128 v[218:221], v129 offset:49152
	ds_read_b128 v[222:225], v129 offset:50176
	s_barrier
	s_waitcnt lgkmcnt(0)
	s_setprio 0
	s_waitcnt lgkmcnt(7)
	v_mfma_f32_16x16x32_bf16 v[16:19], v[152:155], v[0:3], v[60:63]
	s_waitcnt lgkmcnt(6)
	v_mfma_f32_16x16x32_bf16 v[48:51], v[132:135], v[4:7], v[16:19]
	v_mfma_f32_16x16x32_bf16 v[16:19], v[152:155], v[186:189], v[56:59]
	v_mfma_f32_16x16x32_bf16 v[52:55], v[132:135], v[190:193], v[16:19]
	s_waitcnt lgkmcnt(5)
	v_mfma_f32_16x16x32_bf16 v[16:19], v[156:159], v[0:3], v[210:213]
	s_waitcnt lgkmcnt(4)
	v_mfma_f32_16x16x32_bf16 v[32:35], v[160:163], v[4:7], v[16:19]
	v_mfma_f32_16x16x32_bf16 v[16:19], v[156:159], v[186:189], v[214:217]
	v_mfma_f32_16x16x32_bf16 v[36:39], v[160:163], v[190:193], v[16:19]
	s_waitcnt lgkmcnt(3)
	v_mfma_f32_16x16x32_bf16 v[16:19], v[164:167], v[0:3], v[44:47]
	s_waitcnt lgkmcnt(1)
	v_mfma_f32_16x16x32_bf16 v[0:3], v[218:221], v[0:3], v[136:139]
	v_mfma_f32_16x16x32_bf16 v[16:19], v[174:177], v[4:7], v[16:19]
	v_mfma_f32_16x16x32_bf16 v[20:23], v[164:167], v[186:189], v[40:43]
	s_waitcnt lgkmcnt(0)
	v_mfma_f32_16x16x32_bf16 v[0:3], v[222:225], v[4:7], v[0:3]
	v_mfma_f32_16x16x32_bf16 v[4:7], v[218:221], v[186:189], v[140:143]
	v_mfma_f32_16x16x32_bf16 v[20:23], v[174:177], v[190:193], v[20:23]
	v_mfma_f32_16x16x32_bf16 v[4:7], v[222:225], v[190:193], v[4:7]
	s_setprio 1
	s_setprio 0
	v_mfma_f32_16x16x32_bf16 v[24:27], v[152:155], v[202:205], v[24:27]
	v_mfma_f32_16x16x32_bf16 v[60:63], v[132:135], v[206:209], v[24:27]
	v_mfma_f32_16x16x32_bf16 v[24:27], v[156:159], v[194:197], v[144:147]
	v_mfma_f32_16x16x32_bf16 v[28:31], v[152:155], v[194:197], v[28:31]
	v_mfma_f32_16x16x32_bf16 v[40:43], v[160:163], v[198:201], v[24:27]
	v_mfma_f32_16x16x32_bf16 v[24:27], v[156:159], v[202:205], v[148:151]
	v_mfma_f32_16x16x32_bf16 v[12:15], v[164:167], v[194:197], v[12:15]
	v_mfma_f32_16x16x32_bf16 v[8:11], v[164:167], v[202:205], v[8:11]
	v_mfma_f32_16x16x32_bf16 v[56:59], v[132:135], v[198:201], v[28:31]
	v_mfma_f32_16x16x32_bf16 v[44:47], v[160:163], v[206:209], v[24:27]
	v_mfma_f32_16x16x32_bf16 v[24:27], v[174:177], v[198:201], v[12:15]
	v_mfma_f32_16x16x32_bf16 v[28:31], v[174:177], v[206:209], v[8:11]
	v_mfma_f32_16x16x32_bf16 v[8:11], v[218:221], v[194:197], v[178:181]
	v_mfma_f32_16x16x32_bf16 v[12:15], v[218:221], v[202:205], v[182:185]
	v_mfma_f32_16x16x32_bf16 v[8:11], v[222:225], v[198:201], v[8:11]
	v_mfma_f32_16x16x32_bf16 v[12:15], v[222:225], v[206:209], v[12:15]
	s_setprio 1
	v_cmp_gt_u32_e32 vcc, s28, v128
	s_barrier
	s_and_saveexec_b64 s[4:5], vcc
	s_cbranch_execz .LBB0_156
	s_barrier

.Lpf3_join:
	s_add_i32 s14, s16, 0x18000
	s_add_i32 s15, s16, 0x1a000
	v_and_b32_e32 v2, 15, v128
	v_lshlrev_b32_e32 v0, 12, v0
	v_and_b32_e32 v126, 0x3000, v0
	v_lshlrev_b32_e32 v0, 6, v2
	v_lshlrev_b32_e32 v2, 2, v128
	v_and_b32_e32 v26, 48, v128
	v_and_b32_e32 v27, 32, v2
	v_bitop3_b32 v127, v0, v27, v26 bitop3:0x36
	v_add_u32_e32 v0, s69, v127
	v_add_u32_e32 v134, v0, v126
	s_barrier
	ds_read_b128 v[2:5], v134
	ds_read_b128 v[6:9], v134 offset:1024
	ds_read_b128 v[10:13], v134 offset:2048
	ds_read_b128 v[14:17], v134 offset:3072
	v_lshlrev_b32_e32 v0, 13, v1
	v_add_u32_e32 v1, 0, v127
	v_add_u32_e32 v129, v1, v0
	v_lshlrev_b32_e32 v1, 6, v128
	s_movk_i32 s82, 0x3c0
	v_and_or_b32 v1, v1, s82, v26
	v_xad_u32 v1, v1, v27, 0
	v_or_b32_e32 v26, 0x800, v0
	v_or_b32_e32 v34, 0x1000, v0
	v_or_b32_e32 v0, 0x1800, v0
	s_add_i32 s82, s16, 0xc000
	v_add_u32_e32 v130, v1, v26
	v_add_u32_e32 v131, v1, v34
	v_add_u32_e32 v132, v1, v0
	s_mov_b32 m0, s82
	s_add_i32 s83, s16, 0xe000
	ds_read_b128 v[18:21], v129
	ds_read_b128 v[22:25], v129 offset:1024
	ds_read_b128 v[26:29], v130
	ds_read_b128 v[30:33], v130 offset:1024
	ds_read_b128 v[34:37], v131
	ds_read_b128 v[38:41], v131 offset:1024
	ds_read_b128 v[42:45], v132
	ds_read_b128 v[46:49], v132 offset:1024
	buffer_load_dwordx4 v133, s[56:59], s26 offen lds
	s_mov_b32 m0, s83
	s_nop 0
	buffer_load_dwordx4 v133, s[56:59], s27 offen lds
	s_waitcnt lgkmcnt(8)
	s_barrier
	s_waitcnt lgkmcnt(0)
	s_setprio 0
	s_waitcnt lgkmcnt(7)
	v_mfma_f32_16x16x32_bf16 v[50:53], v[18:21], v[2:5], 0
	v_mfma_f32_16x16x32_bf16 v[54:57], v[18:21], v[10:13], 0
	s_waitcnt lgkmcnt(5)
	v_mfma_f32_16x16x32_bf16 v[58:61], v[26:29], v[2:5], 0
	v_mfma_f32_16x16x32_bf16 v[62:65], v[26:29], v[10:13], 0
	s_waitcnt lgkmcnt(3)
	v_mfma_f32_16x16x32_bf16 v[66:69], v[34:37], v[2:5], 0
	v_mfma_f32_16x16x32_bf16 v[70:73], v[34:37], v[10:13], 0
	s_waitcnt lgkmcnt(1)
	v_mfma_f32_16x16x32_bf16 v[74:77], v[42:45], v[2:5], 0
	v_mfma_f32_16x16x32_bf16 v[78:81], v[42:45], v[10:13], 0
	v_mfma_f32_16x16x32_bf16 v[50:53], v[22:25], v[6:9], v[50:53]
	v_mfma_f32_16x16x32_bf16 v[54:57], v[22:25], v[14:17], v[54:57]
	v_mfma_f32_16x16x32_bf16 v[58:61], v[30:33], v[6:9], v[58:61]
	v_mfma_f32_16x16x32_bf16 v[62:65], v[30:33], v[14:17], v[62:65]
	v_mfma_f32_16x16x32_bf16 v[66:69], v[38:41], v[6:9], v[66:69]
	v_mfma_f32_16x16x32_bf16 v[70:73], v[38:41], v[14:17], v[70:73]
	s_waitcnt lgkmcnt(0)
	v_mfma_f32_16x16x32_bf16 v[74:77], v[46:49], v[6:9], v[74:77]
	v_mfma_f32_16x16x32_bf16 v[78:81], v[46:49], v[14:17], v[78:81]
	s_setprio 1
	s_barrier
	v_add_u32_e32 v0, s70, v127
	v_add_u32_e32 v135, v0, v126
	s_mov_b32 m0, s17
	ds_read_b128 v[82:85], v135
	ds_read_b128 v[86:89], v135 offset:1024
	ds_read_b128 v[90:93], v135 offset:2048
	ds_read_b128 v[94:97], v135 offset:3072
	buffer_load_dwordx4 v133, s[4:7], s0 offen lds
	s_mov_b32 m0, s40
	s_nop 0
	buffer_load_dwordx4 v133, s[4:7], s28 offen lds
	s_barrier
	s_waitcnt lgkmcnt(0)
	s_setprio 0
	s_waitcnt lgkmcnt(3)
	v_mfma_f32_16x16x32_bf16 v[98:101], v[18:21], v[82:85], 0
	s_waitcnt lgkmcnt(1)
	v_mfma_f32_16x16x32_bf16 v[18:21], v[18:21], v[90:93], 0
	s_waitcnt lgkmcnt(0)
	v_mfma_f32_16x16x32_bf16 v[102:105], v[22:25], v[94:97], v[18:21]
	v_mfma_f32_16x16x32_bf16 v[18:21], v[26:29], v[82:85], 0
	v_mfma_f32_16x16x32_bf16 v[106:109], v[30:33], v[86:89], v[18:21]
	v_mfma_f32_16x16x32_bf16 v[18:21], v[26:29], v[90:93], 0
	v_mfma_f32_16x16x32_bf16 v[110:113], v[30:33], v[94:97], v[18:21]
	v_mfma_f32_16x16x32_bf16 v[18:21], v[34:37], v[82:85], 0
	v_mfma_f32_16x16x32_bf16 v[114:117], v[38:41], v[86:89], v[18:21]
	v_mfma_f32_16x16x32_bf16 v[18:21], v[34:37], v[90:93], 0
	v_mfma_f32_16x16x32_bf16 v[32:35], v[38:41], v[94:97], v[18:21]
	v_mfma_f32_16x16x32_bf16 v[18:21], v[42:45], v[82:85], 0
	v_mfma_f32_16x16x32_bf16 v[36:39], v[46:49], v[86:89], v[18:21]
	v_mfma_f32_16x16x32_bf16 v[18:21], v[42:45], v[90:93], 0
	v_mfma_f32_16x16x32_bf16 v[98:101], v[22:25], v[86:89], v[98:101]
	v_mfma_f32_16x16x32_bf16 v[118:121], v[46:49], v[94:97], v[18:21]
	s_setprio 1
	s_mov_b32 m0, s16
	s_barrier
	s_nop 2
	ds_read_b128 v[18:21], v129 offset:16384
	ds_read_b128 v[22:25], v129 offset:17408
	ds_read_b128 v[26:29], v130 offset:16384
	ds_read_b128 v[40:43], v130 offset:17408
	ds_read_b128 v[44:47], v131 offset:16384
	ds_read_b128 v[122:125], v131 offset:17408
	ds_read_b128 v[144:147], v132 offset:16384
	ds_read_b128 v[148:151], v132 offset:17408
	buffer_load_dwordx4 v133, s[56:59], s0 offen lds
	s_mov_b32 m0, s41
	s_nop 0
	buffer_load_dwordx4 v133, s[56:59], s28 offen lds
	s_barrier
	s_waitcnt lgkmcnt(0)
	s_setprio 0
	s_waitcnt lgkmcnt(7)
	v_mfma_f32_16x16x32_bf16 v[152:155], v[18:21], v[2:5], 0
	s_waitcnt lgkmcnt(5)
	v_mfma_f32_16x16x32_bf16 v[160:163], v[26:29], v[2:5], 0
	s_waitcnt lgkmcnt(3)
	v_mfma_f32_16x16x32_bf16 v[168:171], v[44:47], v[2:5], 0
	s_waitcnt lgkmcnt(1)
	v_mfma_f32_16x16x32_bf16 v[0:3], v[144:147], v[2:5], 0
	v_mfma_f32_16x16x32_bf16 v[156:159], v[18:21], v[10:13], 0
	v_mfma_f32_16x16x32_bf16 v[164:167], v[26:29], v[10:13], 0
	v_mfma_f32_16x16x32_bf16 v[172:175], v[44:47], v[10:13], 0
	s_waitcnt lgkmcnt(0)
	v_mfma_f32_16x16x32_bf16 v[176:179], v[148:151], v[6:9], v[0:3]
	v_mfma_f32_16x16x32_bf16 v[0:3], v[144:147], v[10:13], 0
	v_mfma_f32_16x16x32_bf16 v[152:155], v[22:25], v[6:9], v[152:155]
	v_mfma_f32_16x16x32_bf16 v[156:159], v[22:25], v[14:17], v[156:159]
	v_mfma_f32_16x16x32_bf16 v[160:163], v[40:43], v[6:9], v[160:163]
	v_mfma_f32_16x16x32_bf16 v[164:167], v[40:43], v[14:17], v[164:167]
	v_mfma_f32_16x16x32_bf16 v[168:171], v[122:125], v[6:9], v[168:171]
	v_mfma_f32_16x16x32_bf16 v[172:175], v[122:125], v[14:17], v[172:175]
	v_mfma_f32_16x16x32_bf16 v[180:183], v[148:151], v[14:17], v[0:3]
	s_setprio 1
	s_barrier
	s_mov_b32 m0, s42
	s_nop 0
	buffer_load_dwordx4 v133, s[4:7], s29 offen lds
	s_mov_b32 m0, s43
	s_nop 0
	buffer_load_dwordx4 v133, s[4:7], s34 offen lds
	s_waitcnt vmcnt(6)
	s_barrier
	s_setprio 0
	v_mfma_f32_16x16x32_bf16 v[0:3], v[18:21], v[82:85], 0
	v_mfma_f32_16x16x32_bf16 v[184:187], v[22:25], v[86:89], v[0:3]
	v_mfma_f32_16x16x32_bf16 v[0:3], v[18:21], v[90:93], 0
	v_mfma_f32_16x16x32_bf16 v[188:191], v[22:25], v[94:97], v[0:3]
	v_mfma_f32_16x16x32_bf16 v[0:3], v[26:29], v[82:85], 0
	v_mfma_f32_16x16x32_bf16 v[192:195], v[40:43], v[86:89], v[0:3]
	v_mfma_f32_16x16x32_bf16 v[0:3], v[26:29], v[90:93], 0
	v_mfma_f32_16x16x32_bf16 v[196:199], v[40:43], v[94:97], v[0:3]
	v_mfma_f32_16x16x32_bf16 v[0:3], v[44:47], v[82:85], 0
	v_mfma_f32_16x16x32_bf16 v[200:203], v[122:125], v[86:89], v[0:3]
	v_mfma_f32_16x16x32_bf16 v[0:3], v[44:47], v[90:93], 0
	v_mfma_f32_16x16x32_bf16 v[204:207], v[122:125], v[94:97], v[0:3]
	v_mfma_f32_16x16x32_bf16 v[0:3], v[144:147], v[82:85], 0
	v_mfma_f32_16x16x32_bf16 v[208:211], v[148:151], v[86:89], v[0:3]
	v_mfma_f32_16x16x32_bf16 v[0:3], v[144:147], v[90:93], 0
	v_mfma_f32_16x16x32_bf16 v[144:147], v[148:151], v[94:97], v[0:3]
	s_setprio 1
	s_nop 5
	v_add_u32_e32 v0, s97, v127
	v_add_u32_e32 v136, v0, v126
	s_barrier
	ds_read_b128 v[122:125], v136
	ds_read_b128 v[148:151], v136 offset:1024
	ds_read_b128 v[212:215], v136 offset:2048
	ds_read_b128 v[216:219], v136 offset:3072
	s_mov_b32 m0, s45
	ds_read_b128 v[40:43], v129 offset:32768
	ds_read_b128 v[44:47], v129 offset:33792
	ds_read_b128 v[82:85], v130 offset:32768
	ds_read_b128 v[86:89], v130 offset:33792
	ds_read_b128 v[90:93], v131 offset:32768
	ds_read_b128 v[94:97], v131 offset:33792
	ds_read_b128 v[220:223], v132 offset:32768
	ds_read_b128 v[224:227], v132 offset:33792
	buffer_load_dwordx4 v133, s[56:59], s29 offen lds
	s_mov_b32 m0, s46
	s_nop 0
	buffer_load_dwordx4 v133, s[56:59], s34 offen lds
	s_waitcnt lgkmcnt(8)
	s_barrier
	s_waitcnt lgkmcnt(0)
	s_setprio 0
	s_waitcnt lgkmcnt(7)
	v_mfma_f32_16x16x32_bf16 v[0:3], v[40:43], v[122:125], v[50:53]
	s_waitcnt lgkmcnt(6)
	v_mfma_f32_16x16x32_bf16 v[28:31], v[44:47], v[148:151], v[0:3]
	v_mfma_f32_16x16x32_bf16 v[0:3], v[40:43], v[212:215], v[54:57]
	v_mfma_f32_16x16x32_bf16 v[24:27], v[44:47], v[216:219], v[0:3]
	s_waitcnt lgkmcnt(5)
	v_mfma_f32_16x16x32_bf16 v[0:3], v[82:85], v[122:125], v[58:61]
	s_waitcnt lgkmcnt(4)
	v_mfma_f32_16x16x32_bf16 v[20:23], v[86:89], v[148:151], v[0:3]
	v_mfma_f32_16x16x32_bf16 v[0:3], v[82:85], v[212:215], v[62:65]
	v_mfma_f32_16x16x32_bf16 v[16:19], v[86:89], v[216:219], v[0:3]
	s_waitcnt lgkmcnt(3)
	v_mfma_f32_16x16x32_bf16 v[0:3], v[90:93], v[122:125], v[66:69]
	s_waitcnt lgkmcnt(2)
	v_mfma_f32_16x16x32_bf16 v[12:15], v[94:97], v[148:151], v[0:3]
	v_mfma_f32_16x16x32_bf16 v[0:3], v[90:93], v[212:215], v[70:73]
	v_mfma_f32_16x16x32_bf16 v[8:11], v[94:97], v[216:219], v[0:3]
	s_waitcnt lgkmcnt(1)
	v_mfma_f32_16x16x32_bf16 v[0:3], v[220:223], v[122:125], v[74:77]
	s_waitcnt lgkmcnt(0)
	v_mfma_f32_16x16x32_bf16 v[4:7], v[224:227], v[148:151], v[0:3]
	v_mfma_f32_16x16x32_bf16 v[0:3], v[220:223], v[212:215], v[78:81]
	v_mfma_f32_16x16x32_bf16 v[0:3], v[224:227], v[216:219], v[0:3]
	s_setprio 1
	s_barrier
	v_add_u32_e32 v48, s68, v127
	v_add_u32_e32 v137, v48, v126
	s_mov_b32 m0, s14
	ds_read_b128 v[228:231], v137
	ds_read_b128 v[232:235], v137 offset:1024
	ds_read_b128 v[236:239], v137 offset:2048
	ds_read_b128 v[240:243], v137 offset:3072
	buffer_load_dwordx4 v133, s[4:7], s35 offen lds
	s_mov_b32 m0, s15
	s_nop 0
	buffer_load_dwordx4 v133, s[4:7], s36 offen lds
	s_barrier
	s_waitcnt lgkmcnt(0)
	s_setprio 0
	s_waitcnt lgkmcnt(3)
	v_mfma_f32_16x16x32_bf16 v[48:51], v[40:43], v[228:231], v[98:101]
	s_waitcnt lgkmcnt(1)
	v_mfma_f32_16x16x32_bf16 v[40:43], v[40:43], v[236:239], v[102:105]
	s_waitcnt lgkmcnt(0)
	v_mfma_f32_16x16x32_bf16 v[56:59], v[44:47], v[240:243], v[40:43]
	v_mfma_f32_16x16x32_bf16 v[40:43], v[82:85], v[228:231], v[106:109]
	v_mfma_f32_16x16x32_bf16 v[52:55], v[86:89], v[232:235], v[40:43]
	v_mfma_f32_16x16x32_bf16 v[40:43], v[82:85], v[236:239], v[110:113]
	v_mfma_f32_16x16x32_bf16 v[60:63], v[44:47], v[232:235], v[48:51]
	v_mfma_f32_16x16x32_bf16 v[48:51], v[86:89], v[240:243], v[40:43]
	v_mfma_f32_16x16x32_bf16 v[40:43], v[90:93], v[228:231], v[114:117]
	v_mfma_f32_16x16x32_bf16 v[32:35], v[90:93], v[236:239], v[32:35]
	v_mfma_f32_16x16x32_bf16 v[44:47], v[94:97], v[232:235], v[40:43]
	v_mfma_f32_16x16x32_bf16 v[40:43], v[94:97], v[240:243], v[32:35]
	v_mfma_f32_16x16x32_bf16 v[32:35], v[220:223], v[228:231], v[36:39]
	v_mfma_f32_16x16x32_bf16 v[36:39], v[224:227], v[232:235], v[32:35]
	v_mfma_f32_16x16x32_bf16 v[32:35], v[220:223], v[236:239], v[118:121]
	v_mfma_f32_16x16x32_bf16 v[32:35], v[224:227], v[240:243], v[32:35]
	s_setprio 1
	s_mov_b32 m0, s47
	s_barrier
	ds_read_b128 v[96:99], v129 offset:49152
	ds_read_b128 v[100:103], v129 offset:50176
	ds_read_b128 v[104:107], v130 offset:49152
	ds_read_b128 v[108:111], v130 offset:50176
	ds_read_b128 v[220:223], v131 offset:49152
	ds_read_b128 v[224:227], v131 offset:50176
	ds_read_b128 v[244:247], v132 offset:49152
	ds_read_b128 v[248:251], v132 offset:50176
	buffer_load_dwordx4 v133, s[56:59], s35 offen lds
	s_mov_b32 m0, s67
	s_nop 0
	buffer_load_dwordx4 v133, s[56:59], s36 offen lds
	s_barrier
	s_waitcnt lgkmcnt(0)
	s_setprio 0
	s_waitcnt lgkmcnt(7)
	v_mfma_f32_16x16x32_bf16 v[64:67], v[96:99], v[122:125], v[152:155]
	s_waitcnt lgkmcnt(6)
	v_mfma_f32_16x16x32_bf16 v[92:95], v[100:103], v[148:151], v[64:67]
	v_mfma_f32_16x16x32_bf16 v[64:67], v[96:99], v[212:215], v[156:159]
	v_mfma_f32_16x16x32_bf16 v[88:91], v[100:103], v[216:219], v[64:67]
	s_waitcnt lgkmcnt(5)
	v_mfma_f32_16x16x32_bf16 v[64:67], v[104:107], v[122:125], v[160:163]
	s_waitcnt lgkmcnt(4)
	v_mfma_f32_16x16x32_bf16 v[84:87], v[108:111], v[148:151], v[64:67]
	v_mfma_f32_16x16x32_bf16 v[64:67], v[104:107], v[212:215], v[164:167]
	v_mfma_f32_16x16x32_bf16 v[80:83], v[108:111], v[216:219], v[64:67]
	s_waitcnt lgkmcnt(3)
	v_mfma_f32_16x16x32_bf16 v[64:67], v[220:223], v[122:125], v[168:171]
	s_waitcnt lgkmcnt(2)
	v_mfma_f32_16x16x32_bf16 v[76:79], v[224:227], v[148:151], v[64:67]
	v_mfma_f32_16x16x32_bf16 v[64:67], v[220:223], v[212:215], v[172:175]
	v_mfma_f32_16x16x32_bf16 v[72:75], v[224:227], v[216:219], v[64:67]
	s_waitcnt lgkmcnt(1)
	v_mfma_f32_16x16x32_bf16 v[64:67], v[244:247], v[122:125], v[176:179]
	s_waitcnt lgkmcnt(0)
	v_mfma_f32_16x16x32_bf16 v[68:71], v[248:251], v[148:151], v[64:67]
	v_mfma_f32_16x16x32_bf16 v[64:67], v[244:247], v[212:215], v[180:183]
	v_mfma_f32_16x16x32_bf16 v[64:67], v[248:251], v[216:219], v[64:67]
	s_setprio 1
	s_barrier
	s_mov_b32 s84, 0x40180
	s_mov_b32 m0, s78
	s_nop 0
	buffer_load_dwordx4 v133, s[4:7], s84 offen lds
	s_mov_b32 m0, s79
	s_nop 0
	buffer_load_dwordx4 v133, s[4:7], s37 offen lds
	s_waitcnt vmcnt(6)
	s_barrier
	s_setprio 0
	v_mfma_f32_16x16x32_bf16 v[112:115], v[96:99], v[228:231], v[184:187]
	v_mfma_f32_16x16x32_bf16 v[96:99], v[96:99], v[236:239], v[188:191]
	v_mfma_f32_16x16x32_bf16 v[120:123], v[100:103], v[240:243], v[96:99]
	v_mfma_f32_16x16x32_bf16 v[96:99], v[104:107], v[228:231], v[192:195]
	v_mfma_f32_16x16x32_bf16 v[116:119], v[108:111], v[232:235], v[96:99]
	v_mfma_f32_16x16x32_bf16 v[96:99], v[104:107], v[236:239], v[196:199]
	v_mfma_f32_16x16x32_bf16 v[124:127], v[100:103], v[232:235], v[112:115]
	v_mfma_f32_16x16x32_bf16 v[112:115], v[108:111], v[240:243], v[96:99]
	v_mfma_f32_16x16x32_bf16 v[96:99], v[220:223], v[228:231], v[200:203]
	v_mfma_f32_16x16x32_bf16 v[108:111], v[224:227], v[232:235], v[96:99]
	v_mfma_f32_16x16x32_bf16 v[96:99], v[220:223], v[236:239], v[204:207]
	v_mfma_f32_16x16x32_bf16 v[104:107], v[224:227], v[240:243], v[96:99]
	v_mfma_f32_16x16x32_bf16 v[96:99], v[244:247], v[228:231], v[208:211]
	v_mfma_f32_16x16x32_bf16 v[100:103], v[248:251], v[232:235], v[96:99]
	v_mfma_f32_16x16x32_bf16 v[96:99], v[244:247], v[236:239], v[144:147]
	v_mfma_f32_16x16x32_bf16 v[96:99], v[248:251], v[240:243], v[96:99]
	s_setprio 1
	s_mov_b32 s84, 0
	s_mov_b32 s85, 0x60280
	s_barrier
.LBB0_265:
	ds_read_b128 v[144:147], v134
	ds_read_b128 v[148:151], v134 offset:1024
	ds_read_b128 v[152:155], v134 offset:2048
	ds_read_b128 v[156:159], v134 offset:3072
	s_mov_b32 m0, s82
	s_add_i32 s86, s85, 0xfffdff00
	ds_read_b128 v[160:163], v129
	ds_read_b128 v[164:167], v129 offset:1024
	ds_read_b128 v[168:171], v130
	ds_read_b128 v[172:175], v130 offset:1024
	ds_read_b128 v[176:179], v131
	ds_read_b128 v[180:183], v131 offset:1024
	ds_read_b128 v[184:187], v132
	ds_read_b128 v[188:191], v132 offset:1024
	buffer_load_dwordx4 v133, s[56:59], s86 offen lds
	s_add_i32 s86, s85, 0xffffff00
	s_mov_b32 m0, s83
	s_nop 0
	buffer_load_dwordx4 v133, s[56:59], s86 offen lds
	s_waitcnt lgkmcnt(8)
	s_barrier
	s_waitcnt lgkmcnt(0)
	s_setprio 0
	s_waitcnt lgkmcnt(7)
	v_mfma_f32_16x16x32_bf16 v[28:31], v[160:163], v[144:147], v[28:31]
	v_mfma_f32_16x16x32_bf16 v[24:27], v[160:163], v[152:155], v[24:27]
	s_waitcnt lgkmcnt(5)
	v_mfma_f32_16x16x32_bf16 v[20:23], v[168:171], v[144:147], v[20:23]
	v_mfma_f32_16x16x32_bf16 v[16:19], v[168:171], v[152:155], v[16:19]
	s_waitcnt lgkmcnt(3)
	v_mfma_f32_16x16x32_bf16 v[12:15], v[176:179], v[144:147], v[12:15]
	v_mfma_f32_16x16x32_bf16 v[8:11], v[176:179], v[152:155], v[8:11]
	s_waitcnt lgkmcnt(1)
	v_mfma_f32_16x16x32_bf16 v[4:7], v[184:187], v[144:147], v[4:7]
	v_mfma_f32_16x16x32_bf16 v[0:3], v[184:187], v[152:155], v[0:3]
	v_mfma_f32_16x16x32_bf16 v[28:31], v[164:167], v[148:151], v[28:31]
	v_mfma_f32_16x16x32_bf16 v[24:27], v[164:167], v[156:159], v[24:27]
	v_mfma_f32_16x16x32_bf16 v[20:23], v[172:175], v[148:151], v[20:23]
	v_mfma_f32_16x16x32_bf16 v[16:19], v[172:175], v[156:159], v[16:19]
	v_mfma_f32_16x16x32_bf16 v[12:15], v[180:183], v[148:151], v[12:15]
	v_mfma_f32_16x16x32_bf16 v[8:11], v[180:183], v[156:159], v[8:11]
	s_waitcnt lgkmcnt(0)
	v_mfma_f32_16x16x32_bf16 v[4:7], v[188:191], v[148:151], v[4:7]
	v_mfma_f32_16x16x32_bf16 v[0:3], v[188:191], v[156:159], v[0:3]
	s_setprio 1
	s_barrier
	s_mov_b32 m0, s17
	s_add_i32 s86, s85, 0xfff9ff80
	ds_read_b128 v[192:195], v135
	ds_read_b128 v[196:199], v135 offset:1024
	ds_read_b128 v[200:203], v135 offset:2048
	ds_read_b128 v[204:207], v135 offset:3072
	buffer_load_dwordx4 v133, s[4:7], s86 offen lds
	s_add_i32 s87, s85, 0xfffbff80
	s_mov_b32 m0, s40
	s_nop 0
	buffer_load_dwordx4 v133, s[4:7], s87 offen lds
	s_barrier
	s_waitcnt lgkmcnt(0)
	s_setprio 0
	s_waitcnt lgkmcnt(3)
	v_mfma_f32_16x16x32_bf16 v[60:63], v[160:163], v[192:195], v[60:63]
	s_waitcnt lgkmcnt(1)
	v_mfma_f32_16x16x32_bf16 v[56:59], v[160:163], v[200:203], v[56:59]
	v_mfma_f32_16x16x32_bf16 v[52:55], v[168:171], v[192:195], v[52:55]
	v_mfma_f32_16x16x32_bf16 v[48:51], v[168:171], v[200:203], v[48:51]
	v_mfma_f32_16x16x32_bf16 v[44:47], v[176:179], v[192:195], v[44:47]
	v_mfma_f32_16x16x32_bf16 v[40:43], v[176:179], v[200:203], v[40:43]
	v_mfma_f32_16x16x32_bf16 v[36:39], v[184:187], v[192:195], v[36:39]
	v_mfma_f32_16x16x32_bf16 v[32:35], v[184:187], v[200:203], v[32:35]
	v_mfma_f32_16x16x32_bf16 v[60:63], v[164:167], v[196:199], v[60:63]
	s_waitcnt lgkmcnt(0)
	v_mfma_f32_16x16x32_bf16 v[56:59], v[164:167], v[204:207], v[56:59]
	v_mfma_f32_16x16x32_bf16 v[52:55], v[172:175], v[196:199], v[52:55]
	v_mfma_f32_16x16x32_bf16 v[48:51], v[172:175], v[204:207], v[48:51]
	v_mfma_f32_16x16x32_bf16 v[44:47], v[180:183], v[196:199], v[44:47]
	v_mfma_f32_16x16x32_bf16 v[40:43], v[180:183], v[204:207], v[40:43]
	v_mfma_f32_16x16x32_bf16 v[36:39], v[188:191], v[196:199], v[36:39]
	v_mfma_f32_16x16x32_bf16 v[32:35], v[188:191], v[204:207], v[32:35]
	s_setprio 1
	s_mov_b32 m0, s16
	s_barrier
	ds_read_b128 v[160:163], v129 offset:16384
	ds_read_b128 v[164:167], v129 offset:17408
	ds_read_b128 v[168:171], v130 offset:16384
	ds_read_b128 v[172:175], v130 offset:17408
	ds_read_b128 v[176:179], v131 offset:16384
	ds_read_b128 v[180:183], v131 offset:17408
	ds_read_b128 v[184:187], v132 offset:16384
	ds_read_b128 v[188:191], v132 offset:17408
	buffer_load_dwordx4 v133, s[56:59], s86 offen lds
	s_mov_b32 m0, s41
	s_nop 0
	buffer_load_dwordx4 v133, s[56:59], s87 offen lds
	s_barrier
	s_waitcnt lgkmcnt(0)
	s_setprio 0
	s_waitcnt lgkmcnt(7)
	v_mfma_f32_16x16x32_bf16 v[92:95], v[160:163], v[144:147], v[92:95]
	v_mfma_f32_16x16x32_bf16 v[88:91], v[160:163], v[152:155], v[88:91]
	s_waitcnt lgkmcnt(5)
	v_mfma_f32_16x16x32_bf16 v[84:87], v[168:171], v[144:147], v[84:87]
	v_mfma_f32_16x16x32_bf16 v[80:83], v[168:171], v[152:155], v[80:83]
	s_waitcnt lgkmcnt(3)
	v_mfma_f32_16x16x32_bf16 v[76:79], v[176:179], v[144:147], v[76:79]
	v_mfma_f32_16x16x32_bf16 v[72:75], v[176:179], v[152:155], v[72:75]
	s_waitcnt lgkmcnt(1)
	v_mfma_f32_16x16x32_bf16 v[68:71], v[184:187], v[144:147], v[68:71]
	v_mfma_f32_16x16x32_bf16 v[64:67], v[184:187], v[152:155], v[64:67]
	v_mfma_f32_16x16x32_bf16 v[92:95], v[164:167], v[148:151], v[92:95]
	v_mfma_f32_16x16x32_bf16 v[88:91], v[164:167], v[156:159], v[88:91]
	v_mfma_f32_16x16x32_bf16 v[84:87], v[172:175], v[148:151], v[84:87]
	v_mfma_f32_16x16x32_bf16 v[80:83], v[172:175], v[156:159], v[80:83]
	v_mfma_f32_16x16x32_bf16 v[76:79], v[180:183], v[148:151], v[76:79]
	v_mfma_f32_16x16x32_bf16 v[72:75], v[180:183], v[156:159], v[72:75]
	s_waitcnt lgkmcnt(0)
	v_mfma_f32_16x16x32_bf16 v[68:71], v[188:191], v[148:151], v[68:71]
	v_mfma_f32_16x16x32_bf16 v[64:67], v[188:191], v[156:159], v[64:67]
	s_setprio 1
	s_barrier
	s_mov_b32 m0, s42
	s_add_i32 s86, s85, 0xfffdff80
	buffer_load_dwordx4 v133, s[4:7], s86 offen lds
	s_add_i32 s87, s85, 0xffffff80
	s_mov_b32 m0, s43
	s_nop 0
	buffer_load_dwordx4 v133, s[4:7], s87 offen lds
	s_waitcnt vmcnt(6)
	s_barrier
	s_setprio 0
	v_mfma_f32_16x16x32_bf16 v[124:127], v[160:163], v[192:195], v[124:127]
	v_mfma_f32_16x16x32_bf16 v[120:123], v[160:163], v[200:203], v[120:123]
	v_mfma_f32_16x16x32_bf16 v[116:119], v[168:171], v[192:195], v[116:119]
	v_mfma_f32_16x16x32_bf16 v[112:115], v[168:171], v[200:203], v[112:115]
	v_mfma_f32_16x16x32_bf16 v[108:111], v[176:179], v[192:195], v[108:111]
	v_mfma_f32_16x16x32_bf16 v[104:107], v[176:179], v[200:203], v[104:107]
	v_mfma_f32_16x16x32_bf16 v[100:103], v[184:187], v[192:195], v[100:103]
	v_mfma_f32_16x16x32_bf16 v[96:99], v[184:187], v[200:203], v[96:99]
	v_mfma_f32_16x16x32_bf16 v[124:127], v[164:167], v[196:199], v[124:127]
	v_mfma_f32_16x16x32_bf16 v[120:123], v[164:167], v[204:207], v[120:123]
	v_mfma_f32_16x16x32_bf16 v[116:119], v[172:175], v[196:199], v[116:119]
	v_mfma_f32_16x16x32_bf16 v[112:115], v[172:175], v[204:207], v[112:115]
	v_mfma_f32_16x16x32_bf16 v[108:111], v[180:183], v[196:199], v[108:111]
	v_mfma_f32_16x16x32_bf16 v[104:107], v[180:183], v[204:207], v[104:107]
	v_mfma_f32_16x16x32_bf16 v[100:103], v[188:191], v[196:199], v[100:103]
	v_mfma_f32_16x16x32_bf16 v[96:99], v[188:191], v[204:207], v[96:99]
	s_setprio 1
	s_barrier
	ds_read_b128 v[144:147], v136
	ds_read_b128 v[148:151], v136 offset:1024
	ds_read_b128 v[152:155], v136 offset:2048
	ds_read_b128 v[156:159], v136 offset:3072
	s_mov_b32 m0, s45
	ds_read_b128 v[160:163], v129 offset:32768
	ds_read_b128 v[164:167], v129 offset:33792
	ds_read_b128 v[168:171], v130 offset:32768
	ds_read_b128 v[172:175], v130 offset:33792
	ds_read_b128 v[176:179], v131 offset:32768
	ds_read_b128 v[180:183], v131 offset:33792
	ds_read_b128 v[184:187], v132 offset:32768
	ds_read_b128 v[188:191], v132 offset:33792
	buffer_load_dwordx4 v133, s[56:59], s86 offen lds
	s_mov_b32 m0, s46
	s_nop 0
	buffer_load_dwordx4 v133, s[56:59], s87 offen lds
	s_waitcnt lgkmcnt(8)
	s_barrier
	s_waitcnt lgkmcnt(0)
	s_setprio 0
	s_waitcnt lgkmcnt(7)
	v_mfma_f32_16x16x32_bf16 v[28:31], v[160:163], v[144:147], v[28:31]
	v_mfma_f32_16x16x32_bf16 v[24:27], v[160:163], v[152:155], v[24:27]
	s_waitcnt lgkmcnt(5)
	v_mfma_f32_16x16x32_bf16 v[20:23], v[168:171], v[144:147], v[20:23]
	v_mfma_f32_16x16x32_bf16 v[16:19], v[168:171], v[152:155], v[16:19]
	s_waitcnt lgkmcnt(3)
	v_mfma_f32_16x16x32_bf16 v[12:15], v[176:179], v[144:147], v[12:15]
	v_mfma_f32_16x16x32_bf16 v[8:11], v[176:179], v[152:155], v[8:11]
	s_waitcnt lgkmcnt(1)
	v_mfma_f32_16x16x32_bf16 v[4:7], v[184:187], v[144:147], v[4:7]
	v_mfma_f32_16x16x32_bf16 v[0:3], v[184:187], v[152:155], v[0:3]
	v_mfma_f32_16x16x32_bf16 v[28:31], v[164:167], v[148:151], v[28:31]
	v_mfma_f32_16x16x32_bf16 v[24:27], v[164:167], v[156:159], v[24:27]
	v_mfma_f32_16x16x32_bf16 v[20:23], v[172:175], v[148:151], v[20:23]
	v_mfma_f32_16x16x32_bf16 v[16:19], v[172:175], v[156:159], v[16:19]
	v_mfma_f32_16x16x32_bf16 v[12:15], v[180:183], v[148:151], v[12:15]
	v_mfma_f32_16x16x32_bf16 v[8:11], v[180:183], v[156:159], v[8:11]
	s_waitcnt lgkmcnt(0)
	v_mfma_f32_16x16x32_bf16 v[4:7], v[188:191], v[148:151], v[4:7]
	v_mfma_f32_16x16x32_bf16 v[0:3], v[188:191], v[156:159], v[0:3]
	s_setprio 1
	s_barrier
	s_mov_b32 m0, s14
	s_add_i32 s86, s85, 0xfffa0000
	ds_read_b128 v[192:195], v137
	ds_read_b128 v[196:199], v137 offset:1024
	ds_read_b128 v[200:203], v137 offset:2048
	ds_read_b128 v[204:207], v137 offset:3072
	buffer_load_dwordx4 v133, s[4:7], s86 offen lds
	s_add_i32 s87, s85, 0xfffc0000
	s_mov_b32 m0, s15
	s_nop 0
	buffer_load_dwordx4 v133, s[4:7], s87 offen lds
	s_barrier
	s_waitcnt lgkmcnt(0)
	s_setprio 0
	s_waitcnt lgkmcnt(3)
	v_mfma_f32_16x16x32_bf16 v[60:63], v[160:163], v[192:195], v[60:63]
	s_waitcnt lgkmcnt(1)
	v_mfma_f32_16x16x32_bf16 v[56:59], v[160:163], v[200:203], v[56:59]
	v_mfma_f32_16x16x32_bf16 v[52:55], v[168:171], v[192:195], v[52:55]
	v_mfma_f32_16x16x32_bf16 v[48:51], v[168:171], v[200:203], v[48:51]
	v_mfma_f32_16x16x32_bf16 v[44:47], v[176:179], v[192:195], v[44:47]
	v_mfma_f32_16x16x32_bf16 v[40:43], v[176:179], v[200:203], v[40:43]
	v_mfma_f32_16x16x32_bf16 v[36:39], v[184:187], v[192:195], v[36:39]
	v_mfma_f32_16x16x32_bf16 v[32:35], v[184:187], v[200:203], v[32:35]
	v_mfma_f32_16x16x32_bf16 v[60:63], v[164:167], v[196:199], v[60:63]
	s_waitcnt lgkmcnt(0)
	v_mfma_f32_16x16x32_bf16 v[56:59], v[164:167], v[204:207], v[56:59]
	v_mfma_f32_16x16x32_bf16 v[52:55], v[172:175], v[196:199], v[52:55]
	v_mfma_f32_16x16x32_bf16 v[48:51], v[172:175], v[204:207], v[48:51]
	v_mfma_f32_16x16x32_bf16 v[44:47], v[180:183], v[196:199], v[44:47]
	v_mfma_f32_16x16x32_bf16 v[40:43], v[180:183], v[204:207], v[40:43]
	v_mfma_f32_16x16x32_bf16 v[36:39], v[188:191], v[196:199], v[36:39]
	v_mfma_f32_16x16x32_bf16 v[32:35], v[188:191], v[204:207], v[32:35]
	s_setprio 1
	s_mov_b32 m0, s47
	s_barrier
	ds_read_b128 v[160:163], v129 offset:49152
	ds_read_b128 v[164:167], v129 offset:50176
	ds_read_b128 v[168:171], v130 offset:49152
	ds_read_b128 v[172:175], v130 offset:50176
	ds_read_b128 v[176:179], v131 offset:49152
	ds_read_b128 v[180:183], v131 offset:50176
	ds_read_b128 v[184:187], v132 offset:49152
	ds_read_b128 v[188:191], v132 offset:50176
	buffer_load_dwordx4 v133, s[56:59], s86 offen lds
	s_mov_b32 m0, s67
	s_nop 0
	buffer_load_dwordx4 v133, s[56:59], s87 offen lds
	s_barrier
	s_waitcnt lgkmcnt(0)
	s_setprio 0
	s_waitcnt lgkmcnt(7)
	v_mfma_f32_16x16x32_bf16 v[92:95], v[160:163], v[144:147], v[92:95]
	v_mfma_f32_16x16x32_bf16 v[88:91], v[160:163], v[152:155], v[88:91]
	s_waitcnt lgkmcnt(5)
	v_mfma_f32_16x16x32_bf16 v[84:87], v[168:171], v[144:147], v[84:87]
	v_mfma_f32_16x16x32_bf16 v[80:83], v[168:171], v[152:155], v[80:83]
	s_waitcnt lgkmcnt(3)
	v_mfma_f32_16x16x32_bf16 v[76:79], v[176:179], v[144:147], v[76:79]
	v_mfma_f32_16x16x32_bf16 v[72:75], v[176:179], v[152:155], v[72:75]
	s_waitcnt lgkmcnt(1)
	v_mfma_f32_16x16x32_bf16 v[68:71], v[184:187], v[144:147], v[68:71]
	v_mfma_f32_16x16x32_bf16 v[64:67], v[184:187], v[152:155], v[64:67]
	v_mfma_f32_16x16x32_bf16 v[92:95], v[164:167], v[148:151], v[92:95]
	v_mfma_f32_16x16x32_bf16 v[88:91], v[164:167], v[156:159], v[88:91]
	v_mfma_f32_16x16x32_bf16 v[84:87], v[172:175], v[148:151], v[84:87]
	v_mfma_f32_16x16x32_bf16 v[80:83], v[172:175], v[156:159], v[80:83]
	v_mfma_f32_16x16x32_bf16 v[76:79], v[180:183], v[148:151], v[76:79]
	v_mfma_f32_16x16x32_bf16 v[72:75], v[180:183], v[156:159], v[72:75]
	s_waitcnt lgkmcnt(0)
	v_mfma_f32_16x16x32_bf16 v[68:71], v[188:191], v[148:151], v[68:71]
	v_mfma_f32_16x16x32_bf16 v[64:67], v[188:191], v[156:159], v[64:67]
	s_setprio 1
	s_barrier
	s_add_i32 s86, s85, 0xfffe0000
	s_mov_b32 m0, s78
	s_nop 0
	buffer_load_dwordx4 v133, s[4:7], s86 offen lds
	s_mov_b32 m0, s79
	s_nop 0
	buffer_load_dwordx4 v133, s[4:7], s85 offen lds
	s_waitcnt vmcnt(6)
	s_barrier
; #define LDA(dst, b, h)                                                                             \
;   _Pragma("unroll") for (int m = 0; m < 4; ++m) _Pragma("unroll") for (int k = 0; k < 2; ++k)      \
;       dst[m][k] = *reinterpret_cast<const bf16x8*>(SA(b, h) + lds_byte(wr * 64 + m * 16 + fr, k * 32 + fq * 8))
; #define LDB(dst, b, h)                                                                             \
;   _Pragma("unroll") for (int n = 0; n < 2; ++n) _Pragma("unroll") for (int k = 0; k < 2; ++k)      \
;       dst[n][k] = *reinterpret_cast<const bf16x8*>(SB(b, h) + lds_byte(wc * 32 + n * 16 + fr, k * 32 + fq * 8))
; #define WAIT_V(n) asm volatile("s_waitcnt vmcnt(" #n ")" ::: "memory")
; #define WAIT_L(n) asm volatile("s_waitcnt lgkmcnt(" #n ")" ::: "memory")
; #define BAR __builtin_amdgcn_s_barrier()
; template <bool PEEL = false>
; __device__ __forceinline__ void gemm_tile(f32x4 (&acc)[2][2][4][2], const u16* __restrict__ A, int lda,
;                                           const u16* __restrict__ B, int K) {
;     ...
;   {
;     LDB(B0, 0, 0); LDA(At, 0, 0); STAGE_A(SA(1, 1), 1, nt - 1);
;     BAR; WAIT_L(0); MMA(0, 0, At, B0); BAR;
;     LDB(B1, 0, 1); BAR; WAIT_L(0); MMA(0, 1, At, B1); BAR;
;     LDA(At, 0, 1); WAIT_V(4); BAR; WAIT_L(0); MMA(1, 0, At, B0); MMA(1, 1, At, B1); BAR;
	s_setprio 0
	v_mfma_f32_16x16x32_bf16 v[124:127], v[160:163], v[192:195], v[124:127]
	v_mfma_f32_16x16x32_bf16 v[120:123], v[160:163], v[200:203], v[120:123]
	v_mfma_f32_16x16x32_bf16 v[116:119], v[168:171], v[192:195], v[116:119]
	v_mfma_f32_16x16x32_bf16 v[112:115], v[168:171], v[200:203], v[112:115]
	v_mfma_f32_16x16x32_bf16 v[108:111], v[176:179], v[192:195], v[108:111]
	v_mfma_f32_16x16x32_bf16 v[104:107], v[176:179], v[200:203], v[104:107]
	v_mfma_f32_16x16x32_bf16 v[100:103], v[184:187], v[192:195], v[100:103]
	v_mfma_f32_16x16x32_bf16 v[96:99], v[184:187], v[200:203], v[96:99]
	v_mfma_f32_16x16x32_bf16 v[124:127], v[164:167], v[196:199], v[124:127]
	v_mfma_f32_16x16x32_bf16 v[120:123], v[164:167], v[204:207], v[120:123]
	v_mfma_f32_16x16x32_bf16 v[116:119], v[172:175], v[196:199], v[116:119]
	v_mfma_f32_16x16x32_bf16 v[112:115], v[172:175], v[204:207], v[112:115]
	v_mfma_f32_16x16x32_bf16 v[108:111], v[180:183], v[196:199], v[108:111]
	v_mfma_f32_16x16x32_bf16 v[104:107], v[180:183], v[204:207], v[104:107]
	v_mfma_f32_16x16x32_bf16 v[100:103], v[188:191], v[196:199], v[100:103]
	v_mfma_f32_16x16x32_bf16 v[96:99], v[188:191], v[204:207], v[96:99]
	s_setprio 1
	s_add_i32 s84, s84, 2
	s_addk_i32 s85, 0x100
	s_cmp_lt_u32 s84, 12
	s_barrier
	s_cbranch_scc1 .LBB0_265
	v_mov_b32_e32 v244, v133
	s_mov_b32 m0, s82
	ds_read_b128 v[144:147], v134
	ds_read_b128 v[148:151], v134 offset:1024
	ds_read_b128 v[152:155], v134 offset:2048
	ds_read_b128 v[156:159], v134 offset:3072
	ds_read_b128 v[160:163], v129
	ds_read_b128 v[164:167], v129 offset:1024
	ds_read_b128 v[168:171], v130
	ds_read_b128 v[172:175], v130 offset:1024
	ds_read_b128 v[176:179], v131
	ds_read_b128 v[180:183], v131 offset:1024
	ds_read_b128 v[184:187], v132
	ds_read_b128 v[188:191], v132 offset:1024
	buffer_load_dwordx4 v133, s[56:59], s38 offen lds
	s_mov_b32 m0, s83
	s_nop 0
	buffer_load_dwordx4 v133, s[56:59], s39 offen lds
	s_barrier
	s_waitcnt lgkmcnt(0)
	s_setprio 0
	s_waitcnt lgkmcnt(7)
	v_mfma_f32_16x16x32_bf16 v[28:31], v[160:163], v[144:147], v[28:31]
	v_mfma_f32_16x16x32_bf16 v[24:27], v[160:163], v[152:155], v[24:27]
	s_waitcnt lgkmcnt(5)
	v_mfma_f32_16x16x32_bf16 v[20:23], v[168:171], v[144:147], v[20:23]
	v_mfma_f32_16x16x32_bf16 v[16:19], v[168:171], v[152:155], v[16:19]
	s_waitcnt lgkmcnt(3)
	v_mfma_f32_16x16x32_bf16 v[12:15], v[176:179], v[144:147], v[12:15]
	v_mfma_f32_16x16x32_bf16 v[8:11], v[176:179], v[152:155], v[8:11]
	s_waitcnt lgkmcnt(1)
	v_mfma_f32_16x16x32_bf16 v[4:7], v[184:187], v[144:147], v[4:7]
	v_mfma_f32_16x16x32_bf16 v[0:3], v[184:187], v[152:155], v[0:3]
	v_mfma_f32_16x16x32_bf16 v[28:31], v[164:167], v[148:151], v[28:31]
	v_mfma_f32_16x16x32_bf16 v[24:27], v[164:167], v[156:159], v[24:27]
	v_mfma_f32_16x16x32_bf16 v[20:23], v[172:175], v[148:151], v[20:23]
	v_mfma_f32_16x16x32_bf16 v[16:19], v[172:175], v[156:159], v[16:19]
	v_mfma_f32_16x16x32_bf16 v[12:15], v[180:183], v[148:151], v[12:15]
	v_mfma_f32_16x16x32_bf16 v[8:11], v[180:183], v[156:159], v[8:11]
	s_waitcnt lgkmcnt(0)
	v_mfma_f32_16x16x32_bf16 v[4:7], v[188:191], v[148:151], v[4:7]
	v_mfma_f32_16x16x32_bf16 v[0:3], v[188:191], v[156:159], v[0:3]
	s_setprio 1
	s_barrier
	ds_read_b128 v[192:195], v135
	ds_read_b128 v[196:199], v135 offset:1024
	ds_read_b128 v[200:203], v135 offset:2048
	ds_read_b128 v[204:207], v135 offset:3072
	s_barrier
	s_waitcnt lgkmcnt(0)
	s_setprio 0
	s_waitcnt lgkmcnt(3)
	v_mfma_f32_16x16x32_bf16 v[60:63], v[160:163], v[192:195], v[60:63]
	s_waitcnt lgkmcnt(1)
	v_mfma_f32_16x16x32_bf16 v[56:59], v[160:163], v[200:203], v[56:59]
	v_mfma_f32_16x16x32_bf16 v[52:55], v[168:171], v[192:195], v[52:55]
	v_mfma_f32_16x16x32_bf16 v[48:51], v[168:171], v[200:203], v[48:51]
	v_mfma_f32_16x16x32_bf16 v[44:47], v[176:179], v[192:195], v[44:47]
	v_mfma_f32_16x16x32_bf16 v[40:43], v[176:179], v[200:203], v[40:43]
	v_mfma_f32_16x16x32_bf16 v[36:39], v[184:187], v[192:195], v[36:39]
	v_mfma_f32_16x16x32_bf16 v[32:35], v[184:187], v[200:203], v[32:35]
	v_mfma_f32_16x16x32_bf16 v[60:63], v[164:167], v[196:199], v[60:63]
	s_waitcnt lgkmcnt(0)
	v_mfma_f32_16x16x32_bf16 v[56:59], v[164:167], v[204:207], v[56:59]
	v_mfma_f32_16x16x32_bf16 v[52:55], v[172:175], v[196:199], v[52:55]
	v_mfma_f32_16x16x32_bf16 v[48:51], v[172:175], v[204:207], v[48:51]
	v_mfma_f32_16x16x32_bf16 v[44:47], v[180:183], v[196:199], v[44:47]
	v_mfma_f32_16x16x32_bf16 v[40:43], v[180:183], v[204:207], v[40:43]
	v_mfma_f32_16x16x32_bf16 v[36:39], v[188:191], v[196:199], v[36:39]
	v_mfma_f32_16x16x32_bf16 v[32:35], v[188:191], v[204:207], v[32:35]
	s_setprio 1
	s_barrier
	ds_read_b128 v[160:163], v129 offset:16384
	ds_read_b128 v[164:167], v129 offset:17408
	ds_read_b128 v[168:171], v130 offset:16384
	ds_read_b128 v[172:175], v130 offset:17408
	ds_read_b128 v[176:179], v131 offset:16384
	ds_read_b128 v[180:183], v131 offset:17408
	ds_read_b128 v[184:187], v132 offset:16384
	ds_read_b128 v[188:191], v132 offset:17408
	s_cmp_eq_u32 s21, 15
	s_cbranch_scc1 .Lt3_a_last
	s_add_i32 s14, s21, 1
	s_lshl_b32 s14, s14, 19
	s_add_u32 s4, s1, s14
	s_addc_u32 s5, s20, 0
	s_and_b32 s5, s5, 0xffff
	s_mov_b32 m0, s17
	s_nop 0
	buffer_load_dwordx4 v244, s[4:7], 0 offen lds
	s_mov_b32 m0, s40
	s_nop 0
	buffer_load_dwordx4 v244, s[4:7], s7 offen lds
	s_mov_b32 m0, s16
	s_nop 0
	buffer_load_dwordx4 v244, s[56:59], 0 offen lds
	s_mov_b32 m0, s41
	s_nop 0
	buffer_load_dwordx4 v244, s[56:59], s7 offen lds
	s_waitcnt vmcnt(8)
	s_branch .Lt3_a_join

; #define LDA(dst, b, h)                                                                             \
;   _Pragma("unroll") for (int m = 0; m < 4; ++m) _Pragma("unroll") for (int k = 0; k < 2; ++k)      \
;       dst[m][k] = *reinterpret_cast<const bf16x8*>(SA(b, h) + lds_byte(wr * 64 + m * 16 + fr, k * 32 + fq * 8))
; #define LDB(dst, b, h)                                                                             \
;   _Pragma("unroll") for (int n = 0; n < 2; ++n) _Pragma("unroll") for (int k = 0; k < 2; ++k)      \
;       dst[n][k] = *reinterpret_cast<const bf16x8*>(SB(b, h) + lds_byte(wc * 32 + n * 16 + fr, k * 32 + fq * 8))
; #define WAIT_V(n) asm volatile("s_waitcnt vmcnt(" #n ")" ::: "memory")
; #define WAIT_L(n) asm volatile("s_waitcnt lgkmcnt(" #n ")" ::: "memory")
; #define BAR __builtin_amdgcn_s_barrier()
; template <bool PEEL = false>
; __device__ __forceinline__ void gemm_tile(f32x4 (&acc)[2][2][4][2], const u16* __restrict__ A, int lda,
;                                           const u16* __restrict__ B, int K) {
;     ...
;     LDA(At, 0, 1); WAIT_V(4); BAR; WAIT_L(0); MMA(1, 0, At, B0); MMA(1, 1, At, B1); BAR;
;   }
;   {
;     LDB(B0, 1, 0); LDA(At, 1, 0); WAIT_V(2); BAR; WAIT_L(0); MMA(0, 0, At, B0); BAR;
.Lt3_a_join:
	s_barrier
	s_waitcnt lgkmcnt(0)
	s_setprio 0
	s_waitcnt lgkmcnt(7)
	v_mfma_f32_16x16x32_bf16 v[92:95], v[160:163], v[144:147], v[92:95]
	v_mfma_f32_16x16x32_bf16 v[88:91], v[160:163], v[152:155], v[88:91]
	s_waitcnt lgkmcnt(5)
	v_mfma_f32_16x16x32_bf16 v[84:87], v[168:171], v[144:147], v[84:87]
	v_mfma_f32_16x16x32_bf16 v[80:83], v[168:171], v[152:155], v[80:83]
	s_waitcnt lgkmcnt(3)
	v_mfma_f32_16x16x32_bf16 v[76:79], v[176:179], v[144:147], v[76:79]
	v_mfma_f32_16x16x32_bf16 v[72:75], v[176:179], v[152:155], v[72:75]
	s_waitcnt lgkmcnt(1)
	v_mfma_f32_16x16x32_bf16 v[68:71], v[184:187], v[144:147], v[68:71]
	v_mfma_f32_16x16x32_bf16 v[64:67], v[184:187], v[152:155], v[64:67]
	v_mfma_f32_16x16x32_bf16 v[208:211], v[164:167], v[148:151], v[92:95]
	v_mfma_f32_16x16x32_bf16 v[212:215], v[164:167], v[156:159], v[88:91]
	v_mfma_f32_16x16x32_bf16 v[216:219], v[172:175], v[148:151], v[84:87]
	v_mfma_f32_16x16x32_bf16 v[220:223], v[172:175], v[156:159], v[80:83]
	v_mfma_f32_16x16x32_bf16 v[224:227], v[180:183], v[148:151], v[76:79]
	v_mfma_f32_16x16x32_bf16 v[228:231], v[180:183], v[156:159], v[72:75]
	s_waitcnt lgkmcnt(0)
	v_mfma_f32_16x16x32_bf16 v[144:147], v[188:191], v[148:151], v[68:71]
	v_mfma_f32_16x16x32_bf16 v[148:151], v[188:191], v[156:159], v[64:67]
	s_setprio 1
	s_setprio 0
	v_mfma_f32_16x16x32_bf16 v[64:67], v[160:163], v[192:195], v[124:127]
	v_mfma_f32_16x16x32_bf16 v[152:155], v[164:167], v[196:199], v[64:67]
	v_mfma_f32_16x16x32_bf16 v[64:67], v[160:163], v[200:203], v[120:123]
	v_mfma_f32_16x16x32_bf16 v[156:159], v[164:167], v[204:207], v[64:67]
	v_mfma_f32_16x16x32_bf16 v[64:67], v[168:171], v[192:195], v[116:119]
	v_mfma_f32_16x16x32_bf16 v[160:163], v[172:175], v[196:199], v[64:67]
	v_mfma_f32_16x16x32_bf16 v[64:67], v[168:171], v[200:203], v[112:115]
	v_mfma_f32_16x16x32_bf16 v[164:167], v[172:175], v[204:207], v[64:67]
	v_mfma_f32_16x16x32_bf16 v[64:67], v[176:179], v[192:195], v[108:111]
	v_mfma_f32_16x16x32_bf16 v[168:171], v[180:183], v[196:199], v[64:67]
	v_mfma_f32_16x16x32_bf16 v[64:67], v[176:179], v[200:203], v[104:107]
	v_mfma_f32_16x16x32_bf16 v[172:175], v[180:183], v[204:207], v[64:67]
	v_mfma_f32_16x16x32_bf16 v[64:67], v[184:187], v[192:195], v[100:103]
	v_mfma_f32_16x16x32_bf16 v[176:179], v[188:191], v[196:199], v[64:67]
	v_mfma_f32_16x16x32_bf16 v[64:67], v[184:187], v[200:203], v[96:99]
	v_mfma_f32_16x16x32_bf16 v[180:183], v[188:191], v[204:207], v[64:67]
	s_setprio 1
	s_barrier
	ds_read_b128 v[184:187], v136
	ds_read_b128 v[188:191], v136 offset:1024
	ds_read_b128 v[192:195], v136 offset:2048
	ds_read_b128 v[196:199], v136 offset:3072
	ds_read_b128 v[72:75], v129 offset:32768
	ds_read_b128 v[76:79], v129 offset:33792
	ds_read_b128 v[88:91], v130 offset:32768
	ds_read_b128 v[92:95], v130 offset:33792
	ds_read_b128 v[200:203], v131 offset:32768
	ds_read_b128 v[204:207], v131 offset:33792
	ds_read_b128 v[232:235], v132 offset:32768
	ds_read_b128 v[236:239], v132 offset:33792
	s_cmp_eq_u32 s21, 15
	s_cbranch_scc1 .Lt3_b_last
	s_mov_b32 m0, s42
	s_nop 0
	buffer_load_dwordx4 v244, s[4:7], s22 offen lds
	s_mov_b32 m0, s43
	s_nop 0
	buffer_load_dwordx4 v244, s[4:7], s23 offen lds
	s_waitcnt vmcnt(8)
	s_branch .Lt3_b_join

; #define LDA(dst, b, h)                                                                             \
;   _Pragma("unroll") for (int m = 0; m < 4; ++m) _Pragma("unroll") for (int k = 0; k < 2; ++k)      \
;       dst[m][k] = *reinterpret_cast<const bf16x8*>(SA(b, h) + lds_byte(wr * 64 + m * 16 + fr, k * 32 + fq * 8))
; #define LDB(dst, b, h)                                                                             \
;   _Pragma("unroll") for (int n = 0; n < 2; ++n) _Pragma("unroll") for (int k = 0; k < 2; ++k)      \
;       dst[n][k] = *reinterpret_cast<const bf16x8*>(SB(b, h) + lds_byte(wc * 32 + n * 16 + fr, k * 32 + fq * 8))
; #define WAIT_V(n) asm volatile("s_waitcnt vmcnt(" #n ")" ::: "memory")
; #define WAIT_L(n) asm volatile("s_waitcnt lgkmcnt(" #n ")" ::: "memory")
; #define BAR __builtin_amdgcn_s_barrier()
; template <bool PEEL = false>
; __device__ __forceinline__ void gemm_tile(f32x4 (&acc)[2][2][4][2], const u16* __restrict__ A, int lda,
;                                           const u16* __restrict__ B, int K) {
;     ...
;     LDB(B0, 1, 0); LDA(At, 1, 0); WAIT_V(2); BAR; WAIT_L(0); MMA(0, 0, At, B0); BAR;
;     LDB(B1, 1, 1); WAIT_V(0); BAR; WAIT_L(0); MMA(0, 1, At, B1); BAR;
.Lt3_b_join:
	s_barrier
	s_waitcnt lgkmcnt(0)
	s_setprio 0
	s_waitcnt lgkmcnt(7)
	v_mfma_f32_16x16x32_bf16 v[28:31], v[72:75], v[184:187], v[28:31]
	v_mfma_f32_16x16x32_bf16 v[24:27], v[72:75], v[192:195], v[24:27]
	s_waitcnt lgkmcnt(5)
	v_mfma_f32_16x16x32_bf16 v[20:23], v[88:91], v[184:187], v[20:23]
	v_mfma_f32_16x16x32_bf16 v[16:19], v[88:91], v[192:195], v[16:19]
	s_waitcnt lgkmcnt(3)
	v_mfma_f32_16x16x32_bf16 v[12:15], v[200:203], v[184:187], v[12:15]
	v_mfma_f32_16x16x32_bf16 v[8:11], v[200:203], v[192:195], v[8:11]
	s_waitcnt lgkmcnt(1)
	v_mfma_f32_16x16x32_bf16 v[4:7], v[232:235], v[184:187], v[4:7]
	v_mfma_f32_16x16x32_bf16 v[0:3], v[232:235], v[192:195], v[0:3]
	v_mfma_f32_16x16x32_bf16 v[112:115], v[76:79], v[188:191], v[28:31]
	v_mfma_f32_16x16x32_bf16 v[116:119], v[76:79], v[196:199], v[24:27]
	v_mfma_f32_16x16x32_bf16 v[96:99], v[92:95], v[188:191], v[20:23]
	v_mfma_f32_16x16x32_bf16 v[100:103], v[92:95], v[196:199], v[16:19]
	v_mfma_f32_16x16x32_bf16 v[80:83], v[204:207], v[188:191], v[12:15]
	v_mfma_f32_16x16x32_bf16 v[84:87], v[204:207], v[196:199], v[8:11]
	s_waitcnt lgkmcnt(0)
	v_mfma_f32_16x16x32_bf16 v[64:67], v[236:239], v[188:191], v[4:7]
	v_mfma_f32_16x16x32_bf16 v[68:71], v[236:239], v[196:199], v[0:3]
	s_setprio 1
	s_barrier
	ds_read_b128 v[8:11], v137
	ds_read_b128 v[12:15], v137 offset:1024
	ds_read_b128 v[240:243], v137 offset:2048
	ds_read_b128 v[134:137], v137 offset:3072
	s_cmp_eq_u32 s21, 15
	s_cbranch_scc1 .Lt3_c_last
	s_mov_b32 m0, s45
	s_nop 0
	buffer_load_dwordx4 v244, s[56:59], s22 offen lds
	s_mov_b32 m0, s46
	s_nop 0
	buffer_load_dwordx4 v244, s[56:59], s23 offen lds
	s_waitcnt vmcnt(8)
	s_branch .Lt3_c_join

; #define LDA(dst, b, h)                                                                             \
;   _Pragma("unroll") for (int m = 0; m < 4; ++m) _Pragma("unroll") for (int k = 0; k < 2; ++k)      \
;       dst[m][k] = *reinterpret_cast<const bf16x8*>(SA(b, h) + lds_byte(wr * 64 + m * 16 + fr, k * 32 + fq * 8))
; #define LDB(dst, b, h)                                                                             \
;   _Pragma("unroll") for (int n = 0; n < 2; ++n) _Pragma("unroll") for (int k = 0; k < 2; ++k)      \
;       dst[n][k] = *reinterpret_cast<const bf16x8*>(SB(b, h) + lds_byte(wc * 32 + n * 16 + fr, k * 32 + fq * 8))
; #define WAIT_V(n) asm volatile("s_waitcnt vmcnt(" #n ")" ::: "memory")
; #define WAIT_L(n) asm volatile("s_waitcnt lgkmcnt(" #n ")" ::: "memory")
; #define BAR __builtin_amdgcn_s_barrier()
; template <bool PEEL = false>
; __device__ __forceinline__ void gemm_tile(f32x4 (&acc)[2][2][4][2], const u16* __restrict__ A, int lda,
;                                           const u16* __restrict__ B, int K) {
;     ...
;     LDB(B1, 1, 1); WAIT_V(0); BAR; WAIT_L(0); MMA(0, 1, At, B1); BAR;
;     LDA(At, 1, 1); BAR; WAIT_L(0); MMA(1, 0, At, B0); MMA(1, 1, At, B1); BAR;
;   }
;   if (wr == 0) BAR;
.Lt3_c_join:
	s_barrier
	s_waitcnt lgkmcnt(0)
	s_setprio 0
	s_waitcnt lgkmcnt(3)
	v_mfma_f32_16x16x32_bf16 v[0:3], v[72:75], v[8:11], v[60:63]
	s_waitcnt lgkmcnt(2)
	v_mfma_f32_16x16x32_bf16 v[120:123], v[76:79], v[12:15], v[0:3]
	s_waitcnt lgkmcnt(1)
	v_mfma_f32_16x16x32_bf16 v[0:3], v[72:75], v[240:243], v[56:59]
	s_waitcnt lgkmcnt(0)
	v_mfma_f32_16x16x32_bf16 v[124:127], v[76:79], v[134:137], v[0:3]
	v_mfma_f32_16x16x32_bf16 v[0:3], v[88:91], v[8:11], v[52:55]
	v_mfma_f32_16x16x32_bf16 v[104:107], v[92:95], v[12:15], v[0:3]
	v_mfma_f32_16x16x32_bf16 v[0:3], v[88:91], v[240:243], v[48:51]
	v_mfma_f32_16x16x32_bf16 v[108:111], v[92:95], v[134:137], v[0:3]
	v_mfma_f32_16x16x32_bf16 v[0:3], v[200:203], v[8:11], v[44:47]
	v_mfma_f32_16x16x32_bf16 v[88:91], v[204:207], v[12:15], v[0:3]
	v_mfma_f32_16x16x32_bf16 v[0:3], v[200:203], v[240:243], v[40:43]
	v_mfma_f32_16x16x32_bf16 v[92:95], v[204:207], v[134:137], v[0:3]
	v_mfma_f32_16x16x32_bf16 v[0:3], v[232:235], v[8:11], v[36:39]
	v_mfma_f32_16x16x32_bf16 v[72:75], v[236:239], v[12:15], v[0:3]
	v_mfma_f32_16x16x32_bf16 v[0:3], v[232:235], v[240:243], v[32:35]
	v_mfma_f32_16x16x32_bf16 v[76:79], v[236:239], v[134:137], v[0:3]
	s_setprio 1
	s_barrier
	ds_read_b128 v[24:27], v129 offset:49152
	ds_read_b128 v[28:31], v129 offset:50176
	ds_read_b128 v[44:47], v130 offset:49152
	ds_read_b128 v[200:203], v130 offset:50176
	ds_read_b128 v[204:207], v131 offset:49152
	ds_read_b128 v[232:235], v131 offset:50176
	ds_read_b128 v[236:239], v132 offset:49152
	ds_read_b128 v[130:133], v132 offset:50176
	s_cmp_eq_u32 s21, 15
	s_cbranch_scc1 .Lt3_d_skip
	s_add_i32 m0, s16, 0x18000
	s_nop 0
	buffer_load_dwordx4 v244, s[4:7], s24 offen lds
	s_add_i32 m0, s16, 0x1a000
	s_nop 0
	buffer_load_dwordx4 v244, s[4:7], s25 offen lds
	s_mov_b32 m0, s47
	s_nop 0
	buffer_load_dwordx4 v244, s[56:59], s24 offen lds
	s_mov_b32 m0, s67
	s_nop 0
	buffer_load_dwordx4 v244, s[56:59], s25 offen lds
.Lt3_d_skip:
	s_barrier
	s_waitcnt lgkmcnt(0)
	s_setprio 0
	s_waitcnt lgkmcnt(7)
	v_mfma_f32_16x16x32_bf16 v[0:3], v[24:27], v[184:187], v[208:211]
	s_waitcnt lgkmcnt(6)
	v_mfma_f32_16x16x32_bf16 v[48:51], v[28:31], v[188:191], v[0:3]
	v_mfma_f32_16x16x32_bf16 v[0:3], v[24:27], v[192:195], v[212:215]
	v_mfma_f32_16x16x32_bf16 v[52:55], v[28:31], v[196:199], v[0:3]
	s_waitcnt lgkmcnt(5)
	v_mfma_f32_16x16x32_bf16 v[0:3], v[44:47], v[184:187], v[216:219]
	s_waitcnt lgkmcnt(4)
	v_mfma_f32_16x16x32_bf16 v[32:35], v[200:203], v[188:191], v[0:3]
	v_mfma_f32_16x16x32_bf16 v[0:3], v[44:47], v[192:195], v[220:223]
	v_mfma_f32_16x16x32_bf16 v[36:39], v[200:203], v[196:199], v[0:3]
	s_waitcnt lgkmcnt(3)
	v_mfma_f32_16x16x32_bf16 v[0:3], v[204:207], v[184:187], v[224:227]
	s_waitcnt lgkmcnt(2)
	v_mfma_f32_16x16x32_bf16 v[16:19], v[232:235], v[188:191], v[0:3]
	v_mfma_f32_16x16x32_bf16 v[0:3], v[204:207], v[192:195], v[228:231]
	v_mfma_f32_16x16x32_bf16 v[20:23], v[232:235], v[196:199], v[0:3]
	s_waitcnt lgkmcnt(1)
	v_mfma_f32_16x16x32_bf16 v[0:3], v[236:239], v[184:187], v[144:147]
	v_mfma_f32_16x16x32_bf16 v[4:7], v[236:239], v[192:195], v[148:151]
	s_waitcnt lgkmcnt(0)
	v_mfma_f32_16x16x32_bf16 v[0:3], v[130:133], v[188:191], v[0:3]
	v_mfma_f32_16x16x32_bf16 v[4:7], v[130:133], v[196:199], v[4:7]
	s_setprio 1
	s_setprio 0
	v_mfma_f32_16x16x32_bf16 v[40:43], v[24:27], v[8:11], v[152:155]
	v_mfma_f32_16x16x32_bf16 v[24:27], v[24:27], v[240:243], v[156:159]
	v_mfma_f32_16x16x32_bf16 v[60:63], v[28:31], v[134:137], v[24:27]
	v_mfma_f32_16x16x32_bf16 v[24:27], v[44:47], v[8:11], v[160:163]
	v_mfma_f32_16x16x32_bf16 v[56:59], v[28:31], v[12:15], v[40:43]
	v_mfma_f32_16x16x32_bf16 v[40:43], v[200:203], v[12:15], v[24:27]
	v_mfma_f32_16x16x32_bf16 v[24:27], v[44:47], v[240:243], v[164:167]
	v_mfma_f32_16x16x32_bf16 v[44:47], v[200:203], v[134:137], v[24:27]
	v_mfma_f32_16x16x32_bf16 v[24:27], v[204:207], v[8:11], v[168:171]
	v_mfma_f32_16x16x32_bf16 v[8:11], v[236:239], v[8:11], v[176:179]
	v_mfma_f32_16x16x32_bf16 v[24:27], v[232:235], v[12:15], v[24:27]
	v_mfma_f32_16x16x32_bf16 v[28:31], v[204:207], v[240:243], v[172:175]
	v_mfma_f32_16x16x32_bf16 v[8:11], v[130:133], v[12:15], v[8:11]
	v_mfma_f32_16x16x32_bf16 v[12:15], v[236:239], v[240:243], v[180:183]
	v_mfma_f32_16x16x32_bf16 v[28:31], v[232:235], v[134:137], v[28:31]
	v_mfma_f32_16x16x32_bf16 v[12:15], v[130:133], v[134:137], v[12:15]
	s_setprio 1
	v_cmp_gt_u32_e32 vcc, s0, v128
	s_barrier
	s_and_saveexec_b64 s[4:5], vcc
	s_cbranch_execz .LBB0_268
	s_barrier

.Lpf4_join:
	s_add_i32 s2, s97, s44
	s_add_i32 s3, s2, 0x2000
	v_and_b32_e32 v2, 15, v129
	v_lshlrev_b32_e32 v0, 12, v0
	v_and_b32_e32 v126, 0x3000, v0
	v_lshlrev_b32_e32 v0, 6, v2
	v_lshlrev_b32_e32 v2, 2, v129
	v_and_b32_e32 v26, 48, v129
	v_and_b32_e32 v27, 32, v2
	v_bitop3_b32 v127, v0, v27, v26 bitop3:0x36
	v_add_u32_e32 v0, s69, v127
	v_add_u32_e32 v140, v0, v126
	s_barrier
	ds_read_b128 v[2:5], v140
	ds_read_b128 v[6:9], v140 offset:1024
	ds_read_b128 v[10:13], v140 offset:2048
	ds_read_b128 v[14:17], v140 offset:3072
	v_lshlrev_b32_e32 v0, 13, v1
	v_add_u32_e32 v1, 0, v127
	v_add_u32_e32 v131, v1, v0
	v_lshlrev_b32_e32 v1, 6, v129
	v_and_or_b32 v1, v1, s24, v26
	v_xad_u32 v1, v1, v27, 0
	v_or_b32_e32 v26, 0x800, v0
	v_or_b32_e32 v34, 0x1000, v0
	v_or_b32_e32 v0, 0x1800, v0
	s_add_i32 s81, s44, 0xc000
	v_add_u32_e32 v137, v1, v26
	v_add_u32_e32 v138, v1, v34
	v_add_u32_e32 v139, v1, v0
	s_mov_b32 m0, s81
	s_add_i32 s82, s44, 0xe000
	ds_read_b128 v[18:21], v131
	ds_read_b128 v[22:25], v131 offset:1024
	ds_read_b128 v[26:29], v137
	ds_read_b128 v[30:33], v137 offset:1024
	ds_read_b128 v[34:37], v138
	ds_read_b128 v[38:41], v138 offset:1024
	ds_read_b128 v[42:45], v139
	ds_read_b128 v[46:49], v139 offset:1024
	buffer_load_dwordx4 v128, s[4:7], s26 offen lds
	s_mov_b32 m0, s82
	s_nop 0
	buffer_load_dwordx4 v128, s[4:7], s27 offen lds
	s_waitcnt lgkmcnt(8)
	s_barrier
	s_waitcnt lgkmcnt(0)
	s_setprio 0
	s_waitcnt lgkmcnt(7)
	v_mfma_f32_16x16x32_bf16 v[50:53], v[18:21], v[2:5], 0
	v_mfma_f32_16x16x32_bf16 v[54:57], v[18:21], v[10:13], 0
	s_waitcnt lgkmcnt(5)
	v_mfma_f32_16x16x32_bf16 v[58:61], v[26:29], v[2:5], 0
	v_mfma_f32_16x16x32_bf16 v[62:65], v[26:29], v[10:13], 0
	s_waitcnt lgkmcnt(3)
	v_mfma_f32_16x16x32_bf16 v[66:69], v[34:37], v[2:5], 0
	v_mfma_f32_16x16x32_bf16 v[70:73], v[34:37], v[10:13], 0
	s_waitcnt lgkmcnt(1)
	v_mfma_f32_16x16x32_bf16 v[74:77], v[42:45], v[2:5], 0
	v_mfma_f32_16x16x32_bf16 v[78:81], v[42:45], v[10:13], 0
	v_mfma_f32_16x16x32_bf16 v[50:53], v[22:25], v[6:9], v[50:53]
	v_mfma_f32_16x16x32_bf16 v[54:57], v[22:25], v[14:17], v[54:57]
	v_mfma_f32_16x16x32_bf16 v[58:61], v[30:33], v[6:9], v[58:61]
	v_mfma_f32_16x16x32_bf16 v[62:65], v[30:33], v[14:17], v[62:65]
	v_mfma_f32_16x16x32_bf16 v[66:69], v[38:41], v[6:9], v[66:69]
	v_mfma_f32_16x16x32_bf16 v[70:73], v[38:41], v[14:17], v[70:73]
	s_waitcnt lgkmcnt(0)
	v_mfma_f32_16x16x32_bf16 v[74:77], v[46:49], v[6:9], v[74:77]
	v_mfma_f32_16x16x32_bf16 v[78:81], v[46:49], v[14:17], v[78:81]
	s_setprio 1
	s_barrier
	v_add_u32_e32 v0, s70, v127
	v_add_u32_e32 v141, v0, v126
	s_mov_b32 m0, s45
	ds_read_b128 v[82:85], v141
	ds_read_b128 v[86:89], v141 offset:1024
	ds_read_b128 v[90:93], v141 offset:2048
	ds_read_b128 v[94:97], v141 offset:3072
	buffer_load_dwordx4 v130, s[8:11], s28 offen lds
	s_mov_b32 m0, s46
	s_nop 0
	buffer_load_dwordx4 v130, s[8:11], s29 offen lds
	s_barrier
	s_waitcnt lgkmcnt(0)
	s_setprio 0
	s_waitcnt lgkmcnt(3)
	v_mfma_f32_16x16x32_bf16 v[98:101], v[18:21], v[82:85], 0
	s_waitcnt lgkmcnt(1)
	v_mfma_f32_16x16x32_bf16 v[18:21], v[18:21], v[90:93], 0
	s_waitcnt lgkmcnt(0)
	v_mfma_f32_16x16x32_bf16 v[102:105], v[22:25], v[94:97], v[18:21]
	v_mfma_f32_16x16x32_bf16 v[18:21], v[26:29], v[82:85], 0
	v_mfma_f32_16x16x32_bf16 v[106:109], v[30:33], v[86:89], v[18:21]
	v_mfma_f32_16x16x32_bf16 v[18:21], v[26:29], v[90:93], 0
	v_mfma_f32_16x16x32_bf16 v[110:113], v[30:33], v[94:97], v[18:21]
	v_mfma_f32_16x16x32_bf16 v[18:21], v[34:37], v[82:85], 0
	v_mfma_f32_16x16x32_bf16 v[114:117], v[38:41], v[86:89], v[18:21]
	v_mfma_f32_16x16x32_bf16 v[18:21], v[34:37], v[90:93], 0
	v_mfma_f32_16x16x32_bf16 v[32:35], v[38:41], v[94:97], v[18:21]
	v_mfma_f32_16x16x32_bf16 v[18:21], v[42:45], v[82:85], 0
	v_mfma_f32_16x16x32_bf16 v[36:39], v[46:49], v[86:89], v[18:21]
	v_mfma_f32_16x16x32_bf16 v[18:21], v[42:45], v[90:93], 0
	v_mfma_f32_16x16x32_bf16 v[98:101], v[22:25], v[86:89], v[98:101]
	v_mfma_f32_16x16x32_bf16 v[118:121], v[46:49], v[94:97], v[18:21]
	s_setprio 1
	s_mov_b32 m0, s44
	s_barrier
	s_nop 2
	ds_read_b128 v[18:21], v131 offset:16384
	ds_read_b128 v[22:25], v131 offset:17408
	ds_read_b128 v[26:29], v137 offset:16384
	ds_read_b128 v[40:43], v137 offset:17408
	ds_read_b128 v[44:47], v138 offset:16384
	ds_read_b128 v[122:125], v138 offset:17408
	ds_read_b128 v[142:145], v139 offset:16384
	ds_read_b128 v[146:149], v139 offset:17408
	buffer_load_dwordx4 v128, s[4:7], s28 offen lds
	s_mov_b32 m0, s47
	s_nop 0
	buffer_load_dwordx4 v128, s[4:7], s30 offen lds
	s_barrier
	s_waitcnt lgkmcnt(0)
	s_setprio 0
	s_waitcnt lgkmcnt(7)
	v_mfma_f32_16x16x32_bf16 v[150:153], v[18:21], v[2:5], 0
	s_waitcnt lgkmcnt(5)
	v_mfma_f32_16x16x32_bf16 v[158:161], v[26:29], v[2:5], 0
	s_waitcnt lgkmcnt(3)
	v_mfma_f32_16x16x32_bf16 v[166:169], v[44:47], v[2:5], 0
	s_waitcnt lgkmcnt(1)
	v_mfma_f32_16x16x32_bf16 v[0:3], v[142:145], v[2:5], 0
	v_mfma_f32_16x16x32_bf16 v[154:157], v[18:21], v[10:13], 0
	v_mfma_f32_16x16x32_bf16 v[162:165], v[26:29], v[10:13], 0
	v_mfma_f32_16x16x32_bf16 v[170:173], v[44:47], v[10:13], 0
	s_waitcnt lgkmcnt(0)
	v_mfma_f32_16x16x32_bf16 v[174:177], v[146:149], v[6:9], v[0:3]
	v_mfma_f32_16x16x32_bf16 v[0:3], v[142:145], v[10:13], 0
	v_mfma_f32_16x16x32_bf16 v[150:153], v[22:25], v[6:9], v[150:153]
	v_mfma_f32_16x16x32_bf16 v[154:157], v[22:25], v[14:17], v[154:157]
	v_mfma_f32_16x16x32_bf16 v[158:161], v[40:43], v[6:9], v[158:161]
	v_mfma_f32_16x16x32_bf16 v[162:165], v[40:43], v[14:17], v[162:165]
	v_mfma_f32_16x16x32_bf16 v[166:169], v[122:125], v[6:9], v[166:169]
	v_mfma_f32_16x16x32_bf16 v[170:173], v[122:125], v[14:17], v[170:173]
	v_mfma_f32_16x16x32_bf16 v[178:181], v[146:149], v[14:17], v[0:3]
	s_setprio 1
	s_barrier
	s_mov_b32 m0, s48
	s_nop 0
	buffer_load_dwordx4 v130, s[8:11], s31 offen lds
	s_mov_b32 m0, s49
	s_nop 0
	buffer_load_dwordx4 v130, s[8:11], s34 offen lds
	s_waitcnt vmcnt(6)
	s_barrier
	s_setprio 0
	v_mfma_f32_16x16x32_bf16 v[0:3], v[18:21], v[82:85], 0
	v_mfma_f32_16x16x32_bf16 v[182:185], v[22:25], v[86:89], v[0:3]
	v_mfma_f32_16x16x32_bf16 v[0:3], v[18:21], v[90:93], 0
	v_mfma_f32_16x16x32_bf16 v[186:189], v[22:25], v[94:97], v[0:3]
	v_mfma_f32_16x16x32_bf16 v[0:3], v[26:29], v[82:85], 0
	v_mfma_f32_16x16x32_bf16 v[190:193], v[40:43], v[86:89], v[0:3]
	v_mfma_f32_16x16x32_bf16 v[0:3], v[26:29], v[90:93], 0
	v_mfma_f32_16x16x32_bf16 v[194:197], v[40:43], v[94:97], v[0:3]
	v_mfma_f32_16x16x32_bf16 v[0:3], v[44:47], v[82:85], 0
	v_mfma_f32_16x16x32_bf16 v[198:201], v[122:125], v[86:89], v[0:3]
	v_mfma_f32_16x16x32_bf16 v[0:3], v[44:47], v[90:93], 0
	v_mfma_f32_16x16x32_bf16 v[202:205], v[122:125], v[94:97], v[0:3]
	v_mfma_f32_16x16x32_bf16 v[0:3], v[142:145], v[82:85], 0
	v_mfma_f32_16x16x32_bf16 v[206:209], v[146:149], v[86:89], v[0:3]
	v_mfma_f32_16x16x32_bf16 v[0:3], v[142:145], v[90:93], 0
	v_mfma_f32_16x16x32_bf16 v[144:147], v[146:149], v[94:97], v[0:3]
	s_setprio 1
	s_nop 5
	v_add_u32_e32 v0, s97, v127
	v_add_u32_e32 v142, v0, v126
	s_barrier
	ds_read_b128 v[122:125], v142
	ds_read_b128 v[210:213], v142 offset:1024
	ds_read_b128 v[214:217], v142 offset:2048
	ds_read_b128 v[218:221], v142 offset:3072
	s_mov_b32 m0, s52
	ds_read_b128 v[40:43], v131 offset:32768
	ds_read_b128 v[44:47], v131 offset:33792
	ds_read_b128 v[82:85], v137 offset:32768
	ds_read_b128 v[86:89], v137 offset:33792
	ds_read_b128 v[90:93], v138 offset:32768
	ds_read_b128 v[94:97], v138 offset:33792
	ds_read_b128 v[222:225], v139 offset:32768
	ds_read_b128 v[226:229], v139 offset:33792
	buffer_load_dwordx4 v128, s[4:7], s35 offen lds
	s_mov_b32 m0, s53
	s_nop 0
	buffer_load_dwordx4 v128, s[4:7], s36 offen lds
	s_waitcnt lgkmcnt(8)
	s_barrier
	s_waitcnt lgkmcnt(0)
	s_setprio 0
	s_waitcnt lgkmcnt(7)
	v_mfma_f32_16x16x32_bf16 v[0:3], v[40:43], v[122:125], v[50:53]
	s_waitcnt lgkmcnt(6)
	v_mfma_f32_16x16x32_bf16 v[28:31], v[44:47], v[210:213], v[0:3]
	v_mfma_f32_16x16x32_bf16 v[0:3], v[40:43], v[214:217], v[54:57]
	v_mfma_f32_16x16x32_bf16 v[24:27], v[44:47], v[218:221], v[0:3]
	s_waitcnt lgkmcnt(5)
	v_mfma_f32_16x16x32_bf16 v[0:3], v[82:85], v[122:125], v[58:61]
	s_waitcnt lgkmcnt(4)
	v_mfma_f32_16x16x32_bf16 v[20:23], v[86:89], v[210:213], v[0:3]
	v_mfma_f32_16x16x32_bf16 v[0:3], v[82:85], v[214:217], v[62:65]
	v_mfma_f32_16x16x32_bf16 v[16:19], v[86:89], v[218:221], v[0:3]
	s_waitcnt lgkmcnt(3)
	v_mfma_f32_16x16x32_bf16 v[0:3], v[90:93], v[122:125], v[66:69]
	s_waitcnt lgkmcnt(2)
	v_mfma_f32_16x16x32_bf16 v[12:15], v[94:97], v[210:213], v[0:3]
	v_mfma_f32_16x16x32_bf16 v[0:3], v[90:93], v[214:217], v[70:73]
	v_mfma_f32_16x16x32_bf16 v[8:11], v[94:97], v[218:221], v[0:3]
	s_waitcnt lgkmcnt(1)
	v_mfma_f32_16x16x32_bf16 v[0:3], v[222:225], v[122:125], v[74:77]
	s_waitcnt lgkmcnt(0)
	v_mfma_f32_16x16x32_bf16 v[4:7], v[226:229], v[210:213], v[0:3]
	v_mfma_f32_16x16x32_bf16 v[0:3], v[222:225], v[214:217], v[78:81]
	v_mfma_f32_16x16x32_bf16 v[0:3], v[226:229], v[218:221], v[0:3]
	s_setprio 1
	s_barrier
	v_add_u32_e32 v48, s68, v127
	v_add_u32_e32 v143, v48, v126
	s_mov_b32 m0, s2
	ds_read_b128 v[230:233], v143
	ds_read_b128 v[234:237], v143 offset:1024
	ds_read_b128 v[238:241], v143 offset:2048
	ds_read_b128 v[242:245], v143 offset:3072
	buffer_load_dwordx4 v130, s[8:11], s37 offen lds
	s_mov_b32 m0, s3
	s_nop 0
	buffer_load_dwordx4 v130, s[8:11], s38 offen lds
	s_barrier
	s_waitcnt lgkmcnt(0)
	s_setprio 0
	s_waitcnt lgkmcnt(3)
	v_mfma_f32_16x16x32_bf16 v[48:51], v[40:43], v[230:233], v[98:101]
	s_waitcnt lgkmcnt(1)
	v_mfma_f32_16x16x32_bf16 v[40:43], v[40:43], v[238:241], v[102:105]
	s_waitcnt lgkmcnt(0)
	v_mfma_f32_16x16x32_bf16 v[56:59], v[44:47], v[242:245], v[40:43]
	v_mfma_f32_16x16x32_bf16 v[40:43], v[82:85], v[230:233], v[106:109]
	v_mfma_f32_16x16x32_bf16 v[52:55], v[86:89], v[234:237], v[40:43]
	v_mfma_f32_16x16x32_bf16 v[40:43], v[82:85], v[238:241], v[110:113]
	v_mfma_f32_16x16x32_bf16 v[60:63], v[44:47], v[234:237], v[48:51]
	v_mfma_f32_16x16x32_bf16 v[48:51], v[86:89], v[242:245], v[40:43]
	v_mfma_f32_16x16x32_bf16 v[40:43], v[90:93], v[230:233], v[114:117]
	v_mfma_f32_16x16x32_bf16 v[32:35], v[90:93], v[238:241], v[32:35]
	v_mfma_f32_16x16x32_bf16 v[44:47], v[94:97], v[234:237], v[40:43]
	v_mfma_f32_16x16x32_bf16 v[40:43], v[94:97], v[242:245], v[32:35]
	v_mfma_f32_16x16x32_bf16 v[32:35], v[222:225], v[230:233], v[36:39]
	v_mfma_f32_16x16x32_bf16 v[36:39], v[226:229], v[234:237], v[32:35]
	v_mfma_f32_16x16x32_bf16 v[32:35], v[222:225], v[238:241], v[118:121]
	v_mfma_f32_16x16x32_bf16 v[32:35], v[226:229], v[242:245], v[32:35]
	s_setprio 1
	s_mov_b32 m0, s66
	s_barrier
	ds_read_b128 v[96:99], v131 offset:49152
	ds_read_b128 v[100:103], v131 offset:50176
	ds_read_b128 v[104:107], v137 offset:49152
	ds_read_b128 v[108:111], v137 offset:50176
	ds_read_b128 v[222:225], v138 offset:49152
	ds_read_b128 v[226:229], v138 offset:50176
	ds_read_b128 v[246:249], v139 offset:49152
	ds_read_b128 v[250:253], v139 offset:50176
	buffer_load_dwordx4 v128, s[4:7], s37 offen lds
	s_mov_b32 m0, s67
	s_nop 0
	buffer_load_dwordx4 v128, s[4:7], s39 offen lds
	s_barrier
	s_waitcnt lgkmcnt(0)
	s_setprio 0
	s_waitcnt lgkmcnt(7)
	v_mfma_f32_16x16x32_bf16 v[64:67], v[96:99], v[122:125], v[150:153]
	s_waitcnt lgkmcnt(6)
	v_mfma_f32_16x16x32_bf16 v[92:95], v[100:103], v[210:213], v[64:67]
	v_mfma_f32_16x16x32_bf16 v[64:67], v[96:99], v[214:217], v[154:157]
	v_mfma_f32_16x16x32_bf16 v[88:91], v[100:103], v[218:221], v[64:67]
	s_waitcnt lgkmcnt(5)
	v_mfma_f32_16x16x32_bf16 v[64:67], v[104:107], v[122:125], v[158:161]
	s_waitcnt lgkmcnt(4)
	v_mfma_f32_16x16x32_bf16 v[84:87], v[108:111], v[210:213], v[64:67]
	v_mfma_f32_16x16x32_bf16 v[64:67], v[104:107], v[214:217], v[162:165]
	v_mfma_f32_16x16x32_bf16 v[80:83], v[108:111], v[218:221], v[64:67]
	s_waitcnt lgkmcnt(3)
	v_mfma_f32_16x16x32_bf16 v[64:67], v[222:225], v[122:125], v[166:169]
	s_waitcnt lgkmcnt(2)
	v_mfma_f32_16x16x32_bf16 v[76:79], v[226:229], v[210:213], v[64:67]
	v_mfma_f32_16x16x32_bf16 v[64:67], v[222:225], v[214:217], v[170:173]
	v_mfma_f32_16x16x32_bf16 v[72:75], v[226:229], v[218:221], v[64:67]
	s_waitcnt lgkmcnt(1)
	v_mfma_f32_16x16x32_bf16 v[64:67], v[246:249], v[122:125], v[174:177]
	s_waitcnt lgkmcnt(0)
	v_mfma_f32_16x16x32_bf16 v[68:71], v[250:253], v[210:213], v[64:67]
	v_mfma_f32_16x16x32_bf16 v[64:67], v[246:249], v[214:217], v[178:181]
	v_mfma_f32_16x16x32_bf16 v[64:67], v[250:253], v[218:221], v[64:67]
	s_setprio 1
	s_barrier
	s_mov_b32 m0, s78
	s_nop 0
	buffer_load_dwordx4 v130, s[8:11], s40 offen lds
	s_mov_b32 m0, s79
	s_nop 0
	buffer_load_dwordx4 v130, s[8:11], s41 offen lds
	s_waitcnt vmcnt(6)
	s_barrier
	s_setprio 0
	v_mfma_f32_16x16x32_bf16 v[112:115], v[96:99], v[230:233], v[182:185]
	v_mfma_f32_16x16x32_bf16 v[96:99], v[96:99], v[238:241], v[186:189]
	v_mfma_f32_16x16x32_bf16 v[120:123], v[100:103], v[242:245], v[96:99]
	v_mfma_f32_16x16x32_bf16 v[96:99], v[104:107], v[230:233], v[190:193]
	v_mfma_f32_16x16x32_bf16 v[116:119], v[108:111], v[234:237], v[96:99]
	v_mfma_f32_16x16x32_bf16 v[96:99], v[104:107], v[238:241], v[194:197]
	v_mfma_f32_16x16x32_bf16 v[124:127], v[100:103], v[234:237], v[112:115]
	v_mfma_f32_16x16x32_bf16 v[112:115], v[108:111], v[242:245], v[96:99]
	v_mfma_f32_16x16x32_bf16 v[96:99], v[222:225], v[230:233], v[198:201]
	v_mfma_f32_16x16x32_bf16 v[108:111], v[226:229], v[234:237], v[96:99]
	v_mfma_f32_16x16x32_bf16 v[96:99], v[222:225], v[238:241], v[202:205]
	v_mfma_f32_16x16x32_bf16 v[104:107], v[226:229], v[242:245], v[96:99]
	v_mfma_f32_16x16x32_bf16 v[96:99], v[246:249], v[230:233], v[206:209]
	v_mfma_f32_16x16x32_bf16 v[100:103], v[250:253], v[234:237], v[96:99]
	v_mfma_f32_16x16x32_bf16 v[96:99], v[246:249], v[238:241], v[144:147]
	v_mfma_f32_16x16x32_bf16 v[96:99], v[250:253], v[242:245], v[96:99]
	s_setprio 1
	s_mov_b32 s83, 0
	s_mov_b32 s84, 0x180200
	s_barrier
.LBB0_364:
	ds_read_b128 v[144:147], v140
	ds_read_b128 v[148:151], v140 offset:1024
	ds_read_b128 v[152:155], v140 offset:2048
	ds_read_b128 v[156:159], v140 offset:3072
	s_mov_b32 m0, s81
	s_add_i32 s85, s84, 0xfff7ff80
	ds_read_b128 v[160:163], v131
	ds_read_b128 v[164:167], v131 offset:1024
	ds_read_b128 v[168:171], v137
	ds_read_b128 v[172:175], v137 offset:1024
	ds_read_b128 v[176:179], v138
	ds_read_b128 v[180:183], v138 offset:1024
	ds_read_b128 v[184:187], v139
	ds_read_b128 v[188:191], v139 offset:1024
	buffer_load_dwordx4 v128, s[4:7], s85 offen lds
	s_add_i32 s85, s84, 0xffffff80
	s_mov_b32 m0, s82
	s_nop 0
	buffer_load_dwordx4 v128, s[4:7], s85 offen lds
	s_waitcnt lgkmcnt(8)
	s_barrier
	s_waitcnt lgkmcnt(0)
	s_setprio 0
	s_waitcnt lgkmcnt(7)
	v_mfma_f32_16x16x32_bf16 v[28:31], v[160:163], v[144:147], v[28:31]
	v_mfma_f32_16x16x32_bf16 v[24:27], v[160:163], v[152:155], v[24:27]
	s_waitcnt lgkmcnt(5)
	v_mfma_f32_16x16x32_bf16 v[20:23], v[168:171], v[144:147], v[20:23]
	v_mfma_f32_16x16x32_bf16 v[16:19], v[168:171], v[152:155], v[16:19]
	s_waitcnt lgkmcnt(3)
	v_mfma_f32_16x16x32_bf16 v[12:15], v[176:179], v[144:147], v[12:15]
	v_mfma_f32_16x16x32_bf16 v[8:11], v[176:179], v[152:155], v[8:11]
	s_waitcnt lgkmcnt(1)
	v_mfma_f32_16x16x32_bf16 v[4:7], v[184:187], v[144:147], v[4:7]
	v_mfma_f32_16x16x32_bf16 v[0:3], v[184:187], v[152:155], v[0:3]
	v_mfma_f32_16x16x32_bf16 v[28:31], v[164:167], v[148:151], v[28:31]
	v_mfma_f32_16x16x32_bf16 v[24:27], v[164:167], v[156:159], v[24:27]
	v_mfma_f32_16x16x32_bf16 v[20:23], v[172:175], v[148:151], v[20:23]
	v_mfma_f32_16x16x32_bf16 v[16:19], v[172:175], v[156:159], v[16:19]
	v_mfma_f32_16x16x32_bf16 v[12:15], v[180:183], v[148:151], v[12:15]
	v_mfma_f32_16x16x32_bf16 v[8:11], v[180:183], v[156:159], v[8:11]
	s_waitcnt lgkmcnt(0)
	v_mfma_f32_16x16x32_bf16 v[4:7], v[188:191], v[148:151], v[4:7]
	v_mfma_f32_16x16x32_bf16 v[0:3], v[188:191], v[156:159], v[0:3]
	s_setprio 1
	s_barrier
	s_mov_b32 m0, s45
	s_add_i32 s85, s84, 0xffe80000
	ds_read_b128 v[192:195], v141
	ds_read_b128 v[196:199], v141 offset:1024
	ds_read_b128 v[200:203], v141 offset:2048
	ds_read_b128 v[204:207], v141 offset:3072
	buffer_load_dwordx4 v130, s[8:11], s85 offen lds
	s_add_i32 s86, s84, 0xffe90000
	s_mov_b32 m0, s46
	s_nop 0
	buffer_load_dwordx4 v130, s[8:11], s86 offen lds
	s_barrier
	s_waitcnt lgkmcnt(0)
	s_setprio 0
	s_waitcnt lgkmcnt(3)
	v_mfma_f32_16x16x32_bf16 v[60:63], v[160:163], v[192:195], v[60:63]
	s_waitcnt lgkmcnt(1)
	v_mfma_f32_16x16x32_bf16 v[56:59], v[160:163], v[200:203], v[56:59]
	v_mfma_f32_16x16x32_bf16 v[52:55], v[168:171], v[192:195], v[52:55]
	v_mfma_f32_16x16x32_bf16 v[48:51], v[168:171], v[200:203], v[48:51]
	v_mfma_f32_16x16x32_bf16 v[44:47], v[176:179], v[192:195], v[44:47]
	v_mfma_f32_16x16x32_bf16 v[40:43], v[176:179], v[200:203], v[40:43]
	v_mfma_f32_16x16x32_bf16 v[36:39], v[184:187], v[192:195], v[36:39]
	v_mfma_f32_16x16x32_bf16 v[32:35], v[184:187], v[200:203], v[32:35]
	v_mfma_f32_16x16x32_bf16 v[60:63], v[164:167], v[196:199], v[60:63]
	s_waitcnt lgkmcnt(0)
	v_mfma_f32_16x16x32_bf16 v[56:59], v[164:167], v[204:207], v[56:59]
	v_mfma_f32_16x16x32_bf16 v[52:55], v[172:175], v[196:199], v[52:55]
	v_mfma_f32_16x16x32_bf16 v[48:51], v[172:175], v[204:207], v[48:51]
	v_mfma_f32_16x16x32_bf16 v[44:47], v[180:183], v[196:199], v[44:47]
	v_mfma_f32_16x16x32_bf16 v[40:43], v[180:183], v[204:207], v[40:43]
	v_mfma_f32_16x16x32_bf16 v[36:39], v[188:191], v[196:199], v[36:39]
	v_mfma_f32_16x16x32_bf16 v[32:35], v[188:191], v[204:207], v[32:35]
	s_setprio 1
	s_mov_b32 m0, s44
	s_barrier
	ds_read_b128 v[160:163], v131 offset:16384
	ds_read_b128 v[164:167], v131 offset:17408
	ds_read_b128 v[168:171], v137 offset:16384
	ds_read_b128 v[172:175], v137 offset:17408
	ds_read_b128 v[176:179], v138 offset:16384
	ds_read_b128 v[180:183], v138 offset:17408
	ds_read_b128 v[184:187], v139 offset:16384
	ds_read_b128 v[188:191], v139 offset:17408
	buffer_load_dwordx4 v128, s[4:7], s85 offen lds
	s_add_i32 s85, s84, 0xfff00000
	s_mov_b32 m0, s47
	s_nop 0
	buffer_load_dwordx4 v128, s[4:7], s85 offen lds
	s_barrier
	s_waitcnt lgkmcnt(0)
	s_setprio 0
	s_waitcnt lgkmcnt(7)
	v_mfma_f32_16x16x32_bf16 v[92:95], v[160:163], v[144:147], v[92:95]
	v_mfma_f32_16x16x32_bf16 v[88:91], v[160:163], v[152:155], v[88:91]
	s_waitcnt lgkmcnt(5)
	v_mfma_f32_16x16x32_bf16 v[84:87], v[168:171], v[144:147], v[84:87]
	v_mfma_f32_16x16x32_bf16 v[80:83], v[168:171], v[152:155], v[80:83]
	s_waitcnt lgkmcnt(3)
	v_mfma_f32_16x16x32_bf16 v[76:79], v[176:179], v[144:147], v[76:79]
	v_mfma_f32_16x16x32_bf16 v[72:75], v[176:179], v[152:155], v[72:75]
	s_waitcnt lgkmcnt(1)
	v_mfma_f32_16x16x32_bf16 v[68:71], v[184:187], v[144:147], v[68:71]
	v_mfma_f32_16x16x32_bf16 v[64:67], v[184:187], v[152:155], v[64:67]
	v_mfma_f32_16x16x32_bf16 v[92:95], v[164:167], v[148:151], v[92:95]
	v_mfma_f32_16x16x32_bf16 v[88:91], v[164:167], v[156:159], v[88:91]
	v_mfma_f32_16x16x32_bf16 v[84:87], v[172:175], v[148:151], v[84:87]
	v_mfma_f32_16x16x32_bf16 v[80:83], v[172:175], v[156:159], v[80:83]
	v_mfma_f32_16x16x32_bf16 v[76:79], v[180:183], v[148:151], v[76:79]
	v_mfma_f32_16x16x32_bf16 v[72:75], v[180:183], v[156:159], v[72:75]
	s_waitcnt lgkmcnt(0)
	v_mfma_f32_16x16x32_bf16 v[68:71], v[188:191], v[148:151], v[68:71]
	v_mfma_f32_16x16x32_bf16 v[64:67], v[188:191], v[156:159], v[64:67]
	s_setprio 1
	s_barrier
	s_mov_b32 m0, s48
	s_add_i32 s85, s84, 0xffea0000
	buffer_load_dwordx4 v130, s[8:11], s85 offen lds
	s_add_i32 s85, s84, 0xffeb0000
	s_mov_b32 m0, s49
	s_nop 0
	buffer_load_dwordx4 v130, s[8:11], s85 offen lds
	s_waitcnt vmcnt(6)
	s_barrier
	s_setprio 0
	v_mfma_f32_16x16x32_bf16 v[124:127], v[160:163], v[192:195], v[124:127]
	v_mfma_f32_16x16x32_bf16 v[120:123], v[160:163], v[200:203], v[120:123]
	v_mfma_f32_16x16x32_bf16 v[116:119], v[168:171], v[192:195], v[116:119]
	v_mfma_f32_16x16x32_bf16 v[112:115], v[168:171], v[200:203], v[112:115]
	v_mfma_f32_16x16x32_bf16 v[108:111], v[176:179], v[192:195], v[108:111]
	v_mfma_f32_16x16x32_bf16 v[104:107], v[176:179], v[200:203], v[104:107]
	v_mfma_f32_16x16x32_bf16 v[100:103], v[184:187], v[192:195], v[100:103]
	v_mfma_f32_16x16x32_bf16 v[96:99], v[184:187], v[200:203], v[96:99]
	v_mfma_f32_16x16x32_bf16 v[124:127], v[164:167], v[196:199], v[124:127]
	v_mfma_f32_16x16x32_bf16 v[120:123], v[164:167], v[204:207], v[120:123]
	v_mfma_f32_16x16x32_bf16 v[116:119], v[172:175], v[196:199], v[116:119]
	v_mfma_f32_16x16x32_bf16 v[112:115], v[172:175], v[204:207], v[112:115]
	v_mfma_f32_16x16x32_bf16 v[108:111], v[180:183], v[196:199], v[108:111]
	v_mfma_f32_16x16x32_bf16 v[104:107], v[180:183], v[204:207], v[104:107]
	v_mfma_f32_16x16x32_bf16 v[100:103], v[188:191], v[196:199], v[100:103]
	v_mfma_f32_16x16x32_bf16 v[96:99], v[188:191], v[204:207], v[96:99]
	s_setprio 1
	s_barrier
	ds_read_b128 v[144:147], v142
	ds_read_b128 v[148:151], v142 offset:1024
	ds_read_b128 v[152:155], v142 offset:2048
	ds_read_b128 v[156:159], v142 offset:3072
	s_add_i32 s85, s84, 0xfff80000
	s_mov_b32 m0, s52
	ds_read_b128 v[160:163], v131 offset:32768
	ds_read_b128 v[164:167], v131 offset:33792
	ds_read_b128 v[168:171], v137 offset:32768
	ds_read_b128 v[172:175], v137 offset:33792
	ds_read_b128 v[176:179], v138 offset:32768
	ds_read_b128 v[180:183], v138 offset:33792
	ds_read_b128 v[184:187], v139 offset:32768
	ds_read_b128 v[188:191], v139 offset:33792
	buffer_load_dwordx4 v128, s[4:7], s85 offen lds
	s_mov_b32 m0, s53
	s_nop 0
	buffer_load_dwordx4 v128, s[4:7], s84 offen lds
	s_waitcnt lgkmcnt(8)
	s_barrier
	s_waitcnt lgkmcnt(0)
	s_setprio 0
	s_waitcnt lgkmcnt(7)
	v_mfma_f32_16x16x32_bf16 v[28:31], v[160:163], v[144:147], v[28:31]
	v_mfma_f32_16x16x32_bf16 v[24:27], v[160:163], v[152:155], v[24:27]
	s_waitcnt lgkmcnt(5)
	v_mfma_f32_16x16x32_bf16 v[20:23], v[168:171], v[144:147], v[20:23]
	v_mfma_f32_16x16x32_bf16 v[16:19], v[168:171], v[152:155], v[16:19]
	s_waitcnt lgkmcnt(3)
	v_mfma_f32_16x16x32_bf16 v[12:15], v[176:179], v[144:147], v[12:15]
	v_mfma_f32_16x16x32_bf16 v[8:11], v[176:179], v[152:155], v[8:11]
	s_waitcnt lgkmcnt(1)
	v_mfma_f32_16x16x32_bf16 v[4:7], v[184:187], v[144:147], v[4:7]
	v_mfma_f32_16x16x32_bf16 v[0:3], v[184:187], v[152:155], v[0:3]
	v_mfma_f32_16x16x32_bf16 v[28:31], v[164:167], v[148:151], v[28:31]
	v_mfma_f32_16x16x32_bf16 v[24:27], v[164:167], v[156:159], v[24:27]
	v_mfma_f32_16x16x32_bf16 v[20:23], v[172:175], v[148:151], v[20:23]
	v_mfma_f32_16x16x32_bf16 v[16:19], v[172:175], v[156:159], v[16:19]
	v_mfma_f32_16x16x32_bf16 v[12:15], v[180:183], v[148:151], v[12:15]
	v_mfma_f32_16x16x32_bf16 v[8:11], v[180:183], v[156:159], v[8:11]
	s_waitcnt lgkmcnt(0)
	v_mfma_f32_16x16x32_bf16 v[4:7], v[188:191], v[148:151], v[4:7]
	v_mfma_f32_16x16x32_bf16 v[0:3], v[188:191], v[156:159], v[0:3]
	s_setprio 1
	s_barrier
	s_mov_b32 m0, s2
	s_add_i32 s85, s84, 0xffe80080
	ds_read_b128 v[192:195], v143
	ds_read_b128 v[196:199], v143 offset:1024
	ds_read_b128 v[200:203], v143 offset:2048
	ds_read_b128 v[204:207], v143 offset:3072
	buffer_load_dwordx4 v130, s[8:11], s85 offen lds
	s_add_i32 s86, s84, 0xffe90080
	s_mov_b32 m0, s3
	s_nop 0
	buffer_load_dwordx4 v130, s[8:11], s86 offen lds
	s_barrier
	s_waitcnt lgkmcnt(0)
	s_setprio 0
	s_waitcnt lgkmcnt(3)
	v_mfma_f32_16x16x32_bf16 v[60:63], v[160:163], v[192:195], v[60:63]
	s_waitcnt lgkmcnt(1)
	v_mfma_f32_16x16x32_bf16 v[56:59], v[160:163], v[200:203], v[56:59]
	v_mfma_f32_16x16x32_bf16 v[52:55], v[168:171], v[192:195], v[52:55]
	v_mfma_f32_16x16x32_bf16 v[48:51], v[168:171], v[200:203], v[48:51]
	v_mfma_f32_16x16x32_bf16 v[44:47], v[176:179], v[192:195], v[44:47]
	v_mfma_f32_16x16x32_bf16 v[40:43], v[176:179], v[200:203], v[40:43]
	v_mfma_f32_16x16x32_bf16 v[36:39], v[184:187], v[192:195], v[36:39]
	v_mfma_f32_16x16x32_bf16 v[32:35], v[184:187], v[200:203], v[32:35]
	v_mfma_f32_16x16x32_bf16 v[60:63], v[164:167], v[196:199], v[60:63]
	s_waitcnt lgkmcnt(0)
	v_mfma_f32_16x16x32_bf16 v[56:59], v[164:167], v[204:207], v[56:59]
	v_mfma_f32_16x16x32_bf16 v[52:55], v[172:175], v[196:199], v[52:55]
	v_mfma_f32_16x16x32_bf16 v[48:51], v[172:175], v[204:207], v[48:51]
	v_mfma_f32_16x16x32_bf16 v[44:47], v[180:183], v[196:199], v[44:47]
	v_mfma_f32_16x16x32_bf16 v[40:43], v[180:183], v[204:207], v[40:43]
	v_mfma_f32_16x16x32_bf16 v[36:39], v[188:191], v[196:199], v[36:39]
	v_mfma_f32_16x16x32_bf16 v[32:35], v[188:191], v[204:207], v[32:35]
	s_setprio 1
	s_mov_b32 m0, s66
	s_barrier
	ds_read_b128 v[160:163], v131 offset:49152
	ds_read_b128 v[164:167], v131 offset:50176
	ds_read_b128 v[168:171], v137 offset:49152
	ds_read_b128 v[172:175], v137 offset:50176
	ds_read_b128 v[176:179], v138 offset:49152
	ds_read_b128 v[180:183], v138 offset:50176
	ds_read_b128 v[184:187], v139 offset:49152
	ds_read_b128 v[188:191], v139 offset:50176
	buffer_load_dwordx4 v128, s[4:7], s85 offen lds
	s_add_i32 s85, s84, 0xfff00080
	s_mov_b32 m0, s67
	s_nop 0
	buffer_load_dwordx4 v128, s[4:7], s85 offen lds
	s_barrier
	s_waitcnt lgkmcnt(0)
	s_setprio 0
	s_waitcnt lgkmcnt(7)
	v_mfma_f32_16x16x32_bf16 v[92:95], v[160:163], v[144:147], v[92:95]
	v_mfma_f32_16x16x32_bf16 v[88:91], v[160:163], v[152:155], v[88:91]
	s_waitcnt lgkmcnt(5)
	v_mfma_f32_16x16x32_bf16 v[84:87], v[168:171], v[144:147], v[84:87]
	v_mfma_f32_16x16x32_bf16 v[80:83], v[168:171], v[152:155], v[80:83]
	s_waitcnt lgkmcnt(3)
	v_mfma_f32_16x16x32_bf16 v[76:79], v[176:179], v[144:147], v[76:79]
	v_mfma_f32_16x16x32_bf16 v[72:75], v[176:179], v[152:155], v[72:75]
	s_waitcnt lgkmcnt(1)
	v_mfma_f32_16x16x32_bf16 v[68:71], v[184:187], v[144:147], v[68:71]
	v_mfma_f32_16x16x32_bf16 v[64:67], v[184:187], v[152:155], v[64:67]
	v_mfma_f32_16x16x32_bf16 v[92:95], v[164:167], v[148:151], v[92:95]
	v_mfma_f32_16x16x32_bf16 v[88:91], v[164:167], v[156:159], v[88:91]
	v_mfma_f32_16x16x32_bf16 v[84:87], v[172:175], v[148:151], v[84:87]
	v_mfma_f32_16x16x32_bf16 v[80:83], v[172:175], v[156:159], v[80:83]
	v_mfma_f32_16x16x32_bf16 v[76:79], v[180:183], v[148:151], v[76:79]
	v_mfma_f32_16x16x32_bf16 v[72:75], v[180:183], v[156:159], v[72:75]
	s_waitcnt lgkmcnt(0)
	v_mfma_f32_16x16x32_bf16 v[68:71], v[188:191], v[148:151], v[68:71]
	v_mfma_f32_16x16x32_bf16 v[64:67], v[188:191], v[156:159], v[64:67]
	s_setprio 1
	s_barrier
	s_mov_b32 m0, s78
	s_add_i32 s85, s84, 0xffea0080
	buffer_load_dwordx4 v130, s[8:11], s85 offen lds
	s_add_i32 s85, s84, 0xffeb0080
	s_mov_b32 m0, s79
	s_nop 0
	buffer_load_dwordx4 v130, s[8:11], s85 offen lds
	s_waitcnt vmcnt(6)
	s_barrier
	s_setprio 0
	v_mfma_f32_16x16x32_bf16 v[124:127], v[160:163], v[192:195], v[124:127]
	v_mfma_f32_16x16x32_bf16 v[120:123], v[160:163], v[200:203], v[120:123]
	v_mfma_f32_16x16x32_bf16 v[116:119], v[168:171], v[192:195], v[116:119]
	v_mfma_f32_16x16x32_bf16 v[112:115], v[168:171], v[200:203], v[112:115]
	v_mfma_f32_16x16x32_bf16 v[108:111], v[176:179], v[192:195], v[108:111]
	v_mfma_f32_16x16x32_bf16 v[104:107], v[176:179], v[200:203], v[104:107]
	v_mfma_f32_16x16x32_bf16 v[100:103], v[184:187], v[192:195], v[100:103]
	v_mfma_f32_16x16x32_bf16 v[96:99], v[184:187], v[200:203], v[96:99]
	v_mfma_f32_16x16x32_bf16 v[124:127], v[164:167], v[196:199], v[124:127]
	v_mfma_f32_16x16x32_bf16 v[120:123], v[164:167], v[204:207], v[120:123]
	v_mfma_f32_16x16x32_bf16 v[116:119], v[172:175], v[196:199], v[116:119]
	v_mfma_f32_16x16x32_bf16 v[112:115], v[172:175], v[204:207], v[112:115]
	v_mfma_f32_16x16x32_bf16 v[108:111], v[180:183], v[196:199], v[108:111]
	v_mfma_f32_16x16x32_bf16 v[104:107], v[180:183], v[204:207], v[104:107]
	v_mfma_f32_16x16x32_bf16 v[100:103], v[188:191], v[196:199], v[100:103]
	v_mfma_f32_16x16x32_bf16 v[96:99], v[188:191], v[204:207], v[96:99]
	s_setprio 1
	s_add_i32 s83, s83, 2
	s_addk_i32 s84, 0x100
	s_cmp_lt_u32 s83, 4
	s_barrier
; #define LDA(dst, b, h)                                                                             \
;   _Pragma("unroll") for (int m = 0; m < 4; ++m) _Pragma("unroll") for (int k = 0; k < 2; ++k)      \
;       dst[m][k] = *reinterpret_cast<const bf16x8*>(SA(b, h) + lds_byte(wr * 64 + m * 16 + fr, k * 32 + fq * 8))
; #define LDB(dst, b, h)                                                                             \
;   _Pragma("unroll") for (int n = 0; n < 2; ++n) _Pragma("unroll") for (int k = 0; k < 2; ++k)      \
;       dst[n][k] = *reinterpret_cast<const bf16x8*>(SB(b, h) + lds_byte(wc * 32 + n * 16 + fr, k * 32 + fq * 8))
; #define WAIT_V(n) asm volatile("s_waitcnt vmcnt(" #n ")" ::: "memory")
; #define WAIT_L(n) asm volatile("s_waitcnt lgkmcnt(" #n ")" ::: "memory")
; #define BAR __builtin_amdgcn_s_barrier()
; template <bool PEEL = false>
; __device__ __forceinline__ void gemm_tile(f32x4 (&acc)[2][2][4][2], const u16* __restrict__ A, int lda,
;                                           const u16* __restrict__ B, int K) {
;     ...
;   {
;     LDB(B0, 0, 0); LDA(At, 0, 0); STAGE_A(SA(1, 1), 1, nt - 1);
;     BAR; WAIT_L(0); MMA(0, 0, At, B0); BAR;
;     LDB(B1, 0, 1); BAR; WAIT_L(0); MMA(0, 1, At, B1); BAR;
;     LDA(At, 0, 1); WAIT_V(4); BAR; WAIT_L(0); MMA(1, 0, At, B0); MMA(1, 1, At, B1); BAR;
;   }
	s_cbranch_scc1 .LBB0_364
	s_mov_b32 m0, s81
	ds_read_b128 v[144:147], v140
	ds_read_b128 v[148:151], v140 offset:1024
	ds_read_b128 v[152:155], v140 offset:2048
	ds_read_b128 v[156:159], v140 offset:3072
	ds_read_b128 v[160:163], v131
	ds_read_b128 v[164:167], v131 offset:1024
	ds_read_b128 v[168:171], v137
	ds_read_b128 v[172:175], v137 offset:1024
	ds_read_b128 v[176:179], v138
	ds_read_b128 v[180:183], v138 offset:1024
	ds_read_b128 v[184:187], v139
	ds_read_b128 v[188:191], v139 offset:1024
	buffer_load_dwordx4 v128, s[4:7], s42 offen lds
	s_mov_b32 m0, s82
	s_nop 0
	buffer_load_dwordx4 v128, s[4:7], s43 offen lds
	s_barrier
	s_waitcnt lgkmcnt(0)
	s_setprio 0
	s_waitcnt lgkmcnt(7)
	v_mfma_f32_16x16x32_bf16 v[28:31], v[160:163], v[144:147], v[28:31]
	v_mfma_f32_16x16x32_bf16 v[24:27], v[160:163], v[152:155], v[24:27]
	s_waitcnt lgkmcnt(5)
	v_mfma_f32_16x16x32_bf16 v[20:23], v[168:171], v[144:147], v[20:23]
	v_mfma_f32_16x16x32_bf16 v[16:19], v[168:171], v[152:155], v[16:19]
	s_waitcnt lgkmcnt(3)
	v_mfma_f32_16x16x32_bf16 v[12:15], v[176:179], v[144:147], v[12:15]
	v_mfma_f32_16x16x32_bf16 v[8:11], v[176:179], v[152:155], v[8:11]
	s_waitcnt lgkmcnt(1)
	v_mfma_f32_16x16x32_bf16 v[4:7], v[184:187], v[144:147], v[4:7]
	v_mfma_f32_16x16x32_bf16 v[0:3], v[184:187], v[152:155], v[0:3]
	v_mfma_f32_16x16x32_bf16 v[28:31], v[164:167], v[148:151], v[28:31]
	v_mfma_f32_16x16x32_bf16 v[24:27], v[164:167], v[156:159], v[24:27]
	v_mfma_f32_16x16x32_bf16 v[20:23], v[172:175], v[148:151], v[20:23]
	v_mfma_f32_16x16x32_bf16 v[16:19], v[172:175], v[156:159], v[16:19]
	v_mfma_f32_16x16x32_bf16 v[12:15], v[180:183], v[148:151], v[12:15]
	v_mfma_f32_16x16x32_bf16 v[8:11], v[180:183], v[156:159], v[8:11]
	s_waitcnt lgkmcnt(0)
	v_mfma_f32_16x16x32_bf16 v[4:7], v[188:191], v[148:151], v[4:7]
	v_mfma_f32_16x16x32_bf16 v[0:3], v[188:191], v[156:159], v[0:3]
	s_setprio 1
	s_barrier
	ds_read_b128 v[192:195], v141
	ds_read_b128 v[196:199], v141 offset:1024
	ds_read_b128 v[200:203], v141 offset:2048
	ds_read_b128 v[204:207], v141 offset:3072
	s_barrier
	s_waitcnt lgkmcnt(0)
	s_setprio 0
	s_waitcnt lgkmcnt(3)
	v_mfma_f32_16x16x32_bf16 v[60:63], v[160:163], v[192:195], v[60:63]
	s_waitcnt lgkmcnt(1)
	v_mfma_f32_16x16x32_bf16 v[56:59], v[160:163], v[200:203], v[56:59]
	v_mfma_f32_16x16x32_bf16 v[52:55], v[168:171], v[192:195], v[52:55]
	v_mfma_f32_16x16x32_bf16 v[48:51], v[168:171], v[200:203], v[48:51]
	v_mfma_f32_16x16x32_bf16 v[44:47], v[176:179], v[192:195], v[44:47]
	v_mfma_f32_16x16x32_bf16 v[40:43], v[176:179], v[200:203], v[40:43]
	v_mfma_f32_16x16x32_bf16 v[36:39], v[184:187], v[192:195], v[36:39]
	v_mfma_f32_16x16x32_bf16 v[32:35], v[184:187], v[200:203], v[32:35]
	v_mfma_f32_16x16x32_bf16 v[60:63], v[164:167], v[196:199], v[60:63]
	s_waitcnt lgkmcnt(0)
	v_mfma_f32_16x16x32_bf16 v[56:59], v[164:167], v[204:207], v[56:59]
	v_mfma_f32_16x16x32_bf16 v[52:55], v[172:175], v[196:199], v[52:55]
	v_mfma_f32_16x16x32_bf16 v[48:51], v[172:175], v[204:207], v[48:51]
	v_mfma_f32_16x16x32_bf16 v[44:47], v[180:183], v[196:199], v[44:47]
	v_mfma_f32_16x16x32_bf16 v[40:43], v[180:183], v[204:207], v[40:43]
	v_mfma_f32_16x16x32_bf16 v[36:39], v[188:191], v[196:199], v[36:39]
	v_mfma_f32_16x16x32_bf16 v[32:35], v[188:191], v[204:207], v[32:35]
	s_setprio 1
	s_barrier
	ds_read_b128 v[160:163], v131 offset:16384
	ds_read_b128 v[164:167], v131 offset:17408
	ds_read_b128 v[168:171], v137 offset:16384
	ds_read_b128 v[172:175], v137 offset:17408
	ds_read_b128 v[176:179], v138 offset:16384
	ds_read_b128 v[180:183], v138 offset:17408
	ds_read_b128 v[184:187], v139 offset:16384
	ds_read_b128 v[188:191], v139 offset:17408
	s_waitcnt vmcnt(4)
	s_barrier
	s_waitcnt lgkmcnt(0)
	s_setprio 0
	s_waitcnt lgkmcnt(7)
	v_mfma_f32_16x16x32_bf16 v[92:95], v[160:163], v[144:147], v[92:95]
	v_mfma_f32_16x16x32_bf16 v[88:91], v[160:163], v[152:155], v[88:91]
	s_waitcnt lgkmcnt(5)
	v_mfma_f32_16x16x32_bf16 v[84:87], v[168:171], v[144:147], v[84:87]
	v_mfma_f32_16x16x32_bf16 v[80:83], v[168:171], v[152:155], v[80:83]
	s_waitcnt lgkmcnt(3)
	v_mfma_f32_16x16x32_bf16 v[76:79], v[176:179], v[144:147], v[76:79]
	v_mfma_f32_16x16x32_bf16 v[72:75], v[176:179], v[152:155], v[72:75]
	s_waitcnt lgkmcnt(1)
	v_mfma_f32_16x16x32_bf16 v[68:71], v[184:187], v[144:147], v[68:71]
	v_mfma_f32_16x16x32_bf16 v[64:67], v[184:187], v[152:155], v[64:67]
	v_mfma_f32_16x16x32_bf16 v[208:211], v[164:167], v[148:151], v[92:95]
	v_mfma_f32_16x16x32_bf16 v[212:215], v[164:167], v[156:159], v[88:91]
	v_mfma_f32_16x16x32_bf16 v[216:219], v[172:175], v[148:151], v[84:87]
	v_mfma_f32_16x16x32_bf16 v[220:223], v[172:175], v[156:159], v[80:83]
	v_mfma_f32_16x16x32_bf16 v[224:227], v[180:183], v[148:151], v[76:79]
	v_mfma_f32_16x16x32_bf16 v[228:231], v[180:183], v[156:159], v[72:75]
	s_waitcnt lgkmcnt(0)
	v_mfma_f32_16x16x32_bf16 v[144:147], v[188:191], v[148:151], v[68:71]
	v_mfma_f32_16x16x32_bf16 v[148:151], v[188:191], v[156:159], v[64:67]
	s_setprio 1
	s_setprio 0
	v_mfma_f32_16x16x32_bf16 v[64:67], v[160:163], v[192:195], v[124:127]
	v_mfma_f32_16x16x32_bf16 v[152:155], v[164:167], v[196:199], v[64:67]
	v_mfma_f32_16x16x32_bf16 v[64:67], v[160:163], v[200:203], v[120:123]
	v_mfma_f32_16x16x32_bf16 v[156:159], v[164:167], v[204:207], v[64:67]
	v_mfma_f32_16x16x32_bf16 v[64:67], v[168:171], v[192:195], v[116:119]
	v_mfma_f32_16x16x32_bf16 v[160:163], v[172:175], v[196:199], v[64:67]
	v_mfma_f32_16x16x32_bf16 v[64:67], v[168:171], v[200:203], v[112:115]
	v_mfma_f32_16x16x32_bf16 v[164:167], v[172:175], v[204:207], v[64:67]
	v_mfma_f32_16x16x32_bf16 v[64:67], v[176:179], v[192:195], v[108:111]
	v_mfma_f32_16x16x32_bf16 v[168:171], v[180:183], v[196:199], v[64:67]
	v_mfma_f32_16x16x32_bf16 v[64:67], v[176:179], v[200:203], v[104:107]
	v_mfma_f32_16x16x32_bf16 v[172:175], v[180:183], v[204:207], v[64:67]
	v_mfma_f32_16x16x32_bf16 v[64:67], v[184:187], v[192:195], v[100:103]
	v_mfma_f32_16x16x32_bf16 v[176:179], v[188:191], v[196:199], v[64:67]
	v_mfma_f32_16x16x32_bf16 v[64:67], v[184:187], v[200:203], v[96:99]
	v_mfma_f32_16x16x32_bf16 v[180:183], v[188:191], v[204:207], v[64:67]
	s_setprio 1
	s_barrier
; #define LDA(dst, b, h)                                                                             \
;   _Pragma("unroll") for (int m = 0; m < 4; ++m) _Pragma("unroll") for (int k = 0; k < 2; ++k)      \
;       dst[m][k] = *reinterpret_cast<const bf16x8*>(SA(b, h) + lds_byte(wr * 64 + m * 16 + fr, k * 32 + fq * 8))
; #define LDB(dst, b, h)                                                                             \
;   _Pragma("unroll") for (int n = 0; n < 2; ++n) _Pragma("unroll") for (int k = 0; k < 2; ++k)      \
;       dst[n][k] = *reinterpret_cast<const bf16x8*>(SB(b, h) + lds_byte(wc * 32 + n * 16 + fr, k * 32 + fq * 8))
; #define WAIT_V(n) asm volatile("s_waitcnt vmcnt(" #n ")" ::: "memory")
; #define WAIT_L(n) asm volatile("s_waitcnt lgkmcnt(" #n ")" ::: "memory")
; #define BAR __builtin_amdgcn_s_barrier()
; template <bool PEEL = false>
; __device__ __forceinline__ void gemm_tile(f32x4 (&acc)[2][2][4][2], const u16* __restrict__ A, int lda,
;                                           const u16* __restrict__ B, int K) {
;     ...
;   {
;     LDB(B0, 1, 0); LDA(At, 1, 0); WAIT_V(2); BAR; WAIT_L(0); MMA(0, 0, At, B0); BAR;
;     LDB(B1, 1, 1); WAIT_V(0); BAR; WAIT_L(0); MMA(0, 1, At, B1); BAR;
;     LDA(At, 1, 1); BAR; WAIT_L(0); MMA(1, 0, At, B0); MMA(1, 1, At, B1); BAR;
;   }
;   if (wr == 0) BAR;
	ds_read_b128 v[184:187], v142
	ds_read_b128 v[188:191], v142 offset:1024
	ds_read_b128 v[192:195], v142 offset:2048
	ds_read_b128 v[196:199], v142 offset:3072
	ds_read_b128 v[68:71], v131 offset:32768
	ds_read_b128 v[76:79], v131 offset:33792
	ds_read_b128 v[84:87], v137 offset:32768
	ds_read_b128 v[92:95], v137 offset:33792
	ds_read_b128 v[200:203], v138 offset:32768
	ds_read_b128 v[204:207], v138 offset:33792
	ds_read_b128 v[232:235], v139 offset:32768
	ds_read_b128 v[236:239], v139 offset:33792
	s_waitcnt vmcnt(2)
	s_barrier
	s_waitcnt lgkmcnt(0)
	s_setprio 0
	s_waitcnt lgkmcnt(7)
	v_mfma_f32_16x16x32_bf16 v[28:31], v[68:71], v[184:187], v[28:31]
	v_mfma_f32_16x16x32_bf16 v[24:27], v[68:71], v[192:195], v[24:27]
	s_waitcnt lgkmcnt(5)
	v_mfma_f32_16x16x32_bf16 v[20:23], v[84:87], v[184:187], v[20:23]
	v_mfma_f32_16x16x32_bf16 v[16:19], v[84:87], v[192:195], v[16:19]
	s_waitcnt lgkmcnt(3)
	v_mfma_f32_16x16x32_bf16 v[12:15], v[200:203], v[184:187], v[12:15]
	v_mfma_f32_16x16x32_bf16 v[8:11], v[200:203], v[192:195], v[8:11]
	s_waitcnt lgkmcnt(1)
	v_mfma_f32_16x16x32_bf16 v[4:7], v[232:235], v[184:187], v[4:7]
	v_mfma_f32_16x16x32_bf16 v[0:3], v[232:235], v[192:195], v[0:3]
	v_mfma_f32_16x16x32_bf16 v[112:115], v[76:79], v[188:191], v[28:31]
	v_mfma_f32_16x16x32_bf16 v[120:123], v[76:79], v[196:199], v[24:27]
	v_mfma_f32_16x16x32_bf16 v[96:99], v[92:95], v[188:191], v[20:23]
	v_mfma_f32_16x16x32_bf16 v[104:107], v[92:95], v[196:199], v[16:19]
	v_mfma_f32_16x16x32_bf16 v[80:83], v[204:207], v[188:191], v[12:15]
	v_mfma_f32_16x16x32_bf16 v[88:91], v[204:207], v[196:199], v[8:11]
	s_waitcnt lgkmcnt(0)
	v_mfma_f32_16x16x32_bf16 v[64:67], v[236:239], v[188:191], v[4:7]
	v_mfma_f32_16x16x32_bf16 v[72:75], v[236:239], v[196:199], v[0:3]
	s_setprio 1
	s_barrier
	ds_read_b128 v[4:7], v143
	ds_read_b128 v[12:15], v143 offset:1024
	ds_read_b128 v[240:243], v143 offset:2048
	ds_read_b128 v[140:143], v143 offset:3072
	s_waitcnt vmcnt(0)
	s_barrier
	s_waitcnt lgkmcnt(0)
	s_setprio 0
	s_waitcnt lgkmcnt(3)
	v_mfma_f32_16x16x32_bf16 v[0:3], v[68:71], v[4:7], v[60:63]
	s_waitcnt lgkmcnt(2)
	v_mfma_f32_16x16x32_bf16 v[116:119], v[76:79], v[12:15], v[0:3]
	s_waitcnt lgkmcnt(1)
	v_mfma_f32_16x16x32_bf16 v[0:3], v[68:71], v[240:243], v[56:59]
	s_waitcnt lgkmcnt(0)
	v_mfma_f32_16x16x32_bf16 v[124:127], v[76:79], v[140:143], v[0:3]
	v_mfma_f32_16x16x32_bf16 v[0:3], v[84:87], v[4:7], v[52:55]
	v_mfma_f32_16x16x32_bf16 v[100:103], v[92:95], v[12:15], v[0:3]
	v_mfma_f32_16x16x32_bf16 v[0:3], v[84:87], v[240:243], v[48:51]
	v_mfma_f32_16x16x32_bf16 v[108:111], v[92:95], v[140:143], v[0:3]
	v_mfma_f32_16x16x32_bf16 v[0:3], v[200:203], v[4:7], v[44:47]
	v_mfma_f32_16x16x32_bf16 v[84:87], v[204:207], v[12:15], v[0:3]
	v_mfma_f32_16x16x32_bf16 v[0:3], v[200:203], v[240:243], v[40:43]
	v_mfma_f32_16x16x32_bf16 v[92:95], v[204:207], v[140:143], v[0:3]
	v_mfma_f32_16x16x32_bf16 v[0:3], v[232:235], v[4:7], v[36:39]
	v_mfma_f32_16x16x32_bf16 v[68:71], v[236:239], v[12:15], v[0:3]
	v_mfma_f32_16x16x32_bf16 v[0:3], v[232:235], v[240:243], v[32:35]
	v_mfma_f32_16x16x32_bf16 v[76:79], v[236:239], v[140:143], v[0:3]
	s_setprio 1
	s_barrier
	ds_read_b128 v[20:23], v131 offset:49152
	ds_read_b128 v[28:31], v131 offset:50176
	ds_read_b128 v[44:47], v137 offset:49152
	ds_read_b128 v[200:203], v137 offset:50176
	ds_read_b128 v[204:207], v138 offset:49152
	ds_read_b128 v[232:235], v138 offset:50176
	ds_read_b128 v[236:239], v139 offset:49152
	ds_read_b128 v[244:247], v139 offset:50176
	s_barrier
	s_waitcnt lgkmcnt(0)
	s_setprio 0
	s_waitcnt lgkmcnt(7)
	v_mfma_f32_16x16x32_bf16 v[0:3], v[20:23], v[184:187], v[208:211]
	s_waitcnt lgkmcnt(6)
	v_mfma_f32_16x16x32_bf16 v[48:51], v[28:31], v[188:191], v[0:3]
	v_mfma_f32_16x16x32_bf16 v[0:3], v[20:23], v[192:195], v[212:215]
	v_mfma_f32_16x16x32_bf16 v[56:59], v[28:31], v[196:199], v[0:3]
	s_waitcnt lgkmcnt(5)
	v_mfma_f32_16x16x32_bf16 v[0:3], v[44:47], v[184:187], v[216:219]
	s_waitcnt lgkmcnt(4)
	v_mfma_f32_16x16x32_bf16 v[32:35], v[200:203], v[188:191], v[0:3]
	v_mfma_f32_16x16x32_bf16 v[0:3], v[44:47], v[192:195], v[220:223]
	v_mfma_f32_16x16x32_bf16 v[40:43], v[200:203], v[196:199], v[0:3]
	s_waitcnt lgkmcnt(3)
	v_mfma_f32_16x16x32_bf16 v[0:3], v[204:207], v[184:187], v[224:227]
	s_waitcnt lgkmcnt(2)
	v_mfma_f32_16x16x32_bf16 v[16:19], v[232:235], v[188:191], v[0:3]
	v_mfma_f32_16x16x32_bf16 v[0:3], v[204:207], v[192:195], v[228:231]
	v_mfma_f32_16x16x32_bf16 v[24:27], v[232:235], v[196:199], v[0:3]
	s_waitcnt lgkmcnt(1)
	v_mfma_f32_16x16x32_bf16 v[0:3], v[236:239], v[184:187], v[144:147]
	v_mfma_f32_16x16x32_bf16 v[8:11], v[236:239], v[192:195], v[148:151]
	s_waitcnt lgkmcnt(0)
	v_mfma_f32_16x16x32_bf16 v[0:3], v[244:247], v[188:191], v[0:3]
	v_mfma_f32_16x16x32_bf16 v[8:11], v[244:247], v[196:199], v[8:11]
	s_setprio 1
	s_setprio 0
	v_mfma_f32_16x16x32_bf16 v[36:39], v[20:23], v[4:7], v[152:155]
	v_mfma_f32_16x16x32_bf16 v[20:23], v[20:23], v[240:243], v[156:159]
	v_mfma_f32_16x16x32_bf16 v[60:63], v[28:31], v[140:143], v[20:23]
	v_mfma_f32_16x16x32_bf16 v[20:23], v[44:47], v[4:7], v[160:163]
	v_mfma_f32_16x16x32_bf16 v[52:55], v[28:31], v[12:15], v[36:39]
	v_mfma_f32_16x16x32_bf16 v[36:39], v[200:203], v[12:15], v[20:23]
	v_mfma_f32_16x16x32_bf16 v[20:23], v[44:47], v[240:243], v[164:167]
	v_mfma_f32_16x16x32_bf16 v[44:47], v[200:203], v[140:143], v[20:23]
	v_mfma_f32_16x16x32_bf16 v[20:23], v[204:207], v[4:7], v[168:171]
	v_mfma_f32_16x16x32_bf16 v[4:7], v[236:239], v[4:7], v[176:179]
	v_mfma_f32_16x16x32_bf16 v[20:23], v[232:235], v[12:15], v[20:23]
	v_mfma_f32_16x16x32_bf16 v[28:31], v[204:207], v[240:243], v[172:175]
	v_mfma_f32_16x16x32_bf16 v[4:7], v[244:247], v[12:15], v[4:7]
	v_mfma_f32_16x16x32_bf16 v[12:15], v[236:239], v[240:243], v[180:183]
	v_mfma_f32_16x16x32_bf16 v[28:31], v[232:235], v[140:143], v[28:31]
	v_mfma_f32_16x16x32_bf16 v[12:15], v[244:247], v[140:143], v[12:15]
	s_setprio 1
	v_cmp_gt_u32_e32 vcc, s28, v129
	s_barrier
	s_and_saveexec_b64 s[2:3], vcc
	s_cbranch_execz .LBB0_360
	s_barrier
	s_branch .LBB0_360

.LBB0_372:
	ds_read_b128 v[140:143], v138
	ds_read_b128 v[144:147], v138 offset:1024
	ds_read_b128 v[148:151], v138 offset:2048
	ds_read_b128 v[152:155], v138 offset:3072
	s_mov_b32 m0, s38
	s_add_i32 s42, s41, 0xfff7ff80
	ds_read_b128 v[156:159], v134
	ds_read_b128 v[160:163], v134 offset:1024
	ds_read_b128 v[164:167], v133
	ds_read_b128 v[168:171], v133 offset:1024
	ds_read_b128 v[172:175], v132
	ds_read_b128 v[176:179], v132 offset:1024
	ds_read_b128 v[180:183], v131
	ds_read_b128 v[184:187], v131 offset:1024
	buffer_load_dwordx4 v128, s[64:67], s42 offen lds
	s_add_i32 s42, s41, 0xffffff80
	s_mov_b32 m0, s37
	s_nop 0
	buffer_load_dwordx4 v128, s[64:67], s42 offen lds
	s_waitcnt lgkmcnt(8)
	s_barrier
	s_waitcnt lgkmcnt(0)
	s_setprio 0
	s_waitcnt lgkmcnt(7)
	v_mfma_f32_16x16x32_bf16 v[124:127], v[156:159], v[140:143], v[124:127]
	v_mfma_f32_16x16x32_bf16 v[120:123], v[156:159], v[148:151], v[120:123]
	s_waitcnt lgkmcnt(5)
	v_mfma_f32_16x16x32_bf16 v[116:119], v[164:167], v[140:143], v[116:119]
	v_mfma_f32_16x16x32_bf16 v[112:115], v[164:167], v[148:151], v[112:115]
	s_waitcnt lgkmcnt(3)
	v_mfma_f32_16x16x32_bf16 v[108:111], v[172:175], v[140:143], v[108:111]
	v_mfma_f32_16x16x32_bf16 v[104:107], v[172:175], v[148:151], v[104:107]
	s_waitcnt lgkmcnt(1)
	v_mfma_f32_16x16x32_bf16 v[100:103], v[180:183], v[140:143], v[100:103]
	v_mfma_f32_16x16x32_bf16 v[96:99], v[180:183], v[148:151], v[96:99]
	v_mfma_f32_16x16x32_bf16 v[124:127], v[160:163], v[144:147], v[124:127]
	v_mfma_f32_16x16x32_bf16 v[120:123], v[160:163], v[152:155], v[120:123]
	v_mfma_f32_16x16x32_bf16 v[116:119], v[168:171], v[144:147], v[116:119]
	v_mfma_f32_16x16x32_bf16 v[112:115], v[168:171], v[152:155], v[112:115]
	v_mfma_f32_16x16x32_bf16 v[108:111], v[176:179], v[144:147], v[108:111]
	v_mfma_f32_16x16x32_bf16 v[104:107], v[176:179], v[152:155], v[104:107]
	s_waitcnt lgkmcnt(0)
	v_mfma_f32_16x16x32_bf16 v[100:103], v[184:187], v[144:147], v[100:103]
	v_mfma_f32_16x16x32_bf16 v[96:99], v[184:187], v[152:155], v[96:99]
	s_setprio 1
	s_barrier
	s_mov_b32 m0, s25
	s_add_i32 s42, s41, 0xffe80000
	ds_read_b128 v[188:191], v137
	ds_read_b128 v[198:201], v137 offset:1024
	ds_read_b128 v[202:205], v137 offset:2048
	ds_read_b128 v[206:209], v137 offset:3072
	buffer_load_dwordx4 v130, s[4:7], s42 offen lds
	s_add_i32 s43, s41, 0xffea0000
	s_mov_b32 m0, s26
	s_nop 0
	buffer_load_dwordx4 v130, s[4:7], s43 offen lds
	s_barrier
	s_waitcnt lgkmcnt(0)
	s_setprio 0
	s_waitcnt lgkmcnt(3)
	v_mfma_f32_16x16x32_bf16 v[92:95], v[156:159], v[188:191], v[92:95]
	s_waitcnt lgkmcnt(1)
	v_mfma_f32_16x16x32_bf16 v[88:91], v[156:159], v[202:205], v[88:91]
	v_mfma_f32_16x16x32_bf16 v[84:87], v[164:167], v[188:191], v[84:87]
	v_mfma_f32_16x16x32_bf16 v[80:83], v[164:167], v[202:205], v[80:83]
	v_mfma_f32_16x16x32_bf16 v[76:79], v[172:175], v[188:191], v[76:79]
	v_mfma_f32_16x16x32_bf16 v[72:75], v[172:175], v[202:205], v[72:75]
	v_mfma_f32_16x16x32_bf16 v[68:71], v[180:183], v[188:191], v[68:71]
	v_mfma_f32_16x16x32_bf16 v[64:67], v[180:183], v[202:205], v[64:67]
	v_mfma_f32_16x16x32_bf16 v[92:95], v[160:163], v[198:201], v[92:95]
	s_waitcnt lgkmcnt(0)
	v_mfma_f32_16x16x32_bf16 v[88:91], v[160:163], v[206:209], v[88:91]
	v_mfma_f32_16x16x32_bf16 v[84:87], v[168:171], v[198:201], v[84:87]
	v_mfma_f32_16x16x32_bf16 v[80:83], v[168:171], v[206:209], v[80:83]
	v_mfma_f32_16x16x32_bf16 v[76:79], v[176:179], v[198:201], v[76:79]
	v_mfma_f32_16x16x32_bf16 v[72:75], v[176:179], v[206:209], v[72:75]
	v_mfma_f32_16x16x32_bf16 v[68:71], v[184:187], v[198:201], v[68:71]
	v_mfma_f32_16x16x32_bf16 v[64:67], v[184:187], v[206:209], v[64:67]
	s_setprio 1
	s_mov_b32 m0, s24
	s_barrier
	ds_read_b128 v[156:159], v134 offset:16384
	ds_read_b128 v[160:163], v134 offset:17408
	ds_read_b128 v[164:167], v133 offset:16384
	ds_read_b128 v[168:171], v133 offset:17408
	ds_read_b128 v[172:175], v132 offset:16384
	ds_read_b128 v[176:179], v132 offset:17408
	ds_read_b128 v[180:183], v131 offset:16384
	ds_read_b128 v[184:187], v131 offset:17408
	buffer_load_dwordx4 v128, s[64:67], s42 offen lds
	s_add_i32 s42, s41, 0xfff00000
	s_mov_b32 m0, s27
	s_nop 0
	buffer_load_dwordx4 v128, s[64:67], s42 offen lds
	s_barrier
	s_waitcnt lgkmcnt(0)
	s_setprio 0
	s_waitcnt lgkmcnt(7)
	v_mfma_f32_16x16x32_bf16 v[60:63], v[156:159], v[140:143], v[60:63]
	v_mfma_f32_16x16x32_bf16 v[56:59], v[156:159], v[148:151], v[56:59]
	s_waitcnt lgkmcnt(5)
	v_mfma_f32_16x16x32_bf16 v[52:55], v[164:167], v[140:143], v[52:55]
	v_mfma_f32_16x16x32_bf16 v[48:51], v[164:167], v[148:151], v[48:51]
	s_waitcnt lgkmcnt(3)
	v_mfma_f32_16x16x32_bf16 v[44:47], v[172:175], v[140:143], v[44:47]
	v_mfma_f32_16x16x32_bf16 v[40:43], v[172:175], v[148:151], v[40:43]
	s_waitcnt lgkmcnt(1)
	v_mfma_f32_16x16x32_bf16 v[36:39], v[180:183], v[140:143], v[36:39]
	v_mfma_f32_16x16x32_bf16 v[32:35], v[180:183], v[148:151], v[32:35]
	v_mfma_f32_16x16x32_bf16 v[60:63], v[160:163], v[144:147], v[60:63]
	v_mfma_f32_16x16x32_bf16 v[56:59], v[160:163], v[152:155], v[56:59]
	v_mfma_f32_16x16x32_bf16 v[52:55], v[168:171], v[144:147], v[52:55]
	v_mfma_f32_16x16x32_bf16 v[48:51], v[168:171], v[152:155], v[48:51]
	v_mfma_f32_16x16x32_bf16 v[44:47], v[176:179], v[144:147], v[44:47]
	v_mfma_f32_16x16x32_bf16 v[40:43], v[176:179], v[152:155], v[40:43]
	s_waitcnt lgkmcnt(0)
	v_mfma_f32_16x16x32_bf16 v[36:39], v[184:187], v[144:147], v[36:39]
	v_mfma_f32_16x16x32_bf16 v[32:35], v[184:187], v[152:155], v[32:35]
	s_setprio 1
	s_barrier
	s_mov_b32 m0, s28
	s_add_i32 s42, s41, 0xffec0000
	buffer_load_dwordx4 v130, s[4:7], s42 offen lds
	s_add_i32 s42, s41, 0xffee0000
	s_mov_b32 m0, s29
	s_nop 0
	buffer_load_dwordx4 v130, s[4:7], s42 offen lds
	s_waitcnt vmcnt(6)
	s_barrier
	s_setprio 0
	v_mfma_f32_16x16x32_bf16 v[28:31], v[156:159], v[188:191], v[28:31]
	v_mfma_f32_16x16x32_bf16 v[24:27], v[156:159], v[202:205], v[24:27]
	v_mfma_f32_16x16x32_bf16 v[20:23], v[164:167], v[188:191], v[20:23]
	v_mfma_f32_16x16x32_bf16 v[16:19], v[164:167], v[202:205], v[16:19]
	v_mfma_f32_16x16x32_bf16 v[12:15], v[172:175], v[188:191], v[12:15]
	v_mfma_f32_16x16x32_bf16 v[8:11], v[172:175], v[202:205], v[8:11]
	v_mfma_f32_16x16x32_bf16 v[4:7], v[180:183], v[188:191], v[4:7]
	v_mfma_f32_16x16x32_bf16 v[0:3], v[180:183], v[202:205], v[0:3]
	v_mfma_f32_16x16x32_bf16 v[28:31], v[160:163], v[198:201], v[28:31]
	v_mfma_f32_16x16x32_bf16 v[24:27], v[160:163], v[206:209], v[24:27]
	v_mfma_f32_16x16x32_bf16 v[20:23], v[168:171], v[198:201], v[20:23]
	v_mfma_f32_16x16x32_bf16 v[16:19], v[168:171], v[206:209], v[16:19]
	v_mfma_f32_16x16x32_bf16 v[12:15], v[176:179], v[198:201], v[12:15]
	v_mfma_f32_16x16x32_bf16 v[8:11], v[176:179], v[206:209], v[8:11]
	v_mfma_f32_16x16x32_bf16 v[4:7], v[184:187], v[198:201], v[4:7]
	v_mfma_f32_16x16x32_bf16 v[0:3], v[184:187], v[206:209], v[0:3]
	s_setprio 1
	s_barrier
	ds_read_b128 v[140:143], v136
	ds_read_b128 v[144:147], v136 offset:1024
	ds_read_b128 v[148:151], v136 offset:2048
	ds_read_b128 v[152:155], v136 offset:3072
	s_add_i32 s42, s41, 0xfff80000
	s_mov_b32 m0, s30
	ds_read_b128 v[156:159], v134 offset:32768
	ds_read_b128 v[160:163], v134 offset:33792
	ds_read_b128 v[164:167], v133 offset:32768
	ds_read_b128 v[168:171], v133 offset:33792
	ds_read_b128 v[172:175], v132 offset:32768
	ds_read_b128 v[176:179], v132 offset:33792
	ds_read_b128 v[180:183], v131 offset:32768
	ds_read_b128 v[184:187], v131 offset:33792
	buffer_load_dwordx4 v128, s[64:67], s42 offen lds
	s_mov_b32 m0, s31
	s_nop 0
	buffer_load_dwordx4 v128, s[64:67], s41 offen lds
	s_waitcnt lgkmcnt(8)
	s_barrier
	s_waitcnt lgkmcnt(0)
	s_setprio 0
	s_waitcnt lgkmcnt(7)
	v_mfma_f32_16x16x32_bf16 v[124:127], v[156:159], v[140:143], v[124:127]
	v_mfma_f32_16x16x32_bf16 v[120:123], v[156:159], v[148:151], v[120:123]
	s_waitcnt lgkmcnt(5)
	v_mfma_f32_16x16x32_bf16 v[116:119], v[164:167], v[140:143], v[116:119]
	v_mfma_f32_16x16x32_bf16 v[112:115], v[164:167], v[148:151], v[112:115]
	s_waitcnt lgkmcnt(3)
	v_mfma_f32_16x16x32_bf16 v[108:111], v[172:175], v[140:143], v[108:111]
	v_mfma_f32_16x16x32_bf16 v[104:107], v[172:175], v[148:151], v[104:107]
	s_waitcnt lgkmcnt(1)
	v_mfma_f32_16x16x32_bf16 v[100:103], v[180:183], v[140:143], v[100:103]
	v_mfma_f32_16x16x32_bf16 v[96:99], v[180:183], v[148:151], v[96:99]
	v_mfma_f32_16x16x32_bf16 v[124:127], v[160:163], v[144:147], v[124:127]
	v_mfma_f32_16x16x32_bf16 v[120:123], v[160:163], v[152:155], v[120:123]
	v_mfma_f32_16x16x32_bf16 v[116:119], v[168:171], v[144:147], v[116:119]
	v_mfma_f32_16x16x32_bf16 v[112:115], v[168:171], v[152:155], v[112:115]
	v_mfma_f32_16x16x32_bf16 v[108:111], v[176:179], v[144:147], v[108:111]
	v_mfma_f32_16x16x32_bf16 v[104:107], v[176:179], v[152:155], v[104:107]
	s_waitcnt lgkmcnt(0)
	v_mfma_f32_16x16x32_bf16 v[100:103], v[184:187], v[144:147], v[100:103]
	v_mfma_f32_16x16x32_bf16 v[96:99], v[184:187], v[152:155], v[96:99]
	s_setprio 1
	s_barrier
	s_mov_b32 m0, s2
	s_add_i32 s42, s41, 0xffe80080
	ds_read_b128 v[188:191], v135
	ds_read_b128 v[198:201], v135 offset:1024
	ds_read_b128 v[202:205], v135 offset:2048
	ds_read_b128 v[206:209], v135 offset:3072
	buffer_load_dwordx4 v130, s[4:7], s42 offen lds
	s_add_i32 s43, s41, 0xffea0080
	s_mov_b32 m0, s3
	s_nop 0
	buffer_load_dwordx4 v130, s[4:7], s43 offen lds
	s_barrier
	s_waitcnt lgkmcnt(0)
	s_setprio 0
	s_waitcnt lgkmcnt(3)
	v_mfma_f32_16x16x32_bf16 v[92:95], v[156:159], v[188:191], v[92:95]
	s_waitcnt lgkmcnt(1)
	v_mfma_f32_16x16x32_bf16 v[88:91], v[156:159], v[202:205], v[88:91]
	v_mfma_f32_16x16x32_bf16 v[84:87], v[164:167], v[188:191], v[84:87]
	v_mfma_f32_16x16x32_bf16 v[80:83], v[164:167], v[202:205], v[80:83]
	v_mfma_f32_16x16x32_bf16 v[76:79], v[172:175], v[188:191], v[76:79]
	v_mfma_f32_16x16x32_bf16 v[72:75], v[172:175], v[202:205], v[72:75]
	v_mfma_f32_16x16x32_bf16 v[68:71], v[180:183], v[188:191], v[68:71]
	v_mfma_f32_16x16x32_bf16 v[64:67], v[180:183], v[202:205], v[64:67]
	v_mfma_f32_16x16x32_bf16 v[92:95], v[160:163], v[198:201], v[92:95]
	s_waitcnt lgkmcnt(0)
	v_mfma_f32_16x16x32_bf16 v[88:91], v[160:163], v[206:209], v[88:91]
	v_mfma_f32_16x16x32_bf16 v[84:87], v[168:171], v[198:201], v[84:87]
	v_mfma_f32_16x16x32_bf16 v[80:83], v[168:171], v[206:209], v[80:83]
	v_mfma_f32_16x16x32_bf16 v[76:79], v[176:179], v[198:201], v[76:79]
	v_mfma_f32_16x16x32_bf16 v[72:75], v[176:179], v[206:209], v[72:75]
	v_mfma_f32_16x16x32_bf16 v[68:71], v[184:187], v[198:201], v[68:71]
	v_mfma_f32_16x16x32_bf16 v[64:67], v[184:187], v[206:209], v[64:67]
	s_setprio 1
	s_mov_b32 m0, s34
	s_barrier
	ds_read_b128 v[156:159], v134 offset:49152
	ds_read_b128 v[160:163], v134 offset:50176
	ds_read_b128 v[164:167], v133 offset:49152
	ds_read_b128 v[168:171], v133 offset:50176
	ds_read_b128 v[172:175], v132 offset:49152
	ds_read_b128 v[176:179], v132 offset:50176
	ds_read_b128 v[180:183], v131 offset:49152
	ds_read_b128 v[184:187], v131 offset:50176
	buffer_load_dwordx4 v128, s[64:67], s42 offen lds
	s_add_i32 s42, s41, 0xfff00080
	s_mov_b32 m0, s35
	s_nop 0
	buffer_load_dwordx4 v128, s[64:67], s42 offen lds
	s_barrier
; #define LDA(dst, b, h)                                                                             \
;   _Pragma("unroll") for (int m = 0; m < 4; ++m) _Pragma("unroll") for (int k = 0; k < 2; ++k)      \
;       dst[m][k] = *reinterpret_cast<const bf16x8*>(SA(b, h) + lds_byte(wr * 64 + m * 16 + fr, k * 32 + fq * 8))
; #define LDB(dst, b, h)                                                                             \
;   _Pragma("unroll") for (int n = 0; n < 2; ++n) _Pragma("unroll") for (int k = 0; k < 2; ++k)      \
;       dst[n][k] = *reinterpret_cast<const bf16x8*>(SB(b, h) + lds_byte(wc * 32 + n * 16 + fr, k * 32 + fq * 8))
; #define WAIT_V(n) asm volatile("s_waitcnt vmcnt(" #n ")" ::: "memory")
; #define WAIT_L(n) asm volatile("s_waitcnt lgkmcnt(" #n ")" ::: "memory")
; #define BAR __builtin_amdgcn_s_barrier()
; template <bool PEEL = false>
; __device__ __forceinline__ void gemm_tile(f32x4 (&acc)[2][2][4][2], const u16* __restrict__ A, int lda,
;                                           const u16* __restrict__ B, int K) {
;     ...
;   {
;     LDB(B0, 0, 0); LDA(At, 0, 0); STAGE_A(SA(1, 1), 1, nt - 1);
;     BAR; WAIT_L(0); MMA(0, 0, At, B0); BAR;
;     LDB(B1, 0, 1); BAR; WAIT_L(0); MMA(0, 1, At, B1); BAR;
;     LDA(At, 0, 1); WAIT_V(4); BAR; WAIT_L(0); MMA(1, 0, At, B0); MMA(1, 1, At, B1); BAR;
	s_waitcnt lgkmcnt(0)
	s_setprio 0
	s_waitcnt lgkmcnt(7)
	v_mfma_f32_16x16x32_bf16 v[60:63], v[156:159], v[140:143], v[60:63]
	v_mfma_f32_16x16x32_bf16 v[56:59], v[156:159], v[148:151], v[56:59]
	s_waitcnt lgkmcnt(5)
	v_mfma_f32_16x16x32_bf16 v[52:55], v[164:167], v[140:143], v[52:55]
	v_mfma_f32_16x16x32_bf16 v[48:51], v[164:167], v[148:151], v[48:51]
	s_waitcnt lgkmcnt(3)
	v_mfma_f32_16x16x32_bf16 v[44:47], v[172:175], v[140:143], v[44:47]
	v_mfma_f32_16x16x32_bf16 v[40:43], v[172:175], v[148:151], v[40:43]
	s_waitcnt lgkmcnt(1)
	v_mfma_f32_16x16x32_bf16 v[36:39], v[180:183], v[140:143], v[36:39]
	v_mfma_f32_16x16x32_bf16 v[32:35], v[180:183], v[148:151], v[32:35]
	v_mfma_f32_16x16x32_bf16 v[60:63], v[160:163], v[144:147], v[60:63]
	v_mfma_f32_16x16x32_bf16 v[56:59], v[160:163], v[152:155], v[56:59]
	v_mfma_f32_16x16x32_bf16 v[52:55], v[168:171], v[144:147], v[52:55]
	v_mfma_f32_16x16x32_bf16 v[48:51], v[168:171], v[152:155], v[48:51]
	v_mfma_f32_16x16x32_bf16 v[44:47], v[176:179], v[144:147], v[44:47]
	v_mfma_f32_16x16x32_bf16 v[40:43], v[176:179], v[152:155], v[40:43]
	s_waitcnt lgkmcnt(0)
	v_mfma_f32_16x16x32_bf16 v[36:39], v[184:187], v[144:147], v[36:39]
	v_mfma_f32_16x16x32_bf16 v[32:35], v[184:187], v[152:155], v[32:35]
	s_setprio 1
	s_barrier
	s_mov_b32 m0, s36
	s_add_i32 s42, s41, 0xffec0080
	buffer_load_dwordx4 v130, s[4:7], s42 offen lds
	s_add_i32 s42, s41, 0xffee0080
	s_mov_b32 m0, s39
	s_nop 0
	buffer_load_dwordx4 v130, s[4:7], s42 offen lds
	s_waitcnt vmcnt(6)
	s_barrier
	s_setprio 0
	v_mfma_f32_16x16x32_bf16 v[28:31], v[156:159], v[188:191], v[28:31]
	v_mfma_f32_16x16x32_bf16 v[24:27], v[156:159], v[202:205], v[24:27]
	v_mfma_f32_16x16x32_bf16 v[20:23], v[164:167], v[188:191], v[20:23]
	v_mfma_f32_16x16x32_bf16 v[16:19], v[164:167], v[202:205], v[16:19]
	v_mfma_f32_16x16x32_bf16 v[12:15], v[172:175], v[188:191], v[12:15]
	v_mfma_f32_16x16x32_bf16 v[8:11], v[172:175], v[202:205], v[8:11]
	v_mfma_f32_16x16x32_bf16 v[4:7], v[180:183], v[188:191], v[4:7]
	v_mfma_f32_16x16x32_bf16 v[0:3], v[180:183], v[202:205], v[0:3]
	v_mfma_f32_16x16x32_bf16 v[28:31], v[160:163], v[198:201], v[28:31]
	v_mfma_f32_16x16x32_bf16 v[24:27], v[160:163], v[206:209], v[24:27]
	v_mfma_f32_16x16x32_bf16 v[20:23], v[168:171], v[198:201], v[20:23]
	v_mfma_f32_16x16x32_bf16 v[16:19], v[168:171], v[206:209], v[16:19]
	v_mfma_f32_16x16x32_bf16 v[12:15], v[176:179], v[198:201], v[12:15]
	v_mfma_f32_16x16x32_bf16 v[8:11], v[176:179], v[206:209], v[8:11]
	v_mfma_f32_16x16x32_bf16 v[4:7], v[184:187], v[198:201], v[4:7]
	v_mfma_f32_16x16x32_bf16 v[0:3], v[184:187], v[206:209], v[0:3]
	s_setprio 1
	s_add_i32 s40, s40, 2
	s_addk_i32 s41, 0x100
	s_cmp_lt_u32 s40, 12
	s_barrier
	s_cbranch_scc1 .LBB0_372
	s_mov_b32 m0, s38
	ds_read_b128 v[140:143], v138
	ds_read_b128 v[144:147], v138 offset:1024
	ds_read_b128 v[148:151], v138 offset:2048
	ds_read_b128 v[152:155], v138 offset:3072
	ds_read_b128 v[156:159], v134
	ds_read_b128 v[160:163], v134 offset:1024
	ds_read_b128 v[164:167], v133
	ds_read_b128 v[168:171], v133 offset:1024
	ds_read_b128 v[172:175], v132
	ds_read_b128 v[176:179], v132 offset:1024
	ds_read_b128 v[180:183], v131
	ds_read_b128 v[184:187], v131 offset:1024
	buffer_load_dwordx4 v128, s[64:67], s22 offen lds
	s_mov_b32 m0, s37
	s_nop 0
	buffer_load_dwordx4 v128, s[64:67], s23 offen lds
	s_barrier
	s_waitcnt lgkmcnt(0)
	s_setprio 0
	s_waitcnt lgkmcnt(7)
	v_mfma_f32_16x16x32_bf16 v[124:127], v[156:159], v[140:143], v[124:127]
	v_mfma_f32_16x16x32_bf16 v[120:123], v[156:159], v[148:151], v[120:123]
	s_waitcnt lgkmcnt(3)
	v_mfma_f32_16x16x32_bf16 v[108:111], v[172:175], v[140:143], v[108:111]
	v_mfma_f32_16x16x32_bf16 v[104:107], v[172:175], v[148:151], v[104:107]
	v_mfma_f32_16x16x32_bf16 v[124:127], v[160:163], v[144:147], v[124:127]
	v_mfma_f32_16x16x32_bf16 v[120:123], v[160:163], v[152:155], v[120:123]
	v_mfma_f32_16x16x32_bf16 v[116:119], v[164:167], v[140:143], v[116:119]
	v_mfma_f32_16x16x32_bf16 v[112:115], v[164:167], v[148:151], v[112:115]
	s_waitcnt lgkmcnt(2)
	v_mfma_f32_16x16x32_bf16 v[108:111], v[176:179], v[144:147], v[108:111]
	v_mfma_f32_16x16x32_bf16 v[104:107], v[176:179], v[152:155], v[104:107]
	s_waitcnt lgkmcnt(1)
	v_mfma_f32_16x16x32_bf16 v[100:103], v[180:183], v[140:143], v[100:103]
	v_mfma_f32_16x16x32_bf16 v[96:99], v[180:183], v[148:151], v[96:99]
	v_mfma_f32_16x16x32_bf16 v[188:191], v[168:171], v[144:147], v[116:119]
	v_mfma_f32_16x16x32_bf16 v[198:201], v[168:171], v[152:155], v[112:115]
	s_waitcnt lgkmcnt(0)
	v_mfma_f32_16x16x32_bf16 v[202:205], v[184:187], v[144:147], v[100:103]
	v_mfma_f32_16x16x32_bf16 v[206:209], v[184:187], v[152:155], v[96:99]
	s_setprio 1
	s_barrier
	s_nop 0
	ds_read_b128 v[96:99], v137
	ds_read_b128 v[100:103], v137 offset:1024
	ds_read_b128 v[112:115], v137 offset:2048
	ds_read_b128 v[116:119], v137 offset:3072
	s_barrier
	s_waitcnt lgkmcnt(0)
	s_setprio 0
	s_waitcnt lgkmcnt(3)
	v_mfma_f32_16x16x32_bf16 v[92:95], v[156:159], v[96:99], v[92:95]
	s_waitcnt lgkmcnt(1)
	v_mfma_f32_16x16x32_bf16 v[88:91], v[156:159], v[112:115], v[88:91]
	v_mfma_f32_16x16x32_bf16 v[76:79], v[172:175], v[96:99], v[76:79]
	v_mfma_f32_16x16x32_bf16 v[72:75], v[172:175], v[112:115], v[72:75]
	v_mfma_f32_16x16x32_bf16 v[92:95], v[160:163], v[100:103], v[92:95]
	s_waitcnt lgkmcnt(0)
	v_mfma_f32_16x16x32_bf16 v[88:91], v[160:163], v[116:119], v[88:91]
	v_mfma_f32_16x16x32_bf16 v[84:87], v[164:167], v[96:99], v[84:87]
	v_mfma_f32_16x16x32_bf16 v[80:83], v[164:167], v[112:115], v[80:83]
	v_mfma_f32_16x16x32_bf16 v[76:79], v[176:179], v[100:103], v[76:79]
	v_mfma_f32_16x16x32_bf16 v[72:75], v[176:179], v[116:119], v[72:75]
	v_mfma_f32_16x16x32_bf16 v[68:71], v[180:183], v[96:99], v[68:71]
	v_mfma_f32_16x16x32_bf16 v[64:67], v[180:183], v[112:115], v[64:67]
	v_mfma_f32_16x16x32_bf16 v[156:159], v[168:171], v[100:103], v[84:87]
	v_mfma_f32_16x16x32_bf16 v[160:163], v[168:171], v[116:119], v[80:83]
	v_mfma_f32_16x16x32_bf16 v[164:167], v[184:187], v[100:103], v[68:71]
	v_mfma_f32_16x16x32_bf16 v[168:171], v[184:187], v[116:119], v[64:67]
	s_setprio 1
	s_barrier
; #define LDA(dst, b, h)                                                                             \
;   _Pragma("unroll") for (int m = 0; m < 4; ++m) _Pragma("unroll") for (int k = 0; k < 2; ++k)      \
;       dst[m][k] = *reinterpret_cast<const bf16x8*>(SA(b, h) + lds_byte(wr * 64 + m * 16 + fr, k * 32 + fq * 8))
; #define LDB(dst, b, h)                                                                             \
;   _Pragma("unroll") for (int n = 0; n < 2; ++n) _Pragma("unroll") for (int k = 0; k < 2; ++k)      \
;       dst[n][k] = *reinterpret_cast<const bf16x8*>(SB(b, h) + lds_byte(wc * 32 + n * 16 + fr, k * 32 + fq * 8))
; #define WAIT_V(n) asm volatile("s_waitcnt vmcnt(" #n ")" ::: "memory")
; #define WAIT_L(n) asm volatile("s_waitcnt lgkmcnt(" #n ")" ::: "memory")
; #define BAR __builtin_amdgcn_s_barrier()
; template <bool PEEL = false>
; __device__ __forceinline__ void gemm_tile(f32x4 (&acc)[2][2][4][2], const u16* __restrict__ A, int lda,
;                                           const u16* __restrict__ B, int K) {
;     ...
;     LDA(At, 0, 1); WAIT_V(4); BAR; WAIT_L(0); MMA(1, 0, At, B0); MMA(1, 1, At, B1); BAR;
;   }
;   {
;     LDB(B0, 1, 0); LDA(At, 1, 0); WAIT_V(2); BAR; WAIT_L(0); MMA(0, 0, At, B0); BAR;
	s_nop 1
	ds_read_b128 v[64:67], v134 offset:16384
	ds_read_b128 v[68:71], v134 offset:17408
	ds_read_b128 v[80:83], v133 offset:16384
	ds_read_b128 v[84:87], v133 offset:17408
	ds_read_b128 v[172:175], v132 offset:16384
	ds_read_b128 v[176:179], v132 offset:17408
	ds_read_b128 v[180:183], v131 offset:16384
	ds_read_b128 v[184:187], v131 offset:17408
	s_waitcnt vmcnt(4)
	s_barrier
	s_waitcnt lgkmcnt(0)
	s_setprio 0
	s_waitcnt lgkmcnt(7)
	v_mfma_f32_16x16x32_bf16 v[60:63], v[64:67], v[140:143], v[60:63]
	v_mfma_f32_16x16x32_bf16 v[56:59], v[64:67], v[148:151], v[56:59]
	s_waitcnt lgkmcnt(3)
	v_mfma_f32_16x16x32_bf16 v[44:47], v[172:175], v[140:143], v[44:47]
	v_mfma_f32_16x16x32_bf16 v[40:43], v[172:175], v[148:151], v[40:43]
	v_mfma_f32_16x16x32_bf16 v[60:63], v[68:71], v[144:147], v[60:63]
	v_mfma_f32_16x16x32_bf16 v[56:59], v[68:71], v[152:155], v[56:59]
	v_mfma_f32_16x16x32_bf16 v[52:55], v[80:83], v[140:143], v[52:55]
	v_mfma_f32_16x16x32_bf16 v[48:51], v[80:83], v[148:151], v[48:51]
	s_waitcnt lgkmcnt(2)
	v_mfma_f32_16x16x32_bf16 v[44:47], v[176:179], v[144:147], v[44:47]
	v_mfma_f32_16x16x32_bf16 v[40:43], v[176:179], v[152:155], v[40:43]
	s_waitcnt lgkmcnt(1)
	v_mfma_f32_16x16x32_bf16 v[36:39], v[180:183], v[140:143], v[36:39]
	v_mfma_f32_16x16x32_bf16 v[32:35], v[180:183], v[148:151], v[32:35]
	v_mfma_f32_16x16x32_bf16 v[210:213], v[84:87], v[144:147], v[52:55]
	v_mfma_f32_16x16x32_bf16 v[214:217], v[84:87], v[152:155], v[48:51]
	s_waitcnt lgkmcnt(0)
	v_mfma_f32_16x16x32_bf16 v[138:141], v[184:187], v[144:147], v[36:39]
	v_mfma_f32_16x16x32_bf16 v[142:145], v[184:187], v[152:155], v[32:35]
	s_setprio 1
	s_setprio 0
	v_mfma_f32_16x16x32_bf16 v[28:31], v[64:67], v[96:99], v[28:31]
	v_mfma_f32_16x16x32_bf16 v[24:27], v[64:67], v[112:115], v[24:27]
	v_mfma_f32_16x16x32_bf16 v[12:15], v[172:175], v[96:99], v[12:15]
	v_mfma_f32_16x16x32_bf16 v[8:11], v[172:175], v[112:115], v[8:11]
	v_mfma_f32_16x16x32_bf16 v[28:31], v[68:71], v[100:103], v[28:31]
	v_mfma_f32_16x16x32_bf16 v[24:27], v[68:71], v[116:119], v[24:27]
	v_mfma_f32_16x16x32_bf16 v[20:23], v[80:83], v[96:99], v[20:23]
	v_mfma_f32_16x16x32_bf16 v[16:19], v[80:83], v[112:115], v[16:19]
	v_mfma_f32_16x16x32_bf16 v[12:15], v[176:179], v[100:103], v[12:15]
	v_mfma_f32_16x16x32_bf16 v[8:11], v[176:179], v[116:119], v[8:11]
	v_mfma_f32_16x16x32_bf16 v[4:7], v[180:183], v[96:99], v[4:7]
	v_mfma_f32_16x16x32_bf16 v[0:3], v[180:183], v[112:115], v[0:3]
	v_mfma_f32_16x16x32_bf16 v[146:149], v[84:87], v[100:103], v[20:23]
	v_mfma_f32_16x16x32_bf16 v[150:153], v[84:87], v[116:119], v[16:19]
	v_mfma_f32_16x16x32_bf16 v[172:175], v[184:187], v[100:103], v[4:7]
	v_mfma_f32_16x16x32_bf16 v[176:179], v[184:187], v[116:119], v[0:3]
	s_setprio 1
	s_barrier
	s_nop 1
	ds_read_b128 v[0:3], v136
	ds_read_b128 v[4:7], v136 offset:1024
	ds_read_b128 v[180:183], v136 offset:2048
	ds_read_b128 v[184:187], v136 offset:3072
	ds_read_b128 v[16:19], v134 offset:32768
	ds_read_b128 v[20:23], v134 offset:33792
	ds_read_b128 v[32:35], v133 offset:32768
	ds_read_b128 v[36:39], v133 offset:33792
	ds_read_b128 v[48:51], v132 offset:32768
	ds_read_b128 v[52:55], v132 offset:33792
	ds_read_b128 v[218:221], v131 offset:32768
	ds_read_b128 v[222:225], v131 offset:33792
	s_waitcnt vmcnt(2)
	s_barrier
	s_waitcnt lgkmcnt(0)
	s_setprio 0
	s_waitcnt lgkmcnt(7)
	v_mfma_f32_16x16x32_bf16 v[64:67], v[16:19], v[0:3], v[124:127]
	s_waitcnt lgkmcnt(6)
	v_mfma_f32_16x16x32_bf16 v[112:115], v[20:23], v[4:7], v[64:67]
	v_mfma_f32_16x16x32_bf16 v[64:67], v[16:19], v[180:183], v[120:123]
	v_mfma_f32_16x16x32_bf16 v[116:119], v[20:23], v[184:187], v[64:67]
	s_waitcnt lgkmcnt(5)
	v_mfma_f32_16x16x32_bf16 v[64:67], v[32:35], v[0:3], v[188:191]
	s_waitcnt lgkmcnt(4)
	v_mfma_f32_16x16x32_bf16 v[96:99], v[36:39], v[4:7], v[64:67]
	v_mfma_f32_16x16x32_bf16 v[64:67], v[32:35], v[180:183], v[198:201]
	v_mfma_f32_16x16x32_bf16 v[100:103], v[36:39], v[184:187], v[64:67]
	s_waitcnt lgkmcnt(3)
	v_mfma_f32_16x16x32_bf16 v[64:67], v[48:51], v[0:3], v[108:111]
	s_waitcnt lgkmcnt(2)
	v_mfma_f32_16x16x32_bf16 v[80:83], v[52:55], v[4:7], v[64:67]
	v_mfma_f32_16x16x32_bf16 v[64:67], v[48:51], v[180:183], v[104:107]
	v_mfma_f32_16x16x32_bf16 v[84:87], v[52:55], v[184:187], v[64:67]
	s_waitcnt lgkmcnt(1)
	v_mfma_f32_16x16x32_bf16 v[64:67], v[218:221], v[0:3], v[202:205]
	v_mfma_f32_16x16x32_bf16 v[68:71], v[218:221], v[180:183], v[206:209]
	s_waitcnt lgkmcnt(0)
	v_mfma_f32_16x16x32_bf16 v[64:67], v[222:225], v[4:7], v[64:67]
	v_mfma_f32_16x16x32_bf16 v[68:71], v[222:225], v[184:187], v[68:71]
	s_setprio 1
	s_barrier
; #define LDA(dst, b, h)                                                                             \
;   _Pragma("unroll") for (int m = 0; m < 4; ++m) _Pragma("unroll") for (int k = 0; k < 2; ++k)      \
;       dst[m][k] = *reinterpret_cast<const bf16x8*>(SA(b, h) + lds_byte(wr * 64 + m * 16 + fr, k * 32 + fq * 8))
; #define LDB(dst, b, h)                                                                             \
;   _Pragma("unroll") for (int n = 0; n < 2; ++n) _Pragma("unroll") for (int k = 0; k < 2; ++k)      \
;       dst[n][k] = *reinterpret_cast<const bf16x8*>(SB(b, h) + lds_byte(wc * 32 + n * 16 + fr, k * 32 + fq * 8))
; #define WAIT_V(n) asm volatile("s_waitcnt vmcnt(" #n ")" ::: "memory")
; #define WAIT_L(n) asm volatile("s_waitcnt lgkmcnt(" #n ")" ::: "memory")
; #define BAR __builtin_amdgcn_s_barrier()
; template <bool PEEL = false>
; __device__ __forceinline__ void gemm_tile(f32x4 (&acc)[2][2][4][2], const u16* __restrict__ A, int lda,
;                                           const u16* __restrict__ B, int K) {
;     ...
;     LDB(B0, 1, 0); LDA(At, 1, 0); WAIT_V(2); BAR; WAIT_L(0); MMA(0, 0, At, B0); BAR;
;     LDB(B1, 1, 1); WAIT_V(0); BAR; WAIT_L(0); MMA(0, 1, At, B1); BAR;
;     LDA(At, 1, 1); BAR; WAIT_L(0); MMA(1, 0, At, B0); MMA(1, 1, At, B1); BAR;
;   }
;   if (wr == 0) BAR;
	ds_read_b128 v[188:191], v135
	ds_read_b128 v[198:201], v135 offset:1024
	ds_read_b128 v[202:205], v135 offset:2048
	ds_read_b128 v[206:209], v135 offset:3072
	s_waitcnt vmcnt(0)
	s_barrier
	s_waitcnt lgkmcnt(0)
	s_setprio 0
	s_waitcnt lgkmcnt(3)
	v_mfma_f32_16x16x32_bf16 v[92:95], v[16:19], v[188:191], v[92:95]
	s_waitcnt lgkmcnt(1)
	v_mfma_f32_16x16x32_bf16 v[16:19], v[16:19], v[202:205], v[88:91]
	s_waitcnt lgkmcnt(0)
	v_mfma_f32_16x16x32_bf16 v[124:127], v[20:23], v[206:209], v[16:19]
	v_mfma_f32_16x16x32_bf16 v[16:19], v[32:35], v[188:191], v[156:159]
	v_mfma_f32_16x16x32_bf16 v[104:107], v[36:39], v[198:201], v[16:19]
	v_mfma_f32_16x16x32_bf16 v[16:19], v[32:35], v[202:205], v[160:163]
	v_mfma_f32_16x16x32_bf16 v[108:111], v[36:39], v[206:209], v[16:19]
	v_mfma_f32_16x16x32_bf16 v[16:19], v[48:51], v[188:191], v[76:79]
	v_mfma_f32_16x16x32_bf16 v[88:91], v[52:55], v[198:201], v[16:19]
	v_mfma_f32_16x16x32_bf16 v[16:19], v[48:51], v[202:205], v[72:75]
	v_mfma_f32_16x16x32_bf16 v[120:123], v[20:23], v[198:201], v[92:95]
	v_mfma_f32_16x16x32_bf16 v[92:95], v[52:55], v[206:209], v[16:19]
	v_mfma_f32_16x16x32_bf16 v[16:19], v[218:221], v[188:191], v[164:167]
	v_mfma_f32_16x16x32_bf16 v[72:75], v[222:225], v[198:201], v[16:19]
	v_mfma_f32_16x16x32_bf16 v[16:19], v[218:221], v[202:205], v[168:171]
	v_mfma_f32_16x16x32_bf16 v[76:79], v[222:225], v[206:209], v[16:19]
	s_setprio 1
	s_barrier
	ds_read_b128 v[154:157], v134 offset:49152
	ds_read_b128 v[134:137], v134 offset:50176
	ds_read_b128 v[158:161], v133 offset:49152
	ds_read_b128 v[162:165], v133 offset:50176
	ds_read_b128 v[166:169], v132 offset:49152
	ds_read_b128 v[218:221], v132 offset:50176
	ds_read_b128 v[222:225], v131 offset:49152
	ds_read_b128 v[130:133], v131 offset:50176
	s_barrier
	s_waitcnt lgkmcnt(0)
	s_setprio 0
	s_waitcnt lgkmcnt(7)
	v_mfma_f32_16x16x32_bf16 v[16:19], v[154:157], v[0:3], v[60:63]
	s_waitcnt lgkmcnt(6)
	v_mfma_f32_16x16x32_bf16 v[48:51], v[134:137], v[4:7], v[16:19]
	v_mfma_f32_16x16x32_bf16 v[16:19], v[154:157], v[180:183], v[56:59]
	v_mfma_f32_16x16x32_bf16 v[52:55], v[134:137], v[184:187], v[16:19]
	s_waitcnt lgkmcnt(5)
	v_mfma_f32_16x16x32_bf16 v[16:19], v[158:161], v[0:3], v[210:213]
	s_waitcnt lgkmcnt(4)
	v_mfma_f32_16x16x32_bf16 v[32:35], v[162:165], v[4:7], v[16:19]
	v_mfma_f32_16x16x32_bf16 v[16:19], v[158:161], v[180:183], v[214:217]
	v_mfma_f32_16x16x32_bf16 v[36:39], v[162:165], v[184:187], v[16:19]
	s_waitcnt lgkmcnt(3)
	v_mfma_f32_16x16x32_bf16 v[16:19], v[166:169], v[0:3], v[44:47]
	s_waitcnt lgkmcnt(1)
	v_mfma_f32_16x16x32_bf16 v[0:3], v[222:225], v[0:3], v[138:141]
	v_mfma_f32_16x16x32_bf16 v[16:19], v[218:221], v[4:7], v[16:19]
	v_mfma_f32_16x16x32_bf16 v[20:23], v[166:169], v[180:183], v[40:43]
	s_waitcnt lgkmcnt(0)
	v_mfma_f32_16x16x32_bf16 v[0:3], v[130:133], v[4:7], v[0:3]
	v_mfma_f32_16x16x32_bf16 v[4:7], v[222:225], v[180:183], v[142:145]
	v_mfma_f32_16x16x32_bf16 v[20:23], v[218:221], v[184:187], v[20:23]
	v_mfma_f32_16x16x32_bf16 v[4:7], v[130:133], v[184:187], v[4:7]
	s_setprio 1
	s_setprio 0
	v_mfma_f32_16x16x32_bf16 v[24:27], v[154:157], v[202:205], v[24:27]
	v_mfma_f32_16x16x32_bf16 v[60:63], v[134:137], v[206:209], v[24:27]
	v_mfma_f32_16x16x32_bf16 v[24:27], v[158:161], v[188:191], v[146:149]
	v_mfma_f32_16x16x32_bf16 v[28:31], v[154:157], v[188:191], v[28:31]
	v_mfma_f32_16x16x32_bf16 v[40:43], v[162:165], v[198:201], v[24:27]
	v_mfma_f32_16x16x32_bf16 v[24:27], v[158:161], v[202:205], v[150:153]
	v_mfma_f32_16x16x32_bf16 v[12:15], v[166:169], v[188:191], v[12:15]
	v_mfma_f32_16x16x32_bf16 v[8:11], v[166:169], v[202:205], v[8:11]
	v_mfma_f32_16x16x32_bf16 v[56:59], v[134:137], v[198:201], v[28:31]
	v_mfma_f32_16x16x32_bf16 v[44:47], v[162:165], v[206:209], v[24:27]
	v_mfma_f32_16x16x32_bf16 v[24:27], v[218:221], v[198:201], v[12:15]
	v_mfma_f32_16x16x32_bf16 v[28:31], v[218:221], v[206:209], v[8:11]
	v_mfma_f32_16x16x32_bf16 v[8:11], v[222:225], v[188:191], v[172:175]
	v_mfma_f32_16x16x32_bf16 v[12:15], v[222:225], v[202:205], v[176:179]
	v_mfma_f32_16x16x32_bf16 v[8:11], v[130:133], v[198:201], v[8:11]
	v_mfma_f32_16x16x32_bf16 v[12:15], v[130:133], v[206:209], v[12:15]
	s_setprio 1
	v_cmp_gt_u32_e32 vcc, s21, v129
	s_barrier
	s_and_saveexec_b64 s[2:3], vcc
	s_cbranch_execz .LBB0_375
	s_barrier

.Lpf2_join:
	s_add_i32 s2, s64, 0x18000
	s_add_i32 s3, s64, 0x1a000
	v_and_b32_e32 v2, 15, v133
	v_lshlrev_b32_e32 v0, 12, v0
	v_and_b32_e32 v126, 0x3000, v0
	v_lshlrev_b32_e32 v0, 6, v2
	v_lshlrev_b32_e32 v2, 2, v133
	v_and_b32_e32 v26, 48, v133
	v_and_b32_e32 v27, 32, v2
	v_bitop3_b32 v127, v0, v27, v26 bitop3:0x36
	v_add_u32_e32 v0, s69, v127
	v_add_u32_e32 v139, v0, v126
	s_barrier
	ds_read_b128 v[2:5], v139
	ds_read_b128 v[6:9], v139 offset:1024
	ds_read_b128 v[10:13], v139 offset:2048
	ds_read_b128 v[14:17], v139 offset:3072
	v_lshlrev_b32_e32 v0, 13, v1
	v_add_u32_e32 v1, 0, v127
	v_add_u32_e32 v134, v1, v0
	v_lshlrev_b32_e32 v1, 6, v133
	s_movk_i32 s86, 0x3c0
	v_and_or_b32 v1, v1, s86, v26
	v_xad_u32 v1, v1, v27, 0
	v_or_b32_e32 v26, 0x800, v0
	v_or_b32_e32 v34, 0x1000, v0
	v_or_b32_e32 v0, 0x1800, v0
	s_add_i32 s87, s64, 0xc000
	v_add_u32_e32 v135, v1, v26
	v_add_u32_e32 v136, v1, v34
	v_add_u32_e32 v137, v1, v0
	s_mov_b32 m0, s87
	s_add_i32 s86, s64, 0xe000
	ds_read_b128 v[18:21], v134
	ds_read_b128 v[22:25], v134 offset:1024
	ds_read_b128 v[26:29], v135
	ds_read_b128 v[30:33], v135 offset:1024
	ds_read_b128 v[34:37], v136
	ds_read_b128 v[38:41], v136 offset:1024
	ds_read_b128 v[42:45], v137
	ds_read_b128 v[46:49], v137 offset:1024
	buffer_load_dwordx4 v138, s[56:59], s14 offen lds
	s_mov_b32 m0, s86
	s_nop 0
	buffer_load_dwordx4 v138, s[56:59], s15 offen lds
	s_waitcnt lgkmcnt(8)
	s_barrier
	s_waitcnt lgkmcnt(0)
	s_setprio 0
	s_waitcnt lgkmcnt(7)
	v_mfma_f32_16x16x32_bf16 v[50:53], v[18:21], v[2:5], 0
	v_mfma_f32_16x16x32_bf16 v[54:57], v[18:21], v[10:13], 0
	s_waitcnt lgkmcnt(5)
	v_mfma_f32_16x16x32_bf16 v[58:61], v[26:29], v[2:5], 0
	v_mfma_f32_16x16x32_bf16 v[62:65], v[26:29], v[10:13], 0
	s_waitcnt lgkmcnt(3)
	v_mfma_f32_16x16x32_bf16 v[66:69], v[34:37], v[2:5], 0
	v_mfma_f32_16x16x32_bf16 v[70:73], v[34:37], v[10:13], 0
	s_waitcnt lgkmcnt(1)
	v_mfma_f32_16x16x32_bf16 v[74:77], v[42:45], v[2:5], 0
	v_mfma_f32_16x16x32_bf16 v[78:81], v[42:45], v[10:13], 0
	v_mfma_f32_16x16x32_bf16 v[50:53], v[22:25], v[6:9], v[50:53]
	v_mfma_f32_16x16x32_bf16 v[54:57], v[22:25], v[14:17], v[54:57]
	v_mfma_f32_16x16x32_bf16 v[58:61], v[30:33], v[6:9], v[58:61]
	v_mfma_f32_16x16x32_bf16 v[62:65], v[30:33], v[14:17], v[62:65]
	v_mfma_f32_16x16x32_bf16 v[66:69], v[38:41], v[6:9], v[66:69]
	v_mfma_f32_16x16x32_bf16 v[70:73], v[38:41], v[14:17], v[70:73]
	s_waitcnt lgkmcnt(0)
	v_mfma_f32_16x16x32_bf16 v[74:77], v[46:49], v[6:9], v[74:77]
	v_mfma_f32_16x16x32_bf16 v[78:81], v[46:49], v[14:17], v[78:81]
	s_setprio 1
	s_barrier
	v_add_u32_e32 v0, s70, v127
	v_add_u32_e32 v140, v0, v126
	s_mov_b32 m0, s65
	ds_read_b128 v[82:85], v140
	ds_read_b128 v[86:89], v140 offset:1024
	ds_read_b128 v[90:93], v140 offset:2048
	ds_read_b128 v[94:97], v140 offset:3072
	buffer_load_dwordx4 v138, s[4:7], s0 offen lds
	s_mov_b32 m0, s66
	s_nop 0
	buffer_load_dwordx4 v138, s[4:7], s16 offen lds
	s_barrier
	s_waitcnt lgkmcnt(0)
	s_setprio 0
	s_waitcnt lgkmcnt(3)
	v_mfma_f32_16x16x32_bf16 v[98:101], v[18:21], v[82:85], 0
	s_waitcnt lgkmcnt(1)
	v_mfma_f32_16x16x32_bf16 v[18:21], v[18:21], v[90:93], 0
	s_waitcnt lgkmcnt(0)
	v_mfma_f32_16x16x32_bf16 v[102:105], v[22:25], v[94:97], v[18:21]
	v_mfma_f32_16x16x32_bf16 v[18:21], v[26:29], v[82:85], 0
	v_mfma_f32_16x16x32_bf16 v[106:109], v[30:33], v[86:89], v[18:21]
	v_mfma_f32_16x16x32_bf16 v[18:21], v[26:29], v[90:93], 0
	v_mfma_f32_16x16x32_bf16 v[110:113], v[30:33], v[94:97], v[18:21]
	v_mfma_f32_16x16x32_bf16 v[18:21], v[34:37], v[82:85], 0
	v_mfma_f32_16x16x32_bf16 v[114:117], v[38:41], v[86:89], v[18:21]
	v_mfma_f32_16x16x32_bf16 v[18:21], v[34:37], v[90:93], 0
	v_mfma_f32_16x16x32_bf16 v[32:35], v[38:41], v[94:97], v[18:21]
	v_mfma_f32_16x16x32_bf16 v[18:21], v[42:45], v[82:85], 0
	v_mfma_f32_16x16x32_bf16 v[36:39], v[46:49], v[86:89], v[18:21]
	v_mfma_f32_16x16x32_bf16 v[18:21], v[42:45], v[90:93], 0
	v_mfma_f32_16x16x32_bf16 v[98:101], v[22:25], v[86:89], v[98:101]
	v_mfma_f32_16x16x32_bf16 v[118:121], v[46:49], v[94:97], v[18:21]
	s_setprio 1
	s_mov_b32 m0, s64
	s_barrier
	s_nop 2
	ds_read_b128 v[18:21], v134 offset:16384
	ds_read_b128 v[22:25], v134 offset:17408
	ds_read_b128 v[26:29], v135 offset:16384
	ds_read_b128 v[40:43], v135 offset:17408
	ds_read_b128 v[44:47], v136 offset:16384
	ds_read_b128 v[122:125], v136 offset:17408
	ds_read_b128 v[142:145], v137 offset:16384
	ds_read_b128 v[146:149], v137 offset:17408
	buffer_load_dwordx4 v138, s[56:59], s0 offen lds
	s_mov_b32 m0, s67
	s_nop 0
	buffer_load_dwordx4 v138, s[56:59], s16 offen lds
	s_barrier
	s_waitcnt lgkmcnt(0)
	s_setprio 0
	s_waitcnt lgkmcnt(7)
	v_mfma_f32_16x16x32_bf16 v[150:153], v[18:21], v[2:5], 0
	s_waitcnt lgkmcnt(5)
	v_mfma_f32_16x16x32_bf16 v[158:161], v[26:29], v[2:5], 0
	s_waitcnt lgkmcnt(3)
	v_mfma_f32_16x16x32_bf16 v[166:169], v[44:47], v[2:5], 0
	s_waitcnt lgkmcnt(1)
	v_mfma_f32_16x16x32_bf16 v[0:3], v[142:145], v[2:5], 0
	v_mfma_f32_16x16x32_bf16 v[154:157], v[18:21], v[10:13], 0
	v_mfma_f32_16x16x32_bf16 v[162:165], v[26:29], v[10:13], 0
	v_mfma_f32_16x16x32_bf16 v[170:173], v[44:47], v[10:13], 0
	s_waitcnt lgkmcnt(0)
	v_mfma_f32_16x16x32_bf16 v[174:177], v[146:149], v[6:9], v[0:3]
	v_mfma_f32_16x16x32_bf16 v[0:3], v[142:145], v[10:13], 0
	v_mfma_f32_16x16x32_bf16 v[150:153], v[22:25], v[6:9], v[150:153]
	v_mfma_f32_16x16x32_bf16 v[154:157], v[22:25], v[14:17], v[154:157]
	v_mfma_f32_16x16x32_bf16 v[158:161], v[40:43], v[6:9], v[158:161]
	v_mfma_f32_16x16x32_bf16 v[162:165], v[40:43], v[14:17], v[162:165]
	v_mfma_f32_16x16x32_bf16 v[166:169], v[122:125], v[6:9], v[166:169]
	v_mfma_f32_16x16x32_bf16 v[170:173], v[122:125], v[14:17], v[170:173]
	v_mfma_f32_16x16x32_bf16 v[178:181], v[146:149], v[14:17], v[0:3]
	s_setprio 1
	s_barrier
	s_mov_b32 m0, s78
	s_nop 0
	buffer_load_dwordx4 v138, s[4:7], s17 offen lds
	s_mov_b32 m0, s79
	s_nop 0
	buffer_load_dwordx4 v138, s[4:7], s18 offen lds
	s_waitcnt vmcnt(6)
	s_barrier
	s_setprio 0
	v_mfma_f32_16x16x32_bf16 v[0:3], v[18:21], v[82:85], 0
	v_mfma_f32_16x16x32_bf16 v[182:185], v[22:25], v[86:89], v[0:3]
	v_mfma_f32_16x16x32_bf16 v[0:3], v[18:21], v[90:93], 0
	v_mfma_f32_16x16x32_bf16 v[186:189], v[22:25], v[94:97], v[0:3]
	v_mfma_f32_16x16x32_bf16 v[0:3], v[26:29], v[82:85], 0
	v_mfma_f32_16x16x32_bf16 v[190:193], v[40:43], v[86:89], v[0:3]
	v_mfma_f32_16x16x32_bf16 v[0:3], v[26:29], v[90:93], 0
	v_mfma_f32_16x16x32_bf16 v[194:197], v[40:43], v[94:97], v[0:3]
	v_mfma_f32_16x16x32_bf16 v[0:3], v[44:47], v[82:85], 0
	v_mfma_f32_16x16x32_bf16 v[198:201], v[122:125], v[86:89], v[0:3]
	v_mfma_f32_16x16x32_bf16 v[0:3], v[44:47], v[90:93], 0
	v_mfma_f32_16x16x32_bf16 v[202:205], v[122:125], v[94:97], v[0:3]
	v_mfma_f32_16x16x32_bf16 v[0:3], v[142:145], v[82:85], 0
	v_mfma_f32_16x16x32_bf16 v[206:209], v[146:149], v[86:89], v[0:3]
	v_mfma_f32_16x16x32_bf16 v[0:3], v[142:145], v[90:93], 0
	v_mfma_f32_16x16x32_bf16 v[144:147], v[146:149], v[94:97], v[0:3]
	s_setprio 1
	s_nop 5
	v_add_u32_e32 v0, s97, v127
	v_add_u32_e32 v141, v0, v126
	s_barrier
	ds_read_b128 v[122:125], v141
	ds_read_b128 v[210:213], v141 offset:1024
	ds_read_b128 v[214:217], v141 offset:2048
	ds_read_b128 v[218:221], v141 offset:3072
	s_mov_b32 m0, s80
	ds_read_b128 v[40:43], v134 offset:32768
	ds_read_b128 v[44:47], v134 offset:33792
	ds_read_b128 v[82:85], v135 offset:32768
	ds_read_b128 v[86:89], v135 offset:33792
	ds_read_b128 v[90:93], v136 offset:32768
	ds_read_b128 v[94:97], v136 offset:33792
	ds_read_b128 v[222:225], v137 offset:32768
	ds_read_b128 v[226:229], v137 offset:33792
	buffer_load_dwordx4 v138, s[56:59], s17 offen lds
	s_mov_b32 m0, s81
	s_nop 0
	buffer_load_dwordx4 v138, s[56:59], s18 offen lds
	s_waitcnt lgkmcnt(8)
	s_barrier
	s_waitcnt lgkmcnt(0)
	s_setprio 0
	s_waitcnt lgkmcnt(7)
	v_mfma_f32_16x16x32_bf16 v[0:3], v[40:43], v[122:125], v[50:53]
	s_waitcnt lgkmcnt(6)
	v_mfma_f32_16x16x32_bf16 v[28:31], v[44:47], v[210:213], v[0:3]
	v_mfma_f32_16x16x32_bf16 v[0:3], v[40:43], v[214:217], v[54:57]
	v_mfma_f32_16x16x32_bf16 v[24:27], v[44:47], v[218:221], v[0:3]
	s_waitcnt lgkmcnt(5)
	v_mfma_f32_16x16x32_bf16 v[0:3], v[82:85], v[122:125], v[58:61]
	s_waitcnt lgkmcnt(4)
	v_mfma_f32_16x16x32_bf16 v[20:23], v[86:89], v[210:213], v[0:3]
	v_mfma_f32_16x16x32_bf16 v[0:3], v[82:85], v[214:217], v[62:65]
	v_mfma_f32_16x16x32_bf16 v[16:19], v[86:89], v[218:221], v[0:3]
	s_waitcnt lgkmcnt(3)
	v_mfma_f32_16x16x32_bf16 v[0:3], v[90:93], v[122:125], v[66:69]
	s_waitcnt lgkmcnt(2)
	v_mfma_f32_16x16x32_bf16 v[12:15], v[94:97], v[210:213], v[0:3]
	v_mfma_f32_16x16x32_bf16 v[0:3], v[90:93], v[214:217], v[70:73]
	v_mfma_f32_16x16x32_bf16 v[8:11], v[94:97], v[218:221], v[0:3]
	s_waitcnt lgkmcnt(1)
	v_mfma_f32_16x16x32_bf16 v[0:3], v[222:225], v[122:125], v[74:77]
	s_waitcnt lgkmcnt(0)
	v_mfma_f32_16x16x32_bf16 v[4:7], v[226:229], v[210:213], v[0:3]
	v_mfma_f32_16x16x32_bf16 v[0:3], v[222:225], v[214:217], v[78:81]
	v_mfma_f32_16x16x32_bf16 v[0:3], v[226:229], v[218:221], v[0:3]
	s_setprio 1
	s_barrier
	v_add_u32_e32 v48, s68, v127
	v_add_u32_e32 v142, v48, v126
	s_mov_b32 m0, s2
	ds_read_b128 v[230:233], v142
	ds_read_b128 v[234:237], v142 offset:1024
	ds_read_b128 v[238:241], v142 offset:2048
	ds_read_b128 v[242:245], v142 offset:3072
	buffer_load_dwordx4 v138, s[4:7], s19 offen lds
	s_mov_b32 m0, s3
	s_nop 0
	buffer_load_dwordx4 v138, s[4:7], s20 offen lds
	s_barrier
	s_waitcnt lgkmcnt(0)
	s_setprio 0
	s_waitcnt lgkmcnt(3)
	v_mfma_f32_16x16x32_bf16 v[48:51], v[40:43], v[230:233], v[98:101]
	s_waitcnt lgkmcnt(1)
	v_mfma_f32_16x16x32_bf16 v[40:43], v[40:43], v[238:241], v[102:105]
	s_waitcnt lgkmcnt(0)
	v_mfma_f32_16x16x32_bf16 v[56:59], v[44:47], v[242:245], v[40:43]
	v_mfma_f32_16x16x32_bf16 v[40:43], v[82:85], v[230:233], v[106:109]
	v_mfma_f32_16x16x32_bf16 v[52:55], v[86:89], v[234:237], v[40:43]
	v_mfma_f32_16x16x32_bf16 v[40:43], v[82:85], v[238:241], v[110:113]
	v_mfma_f32_16x16x32_bf16 v[60:63], v[44:47], v[234:237], v[48:51]
	v_mfma_f32_16x16x32_bf16 v[48:51], v[86:89], v[242:245], v[40:43]
	v_mfma_f32_16x16x32_bf16 v[40:43], v[90:93], v[230:233], v[114:117]
	v_mfma_f32_16x16x32_bf16 v[32:35], v[90:93], v[238:241], v[32:35]
	v_mfma_f32_16x16x32_bf16 v[44:47], v[94:97], v[234:237], v[40:43]
	v_mfma_f32_16x16x32_bf16 v[40:43], v[94:97], v[242:245], v[32:35]
	v_mfma_f32_16x16x32_bf16 v[32:35], v[222:225], v[230:233], v[36:39]
	v_mfma_f32_16x16x32_bf16 v[36:39], v[226:229], v[234:237], v[32:35]
	v_mfma_f32_16x16x32_bf16 v[32:35], v[222:225], v[238:241], v[118:121]
	v_mfma_f32_16x16x32_bf16 v[32:35], v[226:229], v[242:245], v[32:35]
	s_setprio 1
	s_mov_b32 m0, s82
	s_barrier
	ds_read_b128 v[96:99], v134 offset:49152
	ds_read_b128 v[100:103], v134 offset:50176
	ds_read_b128 v[104:107], v135 offset:49152
	ds_read_b128 v[108:111], v135 offset:50176
	ds_read_b128 v[222:225], v136 offset:49152
	ds_read_b128 v[226:229], v136 offset:50176
	ds_read_b128 v[246:249], v137 offset:49152
	ds_read_b128 v[250:253], v137 offset:50176
	buffer_load_dwordx4 v138, s[56:59], s19 offen lds
	s_mov_b32 m0, s83
	s_nop 0
	buffer_load_dwordx4 v138, s[56:59], s20 offen lds
	s_barrier
	s_waitcnt lgkmcnt(0)
	s_setprio 0
	s_waitcnt lgkmcnt(7)
	v_mfma_f32_16x16x32_bf16 v[64:67], v[96:99], v[122:125], v[150:153]
	s_waitcnt lgkmcnt(6)
	v_mfma_f32_16x16x32_bf16 v[92:95], v[100:103], v[210:213], v[64:67]
	v_mfma_f32_16x16x32_bf16 v[64:67], v[96:99], v[214:217], v[154:157]
	v_mfma_f32_16x16x32_bf16 v[88:91], v[100:103], v[218:221], v[64:67]
	s_waitcnt lgkmcnt(5)
	v_mfma_f32_16x16x32_bf16 v[64:67], v[104:107], v[122:125], v[158:161]
	s_waitcnt lgkmcnt(4)
	v_mfma_f32_16x16x32_bf16 v[84:87], v[108:111], v[210:213], v[64:67]
	v_mfma_f32_16x16x32_bf16 v[64:67], v[104:107], v[214:217], v[162:165]
	v_mfma_f32_16x16x32_bf16 v[80:83], v[108:111], v[218:221], v[64:67]
	s_waitcnt lgkmcnt(3)
	v_mfma_f32_16x16x32_bf16 v[64:67], v[222:225], v[122:125], v[166:169]
	s_waitcnt lgkmcnt(2)
	v_mfma_f32_16x16x32_bf16 v[76:79], v[226:229], v[210:213], v[64:67]
	v_mfma_f32_16x16x32_bf16 v[64:67], v[222:225], v[214:217], v[170:173]
	v_mfma_f32_16x16x32_bf16 v[72:75], v[226:229], v[218:221], v[64:67]
	s_waitcnt lgkmcnt(1)
	v_mfma_f32_16x16x32_bf16 v[64:67], v[246:249], v[122:125], v[174:177]
	s_waitcnt lgkmcnt(0)
	v_mfma_f32_16x16x32_bf16 v[68:71], v[250:253], v[210:213], v[64:67]
	v_mfma_f32_16x16x32_bf16 v[64:67], v[246:249], v[214:217], v[178:181]
	v_mfma_f32_16x16x32_bf16 v[64:67], v[250:253], v[218:221], v[64:67]
	s_setprio 1
	s_barrier
	s_mov_b32 m0, s84
	s_mov_b32 s88, 0x40180
	buffer_load_dwordx4 v138, s[4:7], s88 offen lds
	s_mov_b32 m0, s85
	s_mov_b32 s88, 0x60180
	buffer_load_dwordx4 v138, s[4:7], s88 offen lds
	s_waitcnt vmcnt(6)
	s_barrier
	s_setprio 0
	v_mfma_f32_16x16x32_bf16 v[112:115], v[96:99], v[230:233], v[182:185]
	v_mfma_f32_16x16x32_bf16 v[96:99], v[96:99], v[238:241], v[186:189]
	v_mfma_f32_16x16x32_bf16 v[120:123], v[100:103], v[242:245], v[96:99]
	v_mfma_f32_16x16x32_bf16 v[96:99], v[104:107], v[230:233], v[190:193]
	v_mfma_f32_16x16x32_bf16 v[116:119], v[108:111], v[234:237], v[96:99]
	v_mfma_f32_16x16x32_bf16 v[96:99], v[104:107], v[238:241], v[194:197]
	v_mfma_f32_16x16x32_bf16 v[124:127], v[100:103], v[234:237], v[112:115]
	v_mfma_f32_16x16x32_bf16 v[112:115], v[108:111], v[242:245], v[96:99]
	v_mfma_f32_16x16x32_bf16 v[96:99], v[222:225], v[230:233], v[198:201]
	v_mfma_f32_16x16x32_bf16 v[108:111], v[226:229], v[234:237], v[96:99]
	v_mfma_f32_16x16x32_bf16 v[96:99], v[222:225], v[238:241], v[202:205]
	v_mfma_f32_16x16x32_bf16 v[104:107], v[226:229], v[242:245], v[96:99]
	v_mfma_f32_16x16x32_bf16 v[96:99], v[246:249], v[230:233], v[206:209]
	v_mfma_f32_16x16x32_bf16 v[100:103], v[250:253], v[234:237], v[96:99]
	v_mfma_f32_16x16x32_bf16 v[96:99], v[246:249], v[238:241], v[144:147]
	v_mfma_f32_16x16x32_bf16 v[96:99], v[250:253], v[242:245], v[96:99]
	s_setprio 1
	s_mov_b32 s88, 0
	s_mov_b32 s89, 0x60280
	s_barrier
.LBB0_446:
	ds_read_b128 v[144:147], v139
	ds_read_b128 v[148:151], v139 offset:1024
	ds_read_b128 v[152:155], v139 offset:2048
	ds_read_b128 v[156:159], v139 offset:3072
	s_mov_b32 m0, s87
	s_add_i32 s90, s89, 0xfffdff00
	ds_read_b128 v[160:163], v134
	ds_read_b128 v[164:167], v134 offset:1024
	ds_read_b128 v[168:171], v135
	ds_read_b128 v[172:175], v135 offset:1024
	ds_read_b128 v[176:179], v136
	ds_read_b128 v[180:183], v136 offset:1024
	ds_read_b128 v[184:187], v137
	ds_read_b128 v[188:191], v137 offset:1024
	buffer_load_dwordx4 v138, s[56:59], s90 offen lds
	s_add_i32 s90, s89, 0xffffff00
	s_mov_b32 m0, s86
	s_nop 0
	buffer_load_dwordx4 v138, s[56:59], s90 offen lds
	s_waitcnt lgkmcnt(8)
	s_barrier
	s_waitcnt lgkmcnt(0)
	s_setprio 0
	s_waitcnt lgkmcnt(7)
	v_mfma_f32_16x16x32_bf16 v[28:31], v[160:163], v[144:147], v[28:31]
	v_mfma_f32_16x16x32_bf16 v[24:27], v[160:163], v[152:155], v[24:27]
	s_waitcnt lgkmcnt(5)
	v_mfma_f32_16x16x32_bf16 v[20:23], v[168:171], v[144:147], v[20:23]
	v_mfma_f32_16x16x32_bf16 v[16:19], v[168:171], v[152:155], v[16:19]
	s_waitcnt lgkmcnt(3)
	v_mfma_f32_16x16x32_bf16 v[12:15], v[176:179], v[144:147], v[12:15]
	v_mfma_f32_16x16x32_bf16 v[8:11], v[176:179], v[152:155], v[8:11]
	s_waitcnt lgkmcnt(1)
	v_mfma_f32_16x16x32_bf16 v[4:7], v[184:187], v[144:147], v[4:7]
	v_mfma_f32_16x16x32_bf16 v[0:3], v[184:187], v[152:155], v[0:3]
	v_mfma_f32_16x16x32_bf16 v[28:31], v[164:167], v[148:151], v[28:31]
	v_mfma_f32_16x16x32_bf16 v[24:27], v[164:167], v[156:159], v[24:27]
	v_mfma_f32_16x16x32_bf16 v[20:23], v[172:175], v[148:151], v[20:23]
	v_mfma_f32_16x16x32_bf16 v[16:19], v[172:175], v[156:159], v[16:19]
	v_mfma_f32_16x16x32_bf16 v[12:15], v[180:183], v[148:151], v[12:15]
	v_mfma_f32_16x16x32_bf16 v[8:11], v[180:183], v[156:159], v[8:11]
	s_waitcnt lgkmcnt(0)
	v_mfma_f32_16x16x32_bf16 v[4:7], v[188:191], v[148:151], v[4:7]
	v_mfma_f32_16x16x32_bf16 v[0:3], v[188:191], v[156:159], v[0:3]
	s_setprio 1
	s_barrier
	s_mov_b32 m0, s65
	s_add_i32 s90, s89, 0xfff9ff80
	ds_read_b128 v[192:195], v140
	ds_read_b128 v[196:199], v140 offset:1024
	ds_read_b128 v[200:203], v140 offset:2048
	ds_read_b128 v[204:207], v140 offset:3072
	buffer_load_dwordx4 v138, s[4:7], s90 offen lds
	s_add_i32 s91, s89, 0xfffbff80
	s_mov_b32 m0, s66
	s_nop 0
	buffer_load_dwordx4 v138, s[4:7], s91 offen lds
	s_barrier
	s_waitcnt lgkmcnt(0)
	s_setprio 0
	s_waitcnt lgkmcnt(3)
	v_mfma_f32_16x16x32_bf16 v[60:63], v[160:163], v[192:195], v[60:63]
	s_waitcnt lgkmcnt(1)
	v_mfma_f32_16x16x32_bf16 v[56:59], v[160:163], v[200:203], v[56:59]
	v_mfma_f32_16x16x32_bf16 v[52:55], v[168:171], v[192:195], v[52:55]
	v_mfma_f32_16x16x32_bf16 v[48:51], v[168:171], v[200:203], v[48:51]
	v_mfma_f32_16x16x32_bf16 v[44:47], v[176:179], v[192:195], v[44:47]
	v_mfma_f32_16x16x32_bf16 v[40:43], v[176:179], v[200:203], v[40:43]
	v_mfma_f32_16x16x32_bf16 v[36:39], v[184:187], v[192:195], v[36:39]
	v_mfma_f32_16x16x32_bf16 v[32:35], v[184:187], v[200:203], v[32:35]
	v_mfma_f32_16x16x32_bf16 v[60:63], v[164:167], v[196:199], v[60:63]
	s_waitcnt lgkmcnt(0)
	v_mfma_f32_16x16x32_bf16 v[56:59], v[164:167], v[204:207], v[56:59]
	v_mfma_f32_16x16x32_bf16 v[52:55], v[172:175], v[196:199], v[52:55]
	v_mfma_f32_16x16x32_bf16 v[48:51], v[172:175], v[204:207], v[48:51]
	v_mfma_f32_16x16x32_bf16 v[44:47], v[180:183], v[196:199], v[44:47]
	v_mfma_f32_16x16x32_bf16 v[40:43], v[180:183], v[204:207], v[40:43]
	v_mfma_f32_16x16x32_bf16 v[36:39], v[188:191], v[196:199], v[36:39]
	v_mfma_f32_16x16x32_bf16 v[32:35], v[188:191], v[204:207], v[32:35]
	s_setprio 1
	s_mov_b32 m0, s64
	s_barrier
	ds_read_b128 v[160:163], v134 offset:16384
	ds_read_b128 v[164:167], v134 offset:17408
	ds_read_b128 v[168:171], v135 offset:16384
	ds_read_b128 v[172:175], v135 offset:17408
	ds_read_b128 v[176:179], v136 offset:16384
	ds_read_b128 v[180:183], v136 offset:17408
	ds_read_b128 v[184:187], v137 offset:16384
	ds_read_b128 v[188:191], v137 offset:17408
	buffer_load_dwordx4 v138, s[56:59], s90 offen lds
	s_mov_b32 m0, s67
	s_nop 0
	buffer_load_dwordx4 v138, s[56:59], s91 offen lds
	s_barrier
	s_waitcnt lgkmcnt(0)
	s_setprio 0
	s_waitcnt lgkmcnt(7)
	v_mfma_f32_16x16x32_bf16 v[92:95], v[160:163], v[144:147], v[92:95]
	v_mfma_f32_16x16x32_bf16 v[88:91], v[160:163], v[152:155], v[88:91]
	s_waitcnt lgkmcnt(5)
	v_mfma_f32_16x16x32_bf16 v[84:87], v[168:171], v[144:147], v[84:87]
	v_mfma_f32_16x16x32_bf16 v[80:83], v[168:171], v[152:155], v[80:83]
	s_waitcnt lgkmcnt(3)
	v_mfma_f32_16x16x32_bf16 v[76:79], v[176:179], v[144:147], v[76:79]
	v_mfma_f32_16x16x32_bf16 v[72:75], v[176:179], v[152:155], v[72:75]
	s_waitcnt lgkmcnt(1)
	v_mfma_f32_16x16x32_bf16 v[68:71], v[184:187], v[144:147], v[68:71]
	v_mfma_f32_16x16x32_bf16 v[64:67], v[184:187], v[152:155], v[64:67]
	v_mfma_f32_16x16x32_bf16 v[92:95], v[164:167], v[148:151], v[92:95]
	v_mfma_f32_16x16x32_bf16 v[88:91], v[164:167], v[156:159], v[88:91]
	v_mfma_f32_16x16x32_bf16 v[84:87], v[172:175], v[148:151], v[84:87]
	v_mfma_f32_16x16x32_bf16 v[80:83], v[172:175], v[156:159], v[80:83]
	v_mfma_f32_16x16x32_bf16 v[76:79], v[180:183], v[148:151], v[76:79]
	v_mfma_f32_16x16x32_bf16 v[72:75], v[180:183], v[156:159], v[72:75]
	s_waitcnt lgkmcnt(0)
	v_mfma_f32_16x16x32_bf16 v[68:71], v[188:191], v[148:151], v[68:71]
	v_mfma_f32_16x16x32_bf16 v[64:67], v[188:191], v[156:159], v[64:67]
	s_setprio 1
	s_barrier
	s_mov_b32 m0, s78
	s_add_i32 s90, s89, 0xfffdff80
	buffer_load_dwordx4 v138, s[4:7], s90 offen lds
	s_add_i32 s91, s89, 0xffffff80
	s_mov_b32 m0, s79
	s_nop 0
	buffer_load_dwordx4 v138, s[4:7], s91 offen lds
	s_waitcnt vmcnt(6)
	s_barrier
	s_setprio 0
	v_mfma_f32_16x16x32_bf16 v[124:127], v[160:163], v[192:195], v[124:127]
	v_mfma_f32_16x16x32_bf16 v[120:123], v[160:163], v[200:203], v[120:123]
	v_mfma_f32_16x16x32_bf16 v[116:119], v[168:171], v[192:195], v[116:119]
	v_mfma_f32_16x16x32_bf16 v[112:115], v[168:171], v[200:203], v[112:115]
	v_mfma_f32_16x16x32_bf16 v[108:111], v[176:179], v[192:195], v[108:111]
	v_mfma_f32_16x16x32_bf16 v[104:107], v[176:179], v[200:203], v[104:107]
	v_mfma_f32_16x16x32_bf16 v[100:103], v[184:187], v[192:195], v[100:103]
	v_mfma_f32_16x16x32_bf16 v[96:99], v[184:187], v[200:203], v[96:99]
	v_mfma_f32_16x16x32_bf16 v[124:127], v[164:167], v[196:199], v[124:127]
	v_mfma_f32_16x16x32_bf16 v[120:123], v[164:167], v[204:207], v[120:123]
	v_mfma_f32_16x16x32_bf16 v[116:119], v[172:175], v[196:199], v[116:119]
	v_mfma_f32_16x16x32_bf16 v[112:115], v[172:175], v[204:207], v[112:115]
	v_mfma_f32_16x16x32_bf16 v[108:111], v[180:183], v[196:199], v[108:111]
	v_mfma_f32_16x16x32_bf16 v[104:107], v[180:183], v[204:207], v[104:107]
	v_mfma_f32_16x16x32_bf16 v[100:103], v[188:191], v[196:199], v[100:103]
	v_mfma_f32_16x16x32_bf16 v[96:99], v[188:191], v[204:207], v[96:99]
	s_setprio 1
	s_barrier
	ds_read_b128 v[144:147], v141
	ds_read_b128 v[148:151], v141 offset:1024
	ds_read_b128 v[152:155], v141 offset:2048
	ds_read_b128 v[156:159], v141 offset:3072
	s_mov_b32 m0, s80
	ds_read_b128 v[160:163], v134 offset:32768
	ds_read_b128 v[164:167], v134 offset:33792
	ds_read_b128 v[168:171], v135 offset:32768
	ds_read_b128 v[172:175], v135 offset:33792
	ds_read_b128 v[176:179], v136 offset:32768
	ds_read_b128 v[180:183], v136 offset:33792
	ds_read_b128 v[184:187], v137 offset:32768
	ds_read_b128 v[188:191], v137 offset:33792
	buffer_load_dwordx4 v138, s[56:59], s90 offen lds
	s_mov_b32 m0, s81
	s_nop 0
	buffer_load_dwordx4 v138, s[56:59], s91 offen lds
	s_waitcnt lgkmcnt(8)
	s_barrier
	s_waitcnt lgkmcnt(0)
	s_setprio 0
	s_waitcnt lgkmcnt(7)
	v_mfma_f32_16x16x32_bf16 v[28:31], v[160:163], v[144:147], v[28:31]
	v_mfma_f32_16x16x32_bf16 v[24:27], v[160:163], v[152:155], v[24:27]
	s_waitcnt lgkmcnt(5)
	v_mfma_f32_16x16x32_bf16 v[20:23], v[168:171], v[144:147], v[20:23]
	v_mfma_f32_16x16x32_bf16 v[16:19], v[168:171], v[152:155], v[16:19]
	s_waitcnt lgkmcnt(3)
	v_mfma_f32_16x16x32_bf16 v[12:15], v[176:179], v[144:147], v[12:15]
	v_mfma_f32_16x16x32_bf16 v[8:11], v[176:179], v[152:155], v[8:11]
	s_waitcnt lgkmcnt(1)
	v_mfma_f32_16x16x32_bf16 v[4:7], v[184:187], v[144:147], v[4:7]
	v_mfma_f32_16x16x32_bf16 v[0:3], v[184:187], v[152:155], v[0:3]
	v_mfma_f32_16x16x32_bf16 v[28:31], v[164:167], v[148:151], v[28:31]
	v_mfma_f32_16x16x32_bf16 v[24:27], v[164:167], v[156:159], v[24:27]
	v_mfma_f32_16x16x32_bf16 v[20:23], v[172:175], v[148:151], v[20:23]
	v_mfma_f32_16x16x32_bf16 v[16:19], v[172:175], v[156:159], v[16:19]
	v_mfma_f32_16x16x32_bf16 v[12:15], v[180:183], v[148:151], v[12:15]
	v_mfma_f32_16x16x32_bf16 v[8:11], v[180:183], v[156:159], v[8:11]
	s_waitcnt lgkmcnt(0)
	v_mfma_f32_16x16x32_bf16 v[4:7], v[188:191], v[148:151], v[4:7]
	v_mfma_f32_16x16x32_bf16 v[0:3], v[188:191], v[156:159], v[0:3]
	s_setprio 1
	s_barrier
	s_mov_b32 m0, s2
	s_add_i32 s90, s89, 0xfffa0000
	ds_read_b128 v[192:195], v142
	ds_read_b128 v[196:199], v142 offset:1024
	ds_read_b128 v[200:203], v142 offset:2048
	ds_read_b128 v[204:207], v142 offset:3072
	buffer_load_dwordx4 v138, s[4:7], s90 offen lds
	s_add_i32 s91, s89, 0xfffc0000
	s_mov_b32 m0, s3
	s_nop 0
	buffer_load_dwordx4 v138, s[4:7], s91 offen lds
	s_barrier
	s_waitcnt lgkmcnt(0)
	s_setprio 0
	s_waitcnt lgkmcnt(3)
	v_mfma_f32_16x16x32_bf16 v[60:63], v[160:163], v[192:195], v[60:63]
	s_waitcnt lgkmcnt(1)
	v_mfma_f32_16x16x32_bf16 v[56:59], v[160:163], v[200:203], v[56:59]
	v_mfma_f32_16x16x32_bf16 v[52:55], v[168:171], v[192:195], v[52:55]
	v_mfma_f32_16x16x32_bf16 v[48:51], v[168:171], v[200:203], v[48:51]
	v_mfma_f32_16x16x32_bf16 v[44:47], v[176:179], v[192:195], v[44:47]
	v_mfma_f32_16x16x32_bf16 v[40:43], v[176:179], v[200:203], v[40:43]
	v_mfma_f32_16x16x32_bf16 v[36:39], v[184:187], v[192:195], v[36:39]
	v_mfma_f32_16x16x32_bf16 v[32:35], v[184:187], v[200:203], v[32:35]
	v_mfma_f32_16x16x32_bf16 v[60:63], v[164:167], v[196:199], v[60:63]
	s_waitcnt lgkmcnt(0)
	v_mfma_f32_16x16x32_bf16 v[56:59], v[164:167], v[204:207], v[56:59]
	v_mfma_f32_16x16x32_bf16 v[52:55], v[172:175], v[196:199], v[52:55]
	v_mfma_f32_16x16x32_bf16 v[48:51], v[172:175], v[204:207], v[48:51]
	v_mfma_f32_16x16x32_bf16 v[44:47], v[180:183], v[196:199], v[44:47]
	v_mfma_f32_16x16x32_bf16 v[40:43], v[180:183], v[204:207], v[40:43]
	v_mfma_f32_16x16x32_bf16 v[36:39], v[188:191], v[196:199], v[36:39]
	v_mfma_f32_16x16x32_bf16 v[32:35], v[188:191], v[204:207], v[32:35]
	s_setprio 1
	s_mov_b32 m0, s82
	s_barrier
	ds_read_b128 v[160:163], v134 offset:49152
	ds_read_b128 v[164:167], v134 offset:50176
	ds_read_b128 v[168:171], v135 offset:49152
	ds_read_b128 v[172:175], v135 offset:50176
	ds_read_b128 v[176:179], v136 offset:49152
	ds_read_b128 v[180:183], v136 offset:50176
	ds_read_b128 v[184:187], v137 offset:49152
	ds_read_b128 v[188:191], v137 offset:50176
	buffer_load_dwordx4 v138, s[56:59], s90 offen lds
	s_mov_b32 m0, s83
	s_nop 0
	buffer_load_dwordx4 v138, s[56:59], s91 offen lds
	s_barrier
	s_waitcnt lgkmcnt(0)
	s_setprio 0
	s_waitcnt lgkmcnt(7)
	v_mfma_f32_16x16x32_bf16 v[92:95], v[160:163], v[144:147], v[92:95]
	v_mfma_f32_16x16x32_bf16 v[88:91], v[160:163], v[152:155], v[88:91]
	s_waitcnt lgkmcnt(5)
	v_mfma_f32_16x16x32_bf16 v[84:87], v[168:171], v[144:147], v[84:87]
	v_mfma_f32_16x16x32_bf16 v[80:83], v[168:171], v[152:155], v[80:83]
	s_waitcnt lgkmcnt(3)
	v_mfma_f32_16x16x32_bf16 v[76:79], v[176:179], v[144:147], v[76:79]
	v_mfma_f32_16x16x32_bf16 v[72:75], v[176:179], v[152:155], v[72:75]
	s_waitcnt lgkmcnt(1)
	v_mfma_f32_16x16x32_bf16 v[68:71], v[184:187], v[144:147], v[68:71]
	v_mfma_f32_16x16x32_bf16 v[64:67], v[184:187], v[152:155], v[64:67]
	v_mfma_f32_16x16x32_bf16 v[92:95], v[164:167], v[148:151], v[92:95]
	v_mfma_f32_16x16x32_bf16 v[88:91], v[164:167], v[156:159], v[88:91]
	v_mfma_f32_16x16x32_bf16 v[84:87], v[172:175], v[148:151], v[84:87]
	v_mfma_f32_16x16x32_bf16 v[80:83], v[172:175], v[156:159], v[80:83]
	v_mfma_f32_16x16x32_bf16 v[76:79], v[180:183], v[148:151], v[76:79]
	v_mfma_f32_16x16x32_bf16 v[72:75], v[180:183], v[156:159], v[72:75]
	s_waitcnt lgkmcnt(0)
	v_mfma_f32_16x16x32_bf16 v[68:71], v[188:191], v[148:151], v[68:71]
	v_mfma_f32_16x16x32_bf16 v[64:67], v[188:191], v[156:159], v[64:67]
	s_setprio 1
	s_barrier
	s_add_i32 s90, s89, 0xfffe0000
	s_mov_b32 m0, s84
	s_nop 0
	buffer_load_dwordx4 v138, s[4:7], s90 offen lds
	s_mov_b32 m0, s85
	s_nop 0
	buffer_load_dwordx4 v138, s[4:7], s89 offen lds
	s_waitcnt vmcnt(6)
	s_barrier
; #define LDA(dst, b, h)                                                                             \
;   _Pragma("unroll") for (int m = 0; m < 4; ++m) _Pragma("unroll") for (int k = 0; k < 2; ++k)      \
;       dst[m][k] = *reinterpret_cast<const bf16x8*>(SA(b, h) + lds_byte(wr * 64 + m * 16 + fr, k * 32 + fq * 8))
; #define LDB(dst, b, h)                                                                             \
;   _Pragma("unroll") for (int n = 0; n < 2; ++n) _Pragma("unroll") for (int k = 0; k < 2; ++k)      \
;       dst[n][k] = *reinterpret_cast<const bf16x8*>(SB(b, h) + lds_byte(wc * 32 + n * 16 + fr, k * 32 + fq * 8))
; #define WAIT_V(n) asm volatile("s_waitcnt vmcnt(" #n ")" ::: "memory")
; #define WAIT_L(n) asm volatile("s_waitcnt lgkmcnt(" #n ")" ::: "memory")
; #define BAR __builtin_amdgcn_s_barrier()
; template <bool PEEL = false>
; __device__ __forceinline__ void gemm_tile(f32x4 (&acc)[2][2][4][2], const u16* __restrict__ A, int lda,
;                                           const u16* __restrict__ B, int K) {
;     ...
;   {
;     LDB(B0, 0, 0); LDA(At, 0, 0); STAGE_A(SA(1, 1), 1, nt - 1);
;     BAR; WAIT_L(0); MMA(0, 0, At, B0); BAR;
;     LDB(B1, 0, 1); BAR; WAIT_L(0); MMA(0, 1, At, B1); BAR;
;     LDA(At, 0, 1); WAIT_V(4); BAR; WAIT_L(0); MMA(1, 0, At, B0); MMA(1, 1, At, B1); BAR;
	s_setprio 0
	v_mfma_f32_16x16x32_bf16 v[124:127], v[160:163], v[192:195], v[124:127]
	v_mfma_f32_16x16x32_bf16 v[120:123], v[160:163], v[200:203], v[120:123]
	v_mfma_f32_16x16x32_bf16 v[116:119], v[168:171], v[192:195], v[116:119]
	v_mfma_f32_16x16x32_bf16 v[112:115], v[168:171], v[200:203], v[112:115]
	v_mfma_f32_16x16x32_bf16 v[108:111], v[176:179], v[192:195], v[108:111]
	v_mfma_f32_16x16x32_bf16 v[104:107], v[176:179], v[200:203], v[104:107]
	v_mfma_f32_16x16x32_bf16 v[100:103], v[184:187], v[192:195], v[100:103]
	v_mfma_f32_16x16x32_bf16 v[96:99], v[184:187], v[200:203], v[96:99]
	v_mfma_f32_16x16x32_bf16 v[124:127], v[164:167], v[196:199], v[124:127]
	v_mfma_f32_16x16x32_bf16 v[120:123], v[164:167], v[204:207], v[120:123]
	v_mfma_f32_16x16x32_bf16 v[116:119], v[172:175], v[196:199], v[116:119]
	v_mfma_f32_16x16x32_bf16 v[112:115], v[172:175], v[204:207], v[112:115]
	v_mfma_f32_16x16x32_bf16 v[108:111], v[180:183], v[196:199], v[108:111]
	v_mfma_f32_16x16x32_bf16 v[104:107], v[180:183], v[204:207], v[104:107]
	v_mfma_f32_16x16x32_bf16 v[100:103], v[188:191], v[196:199], v[100:103]
	v_mfma_f32_16x16x32_bf16 v[96:99], v[188:191], v[204:207], v[96:99]
	s_setprio 1
	s_add_i32 s88, s88, 2
	s_addk_i32 s89, 0x100
	s_cmp_lt_u32 s88, 12
	s_barrier
	s_cbranch_scc1 .LBB0_446
	v_mov_b32_e32 v244, v138
	s_mov_b32 m0, s87
	s_mov_b32 s2, 0x40780
	ds_read_b128 v[144:147], v139
	ds_read_b128 v[148:151], v139 offset:1024
	ds_read_b128 v[152:155], v139 offset:2048
	ds_read_b128 v[156:159], v139 offset:3072
	ds_read_b128 v[160:163], v134
	ds_read_b128 v[164:167], v134 offset:1024
	ds_read_b128 v[168:171], v135
	ds_read_b128 v[172:175], v135 offset:1024
	ds_read_b128 v[176:179], v136
	ds_read_b128 v[180:183], v136 offset:1024
	ds_read_b128 v[184:187], v137
	ds_read_b128 v[188:191], v137 offset:1024
	buffer_load_dwordx4 v138, s[56:59], s2 offen lds
	s_mov_b32 s2, 0x60780
	s_mov_b32 m0, s86
	s_nop 0
	buffer_load_dwordx4 v138, s[56:59], s2 offen lds
	s_barrier
	s_waitcnt lgkmcnt(0)
	s_setprio 0
	s_waitcnt lgkmcnt(7)
	v_mfma_f32_16x16x32_bf16 v[28:31], v[160:163], v[144:147], v[28:31]
	v_mfma_f32_16x16x32_bf16 v[24:27], v[160:163], v[152:155], v[24:27]
	s_waitcnt lgkmcnt(5)
	v_mfma_f32_16x16x32_bf16 v[20:23], v[168:171], v[144:147], v[20:23]
	v_mfma_f32_16x16x32_bf16 v[16:19], v[168:171], v[152:155], v[16:19]
	s_waitcnt lgkmcnt(3)
	v_mfma_f32_16x16x32_bf16 v[12:15], v[176:179], v[144:147], v[12:15]
	v_mfma_f32_16x16x32_bf16 v[8:11], v[176:179], v[152:155], v[8:11]
	s_waitcnt lgkmcnt(1)
	v_mfma_f32_16x16x32_bf16 v[4:7], v[184:187], v[144:147], v[4:7]
	v_mfma_f32_16x16x32_bf16 v[0:3], v[184:187], v[152:155], v[0:3]
	v_mfma_f32_16x16x32_bf16 v[28:31], v[164:167], v[148:151], v[28:31]
	v_mfma_f32_16x16x32_bf16 v[24:27], v[164:167], v[156:159], v[24:27]
	v_mfma_f32_16x16x32_bf16 v[20:23], v[172:175], v[148:151], v[20:23]
	v_mfma_f32_16x16x32_bf16 v[16:19], v[172:175], v[156:159], v[16:19]
	v_mfma_f32_16x16x32_bf16 v[12:15], v[180:183], v[148:151], v[12:15]
	v_mfma_f32_16x16x32_bf16 v[8:11], v[180:183], v[156:159], v[8:11]
	s_waitcnt lgkmcnt(0)
	v_mfma_f32_16x16x32_bf16 v[4:7], v[188:191], v[148:151], v[4:7]
	v_mfma_f32_16x16x32_bf16 v[0:3], v[188:191], v[156:159], v[0:3]
	s_setprio 1
	s_barrier
	ds_read_b128 v[192:195], v140
	ds_read_b128 v[196:199], v140 offset:1024
	ds_read_b128 v[200:203], v140 offset:2048
	ds_read_b128 v[204:207], v140 offset:3072
	s_barrier
	s_waitcnt lgkmcnt(0)
	s_setprio 0
	s_waitcnt lgkmcnt(3)
	v_mfma_f32_16x16x32_bf16 v[60:63], v[160:163], v[192:195], v[60:63]
	s_waitcnt lgkmcnt(1)
	v_mfma_f32_16x16x32_bf16 v[56:59], v[160:163], v[200:203], v[56:59]
	v_mfma_f32_16x16x32_bf16 v[52:55], v[168:171], v[192:195], v[52:55]
	v_mfma_f32_16x16x32_bf16 v[48:51], v[168:171], v[200:203], v[48:51]
	v_mfma_f32_16x16x32_bf16 v[44:47], v[176:179], v[192:195], v[44:47]
	v_mfma_f32_16x16x32_bf16 v[40:43], v[176:179], v[200:203], v[40:43]
	v_mfma_f32_16x16x32_bf16 v[36:39], v[184:187], v[192:195], v[36:39]
	v_mfma_f32_16x16x32_bf16 v[32:35], v[184:187], v[200:203], v[32:35]
	v_mfma_f32_16x16x32_bf16 v[60:63], v[164:167], v[196:199], v[60:63]
	s_waitcnt lgkmcnt(0)
	v_mfma_f32_16x16x32_bf16 v[56:59], v[164:167], v[204:207], v[56:59]
	v_mfma_f32_16x16x32_bf16 v[52:55], v[172:175], v[196:199], v[52:55]
	v_mfma_f32_16x16x32_bf16 v[48:51], v[172:175], v[204:207], v[48:51]
	v_mfma_f32_16x16x32_bf16 v[44:47], v[180:183], v[196:199], v[44:47]
	v_mfma_f32_16x16x32_bf16 v[40:43], v[180:183], v[204:207], v[40:43]
	v_mfma_f32_16x16x32_bf16 v[36:39], v[188:191], v[196:199], v[36:39]
	v_mfma_f32_16x16x32_bf16 v[32:35], v[188:191], v[204:207], v[32:35]
	s_setprio 1
	s_barrier
	ds_read_b128 v[160:163], v134 offset:16384
	ds_read_b128 v[164:167], v134 offset:17408
	ds_read_b128 v[168:171], v135 offset:16384
	ds_read_b128 v[172:175], v135 offset:17408
	ds_read_b128 v[176:179], v136 offset:16384
	ds_read_b128 v[180:183], v136 offset:17408
	ds_read_b128 v[184:187], v137 offset:16384
	ds_read_b128 v[188:191], v137 offset:17408
	s_cmp_eq_u32 s9, 21
	s_cbranch_scc1 .Lt2_a_last
	s_add_u32 s4, s4, 0x80000
	s_addc_u32 s5, s5, 0
	s_mov_b32 m0, s65
	s_nop 0
	buffer_load_dwordx4 v244, s[4:7], 0 offen lds
	s_mov_b32 m0, s66
	s_nop 0
	buffer_load_dwordx4 v244, s[4:7], s7 offen lds
	s_mov_b32 m0, s64
	s_nop 0
	buffer_load_dwordx4 v244, s[56:59], 0 offen lds
	s_mov_b32 m0, s67
	s_nop 0
	buffer_load_dwordx4 v244, s[56:59], s7 offen lds
	s_waitcnt vmcnt(8)
	s_branch .Lt2_a_join

; #define LDA(dst, b, h)                                                                             \
;   _Pragma("unroll") for (int m = 0; m < 4; ++m) _Pragma("unroll") for (int k = 0; k < 2; ++k)      \
;       dst[m][k] = *reinterpret_cast<const bf16x8*>(SA(b, h) + lds_byte(wr * 64 + m * 16 + fr, k * 32 + fq * 8))
; #define LDB(dst, b, h)                                                                             \
;   _Pragma("unroll") for (int n = 0; n < 2; ++n) _Pragma("unroll") for (int k = 0; k < 2; ++k)      \
;       dst[n][k] = *reinterpret_cast<const bf16x8*>(SB(b, h) + lds_byte(wc * 32 + n * 16 + fr, k * 32 + fq * 8))
; #define WAIT_V(n) asm volatile("s_waitcnt vmcnt(" #n ")" ::: "memory")
; #define WAIT_L(n) asm volatile("s_waitcnt lgkmcnt(" #n ")" ::: "memory")
; #define BAR __builtin_amdgcn_s_barrier()
; template <bool PEEL = false>
; __device__ __forceinline__ void gemm_tile(f32x4 (&acc)[2][2][4][2], const u16* __restrict__ A, int lda,
;                                           const u16* __restrict__ B, int K) {
;     ...
;     LDA(At, 0, 1); WAIT_V(4); BAR; WAIT_L(0); MMA(1, 0, At, B0); MMA(1, 1, At, B1); BAR;
;   }
;   {
;     LDB(B0, 1, 0); LDA(At, 1, 0); WAIT_V(2); BAR; WAIT_L(0); MMA(0, 0, At, B0); BAR;
.Lt2_a_join:
	s_barrier
	s_waitcnt lgkmcnt(0)
	s_setprio 0
	s_waitcnt lgkmcnt(7)
	v_mfma_f32_16x16x32_bf16 v[92:95], v[160:163], v[144:147], v[92:95]
	v_mfma_f32_16x16x32_bf16 v[88:91], v[160:163], v[152:155], v[88:91]
	s_waitcnt lgkmcnt(5)
	v_mfma_f32_16x16x32_bf16 v[84:87], v[168:171], v[144:147], v[84:87]
	v_mfma_f32_16x16x32_bf16 v[80:83], v[168:171], v[152:155], v[80:83]
	s_waitcnt lgkmcnt(3)
	v_mfma_f32_16x16x32_bf16 v[76:79], v[176:179], v[144:147], v[76:79]
	v_mfma_f32_16x16x32_bf16 v[72:75], v[176:179], v[152:155], v[72:75]
	s_waitcnt lgkmcnt(1)
	v_mfma_f32_16x16x32_bf16 v[68:71], v[184:187], v[144:147], v[68:71]
	v_mfma_f32_16x16x32_bf16 v[64:67], v[184:187], v[152:155], v[64:67]
	v_mfma_f32_16x16x32_bf16 v[208:211], v[164:167], v[148:151], v[92:95]
	v_mfma_f32_16x16x32_bf16 v[212:215], v[164:167], v[156:159], v[88:91]
	v_mfma_f32_16x16x32_bf16 v[216:219], v[172:175], v[148:151], v[84:87]
	v_mfma_f32_16x16x32_bf16 v[220:223], v[172:175], v[156:159], v[80:83]
	v_mfma_f32_16x16x32_bf16 v[224:227], v[180:183], v[148:151], v[76:79]
	v_mfma_f32_16x16x32_bf16 v[228:231], v[180:183], v[156:159], v[72:75]
	s_waitcnt lgkmcnt(0)
	v_mfma_f32_16x16x32_bf16 v[144:147], v[188:191], v[148:151], v[68:71]
	v_mfma_f32_16x16x32_bf16 v[148:151], v[188:191], v[156:159], v[64:67]
	s_setprio 1
	s_setprio 0
	v_mfma_f32_16x16x32_bf16 v[64:67], v[160:163], v[192:195], v[124:127]
	v_mfma_f32_16x16x32_bf16 v[152:155], v[164:167], v[196:199], v[64:67]
	v_mfma_f32_16x16x32_bf16 v[64:67], v[160:163], v[200:203], v[120:123]
	v_mfma_f32_16x16x32_bf16 v[156:159], v[164:167], v[204:207], v[64:67]
	v_mfma_f32_16x16x32_bf16 v[64:67], v[168:171], v[192:195], v[116:119]
	v_mfma_f32_16x16x32_bf16 v[160:163], v[172:175], v[196:199], v[64:67]
	v_mfma_f32_16x16x32_bf16 v[64:67], v[168:171], v[200:203], v[112:115]
	v_mfma_f32_16x16x32_bf16 v[164:167], v[172:175], v[204:207], v[64:67]
	v_mfma_f32_16x16x32_bf16 v[64:67], v[176:179], v[192:195], v[108:111]
	v_mfma_f32_16x16x32_bf16 v[168:171], v[180:183], v[196:199], v[64:67]
	v_mfma_f32_16x16x32_bf16 v[64:67], v[176:179], v[200:203], v[104:107]
	v_mfma_f32_16x16x32_bf16 v[172:175], v[180:183], v[204:207], v[64:67]
	v_mfma_f32_16x16x32_bf16 v[64:67], v[184:187], v[192:195], v[100:103]
	v_mfma_f32_16x16x32_bf16 v[176:179], v[188:191], v[196:199], v[64:67]
	v_mfma_f32_16x16x32_bf16 v[64:67], v[184:187], v[200:203], v[96:99]
	v_mfma_f32_16x16x32_bf16 v[180:183], v[188:191], v[204:207], v[64:67]
	s_setprio 1
	s_barrier
	ds_read_b128 v[184:187], v141
	ds_read_b128 v[188:191], v141 offset:1024
	ds_read_b128 v[192:195], v141 offset:2048
	ds_read_b128 v[138:141], v141 offset:3072
	ds_read_b128 v[72:75], v134 offset:32768
	ds_read_b128 v[76:79], v134 offset:33792
	ds_read_b128 v[88:91], v135 offset:32768
	ds_read_b128 v[92:95], v135 offset:33792
	ds_read_b128 v[196:199], v136 offset:32768
	ds_read_b128 v[200:203], v136 offset:33792
	ds_read_b128 v[204:207], v137 offset:32768
	ds_read_b128 v[232:235], v137 offset:33792
	s_cmp_eq_u32 s9, 21
	s_cbranch_scc1 .Lt2_b_last
	s_mov_b32 m0, s78
	s_nop 0
	buffer_load_dwordx4 v244, s[4:7], s10 offen lds
	s_mov_b32 m0, s79
	s_nop 0
	buffer_load_dwordx4 v244, s[4:7], s11 offen lds
	s_waitcnt vmcnt(8)
	s_branch .Lt2_b_join

; #define LDA(dst, b, h)                                                                             \
;   _Pragma("unroll") for (int m = 0; m < 4; ++m) _Pragma("unroll") for (int k = 0; k < 2; ++k)      \
;       dst[m][k] = *reinterpret_cast<const bf16x8*>(SA(b, h) + lds_byte(wr * 64 + m * 16 + fr, k * 32 + fq * 8))
; #define LDB(dst, b, h)                                                                             \
;   _Pragma("unroll") for (int n = 0; n < 2; ++n) _Pragma("unroll") for (int k = 0; k < 2; ++k)      \
;       dst[n][k] = *reinterpret_cast<const bf16x8*>(SB(b, h) + lds_byte(wc * 32 + n * 16 + fr, k * 32 + fq * 8))
; #define WAIT_V(n) asm volatile("s_waitcnt vmcnt(" #n ")" ::: "memory")
; #define WAIT_L(n) asm volatile("s_waitcnt lgkmcnt(" #n ")" ::: "memory")
; #define BAR __builtin_amdgcn_s_barrier()
; template <bool PEEL = false>
; __device__ __forceinline__ void gemm_tile(f32x4 (&acc)[2][2][4][2], const u16* __restrict__ A, int lda,
;                                           const u16* __restrict__ B, int K) {
;     ...
;     LDB(B0, 1, 0); LDA(At, 1, 0); WAIT_V(2); BAR; WAIT_L(0); MMA(0, 0, At, B0); BAR;
;     LDB(B1, 1, 1); WAIT_V(0); BAR; WAIT_L(0); MMA(0, 1, At, B1); BAR;
.Lt2_b_join:
	s_barrier
	s_waitcnt lgkmcnt(0)
	s_setprio 0
	s_waitcnt lgkmcnt(7)
	v_mfma_f32_16x16x32_bf16 v[28:31], v[72:75], v[184:187], v[28:31]
	v_mfma_f32_16x16x32_bf16 v[24:27], v[72:75], v[192:195], v[24:27]
	s_waitcnt lgkmcnt(5)
	v_mfma_f32_16x16x32_bf16 v[20:23], v[88:91], v[184:187], v[20:23]
	v_mfma_f32_16x16x32_bf16 v[16:19], v[88:91], v[192:195], v[16:19]
	s_waitcnt lgkmcnt(3)
	v_mfma_f32_16x16x32_bf16 v[12:15], v[196:199], v[184:187], v[12:15]
	v_mfma_f32_16x16x32_bf16 v[8:11], v[196:199], v[192:195], v[8:11]
	s_waitcnt lgkmcnt(1)
	v_mfma_f32_16x16x32_bf16 v[4:7], v[204:207], v[184:187], v[4:7]
	v_mfma_f32_16x16x32_bf16 v[0:3], v[204:207], v[192:195], v[0:3]
	v_mfma_f32_16x16x32_bf16 v[116:119], v[76:79], v[188:191], v[28:31]
	v_mfma_f32_16x16x32_bf16 v[112:115], v[76:79], v[138:141], v[24:27]
	v_mfma_f32_16x16x32_bf16 v[100:103], v[92:95], v[188:191], v[20:23]
	v_mfma_f32_16x16x32_bf16 v[96:99], v[92:95], v[138:141], v[16:19]
	v_mfma_f32_16x16x32_bf16 v[84:87], v[200:203], v[188:191], v[12:15]
	v_mfma_f32_16x16x32_bf16 v[80:83], v[200:203], v[138:141], v[8:11]
	s_waitcnt lgkmcnt(0)
	v_mfma_f32_16x16x32_bf16 v[68:71], v[232:235], v[188:191], v[4:7]
	v_mfma_f32_16x16x32_bf16 v[64:67], v[232:235], v[138:141], v[0:3]
	s_setprio 1
	s_barrier
	ds_read_b128 v[4:7], v142
	ds_read_b128 v[12:15], v142 offset:1024
	ds_read_b128 v[236:239], v142 offset:2048
	ds_read_b128 v[240:243], v142 offset:3072
	s_cmp_eq_u32 s9, 21
	s_cbranch_scc1 .Lt2_c_last
	s_mov_b32 m0, s80
	s_nop 0
	buffer_load_dwordx4 v244, s[56:59], s10 offen lds
	s_mov_b32 m0, s81
	s_nop 0
	buffer_load_dwordx4 v244, s[56:59], s11 offen lds
	s_waitcnt vmcnt(8)
	s_branch .Lt2_c_join

; #define LDA(dst, b, h)                                                                             \
;   _Pragma("unroll") for (int m = 0; m < 4; ++m) _Pragma("unroll") for (int k = 0; k < 2; ++k)      \
;       dst[m][k] = *reinterpret_cast<const bf16x8*>(SA(b, h) + lds_byte(wr * 64 + m * 16 + fr, k * 32 + fq * 8))
; #define LDB(dst, b, h)                                                                             \
;   _Pragma("unroll") for (int n = 0; n < 2; ++n) _Pragma("unroll") for (int k = 0; k < 2; ++k)      \
;       dst[n][k] = *reinterpret_cast<const bf16x8*>(SB(b, h) + lds_byte(wc * 32 + n * 16 + fr, k * 32 + fq * 8))
; #define WAIT_V(n) asm volatile("s_waitcnt vmcnt(" #n ")" ::: "memory")
; #define WAIT_L(n) asm volatile("s_waitcnt lgkmcnt(" #n ")" ::: "memory")
; #define BAR __builtin_amdgcn_s_barrier()
; template <bool PEEL = false>
; __device__ __forceinline__ void gemm_tile(f32x4 (&acc)[2][2][4][2], const u16* __restrict__ A, int lda,
;                                           const u16* __restrict__ B, int K) {
;     ...
;     LDB(B1, 1, 1); WAIT_V(0); BAR; WAIT_L(0); MMA(0, 1, At, B1); BAR;
;     LDA(At, 1, 1); BAR; WAIT_L(0); MMA(1, 0, At, B0); MMA(1, 1, At, B1); BAR;
;   }
;   if (wr == 0) BAR;
.Lt2_c_join:
	s_barrier
	s_waitcnt lgkmcnt(0)
	s_setprio 0
	s_waitcnt lgkmcnt(3)
	v_mfma_f32_16x16x32_bf16 v[0:3], v[72:75], v[4:7], v[60:63]
	s_waitcnt lgkmcnt(2)
	v_mfma_f32_16x16x32_bf16 v[124:127], v[76:79], v[12:15], v[0:3]
	s_waitcnt lgkmcnt(1)
	v_mfma_f32_16x16x32_bf16 v[0:3], v[72:75], v[236:239], v[56:59]
	s_waitcnt lgkmcnt(0)
	v_mfma_f32_16x16x32_bf16 v[120:123], v[76:79], v[240:243], v[0:3]
	v_mfma_f32_16x16x32_bf16 v[0:3], v[88:91], v[4:7], v[52:55]
	v_mfma_f32_16x16x32_bf16 v[108:111], v[92:95], v[12:15], v[0:3]
	v_mfma_f32_16x16x32_bf16 v[0:3], v[88:91], v[236:239], v[48:51]
	v_mfma_f32_16x16x32_bf16 v[104:107], v[92:95], v[240:243], v[0:3]
	v_mfma_f32_16x16x32_bf16 v[0:3], v[196:199], v[4:7], v[44:47]
	v_mfma_f32_16x16x32_bf16 v[92:95], v[200:203], v[12:15], v[0:3]
	v_mfma_f32_16x16x32_bf16 v[0:3], v[196:199], v[236:239], v[40:43]
	v_mfma_f32_16x16x32_bf16 v[88:91], v[200:203], v[240:243], v[0:3]
	v_mfma_f32_16x16x32_bf16 v[0:3], v[204:207], v[4:7], v[36:39]
	v_mfma_f32_16x16x32_bf16 v[76:79], v[232:235], v[12:15], v[0:3]
	v_mfma_f32_16x16x32_bf16 v[0:3], v[204:207], v[236:239], v[32:35]
	v_mfma_f32_16x16x32_bf16 v[72:75], v[232:235], v[240:243], v[0:3]
	s_setprio 1
	s_barrier
	ds_read_b128 v[24:27], v134 offset:49152
	ds_read_b128 v[28:31], v134 offset:50176
	ds_read_b128 v[36:39], v135 offset:49152
	ds_read_b128 v[196:199], v135 offset:50176
	ds_read_b128 v[200:203], v136 offset:49152
	ds_read_b128 v[204:207], v136 offset:50176
	ds_read_b128 v[232:235], v137 offset:49152
	ds_read_b128 v[134:137], v137 offset:50176
	s_cmp_eq_u32 s9, 21
	s_cbranch_scc1 .Lt2_d_skip
	s_add_i32 m0, s64, 0x18000
	s_nop 0
	buffer_load_dwordx4 v244, s[4:7], s12 offen lds
	s_add_i32 m0, s64, 0x1a000
	s_nop 0
	buffer_load_dwordx4 v244, s[4:7], s13 offen lds
	s_mov_b32 m0, s82
	s_nop 0
	buffer_load_dwordx4 v244, s[56:59], s12 offen lds
	s_mov_b32 m0, s83
	s_nop 0
	buffer_load_dwordx4 v244, s[56:59], s13 offen lds
.Lt2_d_skip:
	s_barrier
	s_waitcnt lgkmcnt(0)
	s_setprio 0
	s_waitcnt lgkmcnt(7)
	v_mfma_f32_16x16x32_bf16 v[0:3], v[24:27], v[184:187], v[208:211]
	s_waitcnt lgkmcnt(6)
	v_mfma_f32_16x16x32_bf16 v[52:55], v[28:31], v[188:191], v[0:3]
	v_mfma_f32_16x16x32_bf16 v[0:3], v[24:27], v[192:195], v[212:215]
	v_mfma_f32_16x16x32_bf16 v[48:51], v[28:31], v[138:141], v[0:3]
	s_waitcnt lgkmcnt(5)
	v_mfma_f32_16x16x32_bf16 v[0:3], v[36:39], v[184:187], v[216:219]
	s_waitcnt lgkmcnt(4)
	v_mfma_f32_16x16x32_bf16 v[40:43], v[196:199], v[188:191], v[0:3]
	v_mfma_f32_16x16x32_bf16 v[0:3], v[36:39], v[192:195], v[220:223]
	v_mfma_f32_16x16x32_bf16 v[32:35], v[196:199], v[138:141], v[0:3]
	s_waitcnt lgkmcnt(3)
	v_mfma_f32_16x16x32_bf16 v[0:3], v[200:203], v[184:187], v[224:227]
	s_waitcnt lgkmcnt(2)
	v_mfma_f32_16x16x32_bf16 v[20:23], v[204:207], v[188:191], v[0:3]
	v_mfma_f32_16x16x32_bf16 v[0:3], v[200:203], v[192:195], v[228:231]
	v_mfma_f32_16x16x32_bf16 v[16:19], v[204:207], v[138:141], v[0:3]
	s_waitcnt lgkmcnt(1)
	v_mfma_f32_16x16x32_bf16 v[0:3], v[232:235], v[184:187], v[144:147]
	s_waitcnt lgkmcnt(0)
	v_mfma_f32_16x16x32_bf16 v[8:11], v[134:137], v[188:191], v[0:3]
	v_mfma_f32_16x16x32_bf16 v[0:3], v[232:235], v[192:195], v[148:151]
	v_mfma_f32_16x16x32_bf16 v[0:3], v[134:137], v[138:141], v[0:3]
	s_setprio 1
	s_setprio 0
	v_mfma_f32_16x16x32_bf16 v[44:47], v[24:27], v[4:7], v[152:155]
	v_mfma_f32_16x16x32_bf16 v[24:27], v[24:27], v[236:239], v[156:159]
	v_mfma_f32_16x16x32_bf16 v[56:59], v[28:31], v[240:243], v[24:27]
	v_mfma_f32_16x16x32_bf16 v[24:27], v[36:39], v[4:7], v[160:163]
	v_mfma_f32_16x16x32_bf16 v[60:63], v[28:31], v[12:15], v[44:47]
	v_mfma_f32_16x16x32_bf16 v[44:47], v[196:199], v[12:15], v[24:27]
	v_mfma_f32_16x16x32_bf16 v[24:27], v[36:39], v[236:239], v[164:167]
	v_mfma_f32_16x16x32_bf16 v[36:39], v[196:199], v[240:243], v[24:27]
	v_mfma_f32_16x16x32_bf16 v[24:27], v[200:203], v[4:7], v[168:171]
	v_mfma_f32_16x16x32_bf16 v[4:7], v[232:235], v[4:7], v[176:179]
	v_mfma_f32_16x16x32_bf16 v[28:31], v[204:207], v[12:15], v[24:27]
	v_mfma_f32_16x16x32_bf16 v[24:27], v[200:203], v[236:239], v[172:175]
	v_mfma_f32_16x16x32_bf16 v[12:15], v[134:137], v[12:15], v[4:7]
	v_mfma_f32_16x16x32_bf16 v[4:7], v[232:235], v[236:239], v[180:183]
	v_mfma_f32_16x16x32_bf16 v[24:27], v[204:207], v[240:243], v[24:27]
	v_mfma_f32_16x16x32_bf16 v[4:7], v[134:137], v[240:243], v[4:7]
	s_setprio 1
	v_cmp_gt_u32_e32 vcc, s0, v133
	s_barrier
	s_and_saveexec_b64 s[2:3], vcc
	s_cbranch_execz .LBB0_442
	s_barrier
	s_branch .LBB0_442

.LBB0_460:
	ds_read_b128 v[140:143], v139
	ds_read_b128 v[144:147], v139 offset:1024
	ds_read_b128 v[148:151], v139 offset:2048
	ds_read_b128 v[152:155], v139 offset:3072
	s_mov_b32 m0, s62
	s_add_i32 s67, s66, 0xfffa7f00
	ds_read_b128 v[156:159], v134
	ds_read_b128 v[160:163], v134 offset:1024
	ds_read_b128 v[164:167], v133
	ds_read_b128 v[178:181], v133 offset:1024
	ds_read_b128 v[182:185], v132
	ds_read_b128 v[186:189], v132 offset:1024
	ds_read_b128 v[190:193], v131
	ds_read_b128 v[194:197], v131 offset:1024
	buffer_load_dwordx4 v136, s[4:7], s67 offen lds
	s_add_i32 s67, s66, 0xffffff00
	s_mov_b32 m0, s60
	s_nop 0
	buffer_load_dwordx4 v136, s[4:7], s67 offen lds
	s_waitcnt lgkmcnt(8)
	s_barrier
	s_waitcnt lgkmcnt(0)
	s_setprio 0
	s_waitcnt lgkmcnt(7)
	v_mfma_f32_16x16x32_bf16 v[124:127], v[156:159], v[140:143], v[124:127]
	v_mfma_f32_16x16x32_bf16 v[120:123], v[156:159], v[148:151], v[120:123]
	s_waitcnt lgkmcnt(5)
	v_mfma_f32_16x16x32_bf16 v[116:119], v[164:167], v[140:143], v[116:119]
	v_mfma_f32_16x16x32_bf16 v[112:115], v[164:167], v[148:151], v[112:115]
	s_waitcnt lgkmcnt(3)
	v_mfma_f32_16x16x32_bf16 v[108:111], v[182:185], v[140:143], v[108:111]
	v_mfma_f32_16x16x32_bf16 v[104:107], v[182:185], v[148:151], v[104:107]
	s_waitcnt lgkmcnt(1)
	v_mfma_f32_16x16x32_bf16 v[100:103], v[190:193], v[140:143], v[100:103]
	v_mfma_f32_16x16x32_bf16 v[96:99], v[190:193], v[148:151], v[96:99]
	v_mfma_f32_16x16x32_bf16 v[124:127], v[160:163], v[144:147], v[124:127]
	v_mfma_f32_16x16x32_bf16 v[120:123], v[160:163], v[152:155], v[120:123]
	v_mfma_f32_16x16x32_bf16 v[116:119], v[178:181], v[144:147], v[116:119]
	v_mfma_f32_16x16x32_bf16 v[112:115], v[178:181], v[152:155], v[112:115]
	v_mfma_f32_16x16x32_bf16 v[108:111], v[186:189], v[144:147], v[108:111]
	v_mfma_f32_16x16x32_bf16 v[104:107], v[186:189], v[152:155], v[104:107]
	s_waitcnt lgkmcnt(0)
	v_mfma_f32_16x16x32_bf16 v[100:103], v[194:197], v[144:147], v[100:103]
	v_mfma_f32_16x16x32_bf16 v[96:99], v[194:197], v[152:155], v[96:99]
	s_setprio 1
	s_barrier
	s_mov_b32 m0, s19
	s_add_i32 s67, s66, 0xffef7f80
	ds_read_b128 v[198:201], v138
	ds_read_b128 v[202:205], v138 offset:1024
	ds_read_b128 v[206:209], v138 offset:2048
	ds_read_b128 v[210:213], v138 offset:3072
	buffer_load_dwordx4 v136, s[8:11], s67 offen lds
	s_add_i32 s72, s66, 0xfff4ff80
	s_mov_b32 m0, s20
	s_nop 0
	buffer_load_dwordx4 v136, s[8:11], s72 offen lds
	s_barrier
	s_waitcnt lgkmcnt(0)
	s_setprio 0
	s_waitcnt lgkmcnt(3)
	v_mfma_f32_16x16x32_bf16 v[92:95], v[156:159], v[198:201], v[92:95]
	s_waitcnt lgkmcnt(1)
	v_mfma_f32_16x16x32_bf16 v[88:91], v[156:159], v[206:209], v[88:91]
	v_mfma_f32_16x16x32_bf16 v[84:87], v[164:167], v[198:201], v[84:87]
	v_mfma_f32_16x16x32_bf16 v[80:83], v[164:167], v[206:209], v[80:83]
	v_mfma_f32_16x16x32_bf16 v[76:79], v[182:185], v[198:201], v[76:79]
	v_mfma_f32_16x16x32_bf16 v[72:75], v[182:185], v[206:209], v[72:75]
	v_mfma_f32_16x16x32_bf16 v[68:71], v[190:193], v[198:201], v[68:71]
	v_mfma_f32_16x16x32_bf16 v[64:67], v[190:193], v[206:209], v[64:67]
	v_mfma_f32_16x16x32_bf16 v[92:95], v[160:163], v[202:205], v[92:95]
	s_waitcnt lgkmcnt(0)
	v_mfma_f32_16x16x32_bf16 v[88:91], v[160:163], v[210:213], v[88:91]
	v_mfma_f32_16x16x32_bf16 v[84:87], v[178:181], v[202:205], v[84:87]
	v_mfma_f32_16x16x32_bf16 v[80:83], v[178:181], v[210:213], v[80:83]
	v_mfma_f32_16x16x32_bf16 v[76:79], v[186:189], v[202:205], v[76:79]
	v_mfma_f32_16x16x32_bf16 v[72:75], v[186:189], v[210:213], v[72:75]
	v_mfma_f32_16x16x32_bf16 v[68:71], v[194:197], v[202:205], v[68:71]
	v_mfma_f32_16x16x32_bf16 v[64:67], v[194:197], v[210:213], v[64:67]
	s_setprio 1
	s_mov_b32 m0, s18
	s_barrier
	ds_read_b128 v[156:159], v134 offset:16384
	ds_read_b128 v[160:163], v134 offset:17408
	ds_read_b128 v[164:167], v133 offset:16384
	ds_read_b128 v[178:181], v133 offset:17408
	ds_read_b128 v[182:185], v132 offset:16384
	ds_read_b128 v[186:189], v132 offset:17408
	ds_read_b128 v[190:193], v131 offset:16384
	ds_read_b128 v[194:197], v131 offset:17408
	buffer_load_dwordx4 v136, s[4:7], s67 offen lds
	s_mov_b32 m0, s21
	s_nop 0
	buffer_load_dwordx4 v136, s[4:7], s72 offen lds
	s_barrier
	s_waitcnt lgkmcnt(0)
	s_setprio 0
	s_waitcnt lgkmcnt(7)
	v_mfma_f32_16x16x32_bf16 v[60:63], v[156:159], v[140:143], v[60:63]
	v_mfma_f32_16x16x32_bf16 v[56:59], v[156:159], v[148:151], v[56:59]
	s_waitcnt lgkmcnt(5)
	v_mfma_f32_16x16x32_bf16 v[52:55], v[164:167], v[140:143], v[52:55]
	v_mfma_f32_16x16x32_bf16 v[48:51], v[164:167], v[148:151], v[48:51]
	s_waitcnt lgkmcnt(3)
	v_mfma_f32_16x16x32_bf16 v[44:47], v[182:185], v[140:143], v[44:47]
	v_mfma_f32_16x16x32_bf16 v[40:43], v[182:185], v[148:151], v[40:43]
	s_waitcnt lgkmcnt(1)
	v_mfma_f32_16x16x32_bf16 v[36:39], v[190:193], v[140:143], v[36:39]
	v_mfma_f32_16x16x32_bf16 v[32:35], v[190:193], v[148:151], v[32:35]
	v_mfma_f32_16x16x32_bf16 v[60:63], v[160:163], v[144:147], v[60:63]
	v_mfma_f32_16x16x32_bf16 v[56:59], v[160:163], v[152:155], v[56:59]
	v_mfma_f32_16x16x32_bf16 v[52:55], v[178:181], v[144:147], v[52:55]
	v_mfma_f32_16x16x32_bf16 v[48:51], v[178:181], v[152:155], v[48:51]
	v_mfma_f32_16x16x32_bf16 v[44:47], v[186:189], v[144:147], v[44:47]
	v_mfma_f32_16x16x32_bf16 v[40:43], v[186:189], v[152:155], v[40:43]
	s_waitcnt lgkmcnt(0)
	v_mfma_f32_16x16x32_bf16 v[36:39], v[194:197], v[144:147], v[36:39]
	v_mfma_f32_16x16x32_bf16 v[32:35], v[194:197], v[152:155], v[32:35]
	s_setprio 1
	s_barrier
	s_mov_b32 m0, s22
	s_add_i32 s67, s66, 0xfffa7f80
	buffer_load_dwordx4 v136, s[8:11], s67 offen lds
	s_add_i32 s72, s66, 0xffffff80
	s_mov_b32 m0, s23
	s_nop 0
	buffer_load_dwordx4 v136, s[8:11], s72 offen lds
	s_waitcnt vmcnt(6)
	s_barrier
	s_setprio 0
	v_mfma_f32_16x16x32_bf16 v[28:31], v[156:159], v[198:201], v[28:31]
	v_mfma_f32_16x16x32_bf16 v[24:27], v[156:159], v[206:209], v[24:27]
	v_mfma_f32_16x16x32_bf16 v[20:23], v[164:167], v[198:201], v[20:23]
	v_mfma_f32_16x16x32_bf16 v[16:19], v[164:167], v[206:209], v[16:19]
	v_mfma_f32_16x16x32_bf16 v[12:15], v[182:185], v[198:201], v[12:15]
	v_mfma_f32_16x16x32_bf16 v[8:11], v[182:185], v[206:209], v[8:11]
	v_mfma_f32_16x16x32_bf16 v[4:7], v[190:193], v[198:201], v[4:7]
	v_mfma_f32_16x16x32_bf16 v[0:3], v[190:193], v[206:209], v[0:3]
	v_mfma_f32_16x16x32_bf16 v[28:31], v[160:163], v[202:205], v[28:31]
	v_mfma_f32_16x16x32_bf16 v[24:27], v[160:163], v[210:213], v[24:27]
	v_mfma_f32_16x16x32_bf16 v[20:23], v[178:181], v[202:205], v[20:23]
	v_mfma_f32_16x16x32_bf16 v[16:19], v[178:181], v[210:213], v[16:19]
	v_mfma_f32_16x16x32_bf16 v[12:15], v[186:189], v[202:205], v[12:15]
	v_mfma_f32_16x16x32_bf16 v[8:11], v[186:189], v[210:213], v[8:11]
	v_mfma_f32_16x16x32_bf16 v[4:7], v[194:197], v[202:205], v[4:7]
	v_mfma_f32_16x16x32_bf16 v[0:3], v[194:197], v[210:213], v[0:3]
	s_setprio 1
	s_barrier
	ds_read_b128 v[140:143], v137
	ds_read_b128 v[144:147], v137 offset:1024
	ds_read_b128 v[148:151], v137 offset:2048
	ds_read_b128 v[152:155], v137 offset:3072
	s_mov_b32 m0, s53
	ds_read_b128 v[156:159], v134 offset:32768
	ds_read_b128 v[160:163], v134 offset:33792
	ds_read_b128 v[164:167], v133 offset:32768
	ds_read_b128 v[178:181], v133 offset:33792
	ds_read_b128 v[182:185], v132 offset:32768
	ds_read_b128 v[186:189], v132 offset:33792
	ds_read_b128 v[190:193], v131 offset:32768
	ds_read_b128 v[194:197], v131 offset:33792
	buffer_load_dwordx4 v136, s[4:7], s67 offen lds
	s_mov_b32 m0, s56
	s_nop 0
	buffer_load_dwordx4 v136, s[4:7], s72 offen lds
	s_waitcnt lgkmcnt(8)
	s_barrier
	s_waitcnt lgkmcnt(0)
	s_setprio 0
	s_waitcnt lgkmcnt(7)
	v_mfma_f32_16x16x32_bf16 v[124:127], v[156:159], v[140:143], v[124:127]
	v_mfma_f32_16x16x32_bf16 v[120:123], v[156:159], v[148:151], v[120:123]
	s_waitcnt lgkmcnt(5)
	v_mfma_f32_16x16x32_bf16 v[116:119], v[164:167], v[140:143], v[116:119]
	v_mfma_f32_16x16x32_bf16 v[112:115], v[164:167], v[148:151], v[112:115]
	s_waitcnt lgkmcnt(3)
	v_mfma_f32_16x16x32_bf16 v[108:111], v[182:185], v[140:143], v[108:111]
	v_mfma_f32_16x16x32_bf16 v[104:107], v[182:185], v[148:151], v[104:107]
	s_waitcnt lgkmcnt(1)
	v_mfma_f32_16x16x32_bf16 v[100:103], v[190:193], v[140:143], v[100:103]
	v_mfma_f32_16x16x32_bf16 v[96:99], v[190:193], v[148:151], v[96:99]
	v_mfma_f32_16x16x32_bf16 v[124:127], v[160:163], v[144:147], v[124:127]
	v_mfma_f32_16x16x32_bf16 v[120:123], v[160:163], v[152:155], v[120:123]
	v_mfma_f32_16x16x32_bf16 v[116:119], v[178:181], v[144:147], v[116:119]
	v_mfma_f32_16x16x32_bf16 v[112:115], v[178:181], v[152:155], v[112:115]
	v_mfma_f32_16x16x32_bf16 v[108:111], v[186:189], v[144:147], v[108:111]
	v_mfma_f32_16x16x32_bf16 v[104:107], v[186:189], v[152:155], v[104:107]
	s_waitcnt lgkmcnt(0)
	v_mfma_f32_16x16x32_bf16 v[100:103], v[194:197], v[144:147], v[100:103]
	v_mfma_f32_16x16x32_bf16 v[96:99], v[194:197], v[152:155], v[96:99]
	s_setprio 1
	s_barrier
	s_mov_b32 m0, s57
	s_add_i32 s67, s66, 0xffef8000
	ds_read_b128 v[198:201], v135
	ds_read_b128 v[202:205], v135 offset:1024
	ds_read_b128 v[206:209], v135 offset:2048
	ds_read_b128 v[210:213], v135 offset:3072
	buffer_load_dwordx4 v136, s[8:11], s67 offen lds
	s_add_i32 s72, s66, 0xfff50000
	s_mov_b32 m0, s58
	s_nop 0
	buffer_load_dwordx4 v136, s[8:11], s72 offen lds
	s_barrier
	s_waitcnt lgkmcnt(0)
	s_setprio 0
	s_waitcnt lgkmcnt(3)
	v_mfma_f32_16x16x32_bf16 v[92:95], v[156:159], v[198:201], v[92:95]
	s_waitcnt lgkmcnt(1)
	v_mfma_f32_16x16x32_bf16 v[88:91], v[156:159], v[206:209], v[88:91]
	v_mfma_f32_16x16x32_bf16 v[84:87], v[164:167], v[198:201], v[84:87]
	v_mfma_f32_16x16x32_bf16 v[80:83], v[164:167], v[206:209], v[80:83]
	v_mfma_f32_16x16x32_bf16 v[76:79], v[182:185], v[198:201], v[76:79]
	v_mfma_f32_16x16x32_bf16 v[72:75], v[182:185], v[206:209], v[72:75]
	v_mfma_f32_16x16x32_bf16 v[68:71], v[190:193], v[198:201], v[68:71]
	v_mfma_f32_16x16x32_bf16 v[64:67], v[190:193], v[206:209], v[64:67]
	v_mfma_f32_16x16x32_bf16 v[92:95], v[160:163], v[202:205], v[92:95]
	s_waitcnt lgkmcnt(0)
	v_mfma_f32_16x16x32_bf16 v[88:91], v[160:163], v[210:213], v[88:91]
	v_mfma_f32_16x16x32_bf16 v[84:87], v[178:181], v[202:205], v[84:87]
	v_mfma_f32_16x16x32_bf16 v[80:83], v[178:181], v[210:213], v[80:83]
	v_mfma_f32_16x16x32_bf16 v[76:79], v[186:189], v[202:205], v[76:79]
	v_mfma_f32_16x16x32_bf16 v[72:75], v[186:189], v[210:213], v[72:75]
	v_mfma_f32_16x16x32_bf16 v[68:71], v[194:197], v[202:205], v[68:71]
	v_mfma_f32_16x16x32_bf16 v[64:67], v[194:197], v[210:213], v[64:67]
	s_setprio 1
	s_mov_b32 m0, s59
	s_barrier
	ds_read_b128 v[156:159], v134 offset:49152
	ds_read_b128 v[160:163], v134 offset:50176
	ds_read_b128 v[164:167], v133 offset:49152
	ds_read_b128 v[178:181], v133 offset:50176
	ds_read_b128 v[182:185], v132 offset:49152
	ds_read_b128 v[186:189], v132 offset:50176
	ds_read_b128 v[190:193], v131 offset:49152
	ds_read_b128 v[194:197], v131 offset:50176
	buffer_load_dwordx4 v136, s[4:7], s67 offen lds
	s_mov_b32 m0, s61
	s_nop 0
	buffer_load_dwordx4 v136, s[4:7], s72 offen lds
	s_barrier
; #define LDA(dst, b, h)                                                                             \
;   _Pragma("unroll") for (int m = 0; m < 4; ++m) _Pragma("unroll") for (int k = 0; k < 2; ++k)      \
;       dst[m][k] = *reinterpret_cast<const bf16x8*>(SA(b, h) + lds_byte(wr * 64 + m * 16 + fr, k * 32 + fq * 8))
; #define LDB(dst, b, h)                                                                             \
;   _Pragma("unroll") for (int n = 0; n < 2; ++n) _Pragma("unroll") for (int k = 0; k < 2; ++k)      \
;       dst[n][k] = *reinterpret_cast<const bf16x8*>(SB(b, h) + lds_byte(wc * 32 + n * 16 + fr, k * 32 + fq * 8))
; #define WAIT_L(n) asm volatile("s_waitcnt lgkmcnt(" #n ")" ::: "memory")
; #define BAR __builtin_amdgcn_s_barrier()
; template <bool PEEL = false>
; __device__ __forceinline__ void gemm_tile(f32x4 (&acc)[2][2][4][2], const u16* __restrict__ A, int lda,
;                                           const u16* __restrict__ B, int K) {
;     ...
;     LDB(B0, 0, 0); LDA(At, 0, 0); STAGE_A(SA(1, 1), 1, nt - 1);
;     BAR; WAIT_L(0); MMA(0, 0, At, B0); BAR;
;     LDB(B1, 0, 1); BAR; WAIT_L(0); MMA(0, 1, At, B1); BAR;
	s_waitcnt lgkmcnt(0)
	s_setprio 0
	s_waitcnt lgkmcnt(7)
	v_mfma_f32_16x16x32_bf16 v[60:63], v[156:159], v[140:143], v[60:63]
	v_mfma_f32_16x16x32_bf16 v[56:59], v[156:159], v[148:151], v[56:59]
	s_waitcnt lgkmcnt(5)
	v_mfma_f32_16x16x32_bf16 v[52:55], v[164:167], v[140:143], v[52:55]
	v_mfma_f32_16x16x32_bf16 v[48:51], v[164:167], v[148:151], v[48:51]
	s_waitcnt lgkmcnt(3)
	v_mfma_f32_16x16x32_bf16 v[44:47], v[182:185], v[140:143], v[44:47]
	v_mfma_f32_16x16x32_bf16 v[40:43], v[182:185], v[148:151], v[40:43]
	s_waitcnt lgkmcnt(1)
	v_mfma_f32_16x16x32_bf16 v[36:39], v[190:193], v[140:143], v[36:39]
	v_mfma_f32_16x16x32_bf16 v[32:35], v[190:193], v[148:151], v[32:35]
	v_mfma_f32_16x16x32_bf16 v[60:63], v[160:163], v[144:147], v[60:63]
	v_mfma_f32_16x16x32_bf16 v[56:59], v[160:163], v[152:155], v[56:59]
	v_mfma_f32_16x16x32_bf16 v[52:55], v[178:181], v[144:147], v[52:55]
	v_mfma_f32_16x16x32_bf16 v[48:51], v[178:181], v[152:155], v[48:51]
	v_mfma_f32_16x16x32_bf16 v[44:47], v[186:189], v[144:147], v[44:47]
	v_mfma_f32_16x16x32_bf16 v[40:43], v[186:189], v[152:155], v[40:43]
	s_waitcnt lgkmcnt(0)
	v_mfma_f32_16x16x32_bf16 v[36:39], v[194:197], v[144:147], v[36:39]
	v_mfma_f32_16x16x32_bf16 v[32:35], v[194:197], v[152:155], v[32:35]
	s_setprio 1
	s_barrier
	s_add_i32 s67, s66, 0xfffa8000
	s_mov_b32 m0, s63
	s_nop 0
	buffer_load_dwordx4 v136, s[8:11], s67 offen lds
	s_mov_b32 m0, s64
	s_nop 0
	buffer_load_dwordx4 v136, s[8:11], s66 offen lds
	s_waitcnt vmcnt(6)
	s_barrier
	s_setprio 0
	v_mfma_f32_16x16x32_bf16 v[28:31], v[156:159], v[198:201], v[28:31]
	v_mfma_f32_16x16x32_bf16 v[24:27], v[156:159], v[206:209], v[24:27]
	v_mfma_f32_16x16x32_bf16 v[20:23], v[164:167], v[198:201], v[20:23]
	v_mfma_f32_16x16x32_bf16 v[16:19], v[164:167], v[206:209], v[16:19]
	v_mfma_f32_16x16x32_bf16 v[12:15], v[182:185], v[198:201], v[12:15]
	v_mfma_f32_16x16x32_bf16 v[8:11], v[182:185], v[206:209], v[8:11]
	v_mfma_f32_16x16x32_bf16 v[4:7], v[190:193], v[198:201], v[4:7]
	v_mfma_f32_16x16x32_bf16 v[0:3], v[190:193], v[206:209], v[0:3]
	v_mfma_f32_16x16x32_bf16 v[28:31], v[160:163], v[202:205], v[28:31]
	v_mfma_f32_16x16x32_bf16 v[24:27], v[160:163], v[210:213], v[24:27]
	v_mfma_f32_16x16x32_bf16 v[20:23], v[178:181], v[202:205], v[20:23]
	v_mfma_f32_16x16x32_bf16 v[16:19], v[178:181], v[210:213], v[16:19]
	v_mfma_f32_16x16x32_bf16 v[12:15], v[186:189], v[202:205], v[12:15]
	v_mfma_f32_16x16x32_bf16 v[8:11], v[186:189], v[210:213], v[8:11]
	v_mfma_f32_16x16x32_bf16 v[4:7], v[194:197], v[202:205], v[4:7]
	v_mfma_f32_16x16x32_bf16 v[0:3], v[194:197], v[210:213], v[0:3]
	s_setprio 1
	s_add_i32 s65, s65, 2
	s_addk_i32 s66, 0x100
	s_cmp_lt_u32 s65, 40
	s_barrier
	s_cbranch_scc1 .LBB0_460
	s_mov_b32 s6, s10
	s_mov_b32 s7, s11
	s_mov_b32 m0, s62
	ds_read_b128 v[140:143], v139
	ds_read_b128 v[144:147], v139 offset:1024
	ds_read_b128 v[148:151], v139 offset:2048
	ds_read_b128 v[152:155], v139 offset:3072
	ds_read_b128 v[156:159], v134
	ds_read_b128 v[160:163], v134 offset:1024
	ds_read_b128 v[164:167], v133
	ds_read_b128 v[178:181], v133 offset:1024
	ds_read_b128 v[182:185], v132
	ds_read_b128 v[186:189], v132 offset:1024
	ds_read_b128 v[190:193], v131
	ds_read_b128 v[194:197], v131 offset:1024
	buffer_load_dwordx4 v136, s[4:7], s45 offen lds
	s_mov_b32 m0, s60
	s_nop 0
	buffer_load_dwordx4 v136, s[4:7], s46 offen lds
	s_barrier
	s_waitcnt lgkmcnt(0)
	s_setprio 0
	s_waitcnt lgkmcnt(7)
	v_mfma_f32_16x16x32_bf16 v[124:127], v[156:159], v[140:143], v[124:127]
	v_mfma_f32_16x16x32_bf16 v[120:123], v[156:159], v[148:151], v[120:123]
	s_waitcnt lgkmcnt(3)
	v_mfma_f32_16x16x32_bf16 v[108:111], v[182:185], v[140:143], v[108:111]
	v_mfma_f32_16x16x32_bf16 v[104:107], v[182:185], v[148:151], v[104:107]
	v_mfma_f32_16x16x32_bf16 v[124:127], v[160:163], v[144:147], v[124:127]
	v_mfma_f32_16x16x32_bf16 v[120:123], v[160:163], v[152:155], v[120:123]
	v_mfma_f32_16x16x32_bf16 v[116:119], v[164:167], v[140:143], v[116:119]
	v_mfma_f32_16x16x32_bf16 v[112:115], v[164:167], v[148:151], v[112:115]
	s_waitcnt lgkmcnt(2)
	v_mfma_f32_16x16x32_bf16 v[108:111], v[186:189], v[144:147], v[108:111]
	v_mfma_f32_16x16x32_bf16 v[104:107], v[186:189], v[152:155], v[104:107]
	s_waitcnt lgkmcnt(1)
	v_mfma_f32_16x16x32_bf16 v[100:103], v[190:193], v[140:143], v[100:103]
	v_mfma_f32_16x16x32_bf16 v[96:99], v[190:193], v[148:151], v[96:99]
	v_mfma_f32_16x16x32_bf16 v[198:201], v[178:181], v[144:147], v[116:119]
	v_mfma_f32_16x16x32_bf16 v[202:205], v[178:181], v[152:155], v[112:115]
	s_waitcnt lgkmcnt(0)
	v_mfma_f32_16x16x32_bf16 v[206:209], v[194:197], v[144:147], v[100:103]
	v_mfma_f32_16x16x32_bf16 v[210:213], v[194:197], v[152:155], v[96:99]
	s_setprio 1
	s_barrier
	s_nop 0
	ds_read_b128 v[96:99], v138
	ds_read_b128 v[100:103], v138 offset:1024
	ds_read_b128 v[112:115], v138 offset:2048
	ds_read_b128 v[116:119], v138 offset:3072
	s_barrier
	s_waitcnt lgkmcnt(0)
	s_setprio 0
	s_waitcnt lgkmcnt(3)
	v_mfma_f32_16x16x32_bf16 v[92:95], v[156:159], v[96:99], v[92:95]
	s_waitcnt lgkmcnt(1)
	v_mfma_f32_16x16x32_bf16 v[88:91], v[156:159], v[112:115], v[88:91]
	v_mfma_f32_16x16x32_bf16 v[76:79], v[182:185], v[96:99], v[76:79]
	v_mfma_f32_16x16x32_bf16 v[72:75], v[182:185], v[112:115], v[72:75]
	v_mfma_f32_16x16x32_bf16 v[92:95], v[160:163], v[100:103], v[92:95]
	s_waitcnt lgkmcnt(0)
	v_mfma_f32_16x16x32_bf16 v[88:91], v[160:163], v[116:119], v[88:91]
	v_mfma_f32_16x16x32_bf16 v[84:87], v[164:167], v[96:99], v[84:87]
	v_mfma_f32_16x16x32_bf16 v[80:83], v[164:167], v[112:115], v[80:83]
	v_mfma_f32_16x16x32_bf16 v[76:79], v[186:189], v[100:103], v[76:79]
	v_mfma_f32_16x16x32_bf16 v[72:75], v[186:189], v[116:119], v[72:75]
	v_mfma_f32_16x16x32_bf16 v[68:71], v[190:193], v[96:99], v[68:71]
	v_mfma_f32_16x16x32_bf16 v[64:67], v[190:193], v[112:115], v[64:67]
	v_mfma_f32_16x16x32_bf16 v[156:159], v[178:181], v[100:103], v[84:87]
	v_mfma_f32_16x16x32_bf16 v[160:163], v[178:181], v[116:119], v[80:83]
	v_mfma_f32_16x16x32_bf16 v[164:167], v[194:197], v[100:103], v[68:71]
	v_mfma_f32_16x16x32_bf16 v[178:181], v[194:197], v[116:119], v[64:67]
	s_setprio 1
	s_barrier
; #define LDA(dst, b, h)                                                                             \
;   _Pragma("unroll") for (int m = 0; m < 4; ++m) _Pragma("unroll") for (int k = 0; k < 2; ++k)      \
;       dst[m][k] = *reinterpret_cast<const bf16x8*>(SA(b, h) + lds_byte(wr * 64 + m * 16 + fr, k * 32 + fq * 8))
; #define LDB(dst, b, h)                                                                             \
;   _Pragma("unroll") for (int n = 0; n < 2; ++n) _Pragma("unroll") for (int k = 0; k < 2; ++k)      \
;       dst[n][k] = *reinterpret_cast<const bf16x8*>(SB(b, h) + lds_byte(wc * 32 + n * 16 + fr, k * 32 + fq * 8))
; #define WAIT_V(n) asm volatile("s_waitcnt vmcnt(" #n ")" ::: "memory")
; #define WAIT_L(n) asm volatile("s_waitcnt lgkmcnt(" #n ")" ::: "memory")
; #define BAR __builtin_amdgcn_s_barrier()
; template <bool PEEL = false>
; __device__ __forceinline__ void gemm_tile(f32x4 (&acc)[2][2][4][2], const u16* __restrict__ A, int lda,
;                                           const u16* __restrict__ B, int K) {
;     ...
;     LDA(At, 0, 1); WAIT_V(4); BAR; WAIT_L(0); MMA(1, 0, At, B0); MMA(1, 1, At, B1); BAR;
;   }
;   {
;     LDB(B0, 1, 0); LDA(At, 1, 0); WAIT_V(2); BAR; WAIT_L(0); MMA(0, 0, At, B0); BAR;
	s_nop 1
	ds_read_b128 v[64:67], v134 offset:16384
	ds_read_b128 v[68:71], v134 offset:17408
	ds_read_b128 v[80:83], v133 offset:16384
	ds_read_b128 v[84:87], v133 offset:17408
	ds_read_b128 v[182:185], v132 offset:16384
	ds_read_b128 v[186:189], v132 offset:17408
	ds_read_b128 v[190:193], v131 offset:16384
	ds_read_b128 v[194:197], v131 offset:17408
	s_waitcnt vmcnt(4)
	s_barrier
	s_waitcnt lgkmcnt(0)
	s_setprio 0
	s_waitcnt lgkmcnt(7)
	v_mfma_f32_16x16x32_bf16 v[60:63], v[64:67], v[140:143], v[60:63]
	v_mfma_f32_16x16x32_bf16 v[56:59], v[64:67], v[148:151], v[56:59]
	s_waitcnt lgkmcnt(3)
	v_mfma_f32_16x16x32_bf16 v[44:47], v[182:185], v[140:143], v[44:47]
	v_mfma_f32_16x16x32_bf16 v[40:43], v[182:185], v[148:151], v[40:43]
	v_mfma_f32_16x16x32_bf16 v[60:63], v[68:71], v[144:147], v[60:63]
	v_mfma_f32_16x16x32_bf16 v[56:59], v[68:71], v[152:155], v[56:59]
	v_mfma_f32_16x16x32_bf16 v[52:55], v[80:83], v[140:143], v[52:55]
	v_mfma_f32_16x16x32_bf16 v[48:51], v[80:83], v[148:151], v[48:51]
	s_waitcnt lgkmcnt(2)
	v_mfma_f32_16x16x32_bf16 v[44:47], v[186:189], v[144:147], v[44:47]
	v_mfma_f32_16x16x32_bf16 v[40:43], v[186:189], v[152:155], v[40:43]
	s_waitcnt lgkmcnt(1)
	v_mfma_f32_16x16x32_bf16 v[36:39], v[190:193], v[140:143], v[36:39]
	v_mfma_f32_16x16x32_bf16 v[32:35], v[190:193], v[148:151], v[32:35]
	v_mfma_f32_16x16x32_bf16 v[214:217], v[84:87], v[144:147], v[52:55]
	v_mfma_f32_16x16x32_bf16 v[218:221], v[84:87], v[152:155], v[48:51]
	s_waitcnt lgkmcnt(0)
	v_mfma_f32_16x16x32_bf16 v[138:141], v[194:197], v[144:147], v[36:39]
	v_mfma_f32_16x16x32_bf16 v[142:145], v[194:197], v[152:155], v[32:35]
	s_setprio 1
	s_setprio 0
	v_mfma_f32_16x16x32_bf16 v[28:31], v[64:67], v[96:99], v[28:31]
	v_mfma_f32_16x16x32_bf16 v[24:27], v[64:67], v[112:115], v[24:27]
	v_mfma_f32_16x16x32_bf16 v[12:15], v[182:185], v[96:99], v[12:15]
	v_mfma_f32_16x16x32_bf16 v[8:11], v[182:185], v[112:115], v[8:11]
	v_mfma_f32_16x16x32_bf16 v[28:31], v[68:71], v[100:103], v[28:31]
	v_mfma_f32_16x16x32_bf16 v[24:27], v[68:71], v[116:119], v[24:27]
	v_mfma_f32_16x16x32_bf16 v[20:23], v[80:83], v[96:99], v[20:23]
	v_mfma_f32_16x16x32_bf16 v[16:19], v[80:83], v[112:115], v[16:19]
	v_mfma_f32_16x16x32_bf16 v[12:15], v[186:189], v[100:103], v[12:15]
	v_mfma_f32_16x16x32_bf16 v[8:11], v[186:189], v[116:119], v[8:11]
	v_mfma_f32_16x16x32_bf16 v[4:7], v[190:193], v[96:99], v[4:7]
	v_mfma_f32_16x16x32_bf16 v[0:3], v[190:193], v[112:115], v[0:3]
	v_mfma_f32_16x16x32_bf16 v[146:149], v[84:87], v[100:103], v[20:23]
	v_mfma_f32_16x16x32_bf16 v[150:153], v[84:87], v[116:119], v[16:19]
	v_mfma_f32_16x16x32_bf16 v[182:185], v[194:197], v[100:103], v[4:7]
	v_mfma_f32_16x16x32_bf16 v[186:189], v[194:197], v[116:119], v[0:3]
	s_setprio 1
	s_barrier
	s_nop 1
	ds_read_b128 v[0:3], v137
	ds_read_b128 v[4:7], v137 offset:1024
	ds_read_b128 v[190:193], v137 offset:2048
	ds_read_b128 v[194:197], v137 offset:3072
	ds_read_b128 v[16:19], v134 offset:32768
	ds_read_b128 v[20:23], v134 offset:33792
	ds_read_b128 v[32:35], v133 offset:32768
	ds_read_b128 v[36:39], v133 offset:33792
	ds_read_b128 v[48:51], v132 offset:32768
	ds_read_b128 v[52:55], v132 offset:33792
	ds_read_b128 v[222:225], v131 offset:32768
	ds_read_b128 v[226:229], v131 offset:33792
	s_waitcnt vmcnt(2)
	s_barrier
	s_waitcnt lgkmcnt(0)
	s_setprio 0
	s_waitcnt lgkmcnt(7)
	v_mfma_f32_16x16x32_bf16 v[64:67], v[16:19], v[0:3], v[124:127]
	s_waitcnt lgkmcnt(6)
	v_mfma_f32_16x16x32_bf16 v[112:115], v[20:23], v[4:7], v[64:67]
	v_mfma_f32_16x16x32_bf16 v[64:67], v[16:19], v[190:193], v[120:123]
	v_mfma_f32_16x16x32_bf16 v[116:119], v[20:23], v[194:197], v[64:67]
	s_waitcnt lgkmcnt(5)
	v_mfma_f32_16x16x32_bf16 v[64:67], v[32:35], v[0:3], v[198:201]
	s_waitcnt lgkmcnt(4)
	v_mfma_f32_16x16x32_bf16 v[96:99], v[36:39], v[4:7], v[64:67]
	v_mfma_f32_16x16x32_bf16 v[64:67], v[32:35], v[190:193], v[202:205]
	v_mfma_f32_16x16x32_bf16 v[100:103], v[36:39], v[194:197], v[64:67]
	s_waitcnt lgkmcnt(3)
	v_mfma_f32_16x16x32_bf16 v[64:67], v[48:51], v[0:3], v[108:111]
	s_waitcnt lgkmcnt(2)
	v_mfma_f32_16x16x32_bf16 v[80:83], v[52:55], v[4:7], v[64:67]
	v_mfma_f32_16x16x32_bf16 v[64:67], v[48:51], v[190:193], v[104:107]
	v_mfma_f32_16x16x32_bf16 v[84:87], v[52:55], v[194:197], v[64:67]
	s_waitcnt lgkmcnt(1)
	v_mfma_f32_16x16x32_bf16 v[64:67], v[222:225], v[0:3], v[206:209]
	v_mfma_f32_16x16x32_bf16 v[68:71], v[222:225], v[190:193], v[210:213]
	s_waitcnt lgkmcnt(0)
	v_mfma_f32_16x16x32_bf16 v[64:67], v[226:229], v[4:7], v[64:67]
	v_mfma_f32_16x16x32_bf16 v[68:71], v[226:229], v[194:197], v[68:71]
	s_setprio 1
	s_barrier
; #define LDA(dst, b, h)                                                                             \
;   _Pragma("unroll") for (int m = 0; m < 4; ++m) _Pragma("unroll") for (int k = 0; k < 2; ++k)      \
;       dst[m][k] = *reinterpret_cast<const bf16x8*>(SA(b, h) + lds_byte(wr * 64 + m * 16 + fr, k * 32 + fq * 8))
; #define LDB(dst, b, h)                                                                             \
;   _Pragma("unroll") for (int n = 0; n < 2; ++n) _Pragma("unroll") for (int k = 0; k < 2; ++k)      \
;       dst[n][k] = *reinterpret_cast<const bf16x8*>(SB(b, h) + lds_byte(wc * 32 + n * 16 + fr, k * 32 + fq * 8))
; #define WAIT_V(n) asm volatile("s_waitcnt vmcnt(" #n ")" ::: "memory")
; #define WAIT_L(n) asm volatile("s_waitcnt lgkmcnt(" #n ")" ::: "memory")
; #define BAR __builtin_amdgcn_s_barrier()
; template <bool PEEL = false>
; __device__ __forceinline__ void gemm_tile(f32x4 (&acc)[2][2][4][2], const u16* __restrict__ A, int lda,
;                                           const u16* __restrict__ B, int K) {
;     ...
;     LDB(B1, 1, 1); WAIT_V(0); BAR; WAIT_L(0); MMA(0, 1, At, B1); BAR;
;     LDA(At, 1, 1); BAR; WAIT_L(0); MMA(1, 0, At, B0); MMA(1, 1, At, B1); BAR;
;   }
;   if (wr == 0) BAR;
	ds_read_b128 v[198:201], v135
	ds_read_b128 v[202:205], v135 offset:1024
	ds_read_b128 v[206:209], v135 offset:2048
	ds_read_b128 v[210:213], v135 offset:3072
	s_waitcnt vmcnt(0)
	s_barrier
	s_waitcnt lgkmcnt(0)
	s_setprio 0
	s_waitcnt lgkmcnt(3)
	v_mfma_f32_16x16x32_bf16 v[92:95], v[16:19], v[198:201], v[92:95]
	s_waitcnt lgkmcnt(1)
	v_mfma_f32_16x16x32_bf16 v[16:19], v[16:19], v[206:209], v[88:91]
	s_waitcnt lgkmcnt(0)
	v_mfma_f32_16x16x32_bf16 v[124:127], v[20:23], v[210:213], v[16:19]
	v_mfma_f32_16x16x32_bf16 v[16:19], v[32:35], v[198:201], v[156:159]
	v_mfma_f32_16x16x32_bf16 v[104:107], v[36:39], v[202:205], v[16:19]
	v_mfma_f32_16x16x32_bf16 v[16:19], v[32:35], v[206:209], v[160:163]
	v_mfma_f32_16x16x32_bf16 v[108:111], v[36:39], v[210:213], v[16:19]
	v_mfma_f32_16x16x32_bf16 v[16:19], v[48:51], v[198:201], v[76:79]
	v_mfma_f32_16x16x32_bf16 v[88:91], v[52:55], v[202:205], v[16:19]
	v_mfma_f32_16x16x32_bf16 v[16:19], v[48:51], v[206:209], v[72:75]
	v_mfma_f32_16x16x32_bf16 v[120:123], v[20:23], v[202:205], v[92:95]
	v_mfma_f32_16x16x32_bf16 v[92:95], v[52:55], v[210:213], v[16:19]
	v_mfma_f32_16x16x32_bf16 v[16:19], v[222:225], v[198:201], v[164:167]
	v_mfma_f32_16x16x32_bf16 v[72:75], v[226:229], v[202:205], v[16:19]
	v_mfma_f32_16x16x32_bf16 v[16:19], v[222:225], v[206:209], v[178:181]
	v_mfma_f32_16x16x32_bf16 v[76:79], v[226:229], v[210:213], v[16:19]
	s_setprio 1
	s_barrier
	ds_read_b128 v[154:157], v134 offset:49152
	ds_read_b128 v[134:137], v134 offset:50176
	ds_read_b128 v[158:161], v133 offset:49152
	ds_read_b128 v[162:165], v133 offset:50176
	ds_read_b128 v[166:169], v132 offset:49152
	ds_read_b128 v[178:181], v132 offset:50176
	ds_read_b128 v[222:225], v131 offset:49152
	ds_read_b128 v[226:229], v131 offset:50176
	s_barrier
	s_waitcnt lgkmcnt(0)
	s_setprio 0
	s_waitcnt lgkmcnt(7)
	v_mfma_f32_16x16x32_bf16 v[16:19], v[154:157], v[0:3], v[60:63]
	s_waitcnt lgkmcnt(6)
	v_mfma_f32_16x16x32_bf16 v[48:51], v[134:137], v[4:7], v[16:19]
	v_mfma_f32_16x16x32_bf16 v[16:19], v[154:157], v[190:193], v[56:59]
	v_mfma_f32_16x16x32_bf16 v[52:55], v[134:137], v[194:197], v[16:19]
	s_waitcnt lgkmcnt(5)
	v_mfma_f32_16x16x32_bf16 v[16:19], v[158:161], v[0:3], v[214:217]
	s_waitcnt lgkmcnt(4)
	v_mfma_f32_16x16x32_bf16 v[32:35], v[162:165], v[4:7], v[16:19]
	v_mfma_f32_16x16x32_bf16 v[16:19], v[158:161], v[190:193], v[218:221]
	v_mfma_f32_16x16x32_bf16 v[36:39], v[162:165], v[194:197], v[16:19]
	s_waitcnt lgkmcnt(3)
	v_mfma_f32_16x16x32_bf16 v[16:19], v[166:169], v[0:3], v[44:47]
	s_waitcnt lgkmcnt(1)
	v_mfma_f32_16x16x32_bf16 v[0:3], v[222:225], v[0:3], v[138:141]
	v_mfma_f32_16x16x32_bf16 v[16:19], v[178:181], v[4:7], v[16:19]
	v_mfma_f32_16x16x32_bf16 v[20:23], v[166:169], v[190:193], v[40:43]
	s_waitcnt lgkmcnt(0)
	v_mfma_f32_16x16x32_bf16 v[0:3], v[226:229], v[4:7], v[0:3]
	v_mfma_f32_16x16x32_bf16 v[4:7], v[222:225], v[190:193], v[142:145]
	v_mfma_f32_16x16x32_bf16 v[20:23], v[178:181], v[194:197], v[20:23]
	v_mfma_f32_16x16x32_bf16 v[4:7], v[226:229], v[194:197], v[4:7]
	s_setprio 1
	s_setprio 0
	v_mfma_f32_16x16x32_bf16 v[24:27], v[154:157], v[206:209], v[24:27]
	v_mfma_f32_16x16x32_bf16 v[60:63], v[134:137], v[210:213], v[24:27]
	v_mfma_f32_16x16x32_bf16 v[24:27], v[158:161], v[198:201], v[146:149]
	v_mfma_f32_16x16x32_bf16 v[28:31], v[154:157], v[198:201], v[28:31]
	v_mfma_f32_16x16x32_bf16 v[40:43], v[162:165], v[202:205], v[24:27]
	v_mfma_f32_16x16x32_bf16 v[24:27], v[158:161], v[206:209], v[150:153]
	v_mfma_f32_16x16x32_bf16 v[12:15], v[166:169], v[198:201], v[12:15]
	v_mfma_f32_16x16x32_bf16 v[8:11], v[166:169], v[206:209], v[8:11]
	v_mfma_f32_16x16x32_bf16 v[56:59], v[134:137], v[202:205], v[28:31]
	v_mfma_f32_16x16x32_bf16 v[44:47], v[162:165], v[210:213], v[24:27]
	v_mfma_f32_16x16x32_bf16 v[24:27], v[178:181], v[202:205], v[12:15]
	v_mfma_f32_16x16x32_bf16 v[28:31], v[178:181], v[210:213], v[8:11]
	v_mfma_f32_16x16x32_bf16 v[8:11], v[222:225], v[198:201], v[182:185]
	v_mfma_f32_16x16x32_bf16 v[12:15], v[222:225], v[206:209], v[186:189]
	v_mfma_f32_16x16x32_bf16 v[8:11], v[226:229], v[202:205], v[8:11]
	v_mfma_f32_16x16x32_bf16 v[12:15], v[226:229], v[210:213], v[12:15]
	s_setprio 1
	v_cmp_gt_u32_e32 vcc, s25, v130
	s_barrier
	s_and_saveexec_b64 s[4:5], vcc
	s_cbranch_execz .LBB0_463
	s_barrier
